# E17: MFMA order in each 32-segment k,m,(Bhalf,n): A-fragment operand stationary for 4 consecutive MFMAs; bitwise same math; on N5 base
# baseline (speedup 1.0000x reference)
.LBB0_303:
	s_lshl_b32 s18, s91, 20
	s_and_b64 s[8:9], s[34:35], exec
	s_cselect_b32 s8, s18, s94
	s_lshl_b32 s19, s90, 20
	s_and_b64 s[42:43], s[34:35], exec
	s_cselect_b32 s9, s19, s95
	s_add_i32 s94, s94, 0x80080
	s_addk_i32 s95, 0x100
	s_mov_b32 vcc_lo, -2
	ds_read_b128 v[142:145], v136
	ds_read_b128 v[170:173], v136 offset:1024
	ds_read_b128 v[174:177], v136 offset:2048
	ds_read_b128 v[178:181], v136 offset:3072
	ds_read_b128 v[182:185], v137
	ds_read_b128 v[186:189], v137 offset:1024
	ds_read_b128 v[190:193], v137 offset:2048
	ds_read_b128 v[194:197], v137 offset:3072
	s_add_i32 s42, s94, 0xfff80080
	s_cmp_eq_u32 vcc_lo, 28
	s_cselect_b32 s97, s8, s42
	s_cselect_b32 s52, s9, s95
	s_or_b32 vcc_hi, s97, 0x80
	s_mov_b32 m0, s72
	ds_read_b128 v[198:201], v138
	ds_read_b128 v[202:205], v138 offset:1024
	ds_read_b128 v[228:231], v138 offset:2048
	ds_read_b128 v[232:235], v138 offset:3072
	ds_read_b128 v[236:239], v138 offset:4096
	ds_read_b128 v[240:243], v138 offset:5120
	ds_read_b128 v[244:247], v138 offset:6144
	ds_read_b128 v[248:251], v138 offset:7168
	buffer_load_dwordx4 v132, s[60:63], s94 offen lds
	s_mov_b32 m0, s47
	s_nop 0
	buffer_load_dwordx4 v134, s[60:63], s94 offen lds
	s_waitcnt vmcnt(8)
	s_waitcnt lgkmcnt(0)
	s_setprio 1
	s_barrier
	v_mfma_f32_16x16x32_bf16 v[114:117], v[142:145], v[198:201], 0
	v_mfma_f32_16x16x32_bf16 v[110:113], v[174:177], v[198:201], 0
	v_mfma_f32_16x16x32_bf16 v[126:129], v[182:185], v[198:201], 0
	v_mfma_f32_16x16x32_bf16 v[122:125], v[190:193], v[198:201], 0
	v_mfma_f32_16x16x32_bf16 v[106:109], v[142:145], v[228:231], 0
	v_mfma_f32_16x16x32_bf16 v[102:105], v[174:177], v[228:231], 0
	v_mfma_f32_16x16x32_bf16 v[118:121], v[182:185], v[228:231], 0
	v_mfma_f32_16x16x32_bf16 v[98:101], v[190:193], v[228:231], 0
	v_mfma_f32_16x16x32_bf16 v[94:97], v[142:145], v[236:239], 0
	v_mfma_f32_16x16x32_bf16 v[86:89], v[174:177], v[236:239], 0
	v_mfma_f32_16x16x32_bf16 v[90:93], v[182:185], v[236:239], 0
	v_mfma_f32_16x16x32_bf16 v[82:85], v[190:193], v[236:239], 0
	v_mfma_f32_16x16x32_bf16 v[78:81], v[142:145], v[244:247], 0
	v_mfma_f32_16x16x32_bf16 v[70:73], v[174:177], v[244:247], 0
	v_mfma_f32_16x16x32_bf16 v[74:77], v[182:185], v[244:247], 0
	v_mfma_f32_16x16x32_bf16 v[66:69], v[190:193], v[244:247], 0
	v_mfma_f32_16x16x32_bf16 v[114:117], v[170:173], v[202:205], v[114:117]
	v_mfma_f32_16x16x32_bf16 v[110:113], v[178:181], v[202:205], v[110:113]
	v_mfma_f32_16x16x32_bf16 v[126:129], v[186:189], v[202:205], v[126:129]
	v_mfma_f32_16x16x32_bf16 v[122:125], v[194:197], v[202:205], v[122:125]
	v_mfma_f32_16x16x32_bf16 v[106:109], v[170:173], v[232:235], v[106:109]
	v_mfma_f32_16x16x32_bf16 v[102:105], v[178:181], v[232:235], v[102:105]
	v_mfma_f32_16x16x32_bf16 v[118:121], v[186:189], v[232:235], v[118:121]
	v_mfma_f32_16x16x32_bf16 v[98:101], v[194:197], v[232:235], v[98:101]
	v_mfma_f32_16x16x32_bf16 v[94:97], v[170:173], v[240:243], v[94:97]
	v_mfma_f32_16x16x32_bf16 v[86:89], v[178:181], v[240:243], v[86:89]
	v_mfma_f32_16x16x32_bf16 v[90:93], v[186:189], v[240:243], v[90:93]
	v_mfma_f32_16x16x32_bf16 v[82:85], v[194:197], v[240:243], v[82:85]
	v_mfma_f32_16x16x32_bf16 v[78:81], v[170:173], v[248:251], v[78:81]
	v_mfma_f32_16x16x32_bf16 v[70:73], v[178:181], v[248:251], v[70:73]
	v_mfma_f32_16x16x32_bf16 v[74:77], v[186:189], v[248:251], v[74:77]
	v_mfma_f32_16x16x32_bf16 v[66:69], v[194:197], v[248:251], v[66:69]
	s_barrier
	s_setprio 0
	s_mov_b32 m0, s13
	s_mov_b32 s42, s62
	s_mov_b32 s43, s63
	ds_read_b128 v[198:201], v138 offset:16384
	ds_read_b128 v[202:205], v138 offset:17408
	ds_read_b128 v[228:231], v138 offset:18432
	ds_read_b128 v[232:235], v138 offset:19456
	ds_read_b128 v[236:239], v138 offset:20480
	ds_read_b128 v[240:243], v138 offset:21504
	ds_read_b128 v[244:247], v138 offset:22528
	ds_read_b128 v[248:251], v138 offset:23552
	buffer_load_dwordx4 v133, s[40:43], s52 offen lds
	s_mov_b32 m0, s14
	s_add_i32 s96, s52, 0x80000
	buffer_load_dwordx4 v135, s[40:43], s52 offen lds
	s_mov_b32 m0, s15
	s_nop 0
	buffer_load_dwordx4 v133, s[40:43], s96 offen lds
	s_mov_b32 m0, s16
	s_nop 0
	buffer_load_dwordx4 v135, s[40:43], s96 offen lds
	s_mov_b32 m0, s2
	s_nop 0
	buffer_load_dwordx4 v132, s[60:63], s97 offen lds
	s_mov_b32 m0, s21
	s_nop 0
	buffer_load_dwordx4 v134, s[60:63], s97 offen lds
	s_waitcnt vmcnt(8)
	s_waitcnt lgkmcnt(0)
	s_setprio 1
	s_barrier
	v_mfma_f32_16x16x32_bf16 v[62:65], v[142:145], v[198:201], 0
	v_mfma_f32_16x16x32_bf16 v[54:57], v[174:177], v[198:201], 0
	v_mfma_f32_16x16x32_bf16 v[58:61], v[182:185], v[198:201], 0
	v_mfma_f32_16x16x32_bf16 v[50:53], v[190:193], v[198:201], 0
	v_mfma_f32_16x16x32_bf16 v[46:49], v[142:145], v[228:231], 0
	v_mfma_f32_16x16x32_bf16 v[38:41], v[174:177], v[228:231], 0
	v_mfma_f32_16x16x32_bf16 v[42:45], v[182:185], v[228:231], 0
	v_mfma_f32_16x16x32_bf16 v[34:37], v[190:193], v[228:231], 0
	v_mfma_f32_16x16x32_bf16 v[30:33], v[142:145], v[236:239], 0
	v_mfma_f32_16x16x32_bf16 v[22:25], v[174:177], v[236:239], 0
	v_mfma_f32_16x16x32_bf16 v[26:29], v[182:185], v[236:239], 0
	v_mfma_f32_16x16x32_bf16 v[18:21], v[190:193], v[236:239], 0
	v_mfma_f32_16x16x32_bf16 v[14:17], v[142:145], v[244:247], 0
	v_mfma_f32_16x16x32_bf16 v[6:9], v[174:177], v[244:247], 0
	v_mfma_f32_16x16x32_bf16 v[10:13], v[182:185], v[244:247], 0
	v_mfma_f32_16x16x32_bf16 v[2:5], v[190:193], v[244:247], 0
	v_mfma_f32_16x16x32_bf16 v[62:65], v[170:173], v[202:205], v[62:65]
	v_mfma_f32_16x16x32_bf16 v[54:57], v[178:181], v[202:205], v[54:57]
	v_mfma_f32_16x16x32_bf16 v[58:61], v[186:189], v[202:205], v[58:61]
	v_mfma_f32_16x16x32_bf16 v[50:53], v[194:197], v[202:205], v[50:53]
	v_mfma_f32_16x16x32_bf16 v[46:49], v[170:173], v[232:235], v[46:49]
	v_mfma_f32_16x16x32_bf16 v[38:41], v[178:181], v[232:235], v[38:41]
	v_mfma_f32_16x16x32_bf16 v[42:45], v[186:189], v[232:235], v[42:45]
	v_mfma_f32_16x16x32_bf16 v[34:37], v[194:197], v[232:235], v[34:37]
	v_mfma_f32_16x16x32_bf16 v[30:33], v[170:173], v[240:243], v[30:33]
	v_mfma_f32_16x16x32_bf16 v[22:25], v[178:181], v[240:243], v[22:25]
	v_mfma_f32_16x16x32_bf16 v[26:29], v[186:189], v[240:243], v[26:29]
	v_mfma_f32_16x16x32_bf16 v[18:21], v[194:197], v[240:243], v[18:21]
	v_mfma_f32_16x16x32_bf16 v[14:17], v[170:173], v[248:251], v[14:17]
	v_mfma_f32_16x16x32_bf16 v[6:9], v[178:181], v[248:251], v[6:9]
	v_mfma_f32_16x16x32_bf16 v[10:13], v[186:189], v[248:251], v[10:13]
	v_mfma_f32_16x16x32_bf16 v[2:5], v[194:197], v[248:251], v[2:5]
	s_barrier
	s_setprio 0
	ds_read_b128 v[142:145], v139
	ds_read_b128 v[170:173], v139 offset:1024
	ds_read_b128 v[174:177], v139 offset:2048
	ds_read_b128 v[178:181], v139 offset:3072
	ds_read_b128 v[182:185], v140
	ds_read_b128 v[186:189], v140 offset:1024
	ds_read_b128 v[190:193], v140 offset:2048
	ds_read_b128 v[194:197], v140 offset:3072
	s_add_i32 s97, s97, 0x80000
	s_mov_b32 m0, s23
	ds_read_b128 v[198:201], v138 offset:32768
	ds_read_b128 v[202:205], v138 offset:33792
	ds_read_b128 v[228:231], v138 offset:34816
	ds_read_b128 v[232:235], v138 offset:35840
	ds_read_b128 v[236:239], v138 offset:36864
	ds_read_b128 v[240:243], v138 offset:37888
	ds_read_b128 v[244:247], v138 offset:38912
	ds_read_b128 v[248:251], v138 offset:39936
	buffer_load_dwordx4 v132, s[60:63], s97 offen lds
	s_mov_b32 m0, s24
	s_nop 0
	buffer_load_dwordx4 v134, s[60:63], s97 offen lds
	s_waitcnt vmcnt(8)
	s_waitcnt lgkmcnt(0)
	s_setprio 1
	s_barrier
	v_mfma_f32_16x16x32_bf16 v[114:117], v[142:145], v[198:201], v[114:117]
	v_mfma_f32_16x16x32_bf16 v[110:113], v[174:177], v[198:201], v[110:113]
	v_mfma_f32_16x16x32_bf16 v[126:129], v[182:185], v[198:201], v[126:129]
	v_mfma_f32_16x16x32_bf16 v[122:125], v[190:193], v[198:201], v[122:125]
	v_mfma_f32_16x16x32_bf16 v[106:109], v[142:145], v[228:231], v[106:109]
	v_mfma_f32_16x16x32_bf16 v[102:105], v[174:177], v[228:231], v[102:105]
	v_mfma_f32_16x16x32_bf16 v[118:121], v[182:185], v[228:231], v[118:121]
	v_mfma_f32_16x16x32_bf16 v[98:101], v[190:193], v[228:231], v[98:101]
	v_mfma_f32_16x16x32_bf16 v[94:97], v[142:145], v[236:239], v[94:97]
	v_mfma_f32_16x16x32_bf16 v[86:89], v[174:177], v[236:239], v[86:89]
	v_mfma_f32_16x16x32_bf16 v[90:93], v[182:185], v[236:239], v[90:93]
	v_mfma_f32_16x16x32_bf16 v[82:85], v[190:193], v[236:239], v[82:85]
	v_mfma_f32_16x16x32_bf16 v[78:81], v[142:145], v[244:247], v[78:81]
	v_mfma_f32_16x16x32_bf16 v[70:73], v[174:177], v[244:247], v[70:73]
	v_mfma_f32_16x16x32_bf16 v[74:77], v[182:185], v[244:247], v[74:77]
	v_mfma_f32_16x16x32_bf16 v[66:69], v[190:193], v[244:247], v[66:69]
	v_mfma_f32_16x16x32_bf16 v[114:117], v[170:173], v[202:205], v[114:117]
	v_mfma_f32_16x16x32_bf16 v[110:113], v[178:181], v[202:205], v[110:113]
	v_mfma_f32_16x16x32_bf16 v[126:129], v[186:189], v[202:205], v[126:129]
	v_mfma_f32_16x16x32_bf16 v[122:125], v[194:197], v[202:205], v[122:125]
	v_mfma_f32_16x16x32_bf16 v[106:109], v[170:173], v[232:235], v[106:109]
	v_mfma_f32_16x16x32_bf16 v[102:105], v[178:181], v[232:235], v[102:105]
	v_mfma_f32_16x16x32_bf16 v[118:121], v[186:189], v[232:235], v[118:121]
	v_mfma_f32_16x16x32_bf16 v[98:101], v[194:197], v[232:235], v[98:101]
	v_mfma_f32_16x16x32_bf16 v[94:97], v[170:173], v[240:243], v[94:97]
	v_mfma_f32_16x16x32_bf16 v[86:89], v[178:181], v[240:243], v[86:89]
	v_mfma_f32_16x16x32_bf16 v[90:93], v[186:189], v[240:243], v[90:93]
	v_mfma_f32_16x16x32_bf16 v[82:85], v[194:197], v[240:243], v[82:85]
	v_mfma_f32_16x16x32_bf16 v[78:81], v[170:173], v[248:251], v[78:81]
	v_mfma_f32_16x16x32_bf16 v[70:73], v[178:181], v[248:251], v[70:73]
	v_mfma_f32_16x16x32_bf16 v[74:77], v[186:189], v[248:251], v[74:77]
	v_mfma_f32_16x16x32_bf16 v[66:69], v[194:197], v[248:251], v[66:69]
	s_barrier
	s_setprio 0
	s_mov_b32 m0, s31
	s_or_b32 s53, s52, 0x80
	ds_read_b128 v[198:201], v138 offset:49152
	ds_read_b128 v[202:205], v138 offset:50176
	ds_read_b128 v[228:231], v138 offset:51200
	ds_read_b128 v[232:235], v138 offset:52224
	ds_read_b128 v[236:239], v138 offset:53248
	ds_read_b128 v[240:243], v138 offset:54272
	ds_read_b128 v[244:247], v138 offset:55296
	ds_read_b128 v[248:251], v138 offset:56320
	buffer_load_dwordx4 v133, s[40:43], s53 offen lds
	s_mov_b32 m0, s33
	s_add_i32 s52, s52, 0x80080
	buffer_load_dwordx4 v135, s[40:43], s53 offen lds
	s_mov_b32 m0, s68
	s_nop 0
	buffer_load_dwordx4 v133, s[40:43], s52 offen lds
	s_mov_b32 m0, s69
	s_nop 0
	buffer_load_dwordx4 v135, s[40:43], s52 offen lds
	s_mov_b32 m0, s36
	s_nop 0
	buffer_load_dwordx4 v132, s[60:63], vcc_hi offen lds
	s_mov_b32 m0, s37
	s_nop 0
	buffer_load_dwordx4 v134, s[60:63], vcc_hi offen lds
	s_waitcnt vmcnt(8)
	s_waitcnt lgkmcnt(0)
	s_setprio 1
	s_barrier
	v_mfma_f32_16x16x32_bf16 v[62:65], v[142:145], v[198:201], v[62:65]
	v_mfma_f32_16x16x32_bf16 v[54:57], v[174:177], v[198:201], v[54:57]
	v_mfma_f32_16x16x32_bf16 v[58:61], v[182:185], v[198:201], v[58:61]
	v_mfma_f32_16x16x32_bf16 v[50:53], v[190:193], v[198:201], v[50:53]
	v_mfma_f32_16x16x32_bf16 v[46:49], v[142:145], v[228:231], v[46:49]
	v_mfma_f32_16x16x32_bf16 v[38:41], v[174:177], v[228:231], v[38:41]
	v_mfma_f32_16x16x32_bf16 v[42:45], v[182:185], v[228:231], v[42:45]
	v_mfma_f32_16x16x32_bf16 v[34:37], v[190:193], v[228:231], v[34:37]
	v_mfma_f32_16x16x32_bf16 v[30:33], v[142:145], v[236:239], v[30:33]
	v_mfma_f32_16x16x32_bf16 v[22:25], v[174:177], v[236:239], v[22:25]
	v_mfma_f32_16x16x32_bf16 v[26:29], v[182:185], v[236:239], v[26:29]
	v_mfma_f32_16x16x32_bf16 v[18:21], v[190:193], v[236:239], v[18:21]
	v_mfma_f32_16x16x32_bf16 v[14:17], v[142:145], v[244:247], v[14:17]
	v_mfma_f32_16x16x32_bf16 v[6:9], v[174:177], v[244:247], v[6:9]
	v_mfma_f32_16x16x32_bf16 v[10:13], v[182:185], v[244:247], v[10:13]
	v_mfma_f32_16x16x32_bf16 v[2:5], v[190:193], v[244:247], v[2:5]
	v_mfma_f32_16x16x32_bf16 v[62:65], v[170:173], v[202:205], v[62:65]
	v_mfma_f32_16x16x32_bf16 v[54:57], v[178:181], v[202:205], v[54:57]
	v_mfma_f32_16x16x32_bf16 v[58:61], v[186:189], v[202:205], v[58:61]
	v_mfma_f32_16x16x32_bf16 v[50:53], v[194:197], v[202:205], v[50:53]
	v_mfma_f32_16x16x32_bf16 v[46:49], v[170:173], v[232:235], v[46:49]
	v_mfma_f32_16x16x32_bf16 v[38:41], v[178:181], v[232:235], v[38:41]
	v_mfma_f32_16x16x32_bf16 v[42:45], v[186:189], v[232:235], v[42:45]
	v_mfma_f32_16x16x32_bf16 v[34:37], v[194:197], v[232:235], v[34:37]
	v_mfma_f32_16x16x32_bf16 v[30:33], v[170:173], v[240:243], v[30:33]
	v_mfma_f32_16x16x32_bf16 v[22:25], v[178:181], v[240:243], v[22:25]
	v_mfma_f32_16x16x32_bf16 v[26:29], v[186:189], v[240:243], v[26:29]
	v_mfma_f32_16x16x32_bf16 v[18:21], v[194:197], v[240:243], v[18:21]
	v_mfma_f32_16x16x32_bf16 v[14:17], v[170:173], v[248:251], v[14:17]
	v_mfma_f32_16x16x32_bf16 v[6:9], v[178:181], v[248:251], v[6:9]
	v_mfma_f32_16x16x32_bf16 v[10:13], v[186:189], v[248:251], v[10:13]
	v_mfma_f32_16x16x32_bf16 v[2:5], v[194:197], v[248:251], v[2:5]
	s_barrier
	s_setprio 0
	s_add_i32 vcc_lo, vcc_lo, 2
	s_addk_i32 s94, 0x100
	s_addk_i32 s95, 0x100
	s_cmp_gt_u32 vcc_lo, 29
.LBB0_304:
	ds_read_b128 v[142:145], v136
	ds_read_b128 v[170:173], v136 offset:1024
	ds_read_b128 v[174:177], v136 offset:2048
	ds_read_b128 v[178:181], v136 offset:3072
	ds_read_b128 v[182:185], v137
	ds_read_b128 v[186:189], v137 offset:1024
	ds_read_b128 v[190:193], v137 offset:2048
	ds_read_b128 v[194:197], v137 offset:3072
	s_add_i32 s42, s94, 0xfff80080
	s_cmp_eq_u32 vcc_lo, 28
	s_cselect_b32 s97, s8, s42
	s_cselect_b32 s52, s9, s95
	s_or_b32 vcc_hi, s97, 0x80
	s_mov_b32 m0, s72
	ds_read_b128 v[198:201], v138
	ds_read_b128 v[202:205], v138 offset:1024
	ds_read_b128 v[228:231], v138 offset:2048
	ds_read_b128 v[232:235], v138 offset:3072
	ds_read_b128 v[236:239], v138 offset:4096
	ds_read_b128 v[240:243], v138 offset:5120
	ds_read_b128 v[244:247], v138 offset:6144
	ds_read_b128 v[248:251], v138 offset:7168
	buffer_load_dwordx4 v132, s[60:63], s94 offen lds
	s_mov_b32 m0, s47
	s_nop 0
	buffer_load_dwordx4 v134, s[60:63], s94 offen lds
	s_waitcnt vmcnt(8)
	s_waitcnt lgkmcnt(0)
	s_setprio 1
	s_barrier
	v_mfma_f32_16x16x32_bf16 v[114:117], v[142:145], v[198:201], v[114:117]
	v_mfma_f32_16x16x32_bf16 v[110:113], v[174:177], v[198:201], v[110:113]
	v_mfma_f32_16x16x32_bf16 v[126:129], v[182:185], v[198:201], v[126:129]
	v_mfma_f32_16x16x32_bf16 v[122:125], v[190:193], v[198:201], v[122:125]
	v_mfma_f32_16x16x32_bf16 v[106:109], v[142:145], v[228:231], v[106:109]
	v_mfma_f32_16x16x32_bf16 v[102:105], v[174:177], v[228:231], v[102:105]
	v_mfma_f32_16x16x32_bf16 v[118:121], v[182:185], v[228:231], v[118:121]
	v_mfma_f32_16x16x32_bf16 v[98:101], v[190:193], v[228:231], v[98:101]
	v_mfma_f32_16x16x32_bf16 v[94:97], v[142:145], v[236:239], v[94:97]
	v_mfma_f32_16x16x32_bf16 v[86:89], v[174:177], v[236:239], v[86:89]
	v_mfma_f32_16x16x32_bf16 v[90:93], v[182:185], v[236:239], v[90:93]
	v_mfma_f32_16x16x32_bf16 v[82:85], v[190:193], v[236:239], v[82:85]
	v_mfma_f32_16x16x32_bf16 v[78:81], v[142:145], v[244:247], v[78:81]
	v_mfma_f32_16x16x32_bf16 v[70:73], v[174:177], v[244:247], v[70:73]
	v_mfma_f32_16x16x32_bf16 v[74:77], v[182:185], v[244:247], v[74:77]
	v_mfma_f32_16x16x32_bf16 v[66:69], v[190:193], v[244:247], v[66:69]
	v_mfma_f32_16x16x32_bf16 v[114:117], v[170:173], v[202:205], v[114:117]
	v_mfma_f32_16x16x32_bf16 v[110:113], v[178:181], v[202:205], v[110:113]
	v_mfma_f32_16x16x32_bf16 v[126:129], v[186:189], v[202:205], v[126:129]
	v_mfma_f32_16x16x32_bf16 v[122:125], v[194:197], v[202:205], v[122:125]
	v_mfma_f32_16x16x32_bf16 v[106:109], v[170:173], v[232:235], v[106:109]
	v_mfma_f32_16x16x32_bf16 v[102:105], v[178:181], v[232:235], v[102:105]
	v_mfma_f32_16x16x32_bf16 v[118:121], v[186:189], v[232:235], v[118:121]
	v_mfma_f32_16x16x32_bf16 v[98:101], v[194:197], v[232:235], v[98:101]
	v_mfma_f32_16x16x32_bf16 v[94:97], v[170:173], v[240:243], v[94:97]
	v_mfma_f32_16x16x32_bf16 v[86:89], v[178:181], v[240:243], v[86:89]
	v_mfma_f32_16x16x32_bf16 v[90:93], v[186:189], v[240:243], v[90:93]
	v_mfma_f32_16x16x32_bf16 v[82:85], v[194:197], v[240:243], v[82:85]
	v_mfma_f32_16x16x32_bf16 v[78:81], v[170:173], v[248:251], v[78:81]
	v_mfma_f32_16x16x32_bf16 v[70:73], v[178:181], v[248:251], v[70:73]
	v_mfma_f32_16x16x32_bf16 v[74:77], v[186:189], v[248:251], v[74:77]
	v_mfma_f32_16x16x32_bf16 v[66:69], v[194:197], v[248:251], v[66:69]
	s_barrier
	s_setprio 0
	s_mov_b32 m0, s13
	s_mov_b32 s42, s62
	s_mov_b32 s43, s63
	ds_read_b128 v[198:201], v138 offset:16384
	ds_read_b128 v[202:205], v138 offset:17408
	ds_read_b128 v[228:231], v138 offset:18432
	ds_read_b128 v[232:235], v138 offset:19456
	ds_read_b128 v[236:239], v138 offset:20480
	ds_read_b128 v[240:243], v138 offset:21504
	ds_read_b128 v[244:247], v138 offset:22528
	ds_read_b128 v[248:251], v138 offset:23552
	buffer_load_dwordx4 v133, s[40:43], s52 offen lds
	s_mov_b32 m0, s14
	s_add_i32 s96, s52, 0x80000
	buffer_load_dwordx4 v135, s[40:43], s52 offen lds
	s_mov_b32 m0, s15
	s_nop 0
	buffer_load_dwordx4 v133, s[40:43], s96 offen lds
	s_mov_b32 m0, s16
	s_nop 0
	buffer_load_dwordx4 v135, s[40:43], s96 offen lds
	s_mov_b32 m0, s2
	s_nop 0
	buffer_load_dwordx4 v132, s[60:63], s97 offen lds
	s_mov_b32 m0, s21
	s_nop 0
	buffer_load_dwordx4 v134, s[60:63], s97 offen lds
	s_waitcnt vmcnt(8)
	s_waitcnt lgkmcnt(0)
	s_setprio 1
	s_barrier
	v_mfma_f32_16x16x32_bf16 v[62:65], v[142:145], v[198:201], v[62:65]
	v_mfma_f32_16x16x32_bf16 v[54:57], v[174:177], v[198:201], v[54:57]
	v_mfma_f32_16x16x32_bf16 v[58:61], v[182:185], v[198:201], v[58:61]
	v_mfma_f32_16x16x32_bf16 v[50:53], v[190:193], v[198:201], v[50:53]
	v_mfma_f32_16x16x32_bf16 v[46:49], v[142:145], v[228:231], v[46:49]
	v_mfma_f32_16x16x32_bf16 v[38:41], v[174:177], v[228:231], v[38:41]
	v_mfma_f32_16x16x32_bf16 v[42:45], v[182:185], v[228:231], v[42:45]
	v_mfma_f32_16x16x32_bf16 v[34:37], v[190:193], v[228:231], v[34:37]
	v_mfma_f32_16x16x32_bf16 v[30:33], v[142:145], v[236:239], v[30:33]
	v_mfma_f32_16x16x32_bf16 v[22:25], v[174:177], v[236:239], v[22:25]
	v_mfma_f32_16x16x32_bf16 v[26:29], v[182:185], v[236:239], v[26:29]
	v_mfma_f32_16x16x32_bf16 v[18:21], v[190:193], v[236:239], v[18:21]
	v_mfma_f32_16x16x32_bf16 v[14:17], v[142:145], v[244:247], v[14:17]
	v_mfma_f32_16x16x32_bf16 v[6:9], v[174:177], v[244:247], v[6:9]
	v_mfma_f32_16x16x32_bf16 v[10:13], v[182:185], v[244:247], v[10:13]
	v_mfma_f32_16x16x32_bf16 v[2:5], v[190:193], v[244:247], v[2:5]
	v_mfma_f32_16x16x32_bf16 v[62:65], v[170:173], v[202:205], v[62:65]
	v_mfma_f32_16x16x32_bf16 v[54:57], v[178:181], v[202:205], v[54:57]
	v_mfma_f32_16x16x32_bf16 v[58:61], v[186:189], v[202:205], v[58:61]
	v_mfma_f32_16x16x32_bf16 v[50:53], v[194:197], v[202:205], v[50:53]
	v_mfma_f32_16x16x32_bf16 v[46:49], v[170:173], v[232:235], v[46:49]
	v_mfma_f32_16x16x32_bf16 v[38:41], v[178:181], v[232:235], v[38:41]
	v_mfma_f32_16x16x32_bf16 v[42:45], v[186:189], v[232:235], v[42:45]
	v_mfma_f32_16x16x32_bf16 v[34:37], v[194:197], v[232:235], v[34:37]
	v_mfma_f32_16x16x32_bf16 v[30:33], v[170:173], v[240:243], v[30:33]
	v_mfma_f32_16x16x32_bf16 v[22:25], v[178:181], v[240:243], v[22:25]
	v_mfma_f32_16x16x32_bf16 v[26:29], v[186:189], v[240:243], v[26:29]
	v_mfma_f32_16x16x32_bf16 v[18:21], v[194:197], v[240:243], v[18:21]
	v_mfma_f32_16x16x32_bf16 v[14:17], v[170:173], v[248:251], v[14:17]
	v_mfma_f32_16x16x32_bf16 v[6:9], v[178:181], v[248:251], v[6:9]
	v_mfma_f32_16x16x32_bf16 v[10:13], v[186:189], v[248:251], v[10:13]
	v_mfma_f32_16x16x32_bf16 v[2:5], v[194:197], v[248:251], v[2:5]
	s_barrier
	s_setprio 0
	ds_read_b128 v[142:145], v139
	ds_read_b128 v[170:173], v139 offset:1024
	ds_read_b128 v[174:177], v139 offset:2048
	ds_read_b128 v[178:181], v139 offset:3072
	ds_read_b128 v[182:185], v140
	ds_read_b128 v[186:189], v140 offset:1024
	ds_read_b128 v[190:193], v140 offset:2048
	ds_read_b128 v[194:197], v140 offset:3072
	s_add_i32 s97, s97, 0x80000
	s_mov_b32 m0, s23
	ds_read_b128 v[198:201], v138 offset:32768
	ds_read_b128 v[202:205], v138 offset:33792
	ds_read_b128 v[228:231], v138 offset:34816
	ds_read_b128 v[232:235], v138 offset:35840
	ds_read_b128 v[236:239], v138 offset:36864
	ds_read_b128 v[240:243], v138 offset:37888
	ds_read_b128 v[244:247], v138 offset:38912
	ds_read_b128 v[248:251], v138 offset:39936
	buffer_load_dwordx4 v132, s[60:63], s97 offen lds
	s_mov_b32 m0, s24
	s_nop 0
	buffer_load_dwordx4 v134, s[60:63], s97 offen lds
	s_waitcnt vmcnt(8)
	s_waitcnt lgkmcnt(0)
	s_setprio 1
	s_barrier
	v_mfma_f32_16x16x32_bf16 v[114:117], v[142:145], v[198:201], v[114:117]
	v_mfma_f32_16x16x32_bf16 v[110:113], v[174:177], v[198:201], v[110:113]
	v_mfma_f32_16x16x32_bf16 v[126:129], v[182:185], v[198:201], v[126:129]
	v_mfma_f32_16x16x32_bf16 v[122:125], v[190:193], v[198:201], v[122:125]
	v_mfma_f32_16x16x32_bf16 v[106:109], v[142:145], v[228:231], v[106:109]
	v_mfma_f32_16x16x32_bf16 v[102:105], v[174:177], v[228:231], v[102:105]
	v_mfma_f32_16x16x32_bf16 v[118:121], v[182:185], v[228:231], v[118:121]
	v_mfma_f32_16x16x32_bf16 v[98:101], v[190:193], v[228:231], v[98:101]
	v_mfma_f32_16x16x32_bf16 v[94:97], v[142:145], v[236:239], v[94:97]
	v_mfma_f32_16x16x32_bf16 v[86:89], v[174:177], v[236:239], v[86:89]
	v_mfma_f32_16x16x32_bf16 v[90:93], v[182:185], v[236:239], v[90:93]
	v_mfma_f32_16x16x32_bf16 v[82:85], v[190:193], v[236:239], v[82:85]
	v_mfma_f32_16x16x32_bf16 v[78:81], v[142:145], v[244:247], v[78:81]
	v_mfma_f32_16x16x32_bf16 v[70:73], v[174:177], v[244:247], v[70:73]
	v_mfma_f32_16x16x32_bf16 v[74:77], v[182:185], v[244:247], v[74:77]
	v_mfma_f32_16x16x32_bf16 v[66:69], v[190:193], v[244:247], v[66:69]
	v_mfma_f32_16x16x32_bf16 v[114:117], v[170:173], v[202:205], v[114:117]
	v_mfma_f32_16x16x32_bf16 v[110:113], v[178:181], v[202:205], v[110:113]
	v_mfma_f32_16x16x32_bf16 v[126:129], v[186:189], v[202:205], v[126:129]
	v_mfma_f32_16x16x32_bf16 v[122:125], v[194:197], v[202:205], v[122:125]
	v_mfma_f32_16x16x32_bf16 v[106:109], v[170:173], v[232:235], v[106:109]
	v_mfma_f32_16x16x32_bf16 v[102:105], v[178:181], v[232:235], v[102:105]
	v_mfma_f32_16x16x32_bf16 v[118:121], v[186:189], v[232:235], v[118:121]
	v_mfma_f32_16x16x32_bf16 v[98:101], v[194:197], v[232:235], v[98:101]
	v_mfma_f32_16x16x32_bf16 v[94:97], v[170:173], v[240:243], v[94:97]
	v_mfma_f32_16x16x32_bf16 v[86:89], v[178:181], v[240:243], v[86:89]
	v_mfma_f32_16x16x32_bf16 v[90:93], v[186:189], v[240:243], v[90:93]
	v_mfma_f32_16x16x32_bf16 v[82:85], v[194:197], v[240:243], v[82:85]
	v_mfma_f32_16x16x32_bf16 v[78:81], v[170:173], v[248:251], v[78:81]
	v_mfma_f32_16x16x32_bf16 v[70:73], v[178:181], v[248:251], v[70:73]
	v_mfma_f32_16x16x32_bf16 v[74:77], v[186:189], v[248:251], v[74:77]
	v_mfma_f32_16x16x32_bf16 v[66:69], v[194:197], v[248:251], v[66:69]
	s_barrier
	s_setprio 0
	s_mov_b32 m0, s31
	s_or_b32 s53, s52, 0x80
	ds_read_b128 v[198:201], v138 offset:49152
	ds_read_b128 v[202:205], v138 offset:50176
	ds_read_b128 v[228:231], v138 offset:51200
	ds_read_b128 v[232:235], v138 offset:52224
	ds_read_b128 v[236:239], v138 offset:53248
	ds_read_b128 v[240:243], v138 offset:54272
	ds_read_b128 v[244:247], v138 offset:55296
	ds_read_b128 v[248:251], v138 offset:56320
	buffer_load_dwordx4 v133, s[40:43], s53 offen lds
	s_mov_b32 m0, s33
	s_add_i32 s52, s52, 0x80080
	buffer_load_dwordx4 v135, s[40:43], s53 offen lds
	s_mov_b32 m0, s68
	s_nop 0
	buffer_load_dwordx4 v133, s[40:43], s52 offen lds
	s_mov_b32 m0, s69
	s_nop 0
	buffer_load_dwordx4 v135, s[40:43], s52 offen lds
	s_mov_b32 m0, s36
	s_nop 0
	buffer_load_dwordx4 v132, s[60:63], vcc_hi offen lds
	s_mov_b32 m0, s37
	s_nop 0
	buffer_load_dwordx4 v134, s[60:63], vcc_hi offen lds
	s_waitcnt vmcnt(8)
	s_waitcnt lgkmcnt(0)
	s_setprio 1
	s_barrier
	v_mfma_f32_16x16x32_bf16 v[62:65], v[142:145], v[198:201], v[62:65]
	v_mfma_f32_16x16x32_bf16 v[54:57], v[174:177], v[198:201], v[54:57]
	v_mfma_f32_16x16x32_bf16 v[58:61], v[182:185], v[198:201], v[58:61]
	v_mfma_f32_16x16x32_bf16 v[50:53], v[190:193], v[198:201], v[50:53]
	v_mfma_f32_16x16x32_bf16 v[46:49], v[142:145], v[228:231], v[46:49]
	v_mfma_f32_16x16x32_bf16 v[38:41], v[174:177], v[228:231], v[38:41]
	v_mfma_f32_16x16x32_bf16 v[42:45], v[182:185], v[228:231], v[42:45]
	v_mfma_f32_16x16x32_bf16 v[34:37], v[190:193], v[228:231], v[34:37]
	v_mfma_f32_16x16x32_bf16 v[30:33], v[142:145], v[236:239], v[30:33]
	v_mfma_f32_16x16x32_bf16 v[22:25], v[174:177], v[236:239], v[22:25]
	v_mfma_f32_16x16x32_bf16 v[26:29], v[182:185], v[236:239], v[26:29]
	v_mfma_f32_16x16x32_bf16 v[18:21], v[190:193], v[236:239], v[18:21]
	v_mfma_f32_16x16x32_bf16 v[14:17], v[142:145], v[244:247], v[14:17]
	v_mfma_f32_16x16x32_bf16 v[6:9], v[174:177], v[244:247], v[6:9]
	v_mfma_f32_16x16x32_bf16 v[10:13], v[182:185], v[244:247], v[10:13]
	v_mfma_f32_16x16x32_bf16 v[2:5], v[190:193], v[244:247], v[2:5]
	v_mfma_f32_16x16x32_bf16 v[62:65], v[170:173], v[202:205], v[62:65]
	v_mfma_f32_16x16x32_bf16 v[54:57], v[178:181], v[202:205], v[54:57]
	v_mfma_f32_16x16x32_bf16 v[58:61], v[186:189], v[202:205], v[58:61]
	v_mfma_f32_16x16x32_bf16 v[50:53], v[194:197], v[202:205], v[50:53]
	v_mfma_f32_16x16x32_bf16 v[46:49], v[170:173], v[232:235], v[46:49]
	v_mfma_f32_16x16x32_bf16 v[38:41], v[178:181], v[232:235], v[38:41]
	v_mfma_f32_16x16x32_bf16 v[42:45], v[186:189], v[232:235], v[42:45]
	v_mfma_f32_16x16x32_bf16 v[34:37], v[194:197], v[232:235], v[34:37]
	v_mfma_f32_16x16x32_bf16 v[30:33], v[170:173], v[240:243], v[30:33]
	v_mfma_f32_16x16x32_bf16 v[22:25], v[178:181], v[240:243], v[22:25]
	v_mfma_f32_16x16x32_bf16 v[26:29], v[186:189], v[240:243], v[26:29]
	v_mfma_f32_16x16x32_bf16 v[18:21], v[194:197], v[240:243], v[18:21]
	v_mfma_f32_16x16x32_bf16 v[14:17], v[170:173], v[248:251], v[14:17]
	v_mfma_f32_16x16x32_bf16 v[6:9], v[178:181], v[248:251], v[6:9]
	v_mfma_f32_16x16x32_bf16 v[10:13], v[186:189], v[248:251], v[10:13]
	v_mfma_f32_16x16x32_bf16 v[2:5], v[194:197], v[248:251], v[2:5]
	s_barrier
	s_setprio 0
	s_add_i32 vcc_lo, vcc_lo, 2
	s_addk_i32 s94, 0x100
	s_addk_i32 s95, 0x100
	s_cmp_gt_u32 vcc_lo, 29
	s_cbranch_scc0 .LBB0_304
	s_and_b64 vcc, exec, s[48:49]
	s_cbranch_vccz .LBB0_307
	s_barrier

.LBB0_579:
	s_mul_i32 s73, s72, 0x2c0000
	s_and_b64 s[8:9], s[42:43], exec
	s_mul_i32 s84, s71, 0x2c0000
	s_cselect_b32 s8, s73, s21
	s_cselect_b32 s9, s84, s13
	s_addk_i32 s13, 0x100
	s_add_i32 s21, s21, 0xc000
	s_mov_b32 s22, -2
	s_waitcnt lgkmcnt(0)
	v_add_u32_e32 v154, 0x10000, v140
	ds_read_b128 v[132:135], v154
	ds_read_b128 v[142:145], v154 offset:1024
	ds_read_b128 v[170:173], v154 offset:2048
	ds_read_b128 v[174:177], v154 offset:3072
	v_add_u32_e32 v154, 0x14000, v140
	ds_read_b128 v[178:181], v154
	ds_read_b128 v[182:185], v154 offset:1024
	ds_read_b128 v[186:189], v154 offset:2048
	ds_read_b128 v[190:193], v154 offset:3072
	s_add_i32 s23, s21, 0x4000
	s_cmpk_eq_i32 s22, 0x54
	s_cselect_b32 s27, s8, s23
	s_cselect_b32 s26, s9, s13
	s_or_b32 s23, s27, 0x8000
	s_mov_b32 m0, s68
	ds_read_b128 v[194:197], v141
	ds_read_b128 v[198:201], v141 offset:1024
	ds_read_b128 v[202:205], v141 offset:2048
	ds_read_b128 v[228:231], v141 offset:3072
	ds_read_b128 v[232:235], v141 offset:4096
	ds_read_b128 v[236:239], v141 offset:5120
	ds_read_b128 v[240:243], v141 offset:6144
	ds_read_b128 v[244:247], v141 offset:7168
	buffer_load_dwordx4 v136, s[60:63], s21 offen lds
	s_mov_b32 m0, s70
	s_nop 0
	buffer_load_dwordx4 v138, s[60:63], s21 offen lds
	s_waitcnt vmcnt(8)
	s_waitcnt lgkmcnt(0)
	s_setprio 1
	s_barrier
	v_mfma_f32_16x16x32_bf16 v[126:129], v[132:135], v[194:197], 0
	v_mfma_f32_16x16x32_bf16 v[106:109], v[170:173], v[194:197], 0
	v_mfma_f32_16x16x32_bf16 v[122:125], v[178:181], v[194:197], 0
	v_mfma_f32_16x16x32_bf16 v[110:113], v[186:189], v[194:197], 0
	v_mfma_f32_16x16x32_bf16 v[118:121], v[132:135], v[202:205], 0
	v_mfma_f32_16x16x32_bf16 v[114:117], v[170:173], v[202:205], 0
	v_mfma_f32_16x16x32_bf16 v[102:105], v[178:181], v[202:205], 0
	v_mfma_f32_16x16x32_bf16 v[98:101], v[186:189], v[202:205], 0
	v_mfma_f32_16x16x32_bf16 v[94:97], v[132:135], v[232:235], 0
	v_mfma_f32_16x16x32_bf16 v[90:93], v[170:173], v[232:235], 0
	v_mfma_f32_16x16x32_bf16 v[86:89], v[178:181], v[232:235], 0
	v_mfma_f32_16x16x32_bf16 v[82:85], v[186:189], v[232:235], 0
	v_mfma_f32_16x16x32_bf16 v[78:81], v[132:135], v[240:243], 0
	v_mfma_f32_16x16x32_bf16 v[74:77], v[170:173], v[240:243], 0
	v_mfma_f32_16x16x32_bf16 v[70:73], v[178:181], v[240:243], 0
	v_mfma_f32_16x16x32_bf16 v[66:69], v[186:189], v[240:243], 0
	v_mfma_f32_16x16x32_bf16 v[126:129], v[142:145], v[198:201], v[126:129]
	v_mfma_f32_16x16x32_bf16 v[106:109], v[174:177], v[198:201], v[106:109]
	v_mfma_f32_16x16x32_bf16 v[122:125], v[182:185], v[198:201], v[122:125]
	v_mfma_f32_16x16x32_bf16 v[110:113], v[190:193], v[198:201], v[110:113]
	v_mfma_f32_16x16x32_bf16 v[118:121], v[142:145], v[228:231], v[118:121]
	v_mfma_f32_16x16x32_bf16 v[114:117], v[174:177], v[228:231], v[114:117]
	v_mfma_f32_16x16x32_bf16 v[102:105], v[182:185], v[228:231], v[102:105]
	v_mfma_f32_16x16x32_bf16 v[98:101], v[190:193], v[228:231], v[98:101]
	v_mfma_f32_16x16x32_bf16 v[94:97], v[142:145], v[236:239], v[94:97]
	v_mfma_f32_16x16x32_bf16 v[90:93], v[174:177], v[236:239], v[90:93]
	v_mfma_f32_16x16x32_bf16 v[86:89], v[182:185], v[236:239], v[86:89]
	v_mfma_f32_16x16x32_bf16 v[82:85], v[190:193], v[236:239], v[82:85]
	v_mfma_f32_16x16x32_bf16 v[78:81], v[142:145], v[244:247], v[78:81]
	v_mfma_f32_16x16x32_bf16 v[74:77], v[174:177], v[244:247], v[74:77]
	v_mfma_f32_16x16x32_bf16 v[70:73], v[182:185], v[244:247], v[70:73]
	v_mfma_f32_16x16x32_bf16 v[66:69], v[190:193], v[244:247], v[66:69]
	s_barrier
	s_setprio 0
	s_mov_b32 m0, s15
	s_mov_b32 s46, s62
	s_mov_b32 s47, s63
	ds_read_b128 v[194:197], v141 offset:16384
	ds_read_b128 v[198:201], v141 offset:17408
	ds_read_b128 v[202:205], v141 offset:18432
	ds_read_b128 v[228:231], v141 offset:19456
	ds_read_b128 v[232:235], v141 offset:20480
	ds_read_b128 v[236:239], v141 offset:21504
	ds_read_b128 v[240:243], v141 offset:22528
	ds_read_b128 v[244:247], v141 offset:23552
	buffer_load_dwordx4 v137, s[44:47], s26 offen lds
	s_mov_b32 m0, s16
	s_add_i32 s52, s26, 0x160000
	buffer_load_dwordx4 v139, s[44:47], s26 offen lds
	s_mov_b32 m0, s18
	s_nop 0
	buffer_load_dwordx4 v137, s[44:47], s52 offen lds
	s_mov_b32 m0, s19
	s_nop 0
	buffer_load_dwordx4 v139, s[44:47], s52 offen lds
	s_mov_b32 m0, s14
	s_nop 0
	buffer_load_dwordx4 v136, s[60:63], s27 offen lds
	s_mov_b32 m0, s24
	s_nop 0
	buffer_load_dwordx4 v138, s[60:63], s27 offen lds
	s_waitcnt vmcnt(8)
	s_waitcnt lgkmcnt(0)
	s_setprio 1
	s_barrier
	v_mfma_f32_16x16x32_bf16 v[62:65], v[132:135], v[194:197], 0
	v_mfma_f32_16x16x32_bf16 v[58:61], v[170:173], v[194:197], 0
	v_mfma_f32_16x16x32_bf16 v[54:57], v[178:181], v[194:197], 0
	v_mfma_f32_16x16x32_bf16 v[50:53], v[186:189], v[194:197], 0
	v_mfma_f32_16x16x32_bf16 v[46:49], v[132:135], v[202:205], 0
	v_mfma_f32_16x16x32_bf16 v[42:45], v[170:173], v[202:205], 0
	v_mfma_f32_16x16x32_bf16 v[38:41], v[178:181], v[202:205], 0
	v_mfma_f32_16x16x32_bf16 v[34:37], v[186:189], v[202:205], 0
	v_mfma_f32_16x16x32_bf16 v[30:33], v[132:135], v[232:235], 0
	v_mfma_f32_16x16x32_bf16 v[26:29], v[170:173], v[232:235], 0
	v_mfma_f32_16x16x32_bf16 v[22:25], v[178:181], v[232:235], 0
	v_mfma_f32_16x16x32_bf16 v[18:21], v[186:189], v[232:235], 0
	v_mfma_f32_16x16x32_bf16 v[14:17], v[132:135], v[240:243], 0
	v_mfma_f32_16x16x32_bf16 v[10:13], v[170:173], v[240:243], 0
	v_mfma_f32_16x16x32_bf16 v[6:9], v[178:181], v[240:243], 0
	v_mfma_f32_16x16x32_bf16 v[2:5], v[186:189], v[240:243], 0
	v_mfma_f32_16x16x32_bf16 v[62:65], v[142:145], v[198:201], v[62:65]
	v_mfma_f32_16x16x32_bf16 v[58:61], v[174:177], v[198:201], v[58:61]
	v_mfma_f32_16x16x32_bf16 v[54:57], v[182:185], v[198:201], v[54:57]
	v_mfma_f32_16x16x32_bf16 v[50:53], v[190:193], v[198:201], v[50:53]
	v_mfma_f32_16x16x32_bf16 v[46:49], v[142:145], v[228:231], v[46:49]
	v_mfma_f32_16x16x32_bf16 v[42:45], v[174:177], v[228:231], v[42:45]
	v_mfma_f32_16x16x32_bf16 v[38:41], v[182:185], v[228:231], v[38:41]
	v_mfma_f32_16x16x32_bf16 v[34:37], v[190:193], v[228:231], v[34:37]
	v_mfma_f32_16x16x32_bf16 v[30:33], v[142:145], v[236:239], v[30:33]
	v_mfma_f32_16x16x32_bf16 v[26:29], v[174:177], v[236:239], v[26:29]
	v_mfma_f32_16x16x32_bf16 v[22:25], v[182:185], v[236:239], v[22:25]
	v_mfma_f32_16x16x32_bf16 v[18:21], v[190:193], v[236:239], v[18:21]
	v_mfma_f32_16x16x32_bf16 v[14:17], v[142:145], v[244:247], v[14:17]
	v_mfma_f32_16x16x32_bf16 v[10:13], v[174:177], v[244:247], v[10:13]
	v_mfma_f32_16x16x32_bf16 v[6:9], v[182:185], v[244:247], v[6:9]
	v_mfma_f32_16x16x32_bf16 v[2:5], v[190:193], v[244:247], v[2:5]
	s_barrier
	s_setprio 0
	v_add_u32_e32 v154, 0x18000, v140
	ds_read_b128 v[132:135], v154
	ds_read_b128 v[142:145], v154 offset:1024
	ds_read_b128 v[170:173], v154 offset:2048
	ds_read_b128 v[174:177], v154 offset:3072
	v_add_u32_e32 v154, 0x1c000, v140
	ds_read_b128 v[178:181], v154
	ds_read_b128 v[182:185], v154 offset:1024
	ds_read_b128 v[186:189], v154 offset:2048
	ds_read_b128 v[190:193], v154 offset:3072
	s_bitset1_b32 s27, 14
	s_mov_b32 m0, s25
	ds_read_b128 v[194:197], v141 offset:32768
	ds_read_b128 v[198:201], v141 offset:33792
	ds_read_b128 v[202:205], v141 offset:34816
	ds_read_b128 v[228:231], v141 offset:35840
	ds_read_b128 v[232:235], v141 offset:36864
	ds_read_b128 v[236:239], v141 offset:37888
	ds_read_b128 v[240:243], v141 offset:38912
	ds_read_b128 v[244:247], v141 offset:39936
	buffer_load_dwordx4 v136, s[60:63], s27 offen lds
	s_mov_b32 m0, s30
	s_nop 0
	buffer_load_dwordx4 v138, s[60:63], s27 offen lds
	s_waitcnt vmcnt(8)
	s_waitcnt lgkmcnt(0)
	s_setprio 1
	s_barrier
	v_mfma_f32_16x16x32_bf16 v[126:129], v[132:135], v[194:197], v[126:129]
	v_mfma_f32_16x16x32_bf16 v[106:109], v[170:173], v[194:197], v[106:109]
	v_mfma_f32_16x16x32_bf16 v[122:125], v[178:181], v[194:197], v[122:125]
	v_mfma_f32_16x16x32_bf16 v[110:113], v[186:189], v[194:197], v[110:113]
	v_mfma_f32_16x16x32_bf16 v[118:121], v[132:135], v[202:205], v[118:121]
	v_mfma_f32_16x16x32_bf16 v[114:117], v[170:173], v[202:205], v[114:117]
	v_mfma_f32_16x16x32_bf16 v[102:105], v[178:181], v[202:205], v[102:105]
	v_mfma_f32_16x16x32_bf16 v[98:101], v[186:189], v[202:205], v[98:101]
	v_mfma_f32_16x16x32_bf16 v[94:97], v[132:135], v[232:235], v[94:97]
	v_mfma_f32_16x16x32_bf16 v[90:93], v[170:173], v[232:235], v[90:93]
	v_mfma_f32_16x16x32_bf16 v[86:89], v[178:181], v[232:235], v[86:89]
	v_mfma_f32_16x16x32_bf16 v[82:85], v[186:189], v[232:235], v[82:85]
	v_mfma_f32_16x16x32_bf16 v[78:81], v[132:135], v[240:243], v[78:81]
	v_mfma_f32_16x16x32_bf16 v[74:77], v[170:173], v[240:243], v[74:77]
	v_mfma_f32_16x16x32_bf16 v[70:73], v[178:181], v[240:243], v[70:73]
	v_mfma_f32_16x16x32_bf16 v[66:69], v[186:189], v[240:243], v[66:69]
	v_mfma_f32_16x16x32_bf16 v[126:129], v[142:145], v[198:201], v[126:129]
	v_mfma_f32_16x16x32_bf16 v[106:109], v[174:177], v[198:201], v[106:109]
	v_mfma_f32_16x16x32_bf16 v[122:125], v[182:185], v[198:201], v[122:125]
	v_mfma_f32_16x16x32_bf16 v[110:113], v[190:193], v[198:201], v[110:113]
	v_mfma_f32_16x16x32_bf16 v[118:121], v[142:145], v[228:231], v[118:121]
	v_mfma_f32_16x16x32_bf16 v[114:117], v[174:177], v[228:231], v[114:117]
	v_mfma_f32_16x16x32_bf16 v[102:105], v[182:185], v[228:231], v[102:105]
	v_mfma_f32_16x16x32_bf16 v[98:101], v[190:193], v[228:231], v[98:101]
	v_mfma_f32_16x16x32_bf16 v[94:97], v[142:145], v[236:239], v[94:97]
	v_mfma_f32_16x16x32_bf16 v[90:93], v[174:177], v[236:239], v[90:93]
	v_mfma_f32_16x16x32_bf16 v[86:89], v[182:185], v[236:239], v[86:89]
	v_mfma_f32_16x16x32_bf16 v[82:85], v[190:193], v[236:239], v[82:85]
	v_mfma_f32_16x16x32_bf16 v[78:81], v[142:145], v[244:247], v[78:81]
	v_mfma_f32_16x16x32_bf16 v[74:77], v[174:177], v[244:247], v[74:77]
	v_mfma_f32_16x16x32_bf16 v[70:73], v[182:185], v[244:247], v[70:73]
	v_mfma_f32_16x16x32_bf16 v[66:69], v[190:193], v[244:247], v[66:69]
	s_barrier
	s_setprio 0
	s_mov_b32 m0, s36
	s_or_b32 s27, s26, 0x80
	ds_read_b128 v[194:197], v141 offset:49152
	ds_read_b128 v[198:201], v141 offset:50176
	ds_read_b128 v[202:205], v141 offset:51200
	ds_read_b128 v[228:231], v141 offset:52224
	ds_read_b128 v[232:235], v141 offset:53248
	ds_read_b128 v[236:239], v141 offset:54272
	ds_read_b128 v[240:243], v141 offset:55296
	ds_read_b128 v[244:247], v141 offset:56320
	buffer_load_dwordx4 v137, s[44:47], s27 offen lds
	s_mov_b32 m0, s37
	s_add_i32 s26, s26, 0x160080
	buffer_load_dwordx4 v139, s[44:47], s27 offen lds
	s_mov_b32 m0, s66
	s_nop 0
	buffer_load_dwordx4 v137, s[44:47], s26 offen lds
	s_mov_b32 m0, s67
	s_nop 0
	buffer_load_dwordx4 v139, s[44:47], s26 offen lds
	s_mov_b32 m0, s48
	s_nop 0
	buffer_load_dwordx4 v136, s[60:63], s23 offen lds
	s_mov_b32 m0, s49
	s_nop 0
	buffer_load_dwordx4 v138, s[60:63], s23 offen lds
	s_waitcnt vmcnt(8)
	s_waitcnt lgkmcnt(0)
	s_setprio 1
	s_barrier
	v_mfma_f32_16x16x32_bf16 v[62:65], v[132:135], v[194:197], v[62:65]
	v_mfma_f32_16x16x32_bf16 v[58:61], v[170:173], v[194:197], v[58:61]
	v_mfma_f32_16x16x32_bf16 v[54:57], v[178:181], v[194:197], v[54:57]
	v_mfma_f32_16x16x32_bf16 v[50:53], v[186:189], v[194:197], v[50:53]
	v_mfma_f32_16x16x32_bf16 v[46:49], v[132:135], v[202:205], v[46:49]
	v_mfma_f32_16x16x32_bf16 v[42:45], v[170:173], v[202:205], v[42:45]
	v_mfma_f32_16x16x32_bf16 v[38:41], v[178:181], v[202:205], v[38:41]
	v_mfma_f32_16x16x32_bf16 v[34:37], v[186:189], v[202:205], v[34:37]
	v_mfma_f32_16x16x32_bf16 v[30:33], v[132:135], v[232:235], v[30:33]
	v_mfma_f32_16x16x32_bf16 v[26:29], v[170:173], v[232:235], v[26:29]
	v_mfma_f32_16x16x32_bf16 v[22:25], v[178:181], v[232:235], v[22:25]
	v_mfma_f32_16x16x32_bf16 v[18:21], v[186:189], v[232:235], v[18:21]
	v_mfma_f32_16x16x32_bf16 v[14:17], v[132:135], v[240:243], v[14:17]
	v_mfma_f32_16x16x32_bf16 v[10:13], v[170:173], v[240:243], v[10:13]
	v_mfma_f32_16x16x32_bf16 v[6:9], v[178:181], v[240:243], v[6:9]
	v_mfma_f32_16x16x32_bf16 v[2:5], v[186:189], v[240:243], v[2:5]
	v_mfma_f32_16x16x32_bf16 v[62:65], v[142:145], v[198:201], v[62:65]
	v_mfma_f32_16x16x32_bf16 v[58:61], v[174:177], v[198:201], v[58:61]
	v_mfma_f32_16x16x32_bf16 v[54:57], v[182:185], v[198:201], v[54:57]
	v_mfma_f32_16x16x32_bf16 v[50:53], v[190:193], v[198:201], v[50:53]
	v_mfma_f32_16x16x32_bf16 v[46:49], v[142:145], v[228:231], v[46:49]
	v_mfma_f32_16x16x32_bf16 v[42:45], v[174:177], v[228:231], v[42:45]
	v_mfma_f32_16x16x32_bf16 v[38:41], v[182:185], v[228:231], v[38:41]
	v_mfma_f32_16x16x32_bf16 v[34:37], v[190:193], v[228:231], v[34:37]
	v_mfma_f32_16x16x32_bf16 v[30:33], v[142:145], v[236:239], v[30:33]
	v_mfma_f32_16x16x32_bf16 v[26:29], v[174:177], v[236:239], v[26:29]
	v_mfma_f32_16x16x32_bf16 v[22:25], v[182:185], v[236:239], v[22:25]
	v_mfma_f32_16x16x32_bf16 v[18:21], v[190:193], v[236:239], v[18:21]
	v_mfma_f32_16x16x32_bf16 v[14:17], v[142:145], v[244:247], v[14:17]
	v_mfma_f32_16x16x32_bf16 v[10:13], v[174:177], v[244:247], v[10:13]
	v_mfma_f32_16x16x32_bf16 v[6:9], v[182:185], v[244:247], v[6:9]
	v_mfma_f32_16x16x32_bf16 v[2:5], v[190:193], v[244:247], v[2:5]
	s_barrier
	s_setprio 0
	s_addk_i32 s13, 0x100
	s_add_i32 s22, s22, 2
	s_add_i32 s21, s21, 0x10000
	s_cmpk_gt_u32 s22, 0x55
.LBB0_580:
	v_add_u32_e32 v154, 0x10000, v140
	ds_read_b128 v[132:135], v154
	ds_read_b128 v[142:145], v154 offset:1024
	ds_read_b128 v[170:173], v154 offset:2048
	ds_read_b128 v[174:177], v154 offset:3072
	v_add_u32_e32 v154, 0x14000, v140
	ds_read_b128 v[178:181], v154
	ds_read_b128 v[182:185], v154 offset:1024
	ds_read_b128 v[186:189], v154 offset:2048
	ds_read_b128 v[190:193], v154 offset:3072
	s_add_i32 s23, s21, 0x4000
	s_cmpk_eq_i32 s22, 0x54
	s_cselect_b32 s27, s8, s23
	s_cselect_b32 s26, s9, s13
	s_or_b32 s23, s27, 0x8000
	s_mov_b32 m0, s68
	ds_read_b128 v[194:197], v141
	ds_read_b128 v[198:201], v141 offset:1024
	ds_read_b128 v[202:205], v141 offset:2048
	ds_read_b128 v[228:231], v141 offset:3072
	ds_read_b128 v[232:235], v141 offset:4096
	ds_read_b128 v[236:239], v141 offset:5120
	ds_read_b128 v[240:243], v141 offset:6144
	ds_read_b128 v[244:247], v141 offset:7168
	buffer_load_dwordx4 v136, s[60:63], s21 offen lds
	s_mov_b32 m0, s70
	s_nop 0
	buffer_load_dwordx4 v138, s[60:63], s21 offen lds
	s_waitcnt vmcnt(8)
	s_waitcnt lgkmcnt(0)
	s_setprio 1
	s_barrier
	v_mfma_f32_16x16x32_bf16 v[126:129], v[132:135], v[194:197], v[126:129]
	v_mfma_f32_16x16x32_bf16 v[106:109], v[170:173], v[194:197], v[106:109]
	v_mfma_f32_16x16x32_bf16 v[122:125], v[178:181], v[194:197], v[122:125]
	v_mfma_f32_16x16x32_bf16 v[110:113], v[186:189], v[194:197], v[110:113]
	v_mfma_f32_16x16x32_bf16 v[118:121], v[132:135], v[202:205], v[118:121]
	v_mfma_f32_16x16x32_bf16 v[114:117], v[170:173], v[202:205], v[114:117]
	v_mfma_f32_16x16x32_bf16 v[102:105], v[178:181], v[202:205], v[102:105]
	v_mfma_f32_16x16x32_bf16 v[98:101], v[186:189], v[202:205], v[98:101]
	v_mfma_f32_16x16x32_bf16 v[94:97], v[132:135], v[232:235], v[94:97]
	v_mfma_f32_16x16x32_bf16 v[90:93], v[170:173], v[232:235], v[90:93]
	v_mfma_f32_16x16x32_bf16 v[86:89], v[178:181], v[232:235], v[86:89]
	v_mfma_f32_16x16x32_bf16 v[82:85], v[186:189], v[232:235], v[82:85]
	v_mfma_f32_16x16x32_bf16 v[78:81], v[132:135], v[240:243], v[78:81]
	v_mfma_f32_16x16x32_bf16 v[74:77], v[170:173], v[240:243], v[74:77]
	v_mfma_f32_16x16x32_bf16 v[70:73], v[178:181], v[240:243], v[70:73]
	v_mfma_f32_16x16x32_bf16 v[66:69], v[186:189], v[240:243], v[66:69]
	v_mfma_f32_16x16x32_bf16 v[126:129], v[142:145], v[198:201], v[126:129]
	v_mfma_f32_16x16x32_bf16 v[106:109], v[174:177], v[198:201], v[106:109]
	v_mfma_f32_16x16x32_bf16 v[122:125], v[182:185], v[198:201], v[122:125]
	v_mfma_f32_16x16x32_bf16 v[110:113], v[190:193], v[198:201], v[110:113]
	v_mfma_f32_16x16x32_bf16 v[118:121], v[142:145], v[228:231], v[118:121]
	v_mfma_f32_16x16x32_bf16 v[114:117], v[174:177], v[228:231], v[114:117]
	v_mfma_f32_16x16x32_bf16 v[102:105], v[182:185], v[228:231], v[102:105]
	v_mfma_f32_16x16x32_bf16 v[98:101], v[190:193], v[228:231], v[98:101]
	v_mfma_f32_16x16x32_bf16 v[94:97], v[142:145], v[236:239], v[94:97]
	v_mfma_f32_16x16x32_bf16 v[90:93], v[174:177], v[236:239], v[90:93]
	v_mfma_f32_16x16x32_bf16 v[86:89], v[182:185], v[236:239], v[86:89]
	v_mfma_f32_16x16x32_bf16 v[82:85], v[190:193], v[236:239], v[82:85]
	v_mfma_f32_16x16x32_bf16 v[78:81], v[142:145], v[244:247], v[78:81]
	v_mfma_f32_16x16x32_bf16 v[74:77], v[174:177], v[244:247], v[74:77]
	v_mfma_f32_16x16x32_bf16 v[70:73], v[182:185], v[244:247], v[70:73]
	v_mfma_f32_16x16x32_bf16 v[66:69], v[190:193], v[244:247], v[66:69]
	s_barrier
	s_setprio 0
	s_mov_b32 m0, s15
	s_mov_b32 s46, s62
	s_mov_b32 s47, s63
	ds_read_b128 v[194:197], v141 offset:16384
	ds_read_b128 v[198:201], v141 offset:17408
	ds_read_b128 v[202:205], v141 offset:18432
	ds_read_b128 v[228:231], v141 offset:19456
	ds_read_b128 v[232:235], v141 offset:20480
	ds_read_b128 v[236:239], v141 offset:21504
	ds_read_b128 v[240:243], v141 offset:22528
	ds_read_b128 v[244:247], v141 offset:23552
	buffer_load_dwordx4 v137, s[44:47], s26 offen lds
	s_mov_b32 m0, s16
	s_add_i32 s52, s26, 0x160000
	buffer_load_dwordx4 v139, s[44:47], s26 offen lds
	s_mov_b32 m0, s18
	s_nop 0
	buffer_load_dwordx4 v137, s[44:47], s52 offen lds
	s_mov_b32 m0, s19
	s_nop 0
	buffer_load_dwordx4 v139, s[44:47], s52 offen lds
	s_mov_b32 m0, s14
	s_nop 0
	buffer_load_dwordx4 v136, s[60:63], s27 offen lds
	s_mov_b32 m0, s24
	s_nop 0
	buffer_load_dwordx4 v138, s[60:63], s27 offen lds
	s_waitcnt vmcnt(8)
	s_waitcnt lgkmcnt(0)
	s_setprio 1
	s_barrier
	v_mfma_f32_16x16x32_bf16 v[62:65], v[132:135], v[194:197], v[62:65]
	v_mfma_f32_16x16x32_bf16 v[58:61], v[170:173], v[194:197], v[58:61]
	v_mfma_f32_16x16x32_bf16 v[54:57], v[178:181], v[194:197], v[54:57]
	v_mfma_f32_16x16x32_bf16 v[50:53], v[186:189], v[194:197], v[50:53]
	v_mfma_f32_16x16x32_bf16 v[46:49], v[132:135], v[202:205], v[46:49]
	v_mfma_f32_16x16x32_bf16 v[42:45], v[170:173], v[202:205], v[42:45]
	v_mfma_f32_16x16x32_bf16 v[38:41], v[178:181], v[202:205], v[38:41]
	v_mfma_f32_16x16x32_bf16 v[34:37], v[186:189], v[202:205], v[34:37]
	v_mfma_f32_16x16x32_bf16 v[30:33], v[132:135], v[232:235], v[30:33]
	v_mfma_f32_16x16x32_bf16 v[26:29], v[170:173], v[232:235], v[26:29]
	v_mfma_f32_16x16x32_bf16 v[22:25], v[178:181], v[232:235], v[22:25]
	v_mfma_f32_16x16x32_bf16 v[18:21], v[186:189], v[232:235], v[18:21]
	v_mfma_f32_16x16x32_bf16 v[14:17], v[132:135], v[240:243], v[14:17]
	v_mfma_f32_16x16x32_bf16 v[10:13], v[170:173], v[240:243], v[10:13]
	v_mfma_f32_16x16x32_bf16 v[6:9], v[178:181], v[240:243], v[6:9]
	v_mfma_f32_16x16x32_bf16 v[2:5], v[186:189], v[240:243], v[2:5]
	v_mfma_f32_16x16x32_bf16 v[62:65], v[142:145], v[198:201], v[62:65]
	v_mfma_f32_16x16x32_bf16 v[58:61], v[174:177], v[198:201], v[58:61]
	v_mfma_f32_16x16x32_bf16 v[54:57], v[182:185], v[198:201], v[54:57]
	v_mfma_f32_16x16x32_bf16 v[50:53], v[190:193], v[198:201], v[50:53]
	v_mfma_f32_16x16x32_bf16 v[46:49], v[142:145], v[228:231], v[46:49]
	v_mfma_f32_16x16x32_bf16 v[42:45], v[174:177], v[228:231], v[42:45]
	v_mfma_f32_16x16x32_bf16 v[38:41], v[182:185], v[228:231], v[38:41]
	v_mfma_f32_16x16x32_bf16 v[34:37], v[190:193], v[228:231], v[34:37]
	v_mfma_f32_16x16x32_bf16 v[30:33], v[142:145], v[236:239], v[30:33]
	v_mfma_f32_16x16x32_bf16 v[26:29], v[174:177], v[236:239], v[26:29]
	v_mfma_f32_16x16x32_bf16 v[22:25], v[182:185], v[236:239], v[22:25]
	v_mfma_f32_16x16x32_bf16 v[18:21], v[190:193], v[236:239], v[18:21]
	v_mfma_f32_16x16x32_bf16 v[14:17], v[142:145], v[244:247], v[14:17]
	v_mfma_f32_16x16x32_bf16 v[10:13], v[174:177], v[244:247], v[10:13]
	v_mfma_f32_16x16x32_bf16 v[6:9], v[182:185], v[244:247], v[6:9]
	v_mfma_f32_16x16x32_bf16 v[2:5], v[190:193], v[244:247], v[2:5]
	s_barrier
	s_setprio 0
	v_add_u32_e32 v154, 0x18000, v140
	ds_read_b128 v[132:135], v154
	ds_read_b128 v[142:145], v154 offset:1024
	ds_read_b128 v[170:173], v154 offset:2048
	ds_read_b128 v[174:177], v154 offset:3072
	v_add_u32_e32 v154, 0x1c000, v140
	ds_read_b128 v[178:181], v154
	ds_read_b128 v[182:185], v154 offset:1024
	ds_read_b128 v[186:189], v154 offset:2048
	ds_read_b128 v[190:193], v154 offset:3072
	s_bitset1_b32 s27, 14
	s_mov_b32 m0, s25
	ds_read_b128 v[194:197], v141 offset:32768
	ds_read_b128 v[198:201], v141 offset:33792
	ds_read_b128 v[202:205], v141 offset:34816
	ds_read_b128 v[228:231], v141 offset:35840
	ds_read_b128 v[232:235], v141 offset:36864
	ds_read_b128 v[236:239], v141 offset:37888
	ds_read_b128 v[240:243], v141 offset:38912
	ds_read_b128 v[244:247], v141 offset:39936
	buffer_load_dwordx4 v136, s[60:63], s27 offen lds
	s_mov_b32 m0, s30
	s_nop 0
	buffer_load_dwordx4 v138, s[60:63], s27 offen lds
	s_waitcnt vmcnt(8)
	s_waitcnt lgkmcnt(0)
	s_setprio 1
	s_barrier
	v_mfma_f32_16x16x32_bf16 v[126:129], v[132:135], v[194:197], v[126:129]
	v_mfma_f32_16x16x32_bf16 v[106:109], v[170:173], v[194:197], v[106:109]
	v_mfma_f32_16x16x32_bf16 v[122:125], v[178:181], v[194:197], v[122:125]
	v_mfma_f32_16x16x32_bf16 v[110:113], v[186:189], v[194:197], v[110:113]
	v_mfma_f32_16x16x32_bf16 v[118:121], v[132:135], v[202:205], v[118:121]
	v_mfma_f32_16x16x32_bf16 v[114:117], v[170:173], v[202:205], v[114:117]
	v_mfma_f32_16x16x32_bf16 v[102:105], v[178:181], v[202:205], v[102:105]
	v_mfma_f32_16x16x32_bf16 v[98:101], v[186:189], v[202:205], v[98:101]
	v_mfma_f32_16x16x32_bf16 v[94:97], v[132:135], v[232:235], v[94:97]
	v_mfma_f32_16x16x32_bf16 v[90:93], v[170:173], v[232:235], v[90:93]
	v_mfma_f32_16x16x32_bf16 v[86:89], v[178:181], v[232:235], v[86:89]
	v_mfma_f32_16x16x32_bf16 v[82:85], v[186:189], v[232:235], v[82:85]
	v_mfma_f32_16x16x32_bf16 v[78:81], v[132:135], v[240:243], v[78:81]
	v_mfma_f32_16x16x32_bf16 v[74:77], v[170:173], v[240:243], v[74:77]
	v_mfma_f32_16x16x32_bf16 v[70:73], v[178:181], v[240:243], v[70:73]
	v_mfma_f32_16x16x32_bf16 v[66:69], v[186:189], v[240:243], v[66:69]
	v_mfma_f32_16x16x32_bf16 v[126:129], v[142:145], v[198:201], v[126:129]
	v_mfma_f32_16x16x32_bf16 v[106:109], v[174:177], v[198:201], v[106:109]
	v_mfma_f32_16x16x32_bf16 v[122:125], v[182:185], v[198:201], v[122:125]
	v_mfma_f32_16x16x32_bf16 v[110:113], v[190:193], v[198:201], v[110:113]
	v_mfma_f32_16x16x32_bf16 v[118:121], v[142:145], v[228:231], v[118:121]
	v_mfma_f32_16x16x32_bf16 v[114:117], v[174:177], v[228:231], v[114:117]
	v_mfma_f32_16x16x32_bf16 v[102:105], v[182:185], v[228:231], v[102:105]
	v_mfma_f32_16x16x32_bf16 v[98:101], v[190:193], v[228:231], v[98:101]
	v_mfma_f32_16x16x32_bf16 v[94:97], v[142:145], v[236:239], v[94:97]
	v_mfma_f32_16x16x32_bf16 v[90:93], v[174:177], v[236:239], v[90:93]
	v_mfma_f32_16x16x32_bf16 v[86:89], v[182:185], v[236:239], v[86:89]
	v_mfma_f32_16x16x32_bf16 v[82:85], v[190:193], v[236:239], v[82:85]
	v_mfma_f32_16x16x32_bf16 v[78:81], v[142:145], v[244:247], v[78:81]
	v_mfma_f32_16x16x32_bf16 v[74:77], v[174:177], v[244:247], v[74:77]
	v_mfma_f32_16x16x32_bf16 v[70:73], v[182:185], v[244:247], v[70:73]
	v_mfma_f32_16x16x32_bf16 v[66:69], v[190:193], v[244:247], v[66:69]
	s_barrier
	s_setprio 0
	s_mov_b32 m0, s36
	s_or_b32 s27, s26, 0x80
	ds_read_b128 v[194:197], v141 offset:49152
	ds_read_b128 v[198:201], v141 offset:50176
	ds_read_b128 v[202:205], v141 offset:51200
	ds_read_b128 v[228:231], v141 offset:52224
	ds_read_b128 v[232:235], v141 offset:53248
	ds_read_b128 v[236:239], v141 offset:54272
	ds_read_b128 v[240:243], v141 offset:55296
	ds_read_b128 v[244:247], v141 offset:56320
	buffer_load_dwordx4 v137, s[44:47], s27 offen lds
	s_mov_b32 m0, s37
	s_add_i32 s26, s26, 0x160080
	buffer_load_dwordx4 v139, s[44:47], s27 offen lds
	s_mov_b32 m0, s66
	s_nop 0
	buffer_load_dwordx4 v137, s[44:47], s26 offen lds
	s_mov_b32 m0, s67
	s_nop 0
	buffer_load_dwordx4 v139, s[44:47], s26 offen lds
	s_mov_b32 m0, s48
	s_nop 0
	buffer_load_dwordx4 v136, s[60:63], s23 offen lds
	s_mov_b32 m0, s49
	s_nop 0
	buffer_load_dwordx4 v138, s[60:63], s23 offen lds
	s_waitcnt vmcnt(8)
	s_waitcnt lgkmcnt(0)
	s_setprio 1
	s_barrier
	v_mfma_f32_16x16x32_bf16 v[62:65], v[132:135], v[194:197], v[62:65]
	v_mfma_f32_16x16x32_bf16 v[58:61], v[170:173], v[194:197], v[58:61]
	v_mfma_f32_16x16x32_bf16 v[54:57], v[178:181], v[194:197], v[54:57]
	v_mfma_f32_16x16x32_bf16 v[50:53], v[186:189], v[194:197], v[50:53]
	v_mfma_f32_16x16x32_bf16 v[46:49], v[132:135], v[202:205], v[46:49]
	v_mfma_f32_16x16x32_bf16 v[42:45], v[170:173], v[202:205], v[42:45]
	v_mfma_f32_16x16x32_bf16 v[38:41], v[178:181], v[202:205], v[38:41]
	v_mfma_f32_16x16x32_bf16 v[34:37], v[186:189], v[202:205], v[34:37]
	v_mfma_f32_16x16x32_bf16 v[30:33], v[132:135], v[232:235], v[30:33]
	v_mfma_f32_16x16x32_bf16 v[26:29], v[170:173], v[232:235], v[26:29]
	v_mfma_f32_16x16x32_bf16 v[22:25], v[178:181], v[232:235], v[22:25]
	v_mfma_f32_16x16x32_bf16 v[18:21], v[186:189], v[232:235], v[18:21]
	v_mfma_f32_16x16x32_bf16 v[14:17], v[132:135], v[240:243], v[14:17]
	v_mfma_f32_16x16x32_bf16 v[10:13], v[170:173], v[240:243], v[10:13]
	v_mfma_f32_16x16x32_bf16 v[6:9], v[178:181], v[240:243], v[6:9]
	v_mfma_f32_16x16x32_bf16 v[2:5], v[186:189], v[240:243], v[2:5]
	v_mfma_f32_16x16x32_bf16 v[62:65], v[142:145], v[198:201], v[62:65]
	v_mfma_f32_16x16x32_bf16 v[58:61], v[174:177], v[198:201], v[58:61]
	v_mfma_f32_16x16x32_bf16 v[54:57], v[182:185], v[198:201], v[54:57]
	v_mfma_f32_16x16x32_bf16 v[50:53], v[190:193], v[198:201], v[50:53]
	v_mfma_f32_16x16x32_bf16 v[46:49], v[142:145], v[228:231], v[46:49]
	v_mfma_f32_16x16x32_bf16 v[42:45], v[174:177], v[228:231], v[42:45]
	v_mfma_f32_16x16x32_bf16 v[38:41], v[182:185], v[228:231], v[38:41]
	v_mfma_f32_16x16x32_bf16 v[34:37], v[190:193], v[228:231], v[34:37]
	v_mfma_f32_16x16x32_bf16 v[30:33], v[142:145], v[236:239], v[30:33]
	v_mfma_f32_16x16x32_bf16 v[26:29], v[174:177], v[236:239], v[26:29]
	v_mfma_f32_16x16x32_bf16 v[22:25], v[182:185], v[236:239], v[22:25]
	v_mfma_f32_16x16x32_bf16 v[18:21], v[190:193], v[236:239], v[18:21]
	v_mfma_f32_16x16x32_bf16 v[14:17], v[142:145], v[244:247], v[14:17]
	v_mfma_f32_16x16x32_bf16 v[10:13], v[174:177], v[244:247], v[10:13]
	v_mfma_f32_16x16x32_bf16 v[6:9], v[182:185], v[244:247], v[6:9]
	v_mfma_f32_16x16x32_bf16 v[2:5], v[190:193], v[244:247], v[2:5]
	s_barrier
	s_setprio 0
	s_addk_i32 s13, 0x100
	s_add_i32 s22, s22, 2
	s_add_i32 s21, s21, 0x10000
	s_cmpk_gt_u32 s22, 0x55
	s_cbranch_scc0 .LBB0_580
	s_and_b64 vcc, exec, s[64:65]
	s_cbranch_vccz .LBB0_583
	s_barrier

.LBB0_858:
	s_lshl_b32 s2, s21, 20
	s_and_b64 s[8:9], s[42:43], exec
	s_cselect_b32 s8, s2, s18
	s_lshl_b32 s82, s71, 20
	s_and_b64 s[26:27], s[42:43], exec
	s_cselect_b32 s9, s82, s19
	s_add_i32 s18, s18, 0x80080
	s_addk_i32 s19, 0x100
	s_mov_b32 s22, -2
	v_add_u32_e32 v146, 0x10000, v195
	ds_read_b128 v[130:133], v146
	ds_read_b128 v[138:141], v146 offset:1024
	ds_read_b128 v[142:145], v146 offset:2048
	ds_read_b128 v[154:157], v146 offset:3072
	v_add_u32_e32 v146, 0x14000, v195
	ds_read_b128 v[170:173], v146
	ds_read_b128 v[174:177], v146 offset:1024
	ds_read_b128 v[178:181], v146 offset:2048
	ds_read_b128 v[182:185], v146 offset:3072
	s_add_i32 s26, s18, 0xfff80080
	s_cmp_eq_u32 s22, 28
	s_cselect_b32 s52, s8, s26
	s_cselect_b32 s27, s9, s19
	s_or_b32 s26, s52, 0x80
	s_mov_b32 m0, s85
	ds_read_b128 v[186:189], v196
	ds_read_b128 v[198:201], v196 offset:1024
	ds_read_b128 v[202:205], v196 offset:2048
	ds_read_b128 v[228:231], v196 offset:3072
	ds_read_b128 v[232:235], v196 offset:4096
	ds_read_b128 v[236:239], v196 offset:5120
	ds_read_b128 v[240:243], v196 offset:6144
	ds_read_b128 v[244:247], v196 offset:7168
	buffer_load_dwordx4 v135, s[44:47], s18 offen lds
	s_mov_b32 m0, s15
	s_nop 0
	buffer_load_dwordx4 v193, s[44:47], s18 offen lds
	s_waitcnt vmcnt(8)
	s_waitcnt lgkmcnt(0)
	s_setprio 1
	s_barrier
	v_mfma_f32_16x16x32_bf16 v[126:129], v[130:133], v[186:189], 0
	v_mfma_f32_16x16x32_bf16 v[122:125], v[142:145], v[186:189], 0
	v_mfma_f32_16x16x32_bf16 v[118:121], v[170:173], v[186:189], 0
	v_mfma_f32_16x16x32_bf16 v[114:117], v[178:181], v[186:189], 0
	v_mfma_f32_16x16x32_bf16 v[110:113], v[130:133], v[202:205], 0
	v_mfma_f32_16x16x32_bf16 v[106:109], v[142:145], v[202:205], 0
	v_mfma_f32_16x16x32_bf16 v[102:105], v[170:173], v[202:205], 0
	v_mfma_f32_16x16x32_bf16 v[98:101], v[178:181], v[202:205], 0
	v_mfma_f32_16x16x32_bf16 v[94:97], v[130:133], v[232:235], 0
	v_mfma_f32_16x16x32_bf16 v[90:93], v[142:145], v[232:235], 0
	v_mfma_f32_16x16x32_bf16 v[86:89], v[170:173], v[232:235], 0
	v_mfma_f32_16x16x32_bf16 v[82:85], v[178:181], v[232:235], 0
	v_mfma_f32_16x16x32_bf16 v[78:81], v[130:133], v[240:243], 0
	v_mfma_f32_16x16x32_bf16 v[74:77], v[142:145], v[240:243], 0
	v_mfma_f32_16x16x32_bf16 v[70:73], v[170:173], v[240:243], 0
	v_mfma_f32_16x16x32_bf16 v[66:69], v[178:181], v[240:243], 0
	v_mfma_f32_16x16x32_bf16 v[126:129], v[138:141], v[198:201], v[126:129]
	v_mfma_f32_16x16x32_bf16 v[122:125], v[154:157], v[198:201], v[122:125]
	v_mfma_f32_16x16x32_bf16 v[118:121], v[174:177], v[198:201], v[118:121]
	v_mfma_f32_16x16x32_bf16 v[114:117], v[182:185], v[198:201], v[114:117]
	v_mfma_f32_16x16x32_bf16 v[110:113], v[138:141], v[228:231], v[110:113]
	v_mfma_f32_16x16x32_bf16 v[106:109], v[154:157], v[228:231], v[106:109]
	v_mfma_f32_16x16x32_bf16 v[102:105], v[174:177], v[228:231], v[102:105]
	v_mfma_f32_16x16x32_bf16 v[98:101], v[182:185], v[228:231], v[98:101]
	v_mfma_f32_16x16x32_bf16 v[94:97], v[138:141], v[236:239], v[94:97]
	v_mfma_f32_16x16x32_bf16 v[90:93], v[154:157], v[236:239], v[90:93]
	v_mfma_f32_16x16x32_bf16 v[86:89], v[174:177], v[236:239], v[86:89]
	v_mfma_f32_16x16x32_bf16 v[82:85], v[182:185], v[236:239], v[82:85]
	v_mfma_f32_16x16x32_bf16 v[78:81], v[138:141], v[244:247], v[78:81]
	v_mfma_f32_16x16x32_bf16 v[74:77], v[154:157], v[244:247], v[74:77]
	v_mfma_f32_16x16x32_bf16 v[70:73], v[174:177], v[244:247], v[70:73]
	v_mfma_f32_16x16x32_bf16 v[66:69], v[182:185], v[244:247], v[66:69]
	s_barrier
	s_setprio 0
	s_mov_b32 m0, s23
	s_mov_b32 s66, s46
	s_mov_b32 s67, s47
	ds_read_b128 v[186:189], v196 offset:16384
	ds_read_b128 v[198:201], v196 offset:17408
	ds_read_b128 v[202:205], v196 offset:18432
	ds_read_b128 v[228:231], v196 offset:19456
	ds_read_b128 v[232:235], v196 offset:20480
	ds_read_b128 v[236:239], v196 offset:21504
	ds_read_b128 v[240:243], v196 offset:22528
	ds_read_b128 v[244:247], v196 offset:23552
	buffer_load_dwordx4 v192, s[64:67], s27 offen lds
	s_mov_b32 m0, s24
	s_add_i32 s53, s27, 0x80000
	buffer_load_dwordx4 v194, s[64:67], s27 offen lds
	s_mov_b32 m0, s25
	s_nop 0
	buffer_load_dwordx4 v192, s[64:67], s53 offen lds
	s_mov_b32 m0, s33
	s_nop 0
	buffer_load_dwordx4 v194, s[64:67], s53 offen lds
	s_mov_b32 m0, s13
	s_nop 0
	buffer_load_dwordx4 v135, s[44:47], s52 offen lds
	s_mov_b32 m0, s34
	s_nop 0
	buffer_load_dwordx4 v193, s[44:47], s52 offen lds
	s_waitcnt vmcnt(8)
	s_waitcnt lgkmcnt(0)
	s_setprio 1
	s_barrier
	v_mfma_f32_16x16x32_bf16 v[62:65], v[130:133], v[186:189], 0
	v_mfma_f32_16x16x32_bf16 v[58:61], v[142:145], v[186:189], 0
	v_mfma_f32_16x16x32_bf16 v[54:57], v[170:173], v[186:189], 0
	v_mfma_f32_16x16x32_bf16 v[50:53], v[178:181], v[186:189], 0
	v_mfma_f32_16x16x32_bf16 v[46:49], v[130:133], v[202:205], 0
	v_mfma_f32_16x16x32_bf16 v[42:45], v[142:145], v[202:205], 0
	v_mfma_f32_16x16x32_bf16 v[38:41], v[170:173], v[202:205], 0
	v_mfma_f32_16x16x32_bf16 v[34:37], v[178:181], v[202:205], 0
	v_mfma_f32_16x16x32_bf16 v[30:33], v[130:133], v[232:235], 0
	v_mfma_f32_16x16x32_bf16 v[26:29], v[142:145], v[232:235], 0
	v_mfma_f32_16x16x32_bf16 v[22:25], v[170:173], v[232:235], 0
	v_mfma_f32_16x16x32_bf16 v[18:21], v[178:181], v[232:235], 0
	v_mfma_f32_16x16x32_bf16 v[14:17], v[130:133], v[240:243], 0
	v_mfma_f32_16x16x32_bf16 v[10:13], v[142:145], v[240:243], 0
	v_mfma_f32_16x16x32_bf16 v[6:9], v[170:173], v[240:243], 0
	v_mfma_f32_16x16x32_bf16 v[2:5], v[178:181], v[240:243], 0
	v_mfma_f32_16x16x32_bf16 v[62:65], v[138:141], v[198:201], v[62:65]
	v_mfma_f32_16x16x32_bf16 v[58:61], v[154:157], v[198:201], v[58:61]
	v_mfma_f32_16x16x32_bf16 v[54:57], v[174:177], v[198:201], v[54:57]
	v_mfma_f32_16x16x32_bf16 v[50:53], v[182:185], v[198:201], v[50:53]
	v_mfma_f32_16x16x32_bf16 v[46:49], v[138:141], v[228:231], v[46:49]
	v_mfma_f32_16x16x32_bf16 v[42:45], v[154:157], v[228:231], v[42:45]
	v_mfma_f32_16x16x32_bf16 v[38:41], v[174:177], v[228:231], v[38:41]
	v_mfma_f32_16x16x32_bf16 v[34:37], v[182:185], v[228:231], v[34:37]
	v_mfma_f32_16x16x32_bf16 v[30:33], v[138:141], v[236:239], v[30:33]
	v_mfma_f32_16x16x32_bf16 v[26:29], v[154:157], v[236:239], v[26:29]
	v_mfma_f32_16x16x32_bf16 v[22:25], v[174:177], v[236:239], v[22:25]
	v_mfma_f32_16x16x32_bf16 v[18:21], v[182:185], v[236:239], v[18:21]
	v_mfma_f32_16x16x32_bf16 v[14:17], v[138:141], v[244:247], v[14:17]
	v_mfma_f32_16x16x32_bf16 v[10:13], v[154:157], v[244:247], v[10:13]
	v_mfma_f32_16x16x32_bf16 v[6:9], v[174:177], v[244:247], v[6:9]
	v_mfma_f32_16x16x32_bf16 v[2:5], v[182:185], v[244:247], v[2:5]
	s_barrier
	s_setprio 0
	v_add_u32_e32 v146, 0x18000, v195
	ds_read_b128 v[130:133], v146
	ds_read_b128 v[138:141], v146 offset:1024
	ds_read_b128 v[142:145], v146 offset:2048
	ds_read_b128 v[154:157], v146 offset:3072
	v_add_u32_e32 v146, 0x1c000, v195
	ds_read_b128 v[170:173], v146
	ds_read_b128 v[174:177], v146 offset:1024
	ds_read_b128 v[178:181], v146 offset:2048
	ds_read_b128 v[182:185], v146 offset:3072
	s_add_i32 s52, s52, 0x80000
	s_mov_b32 m0, s35
	ds_read_b128 v[186:189], v196 offset:32768
	ds_read_b128 v[198:201], v196 offset:33792
	ds_read_b128 v[202:205], v196 offset:34816
	ds_read_b128 v[228:231], v196 offset:35840
	ds_read_b128 v[232:235], v196 offset:36864
	ds_read_b128 v[236:239], v196 offset:37888
	ds_read_b128 v[240:243], v196 offset:38912
	ds_read_b128 v[244:247], v196 offset:39936
	buffer_load_dwordx4 v135, s[44:47], s52 offen lds
	s_mov_b32 m0, s36
	s_nop 0
	buffer_load_dwordx4 v193, s[44:47], s52 offen lds
	s_waitcnt vmcnt(8)
	s_waitcnt lgkmcnt(0)
	s_setprio 1
	s_barrier
	v_mfma_f32_16x16x32_bf16 v[126:129], v[130:133], v[186:189], v[126:129]
	v_mfma_f32_16x16x32_bf16 v[122:125], v[142:145], v[186:189], v[122:125]
	v_mfma_f32_16x16x32_bf16 v[118:121], v[170:173], v[186:189], v[118:121]
	v_mfma_f32_16x16x32_bf16 v[114:117], v[178:181], v[186:189], v[114:117]
	v_mfma_f32_16x16x32_bf16 v[110:113], v[130:133], v[202:205], v[110:113]
	v_mfma_f32_16x16x32_bf16 v[106:109], v[142:145], v[202:205], v[106:109]
	v_mfma_f32_16x16x32_bf16 v[102:105], v[170:173], v[202:205], v[102:105]
	v_mfma_f32_16x16x32_bf16 v[98:101], v[178:181], v[202:205], v[98:101]
	v_mfma_f32_16x16x32_bf16 v[94:97], v[130:133], v[232:235], v[94:97]
	v_mfma_f32_16x16x32_bf16 v[90:93], v[142:145], v[232:235], v[90:93]
	v_mfma_f32_16x16x32_bf16 v[86:89], v[170:173], v[232:235], v[86:89]
	v_mfma_f32_16x16x32_bf16 v[82:85], v[178:181], v[232:235], v[82:85]
	v_mfma_f32_16x16x32_bf16 v[78:81], v[130:133], v[240:243], v[78:81]
	v_mfma_f32_16x16x32_bf16 v[74:77], v[142:145], v[240:243], v[74:77]
	v_mfma_f32_16x16x32_bf16 v[70:73], v[170:173], v[240:243], v[70:73]
	v_mfma_f32_16x16x32_bf16 v[66:69], v[178:181], v[240:243], v[66:69]
	v_mfma_f32_16x16x32_bf16 v[126:129], v[138:141], v[198:201], v[126:129]
	v_mfma_f32_16x16x32_bf16 v[122:125], v[154:157], v[198:201], v[122:125]
	v_mfma_f32_16x16x32_bf16 v[118:121], v[174:177], v[198:201], v[118:121]
	v_mfma_f32_16x16x32_bf16 v[114:117], v[182:185], v[198:201], v[114:117]
	v_mfma_f32_16x16x32_bf16 v[110:113], v[138:141], v[228:231], v[110:113]
	v_mfma_f32_16x16x32_bf16 v[106:109], v[154:157], v[228:231], v[106:109]
	v_mfma_f32_16x16x32_bf16 v[102:105], v[174:177], v[228:231], v[102:105]
	v_mfma_f32_16x16x32_bf16 v[98:101], v[182:185], v[228:231], v[98:101]
	v_mfma_f32_16x16x32_bf16 v[94:97], v[138:141], v[236:239], v[94:97]
	v_mfma_f32_16x16x32_bf16 v[90:93], v[154:157], v[236:239], v[90:93]
	v_mfma_f32_16x16x32_bf16 v[86:89], v[174:177], v[236:239], v[86:89]
	v_mfma_f32_16x16x32_bf16 v[82:85], v[182:185], v[236:239], v[82:85]
	v_mfma_f32_16x16x32_bf16 v[78:81], v[138:141], v[244:247], v[78:81]
	v_mfma_f32_16x16x32_bf16 v[74:77], v[154:157], v[244:247], v[74:77]
	v_mfma_f32_16x16x32_bf16 v[70:73], v[174:177], v[244:247], v[70:73]
	v_mfma_f32_16x16x32_bf16 v[66:69], v[182:185], v[244:247], v[66:69]
	s_barrier
	s_setprio 0
	s_mov_b32 m0, s41
	s_or_b32 s52, s27, 0x80
	ds_read_b128 v[186:189], v196 offset:49152
	ds_read_b128 v[198:201], v196 offset:50176
	ds_read_b128 v[202:205], v196 offset:51200
	ds_read_b128 v[228:231], v196 offset:52224
	ds_read_b128 v[232:235], v196 offset:53248
	ds_read_b128 v[236:239], v196 offset:54272
	ds_read_b128 v[240:243], v196 offset:55296
	ds_read_b128 v[244:247], v196 offset:56320
	buffer_load_dwordx4 v192, s[64:67], s52 offen lds
	s_mov_b32 m0, s48
	s_add_i32 s27, s27, 0x80080
	buffer_load_dwordx4 v194, s[64:67], s52 offen lds
	s_mov_b32 m0, s69
	s_nop 0
	buffer_load_dwordx4 v192, s[64:67], s27 offen lds
	s_mov_b32 m0, s72
	s_nop 0
	buffer_load_dwordx4 v194, s[64:67], s27 offen lds
	s_mov_b32 m0, s49
	s_nop 0
	buffer_load_dwordx4 v135, s[44:47], s26 offen lds
	s_mov_b32 m0, s68
	s_nop 0
	buffer_load_dwordx4 v193, s[44:47], s26 offen lds
	s_waitcnt vmcnt(8)
	s_waitcnt lgkmcnt(0)
	s_setprio 1
	s_barrier
	v_mfma_f32_16x16x32_bf16 v[62:65], v[130:133], v[186:189], v[62:65]
	v_mfma_f32_16x16x32_bf16 v[58:61], v[142:145], v[186:189], v[58:61]
	v_mfma_f32_16x16x32_bf16 v[54:57], v[170:173], v[186:189], v[54:57]
	v_mfma_f32_16x16x32_bf16 v[50:53], v[178:181], v[186:189], v[50:53]
	v_mfma_f32_16x16x32_bf16 v[46:49], v[130:133], v[202:205], v[46:49]
	v_mfma_f32_16x16x32_bf16 v[42:45], v[142:145], v[202:205], v[42:45]
	v_mfma_f32_16x16x32_bf16 v[38:41], v[170:173], v[202:205], v[38:41]
	v_mfma_f32_16x16x32_bf16 v[34:37], v[178:181], v[202:205], v[34:37]
	v_mfma_f32_16x16x32_bf16 v[30:33], v[130:133], v[232:235], v[30:33]
	v_mfma_f32_16x16x32_bf16 v[26:29], v[142:145], v[232:235], v[26:29]
	v_mfma_f32_16x16x32_bf16 v[22:25], v[170:173], v[232:235], v[22:25]
	v_mfma_f32_16x16x32_bf16 v[18:21], v[178:181], v[232:235], v[18:21]
	v_mfma_f32_16x16x32_bf16 v[14:17], v[130:133], v[240:243], v[14:17]
	v_mfma_f32_16x16x32_bf16 v[10:13], v[142:145], v[240:243], v[10:13]
	v_mfma_f32_16x16x32_bf16 v[6:9], v[170:173], v[240:243], v[6:9]
	v_mfma_f32_16x16x32_bf16 v[2:5], v[178:181], v[240:243], v[2:5]
	v_mfma_f32_16x16x32_bf16 v[62:65], v[138:141], v[198:201], v[62:65]
	v_mfma_f32_16x16x32_bf16 v[58:61], v[154:157], v[198:201], v[58:61]
	v_mfma_f32_16x16x32_bf16 v[54:57], v[174:177], v[198:201], v[54:57]
	v_mfma_f32_16x16x32_bf16 v[50:53], v[182:185], v[198:201], v[50:53]
	v_mfma_f32_16x16x32_bf16 v[46:49], v[138:141], v[228:231], v[46:49]
	v_mfma_f32_16x16x32_bf16 v[42:45], v[154:157], v[228:231], v[42:45]
	v_mfma_f32_16x16x32_bf16 v[38:41], v[174:177], v[228:231], v[38:41]
	v_mfma_f32_16x16x32_bf16 v[34:37], v[182:185], v[228:231], v[34:37]
	v_mfma_f32_16x16x32_bf16 v[30:33], v[138:141], v[236:239], v[30:33]
	v_mfma_f32_16x16x32_bf16 v[26:29], v[154:157], v[236:239], v[26:29]
	v_mfma_f32_16x16x32_bf16 v[22:25], v[174:177], v[236:239], v[22:25]
	v_mfma_f32_16x16x32_bf16 v[18:21], v[182:185], v[236:239], v[18:21]
	v_mfma_f32_16x16x32_bf16 v[14:17], v[138:141], v[244:247], v[14:17]
	v_mfma_f32_16x16x32_bf16 v[10:13], v[154:157], v[244:247], v[10:13]
	v_mfma_f32_16x16x32_bf16 v[6:9], v[174:177], v[244:247], v[6:9]
	v_mfma_f32_16x16x32_bf16 v[2:5], v[182:185], v[244:247], v[2:5]
	s_barrier
	s_setprio 0
	s_add_i32 s22, s22, 2
	s_addk_i32 s18, 0x100
	s_addk_i32 s19, 0x100
	s_cmp_gt_u32 s22, 29
.LBB0_859:
	v_add_u32_e32 v146, 0x10000, v195
	ds_read_b128 v[130:133], v146
	ds_read_b128 v[138:141], v146 offset:1024
	ds_read_b128 v[142:145], v146 offset:2048
	ds_read_b128 v[154:157], v146 offset:3072
	v_add_u32_e32 v146, 0x14000, v195
	ds_read_b128 v[170:173], v146
	ds_read_b128 v[174:177], v146 offset:1024
	ds_read_b128 v[178:181], v146 offset:2048
	ds_read_b128 v[182:185], v146 offset:3072
	s_add_i32 s26, s18, 0xfff80080
	s_cmp_eq_u32 s22, 28
	s_cselect_b32 s52, s8, s26
	s_cselect_b32 s27, s9, s19
	s_or_b32 s26, s52, 0x80
	s_mov_b32 m0, s85
	ds_read_b128 v[186:189], v196
	ds_read_b128 v[198:201], v196 offset:1024
	ds_read_b128 v[202:205], v196 offset:2048
	ds_read_b128 v[228:231], v196 offset:3072
	ds_read_b128 v[232:235], v196 offset:4096
	ds_read_b128 v[236:239], v196 offset:5120
	ds_read_b128 v[240:243], v196 offset:6144
	ds_read_b128 v[244:247], v196 offset:7168
	buffer_load_dwordx4 v135, s[44:47], s18 offen lds
	s_mov_b32 m0, s15
	s_nop 0
	buffer_load_dwordx4 v193, s[44:47], s18 offen lds
	s_waitcnt vmcnt(8)
	s_waitcnt lgkmcnt(0)
	s_setprio 1
	s_barrier
	v_mfma_f32_16x16x32_bf16 v[126:129], v[130:133], v[186:189], v[126:129]
	v_mfma_f32_16x16x32_bf16 v[122:125], v[142:145], v[186:189], v[122:125]
	v_mfma_f32_16x16x32_bf16 v[118:121], v[170:173], v[186:189], v[118:121]
	v_mfma_f32_16x16x32_bf16 v[114:117], v[178:181], v[186:189], v[114:117]
	v_mfma_f32_16x16x32_bf16 v[110:113], v[130:133], v[202:205], v[110:113]
	v_mfma_f32_16x16x32_bf16 v[106:109], v[142:145], v[202:205], v[106:109]
	v_mfma_f32_16x16x32_bf16 v[102:105], v[170:173], v[202:205], v[102:105]
	v_mfma_f32_16x16x32_bf16 v[98:101], v[178:181], v[202:205], v[98:101]
	v_mfma_f32_16x16x32_bf16 v[94:97], v[130:133], v[232:235], v[94:97]
	v_mfma_f32_16x16x32_bf16 v[90:93], v[142:145], v[232:235], v[90:93]
	v_mfma_f32_16x16x32_bf16 v[86:89], v[170:173], v[232:235], v[86:89]
	v_mfma_f32_16x16x32_bf16 v[82:85], v[178:181], v[232:235], v[82:85]
	v_mfma_f32_16x16x32_bf16 v[78:81], v[130:133], v[240:243], v[78:81]
	v_mfma_f32_16x16x32_bf16 v[74:77], v[142:145], v[240:243], v[74:77]
	v_mfma_f32_16x16x32_bf16 v[70:73], v[170:173], v[240:243], v[70:73]
	v_mfma_f32_16x16x32_bf16 v[66:69], v[178:181], v[240:243], v[66:69]
	v_mfma_f32_16x16x32_bf16 v[126:129], v[138:141], v[198:201], v[126:129]
	v_mfma_f32_16x16x32_bf16 v[122:125], v[154:157], v[198:201], v[122:125]
	v_mfma_f32_16x16x32_bf16 v[118:121], v[174:177], v[198:201], v[118:121]
	v_mfma_f32_16x16x32_bf16 v[114:117], v[182:185], v[198:201], v[114:117]
	v_mfma_f32_16x16x32_bf16 v[110:113], v[138:141], v[228:231], v[110:113]
	v_mfma_f32_16x16x32_bf16 v[106:109], v[154:157], v[228:231], v[106:109]
	v_mfma_f32_16x16x32_bf16 v[102:105], v[174:177], v[228:231], v[102:105]
	v_mfma_f32_16x16x32_bf16 v[98:101], v[182:185], v[228:231], v[98:101]
	v_mfma_f32_16x16x32_bf16 v[94:97], v[138:141], v[236:239], v[94:97]
	v_mfma_f32_16x16x32_bf16 v[90:93], v[154:157], v[236:239], v[90:93]
	v_mfma_f32_16x16x32_bf16 v[86:89], v[174:177], v[236:239], v[86:89]
	v_mfma_f32_16x16x32_bf16 v[82:85], v[182:185], v[236:239], v[82:85]
	v_mfma_f32_16x16x32_bf16 v[78:81], v[138:141], v[244:247], v[78:81]
	v_mfma_f32_16x16x32_bf16 v[74:77], v[154:157], v[244:247], v[74:77]
	v_mfma_f32_16x16x32_bf16 v[70:73], v[174:177], v[244:247], v[70:73]
	v_mfma_f32_16x16x32_bf16 v[66:69], v[182:185], v[244:247], v[66:69]
	s_barrier
	s_setprio 0
	s_mov_b32 m0, s23
	s_mov_b32 s66, s46
	s_mov_b32 s67, s47
	ds_read_b128 v[186:189], v196 offset:16384
	ds_read_b128 v[198:201], v196 offset:17408
	ds_read_b128 v[202:205], v196 offset:18432
	ds_read_b128 v[228:231], v196 offset:19456
	ds_read_b128 v[232:235], v196 offset:20480
	ds_read_b128 v[236:239], v196 offset:21504
	ds_read_b128 v[240:243], v196 offset:22528
	ds_read_b128 v[244:247], v196 offset:23552
	buffer_load_dwordx4 v192, s[64:67], s27 offen lds
	s_mov_b32 m0, s24
	s_add_i32 s53, s27, 0x80000
	buffer_load_dwordx4 v194, s[64:67], s27 offen lds
	s_mov_b32 m0, s25
	s_nop 0
	buffer_load_dwordx4 v192, s[64:67], s53 offen lds
	s_mov_b32 m0, s33
	s_nop 0
	buffer_load_dwordx4 v194, s[64:67], s53 offen lds
	s_mov_b32 m0, s13
	s_nop 0
	buffer_load_dwordx4 v135, s[44:47], s52 offen lds
	s_mov_b32 m0, s34
	s_nop 0
	buffer_load_dwordx4 v193, s[44:47], s52 offen lds
	s_waitcnt vmcnt(8)
	s_waitcnt lgkmcnt(0)
	s_setprio 1
	s_barrier
	v_mfma_f32_16x16x32_bf16 v[62:65], v[130:133], v[186:189], v[62:65]
	v_mfma_f32_16x16x32_bf16 v[58:61], v[142:145], v[186:189], v[58:61]
	v_mfma_f32_16x16x32_bf16 v[54:57], v[170:173], v[186:189], v[54:57]
	v_mfma_f32_16x16x32_bf16 v[50:53], v[178:181], v[186:189], v[50:53]
	v_mfma_f32_16x16x32_bf16 v[46:49], v[130:133], v[202:205], v[46:49]
	v_mfma_f32_16x16x32_bf16 v[42:45], v[142:145], v[202:205], v[42:45]
	v_mfma_f32_16x16x32_bf16 v[38:41], v[170:173], v[202:205], v[38:41]
	v_mfma_f32_16x16x32_bf16 v[34:37], v[178:181], v[202:205], v[34:37]
	v_mfma_f32_16x16x32_bf16 v[30:33], v[130:133], v[232:235], v[30:33]
	v_mfma_f32_16x16x32_bf16 v[26:29], v[142:145], v[232:235], v[26:29]
	v_mfma_f32_16x16x32_bf16 v[22:25], v[170:173], v[232:235], v[22:25]
	v_mfma_f32_16x16x32_bf16 v[18:21], v[178:181], v[232:235], v[18:21]
	v_mfma_f32_16x16x32_bf16 v[14:17], v[130:133], v[240:243], v[14:17]
	v_mfma_f32_16x16x32_bf16 v[10:13], v[142:145], v[240:243], v[10:13]
	v_mfma_f32_16x16x32_bf16 v[6:9], v[170:173], v[240:243], v[6:9]
	v_mfma_f32_16x16x32_bf16 v[2:5], v[178:181], v[240:243], v[2:5]
	v_mfma_f32_16x16x32_bf16 v[62:65], v[138:141], v[198:201], v[62:65]
	v_mfma_f32_16x16x32_bf16 v[58:61], v[154:157], v[198:201], v[58:61]
	v_mfma_f32_16x16x32_bf16 v[54:57], v[174:177], v[198:201], v[54:57]
	v_mfma_f32_16x16x32_bf16 v[50:53], v[182:185], v[198:201], v[50:53]
	v_mfma_f32_16x16x32_bf16 v[46:49], v[138:141], v[228:231], v[46:49]
	v_mfma_f32_16x16x32_bf16 v[42:45], v[154:157], v[228:231], v[42:45]
	v_mfma_f32_16x16x32_bf16 v[38:41], v[174:177], v[228:231], v[38:41]
	v_mfma_f32_16x16x32_bf16 v[34:37], v[182:185], v[228:231], v[34:37]
	v_mfma_f32_16x16x32_bf16 v[30:33], v[138:141], v[236:239], v[30:33]
	v_mfma_f32_16x16x32_bf16 v[26:29], v[154:157], v[236:239], v[26:29]
	v_mfma_f32_16x16x32_bf16 v[22:25], v[174:177], v[236:239], v[22:25]
	v_mfma_f32_16x16x32_bf16 v[18:21], v[182:185], v[236:239], v[18:21]
	v_mfma_f32_16x16x32_bf16 v[14:17], v[138:141], v[244:247], v[14:17]
	v_mfma_f32_16x16x32_bf16 v[10:13], v[154:157], v[244:247], v[10:13]
	v_mfma_f32_16x16x32_bf16 v[6:9], v[174:177], v[244:247], v[6:9]
	v_mfma_f32_16x16x32_bf16 v[2:5], v[182:185], v[244:247], v[2:5]
	s_barrier
	s_setprio 0
	v_add_u32_e32 v146, 0x18000, v195
	ds_read_b128 v[130:133], v146
	ds_read_b128 v[138:141], v146 offset:1024
	ds_read_b128 v[142:145], v146 offset:2048
	ds_read_b128 v[154:157], v146 offset:3072
	v_add_u32_e32 v146, 0x1c000, v195
	ds_read_b128 v[170:173], v146
	ds_read_b128 v[174:177], v146 offset:1024
	ds_read_b128 v[178:181], v146 offset:2048
	ds_read_b128 v[182:185], v146 offset:3072
	s_add_i32 s52, s52, 0x80000
	s_mov_b32 m0, s35
	ds_read_b128 v[186:189], v196 offset:32768
	ds_read_b128 v[198:201], v196 offset:33792
	ds_read_b128 v[202:205], v196 offset:34816
	ds_read_b128 v[228:231], v196 offset:35840
	ds_read_b128 v[232:235], v196 offset:36864
	ds_read_b128 v[236:239], v196 offset:37888
	ds_read_b128 v[240:243], v196 offset:38912
	ds_read_b128 v[244:247], v196 offset:39936
	buffer_load_dwordx4 v135, s[44:47], s52 offen lds
	s_mov_b32 m0, s36
	s_nop 0
	buffer_load_dwordx4 v193, s[44:47], s52 offen lds
	s_waitcnt vmcnt(8)
	s_waitcnt lgkmcnt(0)
	s_setprio 1
	s_barrier
	v_mfma_f32_16x16x32_bf16 v[126:129], v[130:133], v[186:189], v[126:129]
	v_mfma_f32_16x16x32_bf16 v[122:125], v[142:145], v[186:189], v[122:125]
	v_mfma_f32_16x16x32_bf16 v[118:121], v[170:173], v[186:189], v[118:121]
	v_mfma_f32_16x16x32_bf16 v[114:117], v[178:181], v[186:189], v[114:117]
	v_mfma_f32_16x16x32_bf16 v[110:113], v[130:133], v[202:205], v[110:113]
	v_mfma_f32_16x16x32_bf16 v[106:109], v[142:145], v[202:205], v[106:109]
	v_mfma_f32_16x16x32_bf16 v[102:105], v[170:173], v[202:205], v[102:105]
	v_mfma_f32_16x16x32_bf16 v[98:101], v[178:181], v[202:205], v[98:101]
	v_mfma_f32_16x16x32_bf16 v[94:97], v[130:133], v[232:235], v[94:97]
	v_mfma_f32_16x16x32_bf16 v[90:93], v[142:145], v[232:235], v[90:93]
	v_mfma_f32_16x16x32_bf16 v[86:89], v[170:173], v[232:235], v[86:89]
	v_mfma_f32_16x16x32_bf16 v[82:85], v[178:181], v[232:235], v[82:85]
	v_mfma_f32_16x16x32_bf16 v[78:81], v[130:133], v[240:243], v[78:81]
	v_mfma_f32_16x16x32_bf16 v[74:77], v[142:145], v[240:243], v[74:77]
	v_mfma_f32_16x16x32_bf16 v[70:73], v[170:173], v[240:243], v[70:73]
	v_mfma_f32_16x16x32_bf16 v[66:69], v[178:181], v[240:243], v[66:69]
	v_mfma_f32_16x16x32_bf16 v[126:129], v[138:141], v[198:201], v[126:129]
	v_mfma_f32_16x16x32_bf16 v[122:125], v[154:157], v[198:201], v[122:125]
	v_mfma_f32_16x16x32_bf16 v[118:121], v[174:177], v[198:201], v[118:121]
	v_mfma_f32_16x16x32_bf16 v[114:117], v[182:185], v[198:201], v[114:117]
	v_mfma_f32_16x16x32_bf16 v[110:113], v[138:141], v[228:231], v[110:113]
	v_mfma_f32_16x16x32_bf16 v[106:109], v[154:157], v[228:231], v[106:109]
	v_mfma_f32_16x16x32_bf16 v[102:105], v[174:177], v[228:231], v[102:105]
	v_mfma_f32_16x16x32_bf16 v[98:101], v[182:185], v[228:231], v[98:101]
	v_mfma_f32_16x16x32_bf16 v[94:97], v[138:141], v[236:239], v[94:97]
	v_mfma_f32_16x16x32_bf16 v[90:93], v[154:157], v[236:239], v[90:93]
	v_mfma_f32_16x16x32_bf16 v[86:89], v[174:177], v[236:239], v[86:89]
	v_mfma_f32_16x16x32_bf16 v[82:85], v[182:185], v[236:239], v[82:85]
	v_mfma_f32_16x16x32_bf16 v[78:81], v[138:141], v[244:247], v[78:81]
	v_mfma_f32_16x16x32_bf16 v[74:77], v[154:157], v[244:247], v[74:77]
	v_mfma_f32_16x16x32_bf16 v[70:73], v[174:177], v[244:247], v[70:73]
	v_mfma_f32_16x16x32_bf16 v[66:69], v[182:185], v[244:247], v[66:69]
	s_barrier
	s_setprio 0
	s_mov_b32 m0, s41
	s_or_b32 s52, s27, 0x80
	ds_read_b128 v[186:189], v196 offset:49152
	ds_read_b128 v[198:201], v196 offset:50176
	ds_read_b128 v[202:205], v196 offset:51200
	ds_read_b128 v[228:231], v196 offset:52224
	ds_read_b128 v[232:235], v196 offset:53248
	ds_read_b128 v[236:239], v196 offset:54272
	ds_read_b128 v[240:243], v196 offset:55296
	ds_read_b128 v[244:247], v196 offset:56320
	buffer_load_dwordx4 v192, s[64:67], s52 offen lds
	s_mov_b32 m0, s48
	s_add_i32 s27, s27, 0x80080
	buffer_load_dwordx4 v194, s[64:67], s52 offen lds
	s_mov_b32 m0, s69
	s_nop 0
	buffer_load_dwordx4 v192, s[64:67], s27 offen lds
	s_mov_b32 m0, s72
	s_nop 0
	buffer_load_dwordx4 v194, s[64:67], s27 offen lds
	s_mov_b32 m0, s49
	s_nop 0
	buffer_load_dwordx4 v135, s[44:47], s26 offen lds
	s_mov_b32 m0, s68
	s_nop 0
	buffer_load_dwordx4 v193, s[44:47], s26 offen lds
	s_waitcnt vmcnt(8)
	s_waitcnt lgkmcnt(0)
	s_setprio 1
	s_barrier
	v_mfma_f32_16x16x32_bf16 v[62:65], v[130:133], v[186:189], v[62:65]
	v_mfma_f32_16x16x32_bf16 v[58:61], v[142:145], v[186:189], v[58:61]
	v_mfma_f32_16x16x32_bf16 v[54:57], v[170:173], v[186:189], v[54:57]
	v_mfma_f32_16x16x32_bf16 v[50:53], v[178:181], v[186:189], v[50:53]
	v_mfma_f32_16x16x32_bf16 v[46:49], v[130:133], v[202:205], v[46:49]
	v_mfma_f32_16x16x32_bf16 v[42:45], v[142:145], v[202:205], v[42:45]
	v_mfma_f32_16x16x32_bf16 v[38:41], v[170:173], v[202:205], v[38:41]
	v_mfma_f32_16x16x32_bf16 v[34:37], v[178:181], v[202:205], v[34:37]
	v_mfma_f32_16x16x32_bf16 v[30:33], v[130:133], v[232:235], v[30:33]
	v_mfma_f32_16x16x32_bf16 v[26:29], v[142:145], v[232:235], v[26:29]
	v_mfma_f32_16x16x32_bf16 v[22:25], v[170:173], v[232:235], v[22:25]
	v_mfma_f32_16x16x32_bf16 v[18:21], v[178:181], v[232:235], v[18:21]
	v_mfma_f32_16x16x32_bf16 v[14:17], v[130:133], v[240:243], v[14:17]
	v_mfma_f32_16x16x32_bf16 v[10:13], v[142:145], v[240:243], v[10:13]
	v_mfma_f32_16x16x32_bf16 v[6:9], v[170:173], v[240:243], v[6:9]
	v_mfma_f32_16x16x32_bf16 v[2:5], v[178:181], v[240:243], v[2:5]
	v_mfma_f32_16x16x32_bf16 v[62:65], v[138:141], v[198:201], v[62:65]
	v_mfma_f32_16x16x32_bf16 v[58:61], v[154:157], v[198:201], v[58:61]
	v_mfma_f32_16x16x32_bf16 v[54:57], v[174:177], v[198:201], v[54:57]
	v_mfma_f32_16x16x32_bf16 v[50:53], v[182:185], v[198:201], v[50:53]
	v_mfma_f32_16x16x32_bf16 v[46:49], v[138:141], v[228:231], v[46:49]
	v_mfma_f32_16x16x32_bf16 v[42:45], v[154:157], v[228:231], v[42:45]
	v_mfma_f32_16x16x32_bf16 v[38:41], v[174:177], v[228:231], v[38:41]
	v_mfma_f32_16x16x32_bf16 v[34:37], v[182:185], v[228:231], v[34:37]
	v_mfma_f32_16x16x32_bf16 v[30:33], v[138:141], v[236:239], v[30:33]
	v_mfma_f32_16x16x32_bf16 v[26:29], v[154:157], v[236:239], v[26:29]
	v_mfma_f32_16x16x32_bf16 v[22:25], v[174:177], v[236:239], v[22:25]
	v_mfma_f32_16x16x32_bf16 v[18:21], v[182:185], v[236:239], v[18:21]
	v_mfma_f32_16x16x32_bf16 v[14:17], v[138:141], v[244:247], v[14:17]
	v_mfma_f32_16x16x32_bf16 v[10:13], v[154:157], v[244:247], v[10:13]
	v_mfma_f32_16x16x32_bf16 v[6:9], v[174:177], v[244:247], v[6:9]
	v_mfma_f32_16x16x32_bf16 v[2:5], v[182:185], v[244:247], v[2:5]
	s_barrier
	s_setprio 0
	s_add_i32 s22, s22, 2
	s_addk_i32 s18, 0x100
	s_addk_i32 s19, 0x100
	s_cmp_gt_u32 s22, 29
	s_cbranch_scc0 .LBB0_859
	s_and_b64 vcc, exec, s[60:61]
	s_cbranch_vccz .LBB0_862
	s_barrier

.LBB0_880:
	s_lshl_b32 s14, s85, 20
	s_and_b64 s[8:9], s[42:43], exec
	s_cselect_b32 s8, s14, s12
	s_lshl_b32 s15, s66, 20
	s_and_b64 s[22:23], s[42:43], exec
	s_cselect_b32 s9, s15, s13
	s_add_i32 s12, s12, 0x80080
	s_addk_i32 s13, 0x100
	s_mov_b32 s16, -2
	v_add_u32_e32 v139, 0x10000, v234
	ds_read_b128 v[130:133], v139
	ds_read_b128 v[140:143], v139 offset:1024
	ds_read_b128 v[170:173], v139 offset:2048
	ds_read_b128 v[174:177], v139 offset:3072
	v_add_u32_e32 v139, 0x14000, v234
	ds_read_b128 v[178:181], v139
	ds_read_b128 v[182:185], v139 offset:1024
	ds_read_b128 v[186:189], v139 offset:2048
	ds_read_b128 v[190:193], v139 offset:3072
	s_add_i32 s21, s12, 0xfff80080
	s_cmp_eq_u32 s16, 28
	s_cselect_b32 s23, s8, s21
	s_cselect_b32 s22, s9, s13
	s_or_b32 s21, s23, 0x80
	s_mov_b32 m0, s72
	ds_read_b128 v[194:197], v235
	ds_read_b128 v[198:201], v235 offset:1024
	ds_read_b128 v[202:205], v235 offset:2048
	ds_read_b128 v[236:239], v235 offset:3072
	ds_read_b128 v[240:243], v235 offset:4096
	ds_read_b128 v[244:247], v235 offset:5120
	ds_read_b128 v[248:251], v235 offset:6144
	ds_read_b128 v[154:157], v235 offset:7168
	buffer_load_dwordx4 v228, s[60:63], s12 offen lds
	s_mov_b32 m0, s73
	s_nop 0
	buffer_load_dwordx4 v230, s[60:63], s12 offen lds
	s_waitcnt vmcnt(8)
	s_waitcnt lgkmcnt(0)
	s_setprio 1
	s_barrier
	v_mfma_f32_16x16x32_bf16 v[126:129], v[130:133], v[194:197], 0
	v_mfma_f32_16x16x32_bf16 v[122:125], v[170:173], v[194:197], 0
	v_mfma_f32_16x16x32_bf16 v[118:121], v[178:181], v[194:197], 0
	v_mfma_f32_16x16x32_bf16 v[110:113], v[186:189], v[194:197], 0
	v_mfma_f32_16x16x32_bf16 v[114:117], v[130:133], v[202:205], 0
	v_mfma_f32_16x16x32_bf16 v[106:109], v[170:173], v[202:205], 0
	v_mfma_f32_16x16x32_bf16 v[102:105], v[178:181], v[202:205], 0
	v_mfma_f32_16x16x32_bf16 v[94:97], v[186:189], v[202:205], 0
	v_mfma_f32_16x16x32_bf16 v[98:101], v[130:133], v[240:243], 0
	v_mfma_f32_16x16x32_bf16 v[90:93], v[170:173], v[240:243], 0
	v_mfma_f32_16x16x32_bf16 v[86:89], v[178:181], v[240:243], 0
	v_mfma_f32_16x16x32_bf16 v[78:81], v[186:189], v[240:243], 0
	v_mfma_f32_16x16x32_bf16 v[82:85], v[130:133], v[248:251], 0
	v_mfma_f32_16x16x32_bf16 v[74:77], v[170:173], v[248:251], 0
	v_mfma_f32_16x16x32_bf16 v[70:73], v[178:181], v[248:251], 0
	v_mfma_f32_16x16x32_bf16 v[66:69], v[186:189], v[248:251], 0
	v_mfma_f32_16x16x32_bf16 v[126:129], v[140:143], v[198:201], v[126:129]
	v_mfma_f32_16x16x32_bf16 v[122:125], v[174:177], v[198:201], v[122:125]
	v_mfma_f32_16x16x32_bf16 v[118:121], v[182:185], v[198:201], v[118:121]
	v_mfma_f32_16x16x32_bf16 v[110:113], v[190:193], v[198:201], v[110:113]
	v_mfma_f32_16x16x32_bf16 v[114:117], v[140:143], v[236:239], v[114:117]
	v_mfma_f32_16x16x32_bf16 v[106:109], v[174:177], v[236:239], v[106:109]
	v_mfma_f32_16x16x32_bf16 v[102:105], v[182:185], v[236:239], v[102:105]
	v_mfma_f32_16x16x32_bf16 v[94:97], v[190:193], v[236:239], v[94:97]
	v_mfma_f32_16x16x32_bf16 v[98:101], v[140:143], v[244:247], v[98:101]
	v_mfma_f32_16x16x32_bf16 v[90:93], v[174:177], v[244:247], v[90:93]
	v_mfma_f32_16x16x32_bf16 v[86:89], v[182:185], v[244:247], v[86:89]
	v_mfma_f32_16x16x32_bf16 v[78:81], v[190:193], v[244:247], v[78:81]
	v_mfma_f32_16x16x32_bf16 v[82:85], v[140:143], v[154:157], v[82:85]
	v_mfma_f32_16x16x32_bf16 v[74:77], v[174:177], v[154:157], v[74:77]
	v_mfma_f32_16x16x32_bf16 v[70:73], v[182:185], v[154:157], v[70:73]
	v_mfma_f32_16x16x32_bf16 v[66:69], v[190:193], v[154:157], v[66:69]
	s_barrier
	s_setprio 0
	s_mov_b32 m0, s26
	s_mov_b32 s46, s62
	s_mov_b32 s47, s63
	ds_read_b128 v[154:157], v235 offset:16384
	ds_read_b128 v[194:197], v235 offset:17408
	ds_read_b128 v[198:201], v235 offset:18432
	ds_read_b128 v[202:205], v235 offset:19456
	ds_read_b128 v[236:239], v235 offset:20480
	ds_read_b128 v[240:243], v235 offset:21504
	ds_read_b128 v[244:247], v235 offset:22528
	ds_read_b128 v[248:251], v235 offset:23552
	buffer_load_dwordx4 v229, s[44:47], s22 offen lds
	s_mov_b32 m0, s27
	s_add_i32 s38, s22, 0x80000
	buffer_load_dwordx4 v231, s[44:47], s22 offen lds
	s_mov_b32 m0, s34
	s_nop 0
	buffer_load_dwordx4 v229, s[44:47], s38 offen lds
	s_mov_b32 m0, s35
	s_nop 0
	buffer_load_dwordx4 v231, s[44:47], s38 offen lds
	s_mov_b32 m0, s19
	s_nop 0
	buffer_load_dwordx4 v228, s[60:63], s23 offen lds
	s_mov_b32 m0, s36
	s_nop 0
	buffer_load_dwordx4 v230, s[60:63], s23 offen lds
	s_waitcnt vmcnt(8)
	s_waitcnt lgkmcnt(0)
	s_setprio 1
	s_barrier
	v_mfma_f32_16x16x32_bf16 v[62:65], v[130:133], v[154:157], 0
	v_mfma_f32_16x16x32_bf16 v[58:61], v[170:173], v[154:157], 0
	v_mfma_f32_16x16x32_bf16 v[54:57], v[178:181], v[154:157], 0
	v_mfma_f32_16x16x32_bf16 v[46:49], v[186:189], v[154:157], 0
	v_mfma_f32_16x16x32_bf16 v[50:53], v[130:133], v[198:201], 0
	v_mfma_f32_16x16x32_bf16 v[42:45], v[170:173], v[198:201], 0
	v_mfma_f32_16x16x32_bf16 v[38:41], v[178:181], v[198:201], 0
	v_mfma_f32_16x16x32_bf16 v[30:33], v[186:189], v[198:201], 0
	v_mfma_f32_16x16x32_bf16 v[34:37], v[130:133], v[236:239], 0
	v_mfma_f32_16x16x32_bf16 v[26:29], v[170:173], v[236:239], 0
	v_mfma_f32_16x16x32_bf16 v[22:25], v[178:181], v[236:239], 0
	v_mfma_f32_16x16x32_bf16 v[14:17], v[186:189], v[236:239], 0
	v_mfma_f32_16x16x32_bf16 v[18:21], v[130:133], v[244:247], 0
	v_mfma_f32_16x16x32_bf16 v[10:13], v[170:173], v[244:247], 0
	v_mfma_f32_16x16x32_bf16 v[6:9], v[178:181], v[244:247], 0
	v_mfma_f32_16x16x32_bf16 v[2:5], v[186:189], v[244:247], 0
	v_mfma_f32_16x16x32_bf16 v[62:65], v[140:143], v[194:197], v[62:65]
	v_mfma_f32_16x16x32_bf16 v[58:61], v[174:177], v[194:197], v[58:61]
	v_mfma_f32_16x16x32_bf16 v[54:57], v[182:185], v[194:197], v[54:57]
	v_mfma_f32_16x16x32_bf16 v[46:49], v[190:193], v[194:197], v[46:49]
	v_mfma_f32_16x16x32_bf16 v[50:53], v[140:143], v[202:205], v[50:53]
	v_mfma_f32_16x16x32_bf16 v[42:45], v[174:177], v[202:205], v[42:45]
	v_mfma_f32_16x16x32_bf16 v[38:41], v[182:185], v[202:205], v[38:41]
	v_mfma_f32_16x16x32_bf16 v[30:33], v[190:193], v[202:205], v[30:33]
	v_mfma_f32_16x16x32_bf16 v[34:37], v[140:143], v[240:243], v[34:37]
	v_mfma_f32_16x16x32_bf16 v[26:29], v[174:177], v[240:243], v[26:29]
	v_mfma_f32_16x16x32_bf16 v[22:25], v[182:185], v[240:243], v[22:25]
	v_mfma_f32_16x16x32_bf16 v[14:17], v[190:193], v[240:243], v[14:17]
	v_mfma_f32_16x16x32_bf16 v[18:21], v[140:143], v[248:251], v[18:21]
	v_mfma_f32_16x16x32_bf16 v[10:13], v[174:177], v[248:251], v[10:13]
	v_mfma_f32_16x16x32_bf16 v[6:9], v[182:185], v[248:251], v[6:9]
	v_mfma_f32_16x16x32_bf16 v[2:5], v[190:193], v[248:251], v[2:5]
	s_barrier
	s_setprio 0
	v_add_u32_e32 v139, 0x18000, v234
	ds_read_b128 v[130:133], v139
	ds_read_b128 v[140:143], v139 offset:1024
	ds_read_b128 v[154:157], v139 offset:2048
	ds_read_b128 v[170:173], v139 offset:3072
	v_add_u32_e32 v139, 0x1c000, v234
	ds_read_b128 v[174:177], v139
	ds_read_b128 v[178:181], v139 offset:1024
	ds_read_b128 v[182:185], v139 offset:2048
	ds_read_b128 v[186:189], v139 offset:3072
	s_add_i32 s23, s23, 0x80000
	s_mov_b32 m0, s37
	ds_read_b128 v[190:193], v235 offset:32768
	ds_read_b128 v[194:197], v235 offset:33792
	ds_read_b128 v[198:201], v235 offset:34816
	ds_read_b128 v[202:205], v235 offset:35840
	ds_read_b128 v[236:239], v235 offset:36864
	ds_read_b128 v[240:243], v235 offset:37888
	ds_read_b128 v[244:247], v235 offset:38912
	ds_read_b128 v[248:251], v235 offset:39936
	buffer_load_dwordx4 v228, s[60:63], s23 offen lds
	s_mov_b32 m0, s18
	s_nop 0
	buffer_load_dwordx4 v230, s[60:63], s23 offen lds
	s_waitcnt vmcnt(8)
	s_waitcnt lgkmcnt(0)
	s_setprio 1
	s_barrier
	v_mfma_f32_16x16x32_bf16 v[126:129], v[130:133], v[190:193], v[126:129]
	v_mfma_f32_16x16x32_bf16 v[122:125], v[154:157], v[190:193], v[122:125]
	v_mfma_f32_16x16x32_bf16 v[118:121], v[174:177], v[190:193], v[118:121]
	v_mfma_f32_16x16x32_bf16 v[110:113], v[182:185], v[190:193], v[110:113]
	v_mfma_f32_16x16x32_bf16 v[114:117], v[130:133], v[198:201], v[114:117]
	v_mfma_f32_16x16x32_bf16 v[106:109], v[154:157], v[198:201], v[106:109]
	v_mfma_f32_16x16x32_bf16 v[102:105], v[174:177], v[198:201], v[102:105]
	v_mfma_f32_16x16x32_bf16 v[94:97], v[182:185], v[198:201], v[94:97]
	v_mfma_f32_16x16x32_bf16 v[98:101], v[130:133], v[236:239], v[98:101]
	v_mfma_f32_16x16x32_bf16 v[90:93], v[154:157], v[236:239], v[90:93]
	v_mfma_f32_16x16x32_bf16 v[86:89], v[174:177], v[236:239], v[86:89]
	v_mfma_f32_16x16x32_bf16 v[78:81], v[182:185], v[236:239], v[78:81]
	v_mfma_f32_16x16x32_bf16 v[82:85], v[130:133], v[244:247], v[82:85]
	v_mfma_f32_16x16x32_bf16 v[74:77], v[154:157], v[244:247], v[74:77]
	v_mfma_f32_16x16x32_bf16 v[70:73], v[174:177], v[244:247], v[70:73]
	v_mfma_f32_16x16x32_bf16 v[66:69], v[182:185], v[244:247], v[66:69]
	v_mfma_f32_16x16x32_bf16 v[126:129], v[140:143], v[194:197], v[126:129]
	v_mfma_f32_16x16x32_bf16 v[122:125], v[170:173], v[194:197], v[122:125]
	v_mfma_f32_16x16x32_bf16 v[118:121], v[178:181], v[194:197], v[118:121]
	v_mfma_f32_16x16x32_bf16 v[110:113], v[186:189], v[194:197], v[110:113]
	v_mfma_f32_16x16x32_bf16 v[114:117], v[140:143], v[202:205], v[114:117]
	v_mfma_f32_16x16x32_bf16 v[106:109], v[170:173], v[202:205], v[106:109]
	v_mfma_f32_16x16x32_bf16 v[102:105], v[178:181], v[202:205], v[102:105]
	v_mfma_f32_16x16x32_bf16 v[94:97], v[186:189], v[202:205], v[94:97]
	v_mfma_f32_16x16x32_bf16 v[98:101], v[140:143], v[240:243], v[98:101]
	v_mfma_f32_16x16x32_bf16 v[90:93], v[170:173], v[240:243], v[90:93]
	v_mfma_f32_16x16x32_bf16 v[86:89], v[178:181], v[240:243], v[86:89]
	v_mfma_f32_16x16x32_bf16 v[78:81], v[186:189], v[240:243], v[78:81]
	v_mfma_f32_16x16x32_bf16 v[82:85], v[140:143], v[248:251], v[82:85]
	v_mfma_f32_16x16x32_bf16 v[74:77], v[170:173], v[248:251], v[74:77]
	v_mfma_f32_16x16x32_bf16 v[70:73], v[178:181], v[248:251], v[70:73]
	v_mfma_f32_16x16x32_bf16 v[66:69], v[186:189], v[248:251], v[66:69]
	s_barrier
	s_setprio 0
	s_mov_b32 m0, s24
	s_or_b32 s23, s22, 0x80
	ds_read_b128 v[190:193], v235 offset:49152
	ds_read_b128 v[194:197], v235 offset:50176
	ds_read_b128 v[198:201], v235 offset:51200
	ds_read_b128 v[202:205], v235 offset:52224
	ds_read_b128 v[236:239], v235 offset:53248
	ds_read_b128 v[240:243], v235 offset:54272
	ds_read_b128 v[244:247], v235 offset:55296
	ds_read_b128 v[248:251], v235 offset:56320
	buffer_load_dwordx4 v229, s[44:47], s23 offen lds
	s_mov_b32 m0, s25
	s_add_i32 s22, s22, 0x80080
	buffer_load_dwordx4 v231, s[44:47], s23 offen lds
	s_mov_b32 m0, s64
	s_nop 0
	buffer_load_dwordx4 v229, s[44:47], s22 offen lds
	s_mov_b32 m0, s65
	s_nop 0
	buffer_load_dwordx4 v231, s[44:47], s22 offen lds
	s_mov_b32 m0, s48
	s_nop 0
	buffer_load_dwordx4 v228, s[60:63], s21 offen lds
	s_mov_b32 m0, s49
	s_nop 0
	buffer_load_dwordx4 v230, s[60:63], s21 offen lds
	s_waitcnt vmcnt(8)
	s_waitcnt lgkmcnt(0)
	s_setprio 1
	s_barrier
	v_mfma_f32_16x16x32_bf16 v[62:65], v[130:133], v[190:193], v[62:65]
	v_mfma_f32_16x16x32_bf16 v[58:61], v[154:157], v[190:193], v[58:61]
	v_mfma_f32_16x16x32_bf16 v[54:57], v[174:177], v[190:193], v[54:57]
	v_mfma_f32_16x16x32_bf16 v[46:49], v[182:185], v[190:193], v[46:49]
	v_mfma_f32_16x16x32_bf16 v[50:53], v[130:133], v[198:201], v[50:53]
	v_mfma_f32_16x16x32_bf16 v[42:45], v[154:157], v[198:201], v[42:45]
	v_mfma_f32_16x16x32_bf16 v[38:41], v[174:177], v[198:201], v[38:41]
	v_mfma_f32_16x16x32_bf16 v[30:33], v[182:185], v[198:201], v[30:33]
	v_mfma_f32_16x16x32_bf16 v[34:37], v[130:133], v[236:239], v[34:37]
	v_mfma_f32_16x16x32_bf16 v[26:29], v[154:157], v[236:239], v[26:29]
	v_mfma_f32_16x16x32_bf16 v[22:25], v[174:177], v[236:239], v[22:25]
	v_mfma_f32_16x16x32_bf16 v[14:17], v[182:185], v[236:239], v[14:17]
	v_mfma_f32_16x16x32_bf16 v[18:21], v[130:133], v[244:247], v[18:21]
	v_mfma_f32_16x16x32_bf16 v[10:13], v[154:157], v[244:247], v[10:13]
	v_mfma_f32_16x16x32_bf16 v[6:9], v[174:177], v[244:247], v[6:9]
	v_mfma_f32_16x16x32_bf16 v[2:5], v[182:185], v[244:247], v[2:5]
	v_mfma_f32_16x16x32_bf16 v[62:65], v[140:143], v[194:197], v[62:65]
	v_mfma_f32_16x16x32_bf16 v[58:61], v[170:173], v[194:197], v[58:61]
	v_mfma_f32_16x16x32_bf16 v[54:57], v[178:181], v[194:197], v[54:57]
	v_mfma_f32_16x16x32_bf16 v[46:49], v[186:189], v[194:197], v[46:49]
	v_mfma_f32_16x16x32_bf16 v[50:53], v[140:143], v[202:205], v[50:53]
	v_mfma_f32_16x16x32_bf16 v[42:45], v[170:173], v[202:205], v[42:45]
	v_mfma_f32_16x16x32_bf16 v[38:41], v[178:181], v[202:205], v[38:41]
	v_mfma_f32_16x16x32_bf16 v[30:33], v[186:189], v[202:205], v[30:33]
	v_mfma_f32_16x16x32_bf16 v[34:37], v[140:143], v[240:243], v[34:37]
	v_mfma_f32_16x16x32_bf16 v[26:29], v[170:173], v[240:243], v[26:29]
	v_mfma_f32_16x16x32_bf16 v[22:25], v[178:181], v[240:243], v[22:25]
	v_mfma_f32_16x16x32_bf16 v[14:17], v[186:189], v[240:243], v[14:17]
	v_mfma_f32_16x16x32_bf16 v[18:21], v[140:143], v[248:251], v[18:21]
	v_mfma_f32_16x16x32_bf16 v[10:13], v[170:173], v[248:251], v[10:13]
	v_mfma_f32_16x16x32_bf16 v[6:9], v[178:181], v[248:251], v[6:9]
	v_mfma_f32_16x16x32_bf16 v[2:5], v[186:189], v[248:251], v[2:5]
	s_barrier
	s_setprio 0
	s_add_i32 s16, s16, 2
	s_addk_i32 s12, 0x100
	s_addk_i32 s13, 0x100
	s_cmp_gt_u32 s16, 29
.LBB0_881:
	v_add_u32_e32 v139, 0x10000, v234
	ds_read_b128 v[130:133], v139
	ds_read_b128 v[140:143], v139 offset:1024
	ds_read_b128 v[170:173], v139 offset:2048
	ds_read_b128 v[174:177], v139 offset:3072
	v_add_u32_e32 v139, 0x14000, v234
	ds_read_b128 v[178:181], v139
	ds_read_b128 v[182:185], v139 offset:1024
	ds_read_b128 v[186:189], v139 offset:2048
	ds_read_b128 v[190:193], v139 offset:3072
	s_add_i32 s21, s12, 0xfff80080
	s_cmp_eq_u32 s16, 28
	s_cselect_b32 s23, s8, s21
	s_cselect_b32 s22, s9, s13
	s_or_b32 s21, s23, 0x80
	s_mov_b32 m0, s72
	ds_read_b128 v[194:197], v235
	ds_read_b128 v[198:201], v235 offset:1024
	ds_read_b128 v[202:205], v235 offset:2048
	ds_read_b128 v[236:239], v235 offset:3072
	ds_read_b128 v[240:243], v235 offset:4096
	ds_read_b128 v[244:247], v235 offset:5120
	ds_read_b128 v[248:251], v235 offset:6144
	ds_read_b128 v[154:157], v235 offset:7168
	buffer_load_dwordx4 v228, s[60:63], s12 offen lds
	s_mov_b32 m0, s73
	s_nop 0
	buffer_load_dwordx4 v230, s[60:63], s12 offen lds
	s_waitcnt vmcnt(8)
	s_waitcnt lgkmcnt(0)
	s_setprio 1
	s_barrier
	v_mfma_f32_16x16x32_bf16 v[126:129], v[130:133], v[194:197], v[126:129]
	v_mfma_f32_16x16x32_bf16 v[122:125], v[170:173], v[194:197], v[122:125]
	v_mfma_f32_16x16x32_bf16 v[118:121], v[178:181], v[194:197], v[118:121]
	v_mfma_f32_16x16x32_bf16 v[110:113], v[186:189], v[194:197], v[110:113]
	v_mfma_f32_16x16x32_bf16 v[114:117], v[130:133], v[202:205], v[114:117]
	v_mfma_f32_16x16x32_bf16 v[106:109], v[170:173], v[202:205], v[106:109]
	v_mfma_f32_16x16x32_bf16 v[102:105], v[178:181], v[202:205], v[102:105]
	v_mfma_f32_16x16x32_bf16 v[94:97], v[186:189], v[202:205], v[94:97]
	v_mfma_f32_16x16x32_bf16 v[98:101], v[130:133], v[240:243], v[98:101]
	v_mfma_f32_16x16x32_bf16 v[90:93], v[170:173], v[240:243], v[90:93]
	v_mfma_f32_16x16x32_bf16 v[86:89], v[178:181], v[240:243], v[86:89]
	v_mfma_f32_16x16x32_bf16 v[78:81], v[186:189], v[240:243], v[78:81]
	v_mfma_f32_16x16x32_bf16 v[82:85], v[130:133], v[248:251], v[82:85]
	v_mfma_f32_16x16x32_bf16 v[74:77], v[170:173], v[248:251], v[74:77]
	v_mfma_f32_16x16x32_bf16 v[70:73], v[178:181], v[248:251], v[70:73]
	v_mfma_f32_16x16x32_bf16 v[66:69], v[186:189], v[248:251], v[66:69]
	v_mfma_f32_16x16x32_bf16 v[126:129], v[140:143], v[198:201], v[126:129]
	v_mfma_f32_16x16x32_bf16 v[122:125], v[174:177], v[198:201], v[122:125]
	v_mfma_f32_16x16x32_bf16 v[118:121], v[182:185], v[198:201], v[118:121]
	v_mfma_f32_16x16x32_bf16 v[110:113], v[190:193], v[198:201], v[110:113]
	v_mfma_f32_16x16x32_bf16 v[114:117], v[140:143], v[236:239], v[114:117]
	v_mfma_f32_16x16x32_bf16 v[106:109], v[174:177], v[236:239], v[106:109]
	v_mfma_f32_16x16x32_bf16 v[102:105], v[182:185], v[236:239], v[102:105]
	v_mfma_f32_16x16x32_bf16 v[94:97], v[190:193], v[236:239], v[94:97]
	v_mfma_f32_16x16x32_bf16 v[98:101], v[140:143], v[244:247], v[98:101]
	v_mfma_f32_16x16x32_bf16 v[90:93], v[174:177], v[244:247], v[90:93]
	v_mfma_f32_16x16x32_bf16 v[86:89], v[182:185], v[244:247], v[86:89]
	v_mfma_f32_16x16x32_bf16 v[78:81], v[190:193], v[244:247], v[78:81]
	v_mfma_f32_16x16x32_bf16 v[82:85], v[140:143], v[154:157], v[82:85]
	v_mfma_f32_16x16x32_bf16 v[74:77], v[174:177], v[154:157], v[74:77]
	v_mfma_f32_16x16x32_bf16 v[70:73], v[182:185], v[154:157], v[70:73]
	v_mfma_f32_16x16x32_bf16 v[66:69], v[190:193], v[154:157], v[66:69]
	s_barrier
	s_setprio 0
	s_mov_b32 m0, s26
	s_mov_b32 s46, s62
	s_mov_b32 s47, s63
	ds_read_b128 v[154:157], v235 offset:16384
	ds_read_b128 v[194:197], v235 offset:17408
	ds_read_b128 v[198:201], v235 offset:18432
	ds_read_b128 v[202:205], v235 offset:19456
	ds_read_b128 v[236:239], v235 offset:20480
	ds_read_b128 v[240:243], v235 offset:21504
	ds_read_b128 v[244:247], v235 offset:22528
	ds_read_b128 v[248:251], v235 offset:23552
	buffer_load_dwordx4 v229, s[44:47], s22 offen lds
	s_mov_b32 m0, s27
	s_add_i32 s38, s22, 0x80000
	buffer_load_dwordx4 v231, s[44:47], s22 offen lds
	s_mov_b32 m0, s34
	s_nop 0
	buffer_load_dwordx4 v229, s[44:47], s38 offen lds
	s_mov_b32 m0, s35
	s_nop 0
	buffer_load_dwordx4 v231, s[44:47], s38 offen lds
	s_mov_b32 m0, s19
	s_nop 0
	buffer_load_dwordx4 v228, s[60:63], s23 offen lds
	s_mov_b32 m0, s36
	s_nop 0
	buffer_load_dwordx4 v230, s[60:63], s23 offen lds
	s_waitcnt vmcnt(8)
	s_waitcnt lgkmcnt(0)
	s_setprio 1
	s_barrier
	v_mfma_f32_16x16x32_bf16 v[62:65], v[130:133], v[154:157], v[62:65]
	v_mfma_f32_16x16x32_bf16 v[58:61], v[170:173], v[154:157], v[58:61]
	v_mfma_f32_16x16x32_bf16 v[54:57], v[178:181], v[154:157], v[54:57]
	v_mfma_f32_16x16x32_bf16 v[46:49], v[186:189], v[154:157], v[46:49]
	v_mfma_f32_16x16x32_bf16 v[50:53], v[130:133], v[198:201], v[50:53]
	v_mfma_f32_16x16x32_bf16 v[42:45], v[170:173], v[198:201], v[42:45]
	v_mfma_f32_16x16x32_bf16 v[38:41], v[178:181], v[198:201], v[38:41]
	v_mfma_f32_16x16x32_bf16 v[30:33], v[186:189], v[198:201], v[30:33]
	v_mfma_f32_16x16x32_bf16 v[34:37], v[130:133], v[236:239], v[34:37]
	v_mfma_f32_16x16x32_bf16 v[26:29], v[170:173], v[236:239], v[26:29]
	v_mfma_f32_16x16x32_bf16 v[22:25], v[178:181], v[236:239], v[22:25]
	v_mfma_f32_16x16x32_bf16 v[14:17], v[186:189], v[236:239], v[14:17]
	v_mfma_f32_16x16x32_bf16 v[18:21], v[130:133], v[244:247], v[18:21]
	v_mfma_f32_16x16x32_bf16 v[10:13], v[170:173], v[244:247], v[10:13]
	v_mfma_f32_16x16x32_bf16 v[6:9], v[178:181], v[244:247], v[6:9]
	v_mfma_f32_16x16x32_bf16 v[2:5], v[186:189], v[244:247], v[2:5]
	v_mfma_f32_16x16x32_bf16 v[62:65], v[140:143], v[194:197], v[62:65]
	v_mfma_f32_16x16x32_bf16 v[58:61], v[174:177], v[194:197], v[58:61]
	v_mfma_f32_16x16x32_bf16 v[54:57], v[182:185], v[194:197], v[54:57]
	v_mfma_f32_16x16x32_bf16 v[46:49], v[190:193], v[194:197], v[46:49]
	v_mfma_f32_16x16x32_bf16 v[50:53], v[140:143], v[202:205], v[50:53]
	v_mfma_f32_16x16x32_bf16 v[42:45], v[174:177], v[202:205], v[42:45]
	v_mfma_f32_16x16x32_bf16 v[38:41], v[182:185], v[202:205], v[38:41]
	v_mfma_f32_16x16x32_bf16 v[30:33], v[190:193], v[202:205], v[30:33]
	v_mfma_f32_16x16x32_bf16 v[34:37], v[140:143], v[240:243], v[34:37]
	v_mfma_f32_16x16x32_bf16 v[26:29], v[174:177], v[240:243], v[26:29]
	v_mfma_f32_16x16x32_bf16 v[22:25], v[182:185], v[240:243], v[22:25]
	v_mfma_f32_16x16x32_bf16 v[14:17], v[190:193], v[240:243], v[14:17]
	v_mfma_f32_16x16x32_bf16 v[18:21], v[140:143], v[248:251], v[18:21]
	v_mfma_f32_16x16x32_bf16 v[10:13], v[174:177], v[248:251], v[10:13]
	v_mfma_f32_16x16x32_bf16 v[6:9], v[182:185], v[248:251], v[6:9]
	v_mfma_f32_16x16x32_bf16 v[2:5], v[190:193], v[248:251], v[2:5]
	s_barrier
	s_setprio 0
	v_add_u32_e32 v139, 0x18000, v234
	ds_read_b128 v[130:133], v139
	ds_read_b128 v[140:143], v139 offset:1024
	ds_read_b128 v[154:157], v139 offset:2048
	ds_read_b128 v[170:173], v139 offset:3072
	v_add_u32_e32 v139, 0x1c000, v234
	ds_read_b128 v[174:177], v139
	ds_read_b128 v[178:181], v139 offset:1024
	ds_read_b128 v[182:185], v139 offset:2048
	ds_read_b128 v[186:189], v139 offset:3072
	s_add_i32 s23, s23, 0x80000
	s_mov_b32 m0, s37
	ds_read_b128 v[190:193], v235 offset:32768
	ds_read_b128 v[194:197], v235 offset:33792
	ds_read_b128 v[198:201], v235 offset:34816
	ds_read_b128 v[202:205], v235 offset:35840
	ds_read_b128 v[236:239], v235 offset:36864
	ds_read_b128 v[240:243], v235 offset:37888
	ds_read_b128 v[244:247], v235 offset:38912
	ds_read_b128 v[248:251], v235 offset:39936
	buffer_load_dwordx4 v228, s[60:63], s23 offen lds
	s_mov_b32 m0, s18
	s_nop 0
	buffer_load_dwordx4 v230, s[60:63], s23 offen lds
	s_waitcnt vmcnt(8)
	s_waitcnt lgkmcnt(0)
	s_setprio 1
	s_barrier
	v_mfma_f32_16x16x32_bf16 v[126:129], v[130:133], v[190:193], v[126:129]
	v_mfma_f32_16x16x32_bf16 v[122:125], v[154:157], v[190:193], v[122:125]
	v_mfma_f32_16x16x32_bf16 v[118:121], v[174:177], v[190:193], v[118:121]
	v_mfma_f32_16x16x32_bf16 v[110:113], v[182:185], v[190:193], v[110:113]
	v_mfma_f32_16x16x32_bf16 v[114:117], v[130:133], v[198:201], v[114:117]
	v_mfma_f32_16x16x32_bf16 v[106:109], v[154:157], v[198:201], v[106:109]
	v_mfma_f32_16x16x32_bf16 v[102:105], v[174:177], v[198:201], v[102:105]
	v_mfma_f32_16x16x32_bf16 v[94:97], v[182:185], v[198:201], v[94:97]
	v_mfma_f32_16x16x32_bf16 v[98:101], v[130:133], v[236:239], v[98:101]
	v_mfma_f32_16x16x32_bf16 v[90:93], v[154:157], v[236:239], v[90:93]
	v_mfma_f32_16x16x32_bf16 v[86:89], v[174:177], v[236:239], v[86:89]
	v_mfma_f32_16x16x32_bf16 v[78:81], v[182:185], v[236:239], v[78:81]
	v_mfma_f32_16x16x32_bf16 v[82:85], v[130:133], v[244:247], v[82:85]
	v_mfma_f32_16x16x32_bf16 v[74:77], v[154:157], v[244:247], v[74:77]
	v_mfma_f32_16x16x32_bf16 v[70:73], v[174:177], v[244:247], v[70:73]
	v_mfma_f32_16x16x32_bf16 v[66:69], v[182:185], v[244:247], v[66:69]
	v_mfma_f32_16x16x32_bf16 v[126:129], v[140:143], v[194:197], v[126:129]
	v_mfma_f32_16x16x32_bf16 v[122:125], v[170:173], v[194:197], v[122:125]
	v_mfma_f32_16x16x32_bf16 v[118:121], v[178:181], v[194:197], v[118:121]
	v_mfma_f32_16x16x32_bf16 v[110:113], v[186:189], v[194:197], v[110:113]
	v_mfma_f32_16x16x32_bf16 v[114:117], v[140:143], v[202:205], v[114:117]
	v_mfma_f32_16x16x32_bf16 v[106:109], v[170:173], v[202:205], v[106:109]
	v_mfma_f32_16x16x32_bf16 v[102:105], v[178:181], v[202:205], v[102:105]
	v_mfma_f32_16x16x32_bf16 v[94:97], v[186:189], v[202:205], v[94:97]
	v_mfma_f32_16x16x32_bf16 v[98:101], v[140:143], v[240:243], v[98:101]
	v_mfma_f32_16x16x32_bf16 v[90:93], v[170:173], v[240:243], v[90:93]
	v_mfma_f32_16x16x32_bf16 v[86:89], v[178:181], v[240:243], v[86:89]
	v_mfma_f32_16x16x32_bf16 v[78:81], v[186:189], v[240:243], v[78:81]
	v_mfma_f32_16x16x32_bf16 v[82:85], v[140:143], v[248:251], v[82:85]
	v_mfma_f32_16x16x32_bf16 v[74:77], v[170:173], v[248:251], v[74:77]
	v_mfma_f32_16x16x32_bf16 v[70:73], v[178:181], v[248:251], v[70:73]
	v_mfma_f32_16x16x32_bf16 v[66:69], v[186:189], v[248:251], v[66:69]
	s_barrier
	s_setprio 0
	s_mov_b32 m0, s24
	s_or_b32 s23, s22, 0x80
	ds_read_b128 v[190:193], v235 offset:49152
	ds_read_b128 v[194:197], v235 offset:50176
	ds_read_b128 v[198:201], v235 offset:51200
	ds_read_b128 v[202:205], v235 offset:52224
	ds_read_b128 v[236:239], v235 offset:53248
	ds_read_b128 v[240:243], v235 offset:54272
	ds_read_b128 v[244:247], v235 offset:55296
	ds_read_b128 v[248:251], v235 offset:56320
	buffer_load_dwordx4 v229, s[44:47], s23 offen lds
	s_mov_b32 m0, s25
	s_add_i32 s22, s22, 0x80080
	buffer_load_dwordx4 v231, s[44:47], s23 offen lds
	s_mov_b32 m0, s64
	s_nop 0
	buffer_load_dwordx4 v229, s[44:47], s22 offen lds
	s_mov_b32 m0, s65
	s_nop 0
	buffer_load_dwordx4 v231, s[44:47], s22 offen lds
	s_mov_b32 m0, s48
	s_nop 0
	buffer_load_dwordx4 v228, s[60:63], s21 offen lds
	s_mov_b32 m0, s49
	s_nop 0
	buffer_load_dwordx4 v230, s[60:63], s21 offen lds
	s_waitcnt vmcnt(8)
	s_waitcnt lgkmcnt(0)
	s_setprio 1
	s_barrier
	v_mfma_f32_16x16x32_bf16 v[62:65], v[130:133], v[190:193], v[62:65]
	v_mfma_f32_16x16x32_bf16 v[58:61], v[154:157], v[190:193], v[58:61]
	v_mfma_f32_16x16x32_bf16 v[54:57], v[174:177], v[190:193], v[54:57]
	v_mfma_f32_16x16x32_bf16 v[46:49], v[182:185], v[190:193], v[46:49]
	v_mfma_f32_16x16x32_bf16 v[50:53], v[130:133], v[198:201], v[50:53]
	v_mfma_f32_16x16x32_bf16 v[42:45], v[154:157], v[198:201], v[42:45]
	v_mfma_f32_16x16x32_bf16 v[38:41], v[174:177], v[198:201], v[38:41]
	v_mfma_f32_16x16x32_bf16 v[30:33], v[182:185], v[198:201], v[30:33]
	v_mfma_f32_16x16x32_bf16 v[34:37], v[130:133], v[236:239], v[34:37]
	v_mfma_f32_16x16x32_bf16 v[26:29], v[154:157], v[236:239], v[26:29]
	v_mfma_f32_16x16x32_bf16 v[22:25], v[174:177], v[236:239], v[22:25]
	v_mfma_f32_16x16x32_bf16 v[14:17], v[182:185], v[236:239], v[14:17]
	v_mfma_f32_16x16x32_bf16 v[18:21], v[130:133], v[244:247], v[18:21]
	v_mfma_f32_16x16x32_bf16 v[10:13], v[154:157], v[244:247], v[10:13]
	v_mfma_f32_16x16x32_bf16 v[6:9], v[174:177], v[244:247], v[6:9]
	v_mfma_f32_16x16x32_bf16 v[2:5], v[182:185], v[244:247], v[2:5]
	v_mfma_f32_16x16x32_bf16 v[62:65], v[140:143], v[194:197], v[62:65]
	v_mfma_f32_16x16x32_bf16 v[58:61], v[170:173], v[194:197], v[58:61]
	v_mfma_f32_16x16x32_bf16 v[54:57], v[178:181], v[194:197], v[54:57]
	v_mfma_f32_16x16x32_bf16 v[46:49], v[186:189], v[194:197], v[46:49]
	v_mfma_f32_16x16x32_bf16 v[50:53], v[140:143], v[202:205], v[50:53]
	v_mfma_f32_16x16x32_bf16 v[42:45], v[170:173], v[202:205], v[42:45]
	v_mfma_f32_16x16x32_bf16 v[38:41], v[178:181], v[202:205], v[38:41]
	v_mfma_f32_16x16x32_bf16 v[30:33], v[186:189], v[202:205], v[30:33]
	v_mfma_f32_16x16x32_bf16 v[34:37], v[140:143], v[240:243], v[34:37]
	v_mfma_f32_16x16x32_bf16 v[26:29], v[170:173], v[240:243], v[26:29]
	v_mfma_f32_16x16x32_bf16 v[22:25], v[178:181], v[240:243], v[22:25]
	v_mfma_f32_16x16x32_bf16 v[14:17], v[186:189], v[240:243], v[14:17]
	v_mfma_f32_16x16x32_bf16 v[18:21], v[140:143], v[248:251], v[18:21]
	v_mfma_f32_16x16x32_bf16 v[10:13], v[170:173], v[248:251], v[10:13]
	v_mfma_f32_16x16x32_bf16 v[6:9], v[178:181], v[248:251], v[6:9]
	v_mfma_f32_16x16x32_bf16 v[2:5], v[186:189], v[248:251], v[2:5]
	s_barrier
	s_setprio 0
	s_add_i32 s16, s16, 2
	s_addk_i32 s12, 0x100
	s_addk_i32 s13, 0x100
	s_cmp_gt_u32 s16, 29
	s_cbranch_scc0 .LBB0_881
	v_readlane_b32 s8, v255, 44
	v_readlane_b32 s9, v255, 45
	s_and_b64 vcc, exec, s[8:9]
	s_cbranch_vccz .LBB0_884
	s_barrier

.LBB0_904:
	s_lshl_b32 s73, s72, 20
	s_and_b64 s[8:9], s[42:43], exec
	s_cselect_b32 s8, s73, s13
	s_lshl_b32 s84, s71, 20
	s_and_b64 s[22:23], s[42:43], exec
	s_cselect_b32 s9, s84, s21
	s_add_i32 s13, s13, 0x80080
	s_addk_i32 s21, 0x100
	s_mov_b32 s22, -2
	v_add_u32_e32 v133, 0x10000, v178
	ds_read_b128 v[134:137], v133
	ds_read_b128 v[138:141], v133 offset:1024
	ds_read_b128 v[142:145], v133 offset:2048
	ds_read_b128 v[154:157], v133 offset:3072
	v_add_u32_e32 v133, 0x14000, v178
	ds_read_b128 v[170:173], v133
	ds_read_b128 v[180:183], v133 offset:1024
	ds_read_b128 v[184:187], v133 offset:2048
	ds_read_b128 v[188:191], v133 offset:3072
	s_add_i32 s23, s13, 0xfff80080
	s_cmp_eq_u32 s22, 28
	s_cselect_b32 s27, s8, s23
	s_cselect_b32 s26, s9, s21
	s_or_b32 s23, s27, 0x80
	s_mov_b32 s46, s62
	s_mov_b32 s47, s63
	s_mov_b32 m0, s68
	ds_read_b128 v[192:195], v179
	ds_read_b128 v[196:199], v179 offset:1024
	ds_read_b128 v[200:203], v179 offset:2048
	ds_read_b128 v[204:207], v179 offset:3072
	ds_read_b128 v[228:231], v179 offset:4096
	ds_read_b128 v[232:235], v179 offset:5120
	ds_read_b128 v[236:239], v179 offset:6144
	ds_read_b128 v[240:243], v179 offset:7168
	buffer_load_dwordx4 v174, s[44:47], s13 offen lds
	s_mov_b32 m0, s69
	s_nop 0
	buffer_load_dwordx4 v176, s[44:47], s13 offen lds
	s_waitcnt vmcnt(8)
	s_waitcnt lgkmcnt(0)
	s_setprio 1
	s_barrier
	v_mfma_f32_16x16x32_bf16 v[126:129], v[134:137], v[192:195], 0
	v_mfma_f32_16x16x32_bf16 v[122:125], v[142:145], v[192:195], 0
	v_mfma_f32_16x16x32_bf16 v[118:121], v[170:173], v[192:195], 0
	v_mfma_f32_16x16x32_bf16 v[114:117], v[184:187], v[192:195], 0
	v_mfma_f32_16x16x32_bf16 v[110:113], v[134:137], v[200:203], 0
	v_mfma_f32_16x16x32_bf16 v[106:109], v[142:145], v[200:203], 0
	v_mfma_f32_16x16x32_bf16 v[102:105], v[170:173], v[200:203], 0
	v_mfma_f32_16x16x32_bf16 v[98:101], v[184:187], v[200:203], 0
	v_mfma_f32_16x16x32_bf16 v[94:97], v[134:137], v[228:231], 0
	v_mfma_f32_16x16x32_bf16 v[90:93], v[142:145], v[228:231], 0
	v_mfma_f32_16x16x32_bf16 v[86:89], v[170:173], v[228:231], 0
	v_mfma_f32_16x16x32_bf16 v[82:85], v[184:187], v[228:231], 0
	v_mfma_f32_16x16x32_bf16 v[78:81], v[134:137], v[236:239], 0
	v_mfma_f32_16x16x32_bf16 v[74:77], v[142:145], v[236:239], 0
	v_mfma_f32_16x16x32_bf16 v[70:73], v[170:173], v[236:239], 0
	v_mfma_f32_16x16x32_bf16 v[66:69], v[184:187], v[236:239], 0
	v_mfma_f32_16x16x32_bf16 v[126:129], v[138:141], v[196:199], v[126:129]
	v_mfma_f32_16x16x32_bf16 v[122:125], v[154:157], v[196:199], v[122:125]
	v_mfma_f32_16x16x32_bf16 v[118:121], v[180:183], v[196:199], v[118:121]
	v_mfma_f32_16x16x32_bf16 v[114:117], v[188:191], v[196:199], v[114:117]
	v_mfma_f32_16x16x32_bf16 v[110:113], v[138:141], v[204:207], v[110:113]
	v_mfma_f32_16x16x32_bf16 v[106:109], v[154:157], v[204:207], v[106:109]
	v_mfma_f32_16x16x32_bf16 v[102:105], v[180:183], v[204:207], v[102:105]
	v_mfma_f32_16x16x32_bf16 v[98:101], v[188:191], v[204:207], v[98:101]
	v_mfma_f32_16x16x32_bf16 v[94:97], v[138:141], v[232:235], v[94:97]
	v_mfma_f32_16x16x32_bf16 v[90:93], v[154:157], v[232:235], v[90:93]
	v_mfma_f32_16x16x32_bf16 v[86:89], v[180:183], v[232:235], v[86:89]
	v_mfma_f32_16x16x32_bf16 v[82:85], v[188:191], v[232:235], v[82:85]
	v_mfma_f32_16x16x32_bf16 v[78:81], v[138:141], v[240:243], v[78:81]
	v_mfma_f32_16x16x32_bf16 v[74:77], v[154:157], v[240:243], v[74:77]
	v_mfma_f32_16x16x32_bf16 v[70:73], v[180:183], v[240:243], v[70:73]
	v_mfma_f32_16x16x32_bf16 v[66:69], v[188:191], v[240:243], v[66:69]
	s_barrier
	s_setprio 0
	s_mov_b32 m0, s15
	ds_read_b128 v[192:195], v179 offset:16384
	ds_read_b128 v[196:199], v179 offset:17408
	ds_read_b128 v[200:203], v179 offset:18432
	ds_read_b128 v[204:207], v179 offset:19456
	ds_read_b128 v[228:231], v179 offset:20480
	ds_read_b128 v[232:235], v179 offset:21504
	ds_read_b128 v[236:239], v179 offset:22528
	ds_read_b128 v[240:243], v179 offset:23552
	buffer_load_dwordx4 v175, s[60:63], s26 offen lds
	s_mov_b32 m0, s16
	s_add_i32 s34, s26, 0x80000
	buffer_load_dwordx4 v177, s[60:63], s26 offen lds
	s_mov_b32 m0, s18
	s_nop 0
	buffer_load_dwordx4 v175, s[60:63], s34 offen lds
	s_mov_b32 m0, s19
	s_nop 0
	buffer_load_dwordx4 v177, s[60:63], s34 offen lds
	s_mov_b32 m0, s14
	s_nop 0
	buffer_load_dwordx4 v174, s[44:47], s27 offen lds
	s_mov_b32 m0, s24
	s_nop 0
	buffer_load_dwordx4 v176, s[44:47], s27 offen lds
	s_waitcnt vmcnt(8)
	s_waitcnt lgkmcnt(0)
	s_setprio 1
	s_barrier
	v_mfma_f32_16x16x32_bf16 v[62:65], v[134:137], v[192:195], 0
	v_mfma_f32_16x16x32_bf16 v[58:61], v[142:145], v[192:195], 0
	v_mfma_f32_16x16x32_bf16 v[54:57], v[170:173], v[192:195], 0
	v_mfma_f32_16x16x32_bf16 v[50:53], v[184:187], v[192:195], 0
	v_mfma_f32_16x16x32_bf16 v[46:49], v[134:137], v[200:203], 0
	v_mfma_f32_16x16x32_bf16 v[42:45], v[142:145], v[200:203], 0
	v_mfma_f32_16x16x32_bf16 v[38:41], v[170:173], v[200:203], 0
	v_mfma_f32_16x16x32_bf16 v[34:37], v[184:187], v[200:203], 0
	v_mfma_f32_16x16x32_bf16 v[30:33], v[134:137], v[228:231], 0
	v_mfma_f32_16x16x32_bf16 v[26:29], v[142:145], v[228:231], 0
	v_mfma_f32_16x16x32_bf16 v[22:25], v[170:173], v[228:231], 0
	v_mfma_f32_16x16x32_bf16 v[18:21], v[184:187], v[228:231], 0
	v_mfma_f32_16x16x32_bf16 v[14:17], v[134:137], v[236:239], 0
	v_mfma_f32_16x16x32_bf16 v[10:13], v[142:145], v[236:239], 0
	v_mfma_f32_16x16x32_bf16 v[6:9], v[170:173], v[236:239], 0
	v_mfma_f32_16x16x32_bf16 v[2:5], v[184:187], v[236:239], 0
	v_mfma_f32_16x16x32_bf16 v[62:65], v[138:141], v[196:199], v[62:65]
	v_mfma_f32_16x16x32_bf16 v[58:61], v[154:157], v[196:199], v[58:61]
	v_mfma_f32_16x16x32_bf16 v[54:57], v[180:183], v[196:199], v[54:57]
	v_mfma_f32_16x16x32_bf16 v[50:53], v[188:191], v[196:199], v[50:53]
	v_mfma_f32_16x16x32_bf16 v[46:49], v[138:141], v[204:207], v[46:49]
	v_mfma_f32_16x16x32_bf16 v[42:45], v[154:157], v[204:207], v[42:45]
	v_mfma_f32_16x16x32_bf16 v[38:41], v[180:183], v[204:207], v[38:41]
	v_mfma_f32_16x16x32_bf16 v[34:37], v[188:191], v[204:207], v[34:37]
	v_mfma_f32_16x16x32_bf16 v[30:33], v[138:141], v[232:235], v[30:33]
	v_mfma_f32_16x16x32_bf16 v[26:29], v[154:157], v[232:235], v[26:29]
	v_mfma_f32_16x16x32_bf16 v[22:25], v[180:183], v[232:235], v[22:25]
	v_mfma_f32_16x16x32_bf16 v[18:21], v[188:191], v[232:235], v[18:21]
	v_mfma_f32_16x16x32_bf16 v[14:17], v[138:141], v[240:243], v[14:17]
	v_mfma_f32_16x16x32_bf16 v[10:13], v[154:157], v[240:243], v[10:13]
	v_mfma_f32_16x16x32_bf16 v[6:9], v[180:183], v[240:243], v[6:9]
	v_mfma_f32_16x16x32_bf16 v[2:5], v[188:191], v[240:243], v[2:5]
	s_barrier
	s_setprio 0
	v_add_u32_e32 v133, 0x18000, v178
	ds_read_b128 v[134:137], v133
	ds_read_b128 v[138:141], v133 offset:1024
	ds_read_b128 v[142:145], v133 offset:2048
	ds_read_b128 v[154:157], v133 offset:3072
	v_add_u32_e32 v133, 0x1c000, v178
	ds_read_b128 v[170:173], v133
	ds_read_b128 v[180:183], v133 offset:1024
	ds_read_b128 v[184:187], v133 offset:2048
	ds_read_b128 v[188:191], v133 offset:3072
	s_add_i32 s27, s27, 0x80000
	s_mov_b32 m0, s25
	ds_read_b128 v[192:195], v179 offset:32768
	ds_read_b128 v[196:199], v179 offset:33792
	ds_read_b128 v[200:203], v179 offset:34816
	ds_read_b128 v[204:207], v179 offset:35840
	ds_read_b128 v[228:231], v179 offset:36864
	ds_read_b128 v[232:235], v179 offset:37888
	ds_read_b128 v[236:239], v179 offset:38912
	ds_read_b128 v[240:243], v179 offset:39936
	buffer_load_dwordx4 v174, s[44:47], s27 offen lds
	s_mov_b32 m0, s30
	s_nop 0
	buffer_load_dwordx4 v176, s[44:47], s27 offen lds
	s_waitcnt vmcnt(8)
	s_waitcnt lgkmcnt(0)
	s_setprio 1
	s_barrier
	v_mfma_f32_16x16x32_bf16 v[126:129], v[134:137], v[192:195], v[126:129]
	v_mfma_f32_16x16x32_bf16 v[122:125], v[142:145], v[192:195], v[122:125]
	v_mfma_f32_16x16x32_bf16 v[118:121], v[170:173], v[192:195], v[118:121]
	v_mfma_f32_16x16x32_bf16 v[114:117], v[184:187], v[192:195], v[114:117]
	v_mfma_f32_16x16x32_bf16 v[110:113], v[134:137], v[200:203], v[110:113]
	v_mfma_f32_16x16x32_bf16 v[106:109], v[142:145], v[200:203], v[106:109]
	v_mfma_f32_16x16x32_bf16 v[102:105], v[170:173], v[200:203], v[102:105]
	v_mfma_f32_16x16x32_bf16 v[98:101], v[184:187], v[200:203], v[98:101]
	v_mfma_f32_16x16x32_bf16 v[94:97], v[134:137], v[228:231], v[94:97]
	v_mfma_f32_16x16x32_bf16 v[90:93], v[142:145], v[228:231], v[90:93]
	v_mfma_f32_16x16x32_bf16 v[86:89], v[170:173], v[228:231], v[86:89]
	v_mfma_f32_16x16x32_bf16 v[82:85], v[184:187], v[228:231], v[82:85]
	v_mfma_f32_16x16x32_bf16 v[78:81], v[134:137], v[236:239], v[78:81]
	v_mfma_f32_16x16x32_bf16 v[74:77], v[142:145], v[236:239], v[74:77]
	v_mfma_f32_16x16x32_bf16 v[70:73], v[170:173], v[236:239], v[70:73]
	v_mfma_f32_16x16x32_bf16 v[66:69], v[184:187], v[236:239], v[66:69]
	v_mfma_f32_16x16x32_bf16 v[126:129], v[138:141], v[196:199], v[126:129]
	v_mfma_f32_16x16x32_bf16 v[122:125], v[154:157], v[196:199], v[122:125]
	v_mfma_f32_16x16x32_bf16 v[118:121], v[180:183], v[196:199], v[118:121]
	v_mfma_f32_16x16x32_bf16 v[114:117], v[188:191], v[196:199], v[114:117]
	v_mfma_f32_16x16x32_bf16 v[110:113], v[138:141], v[204:207], v[110:113]
	v_mfma_f32_16x16x32_bf16 v[106:109], v[154:157], v[204:207], v[106:109]
	v_mfma_f32_16x16x32_bf16 v[102:105], v[180:183], v[204:207], v[102:105]
	v_mfma_f32_16x16x32_bf16 v[98:101], v[188:191], v[204:207], v[98:101]
	v_mfma_f32_16x16x32_bf16 v[94:97], v[138:141], v[232:235], v[94:97]
	v_mfma_f32_16x16x32_bf16 v[90:93], v[154:157], v[232:235], v[90:93]
	v_mfma_f32_16x16x32_bf16 v[86:89], v[180:183], v[232:235], v[86:89]
	v_mfma_f32_16x16x32_bf16 v[82:85], v[188:191], v[232:235], v[82:85]
	v_mfma_f32_16x16x32_bf16 v[78:81], v[138:141], v[240:243], v[78:81]
	v_mfma_f32_16x16x32_bf16 v[74:77], v[154:157], v[240:243], v[74:77]
	v_mfma_f32_16x16x32_bf16 v[70:73], v[180:183], v[240:243], v[70:73]
	v_mfma_f32_16x16x32_bf16 v[66:69], v[188:191], v[240:243], v[66:69]
	s_barrier
	s_setprio 0
	s_mov_b32 m0, s36
	s_or_b32 s27, s26, 0x80
	ds_read_b128 v[192:195], v179 offset:49152
	ds_read_b128 v[196:199], v179 offset:50176
	ds_read_b128 v[200:203], v179 offset:51200
	ds_read_b128 v[204:207], v179 offset:52224
	ds_read_b128 v[228:231], v179 offset:53248
	ds_read_b128 v[232:235], v179 offset:54272
	ds_read_b128 v[236:239], v179 offset:55296
	ds_read_b128 v[240:243], v179 offset:56320
	buffer_load_dwordx4 v175, s[60:63], s27 offen lds
	s_mov_b32 m0, s37
	s_add_i32 s26, s26, 0x80080
	buffer_load_dwordx4 v177, s[60:63], s27 offen lds
	s_mov_b32 m0, s48
	s_nop 0
	buffer_load_dwordx4 v175, s[60:63], s26 offen lds
	s_mov_b32 m0, s49
	s_nop 0
	buffer_load_dwordx4 v177, s[60:63], s26 offen lds
	s_mov_b32 m0, s40
	s_nop 0
	buffer_load_dwordx4 v174, s[44:47], s23 offen lds
	s_mov_b32 m0, s41
	s_nop 0
	buffer_load_dwordx4 v176, s[44:47], s23 offen lds
	s_waitcnt vmcnt(8)
	s_waitcnt lgkmcnt(0)
	s_setprio 1
	s_barrier
	v_mfma_f32_16x16x32_bf16 v[62:65], v[134:137], v[192:195], v[62:65]
	v_mfma_f32_16x16x32_bf16 v[58:61], v[142:145], v[192:195], v[58:61]
	v_mfma_f32_16x16x32_bf16 v[54:57], v[170:173], v[192:195], v[54:57]
	v_mfma_f32_16x16x32_bf16 v[50:53], v[184:187], v[192:195], v[50:53]
	v_mfma_f32_16x16x32_bf16 v[46:49], v[134:137], v[200:203], v[46:49]
	v_mfma_f32_16x16x32_bf16 v[42:45], v[142:145], v[200:203], v[42:45]
	v_mfma_f32_16x16x32_bf16 v[38:41], v[170:173], v[200:203], v[38:41]
	v_mfma_f32_16x16x32_bf16 v[34:37], v[184:187], v[200:203], v[34:37]
	v_mfma_f32_16x16x32_bf16 v[30:33], v[134:137], v[228:231], v[30:33]
	v_mfma_f32_16x16x32_bf16 v[26:29], v[142:145], v[228:231], v[26:29]
	v_mfma_f32_16x16x32_bf16 v[22:25], v[170:173], v[228:231], v[22:25]
	v_mfma_f32_16x16x32_bf16 v[18:21], v[184:187], v[228:231], v[18:21]
	v_mfma_f32_16x16x32_bf16 v[14:17], v[134:137], v[236:239], v[14:17]
	v_mfma_f32_16x16x32_bf16 v[10:13], v[142:145], v[236:239], v[10:13]
	v_mfma_f32_16x16x32_bf16 v[6:9], v[170:173], v[236:239], v[6:9]
	v_mfma_f32_16x16x32_bf16 v[2:5], v[184:187], v[236:239], v[2:5]
	v_mfma_f32_16x16x32_bf16 v[62:65], v[138:141], v[196:199], v[62:65]
	v_mfma_f32_16x16x32_bf16 v[58:61], v[154:157], v[196:199], v[58:61]
	v_mfma_f32_16x16x32_bf16 v[54:57], v[180:183], v[196:199], v[54:57]
	v_mfma_f32_16x16x32_bf16 v[50:53], v[188:191], v[196:199], v[50:53]
	v_mfma_f32_16x16x32_bf16 v[46:49], v[138:141], v[204:207], v[46:49]
	v_mfma_f32_16x16x32_bf16 v[42:45], v[154:157], v[204:207], v[42:45]
	v_mfma_f32_16x16x32_bf16 v[38:41], v[180:183], v[204:207], v[38:41]
	v_mfma_f32_16x16x32_bf16 v[34:37], v[188:191], v[204:207], v[34:37]
	v_mfma_f32_16x16x32_bf16 v[30:33], v[138:141], v[232:235], v[30:33]
	v_mfma_f32_16x16x32_bf16 v[26:29], v[154:157], v[232:235], v[26:29]
	v_mfma_f32_16x16x32_bf16 v[22:25], v[180:183], v[232:235], v[22:25]
	v_mfma_f32_16x16x32_bf16 v[18:21], v[188:191], v[232:235], v[18:21]
	v_mfma_f32_16x16x32_bf16 v[14:17], v[138:141], v[240:243], v[14:17]
	v_mfma_f32_16x16x32_bf16 v[10:13], v[154:157], v[240:243], v[10:13]
	v_mfma_f32_16x16x32_bf16 v[6:9], v[180:183], v[240:243], v[6:9]
	v_mfma_f32_16x16x32_bf16 v[2:5], v[188:191], v[240:243], v[2:5]
	s_barrier
	s_setprio 0
	s_add_i32 s22, s22, 2
	s_addk_i32 s13, 0x100
	s_addk_i32 s21, 0x100
	s_cmp_gt_u32 s22, 29
.LBB0_905:
	v_add_u32_e32 v133, 0x10000, v178
	ds_read_b128 v[134:137], v133
	ds_read_b128 v[138:141], v133 offset:1024
	ds_read_b128 v[142:145], v133 offset:2048
	ds_read_b128 v[154:157], v133 offset:3072
	v_add_u32_e32 v133, 0x14000, v178
	ds_read_b128 v[170:173], v133
	ds_read_b128 v[180:183], v133 offset:1024
	ds_read_b128 v[184:187], v133 offset:2048
	ds_read_b128 v[188:191], v133 offset:3072
	s_add_i32 s23, s13, 0xfff80080
	s_cmp_eq_u32 s22, 28
	s_cselect_b32 s27, s8, s23
	s_cselect_b32 s26, s9, s21
	s_or_b32 s23, s27, 0x80
	s_mov_b32 s46, s62
	s_mov_b32 s47, s63
	s_mov_b32 m0, s68
	ds_read_b128 v[192:195], v179
	ds_read_b128 v[196:199], v179 offset:1024
	ds_read_b128 v[200:203], v179 offset:2048
	ds_read_b128 v[204:207], v179 offset:3072
	ds_read_b128 v[228:231], v179 offset:4096
	ds_read_b128 v[232:235], v179 offset:5120
	ds_read_b128 v[236:239], v179 offset:6144
	ds_read_b128 v[240:243], v179 offset:7168
	buffer_load_dwordx4 v174, s[44:47], s13 offen lds
	s_mov_b32 m0, s69
	s_nop 0
	buffer_load_dwordx4 v176, s[44:47], s13 offen lds
	s_waitcnt vmcnt(8)
	s_waitcnt lgkmcnt(0)
	s_setprio 1
	s_barrier
	v_mfma_f32_16x16x32_bf16 v[126:129], v[134:137], v[192:195], v[126:129]
	v_mfma_f32_16x16x32_bf16 v[122:125], v[142:145], v[192:195], v[122:125]
	v_mfma_f32_16x16x32_bf16 v[118:121], v[170:173], v[192:195], v[118:121]
	v_mfma_f32_16x16x32_bf16 v[114:117], v[184:187], v[192:195], v[114:117]
	v_mfma_f32_16x16x32_bf16 v[110:113], v[134:137], v[200:203], v[110:113]
	v_mfma_f32_16x16x32_bf16 v[106:109], v[142:145], v[200:203], v[106:109]
	v_mfma_f32_16x16x32_bf16 v[102:105], v[170:173], v[200:203], v[102:105]
	v_mfma_f32_16x16x32_bf16 v[98:101], v[184:187], v[200:203], v[98:101]
	v_mfma_f32_16x16x32_bf16 v[94:97], v[134:137], v[228:231], v[94:97]
	v_mfma_f32_16x16x32_bf16 v[90:93], v[142:145], v[228:231], v[90:93]
	v_mfma_f32_16x16x32_bf16 v[86:89], v[170:173], v[228:231], v[86:89]
	v_mfma_f32_16x16x32_bf16 v[82:85], v[184:187], v[228:231], v[82:85]
	v_mfma_f32_16x16x32_bf16 v[78:81], v[134:137], v[236:239], v[78:81]
	v_mfma_f32_16x16x32_bf16 v[74:77], v[142:145], v[236:239], v[74:77]
	v_mfma_f32_16x16x32_bf16 v[70:73], v[170:173], v[236:239], v[70:73]
	v_mfma_f32_16x16x32_bf16 v[66:69], v[184:187], v[236:239], v[66:69]
	v_mfma_f32_16x16x32_bf16 v[126:129], v[138:141], v[196:199], v[126:129]
	v_mfma_f32_16x16x32_bf16 v[122:125], v[154:157], v[196:199], v[122:125]
	v_mfma_f32_16x16x32_bf16 v[118:121], v[180:183], v[196:199], v[118:121]
	v_mfma_f32_16x16x32_bf16 v[114:117], v[188:191], v[196:199], v[114:117]
	v_mfma_f32_16x16x32_bf16 v[110:113], v[138:141], v[204:207], v[110:113]
	v_mfma_f32_16x16x32_bf16 v[106:109], v[154:157], v[204:207], v[106:109]
	v_mfma_f32_16x16x32_bf16 v[102:105], v[180:183], v[204:207], v[102:105]
	v_mfma_f32_16x16x32_bf16 v[98:101], v[188:191], v[204:207], v[98:101]
	v_mfma_f32_16x16x32_bf16 v[94:97], v[138:141], v[232:235], v[94:97]
	v_mfma_f32_16x16x32_bf16 v[90:93], v[154:157], v[232:235], v[90:93]
	v_mfma_f32_16x16x32_bf16 v[86:89], v[180:183], v[232:235], v[86:89]
	v_mfma_f32_16x16x32_bf16 v[82:85], v[188:191], v[232:235], v[82:85]
	v_mfma_f32_16x16x32_bf16 v[78:81], v[138:141], v[240:243], v[78:81]
	v_mfma_f32_16x16x32_bf16 v[74:77], v[154:157], v[240:243], v[74:77]
	v_mfma_f32_16x16x32_bf16 v[70:73], v[180:183], v[240:243], v[70:73]
	v_mfma_f32_16x16x32_bf16 v[66:69], v[188:191], v[240:243], v[66:69]
	s_barrier
	s_setprio 0
	s_mov_b32 m0, s15
	ds_read_b128 v[192:195], v179 offset:16384
	ds_read_b128 v[196:199], v179 offset:17408
	ds_read_b128 v[200:203], v179 offset:18432
	ds_read_b128 v[204:207], v179 offset:19456
	ds_read_b128 v[228:231], v179 offset:20480
	ds_read_b128 v[232:235], v179 offset:21504
	ds_read_b128 v[236:239], v179 offset:22528
	ds_read_b128 v[240:243], v179 offset:23552
	buffer_load_dwordx4 v175, s[60:63], s26 offen lds
	s_mov_b32 m0, s16
	s_add_i32 s34, s26, 0x80000
	buffer_load_dwordx4 v177, s[60:63], s26 offen lds
	s_mov_b32 m0, s18
	s_nop 0
	buffer_load_dwordx4 v175, s[60:63], s34 offen lds
	s_mov_b32 m0, s19
	s_nop 0
	buffer_load_dwordx4 v177, s[60:63], s34 offen lds
	s_mov_b32 m0, s14
	s_nop 0
	buffer_load_dwordx4 v174, s[44:47], s27 offen lds
	s_mov_b32 m0, s24
	s_nop 0
	buffer_load_dwordx4 v176, s[44:47], s27 offen lds
	s_waitcnt vmcnt(8)
	s_waitcnt lgkmcnt(0)
	s_setprio 1
	s_barrier
	v_mfma_f32_16x16x32_bf16 v[62:65], v[134:137], v[192:195], v[62:65]
	v_mfma_f32_16x16x32_bf16 v[58:61], v[142:145], v[192:195], v[58:61]
	v_mfma_f32_16x16x32_bf16 v[54:57], v[170:173], v[192:195], v[54:57]
	v_mfma_f32_16x16x32_bf16 v[50:53], v[184:187], v[192:195], v[50:53]
	v_mfma_f32_16x16x32_bf16 v[46:49], v[134:137], v[200:203], v[46:49]
	v_mfma_f32_16x16x32_bf16 v[42:45], v[142:145], v[200:203], v[42:45]
	v_mfma_f32_16x16x32_bf16 v[38:41], v[170:173], v[200:203], v[38:41]
	v_mfma_f32_16x16x32_bf16 v[34:37], v[184:187], v[200:203], v[34:37]
	v_mfma_f32_16x16x32_bf16 v[30:33], v[134:137], v[228:231], v[30:33]
	v_mfma_f32_16x16x32_bf16 v[26:29], v[142:145], v[228:231], v[26:29]
	v_mfma_f32_16x16x32_bf16 v[22:25], v[170:173], v[228:231], v[22:25]
	v_mfma_f32_16x16x32_bf16 v[18:21], v[184:187], v[228:231], v[18:21]
	v_mfma_f32_16x16x32_bf16 v[14:17], v[134:137], v[236:239], v[14:17]
	v_mfma_f32_16x16x32_bf16 v[10:13], v[142:145], v[236:239], v[10:13]
	v_mfma_f32_16x16x32_bf16 v[6:9], v[170:173], v[236:239], v[6:9]
	v_mfma_f32_16x16x32_bf16 v[2:5], v[184:187], v[236:239], v[2:5]
	v_mfma_f32_16x16x32_bf16 v[62:65], v[138:141], v[196:199], v[62:65]
	v_mfma_f32_16x16x32_bf16 v[58:61], v[154:157], v[196:199], v[58:61]
	v_mfma_f32_16x16x32_bf16 v[54:57], v[180:183], v[196:199], v[54:57]
	v_mfma_f32_16x16x32_bf16 v[50:53], v[188:191], v[196:199], v[50:53]
	v_mfma_f32_16x16x32_bf16 v[46:49], v[138:141], v[204:207], v[46:49]
	v_mfma_f32_16x16x32_bf16 v[42:45], v[154:157], v[204:207], v[42:45]
	v_mfma_f32_16x16x32_bf16 v[38:41], v[180:183], v[204:207], v[38:41]
	v_mfma_f32_16x16x32_bf16 v[34:37], v[188:191], v[204:207], v[34:37]
	v_mfma_f32_16x16x32_bf16 v[30:33], v[138:141], v[232:235], v[30:33]
	v_mfma_f32_16x16x32_bf16 v[26:29], v[154:157], v[232:235], v[26:29]
	v_mfma_f32_16x16x32_bf16 v[22:25], v[180:183], v[232:235], v[22:25]
	v_mfma_f32_16x16x32_bf16 v[18:21], v[188:191], v[232:235], v[18:21]
	v_mfma_f32_16x16x32_bf16 v[14:17], v[138:141], v[240:243], v[14:17]
	v_mfma_f32_16x16x32_bf16 v[10:13], v[154:157], v[240:243], v[10:13]
	v_mfma_f32_16x16x32_bf16 v[6:9], v[180:183], v[240:243], v[6:9]
	v_mfma_f32_16x16x32_bf16 v[2:5], v[188:191], v[240:243], v[2:5]
	s_barrier
	s_setprio 0
	v_add_u32_e32 v133, 0x18000, v178
	ds_read_b128 v[134:137], v133
	ds_read_b128 v[138:141], v133 offset:1024
	ds_read_b128 v[142:145], v133 offset:2048
	ds_read_b128 v[154:157], v133 offset:3072
	v_add_u32_e32 v133, 0x1c000, v178
	ds_read_b128 v[170:173], v133
	ds_read_b128 v[180:183], v133 offset:1024
	ds_read_b128 v[184:187], v133 offset:2048
	ds_read_b128 v[188:191], v133 offset:3072
	s_add_i32 s27, s27, 0x80000
	s_mov_b32 m0, s25
	ds_read_b128 v[192:195], v179 offset:32768
	ds_read_b128 v[196:199], v179 offset:33792
	ds_read_b128 v[200:203], v179 offset:34816
	ds_read_b128 v[204:207], v179 offset:35840
	ds_read_b128 v[228:231], v179 offset:36864
	ds_read_b128 v[232:235], v179 offset:37888
	ds_read_b128 v[236:239], v179 offset:38912
	ds_read_b128 v[240:243], v179 offset:39936
	buffer_load_dwordx4 v174, s[44:47], s27 offen lds
	s_mov_b32 m0, s30
	s_nop 0
	buffer_load_dwordx4 v176, s[44:47], s27 offen lds
	s_waitcnt vmcnt(8)
	s_waitcnt lgkmcnt(0)
	s_setprio 1
	s_barrier
	v_mfma_f32_16x16x32_bf16 v[126:129], v[134:137], v[192:195], v[126:129]
	v_mfma_f32_16x16x32_bf16 v[122:125], v[142:145], v[192:195], v[122:125]
	v_mfma_f32_16x16x32_bf16 v[118:121], v[170:173], v[192:195], v[118:121]
	v_mfma_f32_16x16x32_bf16 v[114:117], v[184:187], v[192:195], v[114:117]
	v_mfma_f32_16x16x32_bf16 v[110:113], v[134:137], v[200:203], v[110:113]
	v_mfma_f32_16x16x32_bf16 v[106:109], v[142:145], v[200:203], v[106:109]
	v_mfma_f32_16x16x32_bf16 v[102:105], v[170:173], v[200:203], v[102:105]
	v_mfma_f32_16x16x32_bf16 v[98:101], v[184:187], v[200:203], v[98:101]
	v_mfma_f32_16x16x32_bf16 v[94:97], v[134:137], v[228:231], v[94:97]
	v_mfma_f32_16x16x32_bf16 v[90:93], v[142:145], v[228:231], v[90:93]
	v_mfma_f32_16x16x32_bf16 v[86:89], v[170:173], v[228:231], v[86:89]
	v_mfma_f32_16x16x32_bf16 v[82:85], v[184:187], v[228:231], v[82:85]
	v_mfma_f32_16x16x32_bf16 v[78:81], v[134:137], v[236:239], v[78:81]
	v_mfma_f32_16x16x32_bf16 v[74:77], v[142:145], v[236:239], v[74:77]
	v_mfma_f32_16x16x32_bf16 v[70:73], v[170:173], v[236:239], v[70:73]
	v_mfma_f32_16x16x32_bf16 v[66:69], v[184:187], v[236:239], v[66:69]
	v_mfma_f32_16x16x32_bf16 v[126:129], v[138:141], v[196:199], v[126:129]
	v_mfma_f32_16x16x32_bf16 v[122:125], v[154:157], v[196:199], v[122:125]
	v_mfma_f32_16x16x32_bf16 v[118:121], v[180:183], v[196:199], v[118:121]
	v_mfma_f32_16x16x32_bf16 v[114:117], v[188:191], v[196:199], v[114:117]
	v_mfma_f32_16x16x32_bf16 v[110:113], v[138:141], v[204:207], v[110:113]
	v_mfma_f32_16x16x32_bf16 v[106:109], v[154:157], v[204:207], v[106:109]
	v_mfma_f32_16x16x32_bf16 v[102:105], v[180:183], v[204:207], v[102:105]
	v_mfma_f32_16x16x32_bf16 v[98:101], v[188:191], v[204:207], v[98:101]
	v_mfma_f32_16x16x32_bf16 v[94:97], v[138:141], v[232:235], v[94:97]
	v_mfma_f32_16x16x32_bf16 v[90:93], v[154:157], v[232:235], v[90:93]
	v_mfma_f32_16x16x32_bf16 v[86:89], v[180:183], v[232:235], v[86:89]
	v_mfma_f32_16x16x32_bf16 v[82:85], v[188:191], v[232:235], v[82:85]
	v_mfma_f32_16x16x32_bf16 v[78:81], v[138:141], v[240:243], v[78:81]
	v_mfma_f32_16x16x32_bf16 v[74:77], v[154:157], v[240:243], v[74:77]
	v_mfma_f32_16x16x32_bf16 v[70:73], v[180:183], v[240:243], v[70:73]
	v_mfma_f32_16x16x32_bf16 v[66:69], v[188:191], v[240:243], v[66:69]
	s_barrier
	s_setprio 0
	s_mov_b32 m0, s36
	s_or_b32 s27, s26, 0x80
	ds_read_b128 v[192:195], v179 offset:49152
	ds_read_b128 v[196:199], v179 offset:50176
	ds_read_b128 v[200:203], v179 offset:51200
	ds_read_b128 v[204:207], v179 offset:52224
	ds_read_b128 v[228:231], v179 offset:53248
	ds_read_b128 v[232:235], v179 offset:54272
	ds_read_b128 v[236:239], v179 offset:55296
	ds_read_b128 v[240:243], v179 offset:56320
	buffer_load_dwordx4 v175, s[60:63], s27 offen lds
	s_mov_b32 m0, s37
	s_add_i32 s26, s26, 0x80080
	buffer_load_dwordx4 v177, s[60:63], s27 offen lds
	s_mov_b32 m0, s48
	s_nop 0
	buffer_load_dwordx4 v175, s[60:63], s26 offen lds
	s_mov_b32 m0, s49
	s_nop 0
	buffer_load_dwordx4 v177, s[60:63], s26 offen lds
	s_mov_b32 m0, s40
	s_nop 0
	buffer_load_dwordx4 v174, s[44:47], s23 offen lds
	s_mov_b32 m0, s41
	s_nop 0
	buffer_load_dwordx4 v176, s[44:47], s23 offen lds
	s_waitcnt vmcnt(8)
	s_waitcnt lgkmcnt(0)
	s_setprio 1
	s_barrier
	v_mfma_f32_16x16x32_bf16 v[62:65], v[134:137], v[192:195], v[62:65]
	v_mfma_f32_16x16x32_bf16 v[58:61], v[142:145], v[192:195], v[58:61]
	v_mfma_f32_16x16x32_bf16 v[54:57], v[170:173], v[192:195], v[54:57]
	v_mfma_f32_16x16x32_bf16 v[50:53], v[184:187], v[192:195], v[50:53]
	v_mfma_f32_16x16x32_bf16 v[46:49], v[134:137], v[200:203], v[46:49]
	v_mfma_f32_16x16x32_bf16 v[42:45], v[142:145], v[200:203], v[42:45]
	v_mfma_f32_16x16x32_bf16 v[38:41], v[170:173], v[200:203], v[38:41]
	v_mfma_f32_16x16x32_bf16 v[34:37], v[184:187], v[200:203], v[34:37]
	v_mfma_f32_16x16x32_bf16 v[30:33], v[134:137], v[228:231], v[30:33]
	v_mfma_f32_16x16x32_bf16 v[26:29], v[142:145], v[228:231], v[26:29]
	v_mfma_f32_16x16x32_bf16 v[22:25], v[170:173], v[228:231], v[22:25]
	v_mfma_f32_16x16x32_bf16 v[18:21], v[184:187], v[228:231], v[18:21]
	v_mfma_f32_16x16x32_bf16 v[14:17], v[134:137], v[236:239], v[14:17]
	v_mfma_f32_16x16x32_bf16 v[10:13], v[142:145], v[236:239], v[10:13]
	v_mfma_f32_16x16x32_bf16 v[6:9], v[170:173], v[236:239], v[6:9]
	v_mfma_f32_16x16x32_bf16 v[2:5], v[184:187], v[236:239], v[2:5]
	v_mfma_f32_16x16x32_bf16 v[62:65], v[138:141], v[196:199], v[62:65]
	v_mfma_f32_16x16x32_bf16 v[58:61], v[154:157], v[196:199], v[58:61]
	v_mfma_f32_16x16x32_bf16 v[54:57], v[180:183], v[196:199], v[54:57]
	v_mfma_f32_16x16x32_bf16 v[50:53], v[188:191], v[196:199], v[50:53]
	v_mfma_f32_16x16x32_bf16 v[46:49], v[138:141], v[204:207], v[46:49]
	v_mfma_f32_16x16x32_bf16 v[42:45], v[154:157], v[204:207], v[42:45]
	v_mfma_f32_16x16x32_bf16 v[38:41], v[180:183], v[204:207], v[38:41]
	v_mfma_f32_16x16x32_bf16 v[34:37], v[188:191], v[204:207], v[34:37]
	v_mfma_f32_16x16x32_bf16 v[30:33], v[138:141], v[232:235], v[30:33]
	v_mfma_f32_16x16x32_bf16 v[26:29], v[154:157], v[232:235], v[26:29]
	v_mfma_f32_16x16x32_bf16 v[22:25], v[180:183], v[232:235], v[22:25]
	v_mfma_f32_16x16x32_bf16 v[18:21], v[188:191], v[232:235], v[18:21]
	v_mfma_f32_16x16x32_bf16 v[14:17], v[138:141], v[240:243], v[14:17]
	v_mfma_f32_16x16x32_bf16 v[10:13], v[154:157], v[240:243], v[10:13]
	v_mfma_f32_16x16x32_bf16 v[6:9], v[180:183], v[240:243], v[6:9]
	v_mfma_f32_16x16x32_bf16 v[2:5], v[188:191], v[240:243], v[2:5]
	s_barrier
	s_setprio 0
	s_add_i32 s22, s22, 2
	s_addk_i32 s13, 0x100
	s_addk_i32 s21, 0x100
	s_cmp_gt_u32 s22, 29
	s_cbranch_scc0 .LBB0_905
	s_and_b64 vcc, exec, s[64:65]
	s_cbranch_vccz .LBB0_908
	s_barrier

.LBB0_1192:
	s_lshl_b32 s12, s70, 22
	s_and_b64 s[8:9], s[26:27], exec
	s_cselect_b32 s8, s12, s30
	s_lshl_b32 s22, s71, 22
	s_and_b64 s[66:67], s[26:27], exec
	s_cselect_b32 s9, s22, s31
	s_add_i32 s30, s30, 0x200080
	s_addk_i32 s31, 0x100
	s_mov_b32 s72, -2
	v_add_u32_e32 v141, 0x10000, v139
	ds_read_b128 v[142:145], v141
	ds_read_b128 v[154:157], v141 offset:1024
	ds_read_b128 v[170:173], v141 offset:2048
	ds_read_b128 v[174:177], v141 offset:3072
	v_add_u32_e32 v141, 0x14000, v139
	ds_read_b128 v[178:181], v141
	ds_read_b128 v[182:185], v141 offset:1024
	ds_read_b128 v[186:189], v141 offset:2048
	ds_read_b128 v[190:193], v141 offset:3072
	s_add_i32 s52, s30, 0xffe00080
	s_cmpk_eq_i32 s72, 0x7c
	s_cselect_b32 s52, s8, s52
	s_cselect_b32 s82, s9, s31
	s_or_b32 s73, s52, 0x80
	s_mov_b32 m0, s69
	ds_read_b128 v[194:197], v140
	ds_read_b128 v[198:201], v140 offset:1024
	ds_read_b128 v[202:205], v140 offset:2048
	ds_read_b128 v[228:231], v140 offset:3072
	ds_read_b128 v[232:235], v140 offset:4096
	ds_read_b128 v[236:239], v140 offset:5120
	ds_read_b128 v[240:243], v140 offset:6144
	ds_read_b128 v[244:247], v140 offset:7168
	buffer_load_dwordx4 v131, s[60:63], s30 offen lds
	s_mov_b32 m0, s46
	s_nop 0
	buffer_load_dwordx4 v135, s[60:63], s30 offen lds
	s_waitcnt vmcnt(8)
	s_waitcnt lgkmcnt(0)
	s_setprio 1
	s_barrier
	v_mfma_f32_16x16x32_bf16 v[126:129], v[142:145], v[194:197], 0
	v_mfma_f32_16x16x32_bf16 v[122:125], v[170:173], v[194:197], 0
	v_mfma_f32_16x16x32_bf16 v[62:65], v[178:181], v[194:197], 0
	v_mfma_f32_16x16x32_bf16 v[58:61], v[186:189], v[194:197], 0
	v_mfma_f32_16x16x32_bf16 v[118:121], v[142:145], v[202:205], 0
	v_mfma_f32_16x16x32_bf16 v[114:117], v[170:173], v[202:205], 0
	v_mfma_f32_16x16x32_bf16 v[54:57], v[178:181], v[202:205], 0
	v_mfma_f32_16x16x32_bf16 v[50:53], v[186:189], v[202:205], 0
	v_mfma_f32_16x16x32_bf16 v[110:113], v[142:145], v[232:235], 0
	v_mfma_f32_16x16x32_bf16 v[106:109], v[170:173], v[232:235], 0
	v_mfma_f32_16x16x32_bf16 v[46:49], v[178:181], v[232:235], 0
	v_mfma_f32_16x16x32_bf16 v[42:45], v[186:189], v[232:235], 0
	v_mfma_f32_16x16x32_bf16 v[102:105], v[142:145], v[240:243], 0
	v_mfma_f32_16x16x32_bf16 v[98:101], v[170:173], v[240:243], 0
	v_mfma_f32_16x16x32_bf16 v[38:41], v[178:181], v[240:243], 0
	v_mfma_f32_16x16x32_bf16 v[34:37], v[186:189], v[240:243], 0
	v_mfma_f32_16x16x32_bf16 v[126:129], v[154:157], v[198:201], v[126:129]
	v_mfma_f32_16x16x32_bf16 v[122:125], v[174:177], v[198:201], v[122:125]
	v_mfma_f32_16x16x32_bf16 v[62:65], v[182:185], v[198:201], v[62:65]
	v_mfma_f32_16x16x32_bf16 v[58:61], v[190:193], v[198:201], v[58:61]
	v_mfma_f32_16x16x32_bf16 v[118:121], v[154:157], v[228:231], v[118:121]
	v_mfma_f32_16x16x32_bf16 v[114:117], v[174:177], v[228:231], v[114:117]
	v_mfma_f32_16x16x32_bf16 v[54:57], v[182:185], v[228:231], v[54:57]
	v_mfma_f32_16x16x32_bf16 v[50:53], v[190:193], v[228:231], v[50:53]
	v_mfma_f32_16x16x32_bf16 v[110:113], v[154:157], v[236:239], v[110:113]
	v_mfma_f32_16x16x32_bf16 v[106:109], v[174:177], v[236:239], v[106:109]
	v_mfma_f32_16x16x32_bf16 v[46:49], v[182:185], v[236:239], v[46:49]
	v_mfma_f32_16x16x32_bf16 v[42:45], v[190:193], v[236:239], v[42:45]
	v_mfma_f32_16x16x32_bf16 v[102:105], v[154:157], v[244:247], v[102:105]
	v_mfma_f32_16x16x32_bf16 v[98:101], v[174:177], v[244:247], v[98:101]
	v_mfma_f32_16x16x32_bf16 v[38:41], v[182:185], v[244:247], v[38:41]
	v_mfma_f32_16x16x32_bf16 v[34:37], v[190:193], v[244:247], v[34:37]
	s_barrier
	s_setprio 0
	s_mov_b32 m0, s15
	s_mov_b32 s66, s62
	s_mov_b32 s67, s63
	ds_read_b128 v[194:197], v140 offset:16384
	ds_read_b128 v[198:201], v140 offset:17408
	ds_read_b128 v[202:205], v140 offset:18432
	ds_read_b128 v[228:231], v140 offset:19456
	ds_read_b128 v[232:235], v140 offset:20480
	ds_read_b128 v[236:239], v140 offset:21504
	ds_read_b128 v[240:243], v140 offset:22528
	ds_read_b128 v[244:247], v140 offset:23552
	buffer_load_dwordx4 v134, s[64:67], s82 offen lds
	s_mov_b32 m0, s16
	s_add_i32 s53, s82, 0x200000
	buffer_load_dwordx4 v136, s[64:67], s82 offen lds
	s_mov_b32 m0, s21
	s_nop 0
	buffer_load_dwordx4 v134, s[64:67], s53 offen lds
	s_mov_b32 m0, s23
	s_nop 0
	buffer_load_dwordx4 v136, s[64:67], s53 offen lds
	s_mov_b32 m0, s2
	s_nop 0
	buffer_load_dwordx4 v131, s[60:63], s52 offen lds
	s_mov_b32 m0, s24
	s_nop 0
	buffer_load_dwordx4 v135, s[60:63], s52 offen lds
	s_waitcnt vmcnt(8)
	s_waitcnt lgkmcnt(0)
	s_setprio 1
	s_barrier
	v_mfma_f32_16x16x32_bf16 v[94:97], v[142:145], v[194:197], 0
	v_mfma_f32_16x16x32_bf16 v[90:93], v[170:173], v[194:197], 0
	v_mfma_f32_16x16x32_bf16 v[30:33], v[178:181], v[194:197], 0
	v_mfma_f32_16x16x32_bf16 v[26:29], v[186:189], v[194:197], 0
	v_mfma_f32_16x16x32_bf16 v[86:89], v[142:145], v[202:205], 0
	v_mfma_f32_16x16x32_bf16 v[82:85], v[170:173], v[202:205], 0
	v_mfma_f32_16x16x32_bf16 v[22:25], v[178:181], v[202:205], 0
	v_mfma_f32_16x16x32_bf16 v[18:21], v[186:189], v[202:205], 0
	v_mfma_f32_16x16x32_bf16 v[78:81], v[142:145], v[232:235], 0
	v_mfma_f32_16x16x32_bf16 v[74:77], v[170:173], v[232:235], 0
	v_mfma_f32_16x16x32_bf16 v[14:17], v[178:181], v[232:235], 0
	v_mfma_f32_16x16x32_bf16 v[10:13], v[186:189], v[232:235], 0
	v_mfma_f32_16x16x32_bf16 v[70:73], v[142:145], v[240:243], 0
	v_mfma_f32_16x16x32_bf16 v[66:69], v[170:173], v[240:243], 0
	v_mfma_f32_16x16x32_bf16 v[6:9], v[178:181], v[240:243], 0
	v_mfma_f32_16x16x32_bf16 v[2:5], v[186:189], v[240:243], 0
	v_mfma_f32_16x16x32_bf16 v[94:97], v[154:157], v[198:201], v[94:97]
	v_mfma_f32_16x16x32_bf16 v[90:93], v[174:177], v[198:201], v[90:93]
	v_mfma_f32_16x16x32_bf16 v[30:33], v[182:185], v[198:201], v[30:33]
	v_mfma_f32_16x16x32_bf16 v[26:29], v[190:193], v[198:201], v[26:29]
	v_mfma_f32_16x16x32_bf16 v[86:89], v[154:157], v[228:231], v[86:89]
	v_mfma_f32_16x16x32_bf16 v[82:85], v[174:177], v[228:231], v[82:85]
	v_mfma_f32_16x16x32_bf16 v[22:25], v[182:185], v[228:231], v[22:25]
	v_mfma_f32_16x16x32_bf16 v[18:21], v[190:193], v[228:231], v[18:21]
	v_mfma_f32_16x16x32_bf16 v[78:81], v[154:157], v[236:239], v[78:81]
	v_mfma_f32_16x16x32_bf16 v[74:77], v[174:177], v[236:239], v[74:77]
	v_mfma_f32_16x16x32_bf16 v[14:17], v[182:185], v[236:239], v[14:17]
	v_mfma_f32_16x16x32_bf16 v[10:13], v[190:193], v[236:239], v[10:13]
	v_mfma_f32_16x16x32_bf16 v[70:73], v[154:157], v[244:247], v[70:73]
	v_mfma_f32_16x16x32_bf16 v[66:69], v[174:177], v[244:247], v[66:69]
	v_mfma_f32_16x16x32_bf16 v[6:9], v[182:185], v[244:247], v[6:9]
	v_mfma_f32_16x16x32_bf16 v[2:5], v[190:193], v[244:247], v[2:5]
	s_barrier
	s_setprio 0
	v_add_u32_e32 v141, 0x18000, v139
	ds_read_b128 v[142:145], v141
	ds_read_b128 v[154:157], v141 offset:1024
	ds_read_b128 v[170:173], v141 offset:2048
	ds_read_b128 v[174:177], v141 offset:3072
	v_add_u32_e32 v141, 0x1c000, v139
	ds_read_b128 v[178:181], v141
	ds_read_b128 v[182:185], v141 offset:1024
	ds_read_b128 v[186:189], v141 offset:2048
	ds_read_b128 v[190:193], v141 offset:3072
	s_add_i32 s52, s52, 0x200000
	s_mov_b32 m0, s25
	ds_read_b128 v[194:197], v140 offset:32768
	ds_read_b128 v[198:201], v140 offset:33792
	ds_read_b128 v[202:205], v140 offset:34816
	ds_read_b128 v[228:231], v140 offset:35840
	ds_read_b128 v[232:235], v140 offset:36864
	ds_read_b128 v[236:239], v140 offset:37888
	ds_read_b128 v[240:243], v140 offset:38912
	ds_read_b128 v[244:247], v140 offset:39936
	buffer_load_dwordx4 v131, s[60:63], s52 offen lds
	s_mov_b32 m0, s33
	s_nop 0
	buffer_load_dwordx4 v135, s[60:63], s52 offen lds
	s_waitcnt vmcnt(8)
	s_waitcnt lgkmcnt(0)
	s_setprio 1
	s_barrier
	v_mfma_f32_16x16x32_bf16 v[126:129], v[142:145], v[194:197], v[126:129]
	v_mfma_f32_16x16x32_bf16 v[122:125], v[170:173], v[194:197], v[122:125]
	v_mfma_f32_16x16x32_bf16 v[62:65], v[178:181], v[194:197], v[62:65]
	v_mfma_f32_16x16x32_bf16 v[58:61], v[186:189], v[194:197], v[58:61]
	v_mfma_f32_16x16x32_bf16 v[118:121], v[142:145], v[202:205], v[118:121]
	v_mfma_f32_16x16x32_bf16 v[114:117], v[170:173], v[202:205], v[114:117]
	v_mfma_f32_16x16x32_bf16 v[54:57], v[178:181], v[202:205], v[54:57]
	v_mfma_f32_16x16x32_bf16 v[50:53], v[186:189], v[202:205], v[50:53]
	v_mfma_f32_16x16x32_bf16 v[110:113], v[142:145], v[232:235], v[110:113]
	v_mfma_f32_16x16x32_bf16 v[106:109], v[170:173], v[232:235], v[106:109]
	v_mfma_f32_16x16x32_bf16 v[46:49], v[178:181], v[232:235], v[46:49]
	v_mfma_f32_16x16x32_bf16 v[42:45], v[186:189], v[232:235], v[42:45]
	v_mfma_f32_16x16x32_bf16 v[102:105], v[142:145], v[240:243], v[102:105]
	v_mfma_f32_16x16x32_bf16 v[98:101], v[170:173], v[240:243], v[98:101]
	v_mfma_f32_16x16x32_bf16 v[38:41], v[178:181], v[240:243], v[38:41]
	v_mfma_f32_16x16x32_bf16 v[34:37], v[186:189], v[240:243], v[34:37]
	v_mfma_f32_16x16x32_bf16 v[126:129], v[154:157], v[198:201], v[126:129]
	v_mfma_f32_16x16x32_bf16 v[122:125], v[174:177], v[198:201], v[122:125]
	v_mfma_f32_16x16x32_bf16 v[62:65], v[182:185], v[198:201], v[62:65]
	v_mfma_f32_16x16x32_bf16 v[58:61], v[190:193], v[198:201], v[58:61]
	v_mfma_f32_16x16x32_bf16 v[118:121], v[154:157], v[228:231], v[118:121]
	v_mfma_f32_16x16x32_bf16 v[114:117], v[174:177], v[228:231], v[114:117]
	v_mfma_f32_16x16x32_bf16 v[54:57], v[182:185], v[228:231], v[54:57]
	v_mfma_f32_16x16x32_bf16 v[50:53], v[190:193], v[228:231], v[50:53]
	v_mfma_f32_16x16x32_bf16 v[110:113], v[154:157], v[236:239], v[110:113]
	v_mfma_f32_16x16x32_bf16 v[106:109], v[174:177], v[236:239], v[106:109]
	v_mfma_f32_16x16x32_bf16 v[46:49], v[182:185], v[236:239], v[46:49]
	v_mfma_f32_16x16x32_bf16 v[42:45], v[190:193], v[236:239], v[42:45]
	v_mfma_f32_16x16x32_bf16 v[102:105], v[154:157], v[244:247], v[102:105]
	v_mfma_f32_16x16x32_bf16 v[98:101], v[174:177], v[244:247], v[98:101]
	v_mfma_f32_16x16x32_bf16 v[38:41], v[182:185], v[244:247], v[38:41]
	v_mfma_f32_16x16x32_bf16 v[34:37], v[190:193], v[244:247], v[34:37]
	s_barrier
	s_setprio 0
	s_mov_b32 m0, s34
	s_or_b32 s52, s82, 0x80
	ds_read_b128 v[194:197], v140 offset:49152
	ds_read_b128 v[198:201], v140 offset:50176
	ds_read_b128 v[202:205], v140 offset:51200
	ds_read_b128 v[228:231], v140 offset:52224
	ds_read_b128 v[232:235], v140 offset:53248
	ds_read_b128 v[236:239], v140 offset:54272
	ds_read_b128 v[240:243], v140 offset:55296
	ds_read_b128 v[244:247], v140 offset:56320
	buffer_load_dwordx4 v134, s[64:67], s52 offen lds
	s_mov_b32 m0, s35
	s_add_i32 s82, s82, 0x200080
	buffer_load_dwordx4 v136, s[64:67], s52 offen lds
	s_mov_b32 m0, s37
	s_nop 0
	buffer_load_dwordx4 v134, s[64:67], s82 offen lds
	s_mov_b32 m0, s44
	s_nop 0
	buffer_load_dwordx4 v136, s[64:67], s82 offen lds
	s_mov_b32 m0, s14
	s_nop 0
	buffer_load_dwordx4 v131, s[60:63], s73 offen lds
	s_mov_b32 m0, s36
	s_nop 0
	buffer_load_dwordx4 v135, s[60:63], s73 offen lds
	s_waitcnt vmcnt(8)
	s_waitcnt lgkmcnt(0)
	s_setprio 1
	s_barrier
	v_mfma_f32_16x16x32_bf16 v[94:97], v[142:145], v[194:197], v[94:97]
	v_mfma_f32_16x16x32_bf16 v[90:93], v[170:173], v[194:197], v[90:93]
	v_mfma_f32_16x16x32_bf16 v[30:33], v[178:181], v[194:197], v[30:33]
	v_mfma_f32_16x16x32_bf16 v[26:29], v[186:189], v[194:197], v[26:29]
	v_mfma_f32_16x16x32_bf16 v[86:89], v[142:145], v[202:205], v[86:89]
	v_mfma_f32_16x16x32_bf16 v[82:85], v[170:173], v[202:205], v[82:85]
	v_mfma_f32_16x16x32_bf16 v[22:25], v[178:181], v[202:205], v[22:25]
	v_mfma_f32_16x16x32_bf16 v[18:21], v[186:189], v[202:205], v[18:21]
	v_mfma_f32_16x16x32_bf16 v[78:81], v[142:145], v[232:235], v[78:81]
	v_mfma_f32_16x16x32_bf16 v[74:77], v[170:173], v[232:235], v[74:77]
	v_mfma_f32_16x16x32_bf16 v[14:17], v[178:181], v[232:235], v[14:17]
	v_mfma_f32_16x16x32_bf16 v[10:13], v[186:189], v[232:235], v[10:13]
	v_mfma_f32_16x16x32_bf16 v[70:73], v[142:145], v[240:243], v[70:73]
	v_mfma_f32_16x16x32_bf16 v[66:69], v[170:173], v[240:243], v[66:69]
	v_mfma_f32_16x16x32_bf16 v[6:9], v[178:181], v[240:243], v[6:9]
	v_mfma_f32_16x16x32_bf16 v[2:5], v[186:189], v[240:243], v[2:5]
	v_mfma_f32_16x16x32_bf16 v[94:97], v[154:157], v[198:201], v[94:97]
	v_mfma_f32_16x16x32_bf16 v[90:93], v[174:177], v[198:201], v[90:93]
	v_mfma_f32_16x16x32_bf16 v[30:33], v[182:185], v[198:201], v[30:33]
	v_mfma_f32_16x16x32_bf16 v[26:29], v[190:193], v[198:201], v[26:29]
	v_mfma_f32_16x16x32_bf16 v[86:89], v[154:157], v[228:231], v[86:89]
	v_mfma_f32_16x16x32_bf16 v[82:85], v[174:177], v[228:231], v[82:85]
	v_mfma_f32_16x16x32_bf16 v[22:25], v[182:185], v[228:231], v[22:25]
	v_mfma_f32_16x16x32_bf16 v[18:21], v[190:193], v[228:231], v[18:21]
	v_mfma_f32_16x16x32_bf16 v[78:81], v[154:157], v[236:239], v[78:81]
	v_mfma_f32_16x16x32_bf16 v[74:77], v[174:177], v[236:239], v[74:77]
	v_mfma_f32_16x16x32_bf16 v[14:17], v[182:185], v[236:239], v[14:17]
	v_mfma_f32_16x16x32_bf16 v[10:13], v[190:193], v[236:239], v[10:13]
	v_mfma_f32_16x16x32_bf16 v[70:73], v[154:157], v[244:247], v[70:73]
	v_mfma_f32_16x16x32_bf16 v[66:69], v[174:177], v[244:247], v[66:69]
	v_mfma_f32_16x16x32_bf16 v[6:9], v[182:185], v[244:247], v[6:9]
	v_mfma_f32_16x16x32_bf16 v[2:5], v[190:193], v[244:247], v[2:5]
	s_barrier
	s_setprio 0
	s_add_i32 s72, s72, 2
	s_addk_i32 s30, 0x100
	s_addk_i32 s31, 0x100
	s_cmpk_gt_u32 s72, 0x7d
.LBB0_1193:
	v_add_u32_e32 v141, 0x10000, v139
	ds_read_b128 v[142:145], v141
	ds_read_b128 v[154:157], v141 offset:1024
	ds_read_b128 v[170:173], v141 offset:2048
	ds_read_b128 v[174:177], v141 offset:3072
	v_add_u32_e32 v141, 0x14000, v139
	ds_read_b128 v[178:181], v141
	ds_read_b128 v[182:185], v141 offset:1024
	ds_read_b128 v[186:189], v141 offset:2048
	ds_read_b128 v[190:193], v141 offset:3072
	s_add_i32 s52, s30, 0xffe00080
	s_cmpk_eq_i32 s72, 0x7c
	s_cselect_b32 s52, s8, s52
	s_cselect_b32 s82, s9, s31
	s_or_b32 s73, s52, 0x80
	s_mov_b32 m0, s69
	ds_read_b128 v[194:197], v140
	ds_read_b128 v[198:201], v140 offset:1024
	ds_read_b128 v[202:205], v140 offset:2048
	ds_read_b128 v[228:231], v140 offset:3072
	ds_read_b128 v[232:235], v140 offset:4096
	ds_read_b128 v[236:239], v140 offset:5120
	ds_read_b128 v[240:243], v140 offset:6144
	ds_read_b128 v[244:247], v140 offset:7168
	buffer_load_dwordx4 v131, s[60:63], s30 offen lds
	s_mov_b32 m0, s46
	s_nop 0
	buffer_load_dwordx4 v135, s[60:63], s30 offen lds
	s_waitcnt vmcnt(8)
	s_waitcnt lgkmcnt(0)
	s_setprio 1
	s_barrier
	v_mfma_f32_16x16x32_bf16 v[126:129], v[142:145], v[194:197], v[126:129]
	v_mfma_f32_16x16x32_bf16 v[122:125], v[170:173], v[194:197], v[122:125]
	v_mfma_f32_16x16x32_bf16 v[62:65], v[178:181], v[194:197], v[62:65]
	v_mfma_f32_16x16x32_bf16 v[58:61], v[186:189], v[194:197], v[58:61]
	v_mfma_f32_16x16x32_bf16 v[118:121], v[142:145], v[202:205], v[118:121]
	v_mfma_f32_16x16x32_bf16 v[114:117], v[170:173], v[202:205], v[114:117]
	v_mfma_f32_16x16x32_bf16 v[54:57], v[178:181], v[202:205], v[54:57]
	v_mfma_f32_16x16x32_bf16 v[50:53], v[186:189], v[202:205], v[50:53]
	v_mfma_f32_16x16x32_bf16 v[110:113], v[142:145], v[232:235], v[110:113]
	v_mfma_f32_16x16x32_bf16 v[106:109], v[170:173], v[232:235], v[106:109]
	v_mfma_f32_16x16x32_bf16 v[46:49], v[178:181], v[232:235], v[46:49]
	v_mfma_f32_16x16x32_bf16 v[42:45], v[186:189], v[232:235], v[42:45]
	v_mfma_f32_16x16x32_bf16 v[102:105], v[142:145], v[240:243], v[102:105]
	v_mfma_f32_16x16x32_bf16 v[98:101], v[170:173], v[240:243], v[98:101]
	v_mfma_f32_16x16x32_bf16 v[38:41], v[178:181], v[240:243], v[38:41]
	v_mfma_f32_16x16x32_bf16 v[34:37], v[186:189], v[240:243], v[34:37]
	v_mfma_f32_16x16x32_bf16 v[126:129], v[154:157], v[198:201], v[126:129]
	v_mfma_f32_16x16x32_bf16 v[122:125], v[174:177], v[198:201], v[122:125]
	v_mfma_f32_16x16x32_bf16 v[62:65], v[182:185], v[198:201], v[62:65]
	v_mfma_f32_16x16x32_bf16 v[58:61], v[190:193], v[198:201], v[58:61]
	v_mfma_f32_16x16x32_bf16 v[118:121], v[154:157], v[228:231], v[118:121]
	v_mfma_f32_16x16x32_bf16 v[114:117], v[174:177], v[228:231], v[114:117]
	v_mfma_f32_16x16x32_bf16 v[54:57], v[182:185], v[228:231], v[54:57]
	v_mfma_f32_16x16x32_bf16 v[50:53], v[190:193], v[228:231], v[50:53]
	v_mfma_f32_16x16x32_bf16 v[110:113], v[154:157], v[236:239], v[110:113]
	v_mfma_f32_16x16x32_bf16 v[106:109], v[174:177], v[236:239], v[106:109]
	v_mfma_f32_16x16x32_bf16 v[46:49], v[182:185], v[236:239], v[46:49]
	v_mfma_f32_16x16x32_bf16 v[42:45], v[190:193], v[236:239], v[42:45]
	v_mfma_f32_16x16x32_bf16 v[102:105], v[154:157], v[244:247], v[102:105]
	v_mfma_f32_16x16x32_bf16 v[98:101], v[174:177], v[244:247], v[98:101]
	v_mfma_f32_16x16x32_bf16 v[38:41], v[182:185], v[244:247], v[38:41]
	v_mfma_f32_16x16x32_bf16 v[34:37], v[190:193], v[244:247], v[34:37]
	s_barrier
	s_setprio 0
	s_mov_b32 m0, s15
	s_mov_b32 s66, s62
	s_mov_b32 s67, s63
	ds_read_b128 v[194:197], v140 offset:16384
	ds_read_b128 v[198:201], v140 offset:17408
	ds_read_b128 v[202:205], v140 offset:18432
	ds_read_b128 v[228:231], v140 offset:19456
	ds_read_b128 v[232:235], v140 offset:20480
	ds_read_b128 v[236:239], v140 offset:21504
	ds_read_b128 v[240:243], v140 offset:22528
	ds_read_b128 v[244:247], v140 offset:23552
	buffer_load_dwordx4 v134, s[64:67], s82 offen lds
	s_mov_b32 m0, s16
	s_add_i32 s53, s82, 0x200000
	buffer_load_dwordx4 v136, s[64:67], s82 offen lds
	s_mov_b32 m0, s21
	s_nop 0
	buffer_load_dwordx4 v134, s[64:67], s53 offen lds
	s_mov_b32 m0, s23
	s_nop 0
	buffer_load_dwordx4 v136, s[64:67], s53 offen lds
	s_mov_b32 m0, s2
	s_nop 0
	buffer_load_dwordx4 v131, s[60:63], s52 offen lds
	s_mov_b32 m0, s24
	s_nop 0
	buffer_load_dwordx4 v135, s[60:63], s52 offen lds
	s_waitcnt vmcnt(8)
	s_waitcnt lgkmcnt(0)
	s_setprio 1
	s_barrier
	v_mfma_f32_16x16x32_bf16 v[94:97], v[142:145], v[194:197], v[94:97]
	v_mfma_f32_16x16x32_bf16 v[90:93], v[170:173], v[194:197], v[90:93]
	v_mfma_f32_16x16x32_bf16 v[30:33], v[178:181], v[194:197], v[30:33]
	v_mfma_f32_16x16x32_bf16 v[26:29], v[186:189], v[194:197], v[26:29]
	v_mfma_f32_16x16x32_bf16 v[86:89], v[142:145], v[202:205], v[86:89]
	v_mfma_f32_16x16x32_bf16 v[82:85], v[170:173], v[202:205], v[82:85]
	v_mfma_f32_16x16x32_bf16 v[22:25], v[178:181], v[202:205], v[22:25]
	v_mfma_f32_16x16x32_bf16 v[18:21], v[186:189], v[202:205], v[18:21]
	v_mfma_f32_16x16x32_bf16 v[78:81], v[142:145], v[232:235], v[78:81]
	v_mfma_f32_16x16x32_bf16 v[74:77], v[170:173], v[232:235], v[74:77]
	v_mfma_f32_16x16x32_bf16 v[14:17], v[178:181], v[232:235], v[14:17]
	v_mfma_f32_16x16x32_bf16 v[10:13], v[186:189], v[232:235], v[10:13]
	v_mfma_f32_16x16x32_bf16 v[70:73], v[142:145], v[240:243], v[70:73]
	v_mfma_f32_16x16x32_bf16 v[66:69], v[170:173], v[240:243], v[66:69]
	v_mfma_f32_16x16x32_bf16 v[6:9], v[178:181], v[240:243], v[6:9]
	v_mfma_f32_16x16x32_bf16 v[2:5], v[186:189], v[240:243], v[2:5]
	v_mfma_f32_16x16x32_bf16 v[94:97], v[154:157], v[198:201], v[94:97]
	v_mfma_f32_16x16x32_bf16 v[90:93], v[174:177], v[198:201], v[90:93]
	v_mfma_f32_16x16x32_bf16 v[30:33], v[182:185], v[198:201], v[30:33]
	v_mfma_f32_16x16x32_bf16 v[26:29], v[190:193], v[198:201], v[26:29]
	v_mfma_f32_16x16x32_bf16 v[86:89], v[154:157], v[228:231], v[86:89]
	v_mfma_f32_16x16x32_bf16 v[82:85], v[174:177], v[228:231], v[82:85]
	v_mfma_f32_16x16x32_bf16 v[22:25], v[182:185], v[228:231], v[22:25]
	v_mfma_f32_16x16x32_bf16 v[18:21], v[190:193], v[228:231], v[18:21]
	v_mfma_f32_16x16x32_bf16 v[78:81], v[154:157], v[236:239], v[78:81]
	v_mfma_f32_16x16x32_bf16 v[74:77], v[174:177], v[236:239], v[74:77]
	v_mfma_f32_16x16x32_bf16 v[14:17], v[182:185], v[236:239], v[14:17]
	v_mfma_f32_16x16x32_bf16 v[10:13], v[190:193], v[236:239], v[10:13]
	v_mfma_f32_16x16x32_bf16 v[70:73], v[154:157], v[244:247], v[70:73]
	v_mfma_f32_16x16x32_bf16 v[66:69], v[174:177], v[244:247], v[66:69]
	v_mfma_f32_16x16x32_bf16 v[6:9], v[182:185], v[244:247], v[6:9]
	v_mfma_f32_16x16x32_bf16 v[2:5], v[190:193], v[244:247], v[2:5]
	s_barrier
	s_setprio 0
	v_add_u32_e32 v141, 0x18000, v139
	ds_read_b128 v[142:145], v141
	ds_read_b128 v[154:157], v141 offset:1024
	ds_read_b128 v[170:173], v141 offset:2048
	ds_read_b128 v[174:177], v141 offset:3072
	v_add_u32_e32 v141, 0x1c000, v139
	ds_read_b128 v[178:181], v141
	ds_read_b128 v[182:185], v141 offset:1024
	ds_read_b128 v[186:189], v141 offset:2048
	ds_read_b128 v[190:193], v141 offset:3072
	s_add_i32 s52, s52, 0x200000
	s_mov_b32 m0, s25
	ds_read_b128 v[194:197], v140 offset:32768
	ds_read_b128 v[198:201], v140 offset:33792
	ds_read_b128 v[202:205], v140 offset:34816
	ds_read_b128 v[228:231], v140 offset:35840
	ds_read_b128 v[232:235], v140 offset:36864
	ds_read_b128 v[236:239], v140 offset:37888
	ds_read_b128 v[240:243], v140 offset:38912
	ds_read_b128 v[244:247], v140 offset:39936
	buffer_load_dwordx4 v131, s[60:63], s52 offen lds
	s_mov_b32 m0, s33
	s_nop 0
	buffer_load_dwordx4 v135, s[60:63], s52 offen lds
	s_waitcnt vmcnt(8)
	s_waitcnt lgkmcnt(0)
	s_setprio 1
	s_barrier
	v_mfma_f32_16x16x32_bf16 v[126:129], v[142:145], v[194:197], v[126:129]
	v_mfma_f32_16x16x32_bf16 v[122:125], v[170:173], v[194:197], v[122:125]
	v_mfma_f32_16x16x32_bf16 v[62:65], v[178:181], v[194:197], v[62:65]
	v_mfma_f32_16x16x32_bf16 v[58:61], v[186:189], v[194:197], v[58:61]
	v_mfma_f32_16x16x32_bf16 v[118:121], v[142:145], v[202:205], v[118:121]
	v_mfma_f32_16x16x32_bf16 v[114:117], v[170:173], v[202:205], v[114:117]
	v_mfma_f32_16x16x32_bf16 v[54:57], v[178:181], v[202:205], v[54:57]
	v_mfma_f32_16x16x32_bf16 v[50:53], v[186:189], v[202:205], v[50:53]
	v_mfma_f32_16x16x32_bf16 v[110:113], v[142:145], v[232:235], v[110:113]
	v_mfma_f32_16x16x32_bf16 v[106:109], v[170:173], v[232:235], v[106:109]
	v_mfma_f32_16x16x32_bf16 v[46:49], v[178:181], v[232:235], v[46:49]
	v_mfma_f32_16x16x32_bf16 v[42:45], v[186:189], v[232:235], v[42:45]
	v_mfma_f32_16x16x32_bf16 v[102:105], v[142:145], v[240:243], v[102:105]
	v_mfma_f32_16x16x32_bf16 v[98:101], v[170:173], v[240:243], v[98:101]
	v_mfma_f32_16x16x32_bf16 v[38:41], v[178:181], v[240:243], v[38:41]
	v_mfma_f32_16x16x32_bf16 v[34:37], v[186:189], v[240:243], v[34:37]
	v_mfma_f32_16x16x32_bf16 v[126:129], v[154:157], v[198:201], v[126:129]
	v_mfma_f32_16x16x32_bf16 v[122:125], v[174:177], v[198:201], v[122:125]
	v_mfma_f32_16x16x32_bf16 v[62:65], v[182:185], v[198:201], v[62:65]
	v_mfma_f32_16x16x32_bf16 v[58:61], v[190:193], v[198:201], v[58:61]
	v_mfma_f32_16x16x32_bf16 v[118:121], v[154:157], v[228:231], v[118:121]
	v_mfma_f32_16x16x32_bf16 v[114:117], v[174:177], v[228:231], v[114:117]
	v_mfma_f32_16x16x32_bf16 v[54:57], v[182:185], v[228:231], v[54:57]
	v_mfma_f32_16x16x32_bf16 v[50:53], v[190:193], v[228:231], v[50:53]
	v_mfma_f32_16x16x32_bf16 v[110:113], v[154:157], v[236:239], v[110:113]
	v_mfma_f32_16x16x32_bf16 v[106:109], v[174:177], v[236:239], v[106:109]
	v_mfma_f32_16x16x32_bf16 v[46:49], v[182:185], v[236:239], v[46:49]
	v_mfma_f32_16x16x32_bf16 v[42:45], v[190:193], v[236:239], v[42:45]
	v_mfma_f32_16x16x32_bf16 v[102:105], v[154:157], v[244:247], v[102:105]
	v_mfma_f32_16x16x32_bf16 v[98:101], v[174:177], v[244:247], v[98:101]
	v_mfma_f32_16x16x32_bf16 v[38:41], v[182:185], v[244:247], v[38:41]
	v_mfma_f32_16x16x32_bf16 v[34:37], v[190:193], v[244:247], v[34:37]
	s_barrier
	s_setprio 0
	s_mov_b32 m0, s34
	s_or_b32 s52, s82, 0x80
	ds_read_b128 v[194:197], v140 offset:49152
	ds_read_b128 v[198:201], v140 offset:50176
	ds_read_b128 v[202:205], v140 offset:51200
	ds_read_b128 v[228:231], v140 offset:52224
	ds_read_b128 v[232:235], v140 offset:53248
	ds_read_b128 v[236:239], v140 offset:54272
	ds_read_b128 v[240:243], v140 offset:55296
	ds_read_b128 v[244:247], v140 offset:56320
	buffer_load_dwordx4 v134, s[64:67], s52 offen lds
	s_mov_b32 m0, s35
	s_add_i32 s82, s82, 0x200080
	buffer_load_dwordx4 v136, s[64:67], s52 offen lds
	s_mov_b32 m0, s37
	s_nop 0
	buffer_load_dwordx4 v134, s[64:67], s82 offen lds
	s_mov_b32 m0, s44
	s_nop 0
	buffer_load_dwordx4 v136, s[64:67], s82 offen lds
	s_mov_b32 m0, s14
	s_nop 0
	buffer_load_dwordx4 v131, s[60:63], s73 offen lds
	s_mov_b32 m0, s36
	s_nop 0
	buffer_load_dwordx4 v135, s[60:63], s73 offen lds
	s_waitcnt vmcnt(8)
	s_waitcnt lgkmcnt(0)
	s_setprio 1
	s_barrier
	v_mfma_f32_16x16x32_bf16 v[94:97], v[142:145], v[194:197], v[94:97]
	v_mfma_f32_16x16x32_bf16 v[90:93], v[170:173], v[194:197], v[90:93]
	v_mfma_f32_16x16x32_bf16 v[30:33], v[178:181], v[194:197], v[30:33]
	v_mfma_f32_16x16x32_bf16 v[26:29], v[186:189], v[194:197], v[26:29]
	v_mfma_f32_16x16x32_bf16 v[86:89], v[142:145], v[202:205], v[86:89]
	v_mfma_f32_16x16x32_bf16 v[82:85], v[170:173], v[202:205], v[82:85]
	v_mfma_f32_16x16x32_bf16 v[22:25], v[178:181], v[202:205], v[22:25]
	v_mfma_f32_16x16x32_bf16 v[18:21], v[186:189], v[202:205], v[18:21]
	v_mfma_f32_16x16x32_bf16 v[78:81], v[142:145], v[232:235], v[78:81]
	v_mfma_f32_16x16x32_bf16 v[74:77], v[170:173], v[232:235], v[74:77]
	v_mfma_f32_16x16x32_bf16 v[14:17], v[178:181], v[232:235], v[14:17]
	v_mfma_f32_16x16x32_bf16 v[10:13], v[186:189], v[232:235], v[10:13]
	v_mfma_f32_16x16x32_bf16 v[70:73], v[142:145], v[240:243], v[70:73]
	v_mfma_f32_16x16x32_bf16 v[66:69], v[170:173], v[240:243], v[66:69]
	v_mfma_f32_16x16x32_bf16 v[6:9], v[178:181], v[240:243], v[6:9]
	v_mfma_f32_16x16x32_bf16 v[2:5], v[186:189], v[240:243], v[2:5]
	v_mfma_f32_16x16x32_bf16 v[94:97], v[154:157], v[198:201], v[94:97]
	v_mfma_f32_16x16x32_bf16 v[90:93], v[174:177], v[198:201], v[90:93]
	v_mfma_f32_16x16x32_bf16 v[30:33], v[182:185], v[198:201], v[30:33]
	v_mfma_f32_16x16x32_bf16 v[26:29], v[190:193], v[198:201], v[26:29]
	v_mfma_f32_16x16x32_bf16 v[86:89], v[154:157], v[228:231], v[86:89]
	v_mfma_f32_16x16x32_bf16 v[82:85], v[174:177], v[228:231], v[82:85]
	v_mfma_f32_16x16x32_bf16 v[22:25], v[182:185], v[228:231], v[22:25]
	v_mfma_f32_16x16x32_bf16 v[18:21], v[190:193], v[228:231], v[18:21]
	v_mfma_f32_16x16x32_bf16 v[78:81], v[154:157], v[236:239], v[78:81]
	v_mfma_f32_16x16x32_bf16 v[74:77], v[174:177], v[236:239], v[74:77]
	v_mfma_f32_16x16x32_bf16 v[14:17], v[182:185], v[236:239], v[14:17]
	v_mfma_f32_16x16x32_bf16 v[10:13], v[190:193], v[236:239], v[10:13]
	v_mfma_f32_16x16x32_bf16 v[70:73], v[154:157], v[244:247], v[70:73]
	v_mfma_f32_16x16x32_bf16 v[66:69], v[174:177], v[244:247], v[66:69]
	v_mfma_f32_16x16x32_bf16 v[6:9], v[182:185], v[244:247], v[6:9]
	v_mfma_f32_16x16x32_bf16 v[2:5], v[190:193], v[244:247], v[2:5]
	s_barrier
	s_setprio 0
	s_add_i32 s72, s72, 2
	s_addk_i32 s30, 0x100
	s_addk_i32 s31, 0x100
	s_cmpk_gt_u32 s72, 0x7d
	s_cbranch_scc0 .LBB0_1193
	s_and_b64 vcc, exec, s[42:43]
	s_cbranch_vccz .LBB0_1196
	s_barrier

.LBB0_1222:
	s_lshl_b32 s14, s82, 22
	s_and_b64 s[8:9], s[44:45], exec
	s_cselect_b32 s8, s14, s19
	s_lshl_b32 s46, s84, 22
	s_and_b64 s[26:27], s[44:45], exec
	s_cselect_b32 s9, s46, s22
	s_add_i32 s19, s19, 0x200080
	s_addk_i32 s22, 0x100
	s_mov_b32 s26, -2
	v_add_u32_e32 v141, 0x10000, v139
	ds_read_b128 v[142:145], v141
	ds_read_b128 v[154:157], v141 offset:1024
	ds_read_b128 v[170:173], v141 offset:2048
	ds_read_b128 v[174:177], v141 offset:3072
	v_add_u32_e32 v141, 0x14000, v139
	ds_read_b128 v[178:181], v141
	ds_read_b128 v[182:185], v141 offset:1024
	ds_read_b128 v[186:189], v141 offset:2048
	ds_read_b128 v[190:193], v141 offset:3072
	s_add_i32 s27, s19, 0xffe00080
	s_cmpk_eq_i32 s26, 0x7c
	s_cselect_b32 s52, s8, s27
	s_cselect_b32 s47, s9, s22
	s_or_b32 s27, s52, 0x80
	s_mov_b32 m0, s71
	ds_read_b128 v[194:197], v140
	ds_read_b128 v[198:201], v140 offset:1024
	ds_read_b128 v[202:205], v140 offset:2048
	ds_read_b128 v[228:231], v140 offset:3072
	ds_read_b128 v[232:235], v140 offset:4096
	ds_read_b128 v[236:239], v140 offset:5120
	ds_read_b128 v[240:243], v140 offset:6144
	ds_read_b128 v[244:247], v140 offset:7168
	buffer_load_dwordx4 v131, s[60:63], s19 offen lds
	s_mov_b32 m0, s72
	s_nop 0
	buffer_load_dwordx4 v135, s[60:63], s19 offen lds
	s_waitcnt vmcnt(8)
	s_waitcnt lgkmcnt(0)
	s_setprio 1
	s_barrier
	v_mfma_f32_16x16x32_bf16 v[126:129], v[142:145], v[194:197], 0
	v_mfma_f32_16x16x32_bf16 v[122:125], v[170:173], v[194:197], 0
	v_mfma_f32_16x16x32_bf16 v[62:65], v[178:181], v[194:197], 0
	v_mfma_f32_16x16x32_bf16 v[58:61], v[186:189], v[194:197], 0
	v_mfma_f32_16x16x32_bf16 v[118:121], v[142:145], v[202:205], 0
	v_mfma_f32_16x16x32_bf16 v[114:117], v[170:173], v[202:205], 0
	v_mfma_f32_16x16x32_bf16 v[54:57], v[178:181], v[202:205], 0
	v_mfma_f32_16x16x32_bf16 v[50:53], v[186:189], v[202:205], 0
	v_mfma_f32_16x16x32_bf16 v[110:113], v[142:145], v[232:235], 0
	v_mfma_f32_16x16x32_bf16 v[106:109], v[170:173], v[232:235], 0
	v_mfma_f32_16x16x32_bf16 v[46:49], v[178:181], v[232:235], 0
	v_mfma_f32_16x16x32_bf16 v[42:45], v[186:189], v[232:235], 0
	v_mfma_f32_16x16x32_bf16 v[102:105], v[142:145], v[240:243], 0
	v_mfma_f32_16x16x32_bf16 v[98:101], v[170:173], v[240:243], 0
	v_mfma_f32_16x16x32_bf16 v[38:41], v[178:181], v[240:243], 0
	v_mfma_f32_16x16x32_bf16 v[34:37], v[186:189], v[240:243], 0
	v_mfma_f32_16x16x32_bf16 v[126:129], v[154:157], v[198:201], v[126:129]
	v_mfma_f32_16x16x32_bf16 v[122:125], v[174:177], v[198:201], v[122:125]
	v_mfma_f32_16x16x32_bf16 v[62:65], v[182:185], v[198:201], v[62:65]
	v_mfma_f32_16x16x32_bf16 v[58:61], v[190:193], v[198:201], v[58:61]
	v_mfma_f32_16x16x32_bf16 v[118:121], v[154:157], v[228:231], v[118:121]
	v_mfma_f32_16x16x32_bf16 v[114:117], v[174:177], v[228:231], v[114:117]
	v_mfma_f32_16x16x32_bf16 v[54:57], v[182:185], v[228:231], v[54:57]
	v_mfma_f32_16x16x32_bf16 v[50:53], v[190:193], v[228:231], v[50:53]
	v_mfma_f32_16x16x32_bf16 v[110:113], v[154:157], v[236:239], v[110:113]
	v_mfma_f32_16x16x32_bf16 v[106:109], v[174:177], v[236:239], v[106:109]
	v_mfma_f32_16x16x32_bf16 v[46:49], v[182:185], v[236:239], v[46:49]
	v_mfma_f32_16x16x32_bf16 v[42:45], v[190:193], v[236:239], v[42:45]
	v_mfma_f32_16x16x32_bf16 v[102:105], v[154:157], v[244:247], v[102:105]
	v_mfma_f32_16x16x32_bf16 v[98:101], v[174:177], v[244:247], v[98:101]
	v_mfma_f32_16x16x32_bf16 v[38:41], v[182:185], v[244:247], v[38:41]
	v_mfma_f32_16x16x32_bf16 v[34:37], v[190:193], v[244:247], v[34:37]
	s_barrier
	s_setprio 0
	s_mov_b32 m0, s2
	s_mov_b32 s66, s62
	s_mov_b32 s67, s63
	ds_read_b128 v[194:197], v140 offset:16384
	ds_read_b128 v[198:201], v140 offset:17408
	ds_read_b128 v[202:205], v140 offset:18432
	ds_read_b128 v[228:231], v140 offset:19456
	ds_read_b128 v[232:235], v140 offset:20480
	ds_read_b128 v[236:239], v140 offset:21504
	ds_read_b128 v[240:243], v140 offset:22528
	ds_read_b128 v[244:247], v140 offset:23552
	buffer_load_dwordx4 v134, s[64:67], s47 offen lds
	s_mov_b32 m0, s21
	s_add_i32 s53, s47, 0x200000
	buffer_load_dwordx4 v136, s[64:67], s47 offen lds
	s_mov_b32 m0, s23
	s_nop 0
	buffer_load_dwordx4 v134, s[64:67], s53 offen lds
	s_mov_b32 m0, s24
	s_nop 0
	buffer_load_dwordx4 v136, s[64:67], s53 offen lds
	s_mov_b32 m0, s16
	s_nop 0
	buffer_load_dwordx4 v131, s[60:63], s52 offen lds
	s_mov_b32 m0, s25
	s_nop 0
	buffer_load_dwordx4 v135, s[60:63], s52 offen lds
	s_waitcnt vmcnt(8)
	s_waitcnt lgkmcnt(0)
	s_setprio 1
	s_barrier
	v_mfma_f32_16x16x32_bf16 v[94:97], v[142:145], v[194:197], 0
	v_mfma_f32_16x16x32_bf16 v[90:93], v[170:173], v[194:197], 0
	v_mfma_f32_16x16x32_bf16 v[30:33], v[178:181], v[194:197], 0
	v_mfma_f32_16x16x32_bf16 v[26:29], v[186:189], v[194:197], 0
	v_mfma_f32_16x16x32_bf16 v[86:89], v[142:145], v[202:205], 0
	v_mfma_f32_16x16x32_bf16 v[82:85], v[170:173], v[202:205], 0
	v_mfma_f32_16x16x32_bf16 v[22:25], v[178:181], v[202:205], 0
	v_mfma_f32_16x16x32_bf16 v[18:21], v[186:189], v[202:205], 0
	v_mfma_f32_16x16x32_bf16 v[78:81], v[142:145], v[232:235], 0
	v_mfma_f32_16x16x32_bf16 v[74:77], v[170:173], v[232:235], 0
	v_mfma_f32_16x16x32_bf16 v[14:17], v[178:181], v[232:235], 0
	v_mfma_f32_16x16x32_bf16 v[10:13], v[186:189], v[232:235], 0
	v_mfma_f32_16x16x32_bf16 v[70:73], v[142:145], v[240:243], 0
	v_mfma_f32_16x16x32_bf16 v[66:69], v[170:173], v[240:243], 0
	v_mfma_f32_16x16x32_bf16 v[6:9], v[178:181], v[240:243], 0
	v_mfma_f32_16x16x32_bf16 v[2:5], v[186:189], v[240:243], 0
	v_mfma_f32_16x16x32_bf16 v[94:97], v[154:157], v[198:201], v[94:97]
	v_mfma_f32_16x16x32_bf16 v[90:93], v[174:177], v[198:201], v[90:93]
	v_mfma_f32_16x16x32_bf16 v[30:33], v[182:185], v[198:201], v[30:33]
	v_mfma_f32_16x16x32_bf16 v[26:29], v[190:193], v[198:201], v[26:29]
	v_mfma_f32_16x16x32_bf16 v[86:89], v[154:157], v[228:231], v[86:89]
	v_mfma_f32_16x16x32_bf16 v[82:85], v[174:177], v[228:231], v[82:85]
	v_mfma_f32_16x16x32_bf16 v[22:25], v[182:185], v[228:231], v[22:25]
	v_mfma_f32_16x16x32_bf16 v[18:21], v[190:193], v[228:231], v[18:21]
	v_mfma_f32_16x16x32_bf16 v[78:81], v[154:157], v[236:239], v[78:81]
	v_mfma_f32_16x16x32_bf16 v[74:77], v[174:177], v[236:239], v[74:77]
	v_mfma_f32_16x16x32_bf16 v[14:17], v[182:185], v[236:239], v[14:17]
	v_mfma_f32_16x16x32_bf16 v[10:13], v[190:193], v[236:239], v[10:13]
	v_mfma_f32_16x16x32_bf16 v[70:73], v[154:157], v[244:247], v[70:73]
	v_mfma_f32_16x16x32_bf16 v[66:69], v[174:177], v[244:247], v[66:69]
	v_mfma_f32_16x16x32_bf16 v[6:9], v[182:185], v[244:247], v[6:9]
	v_mfma_f32_16x16x32_bf16 v[2:5], v[190:193], v[244:247], v[2:5]
	s_barrier
	s_setprio 0
	v_add_u32_e32 v141, 0x18000, v139
	ds_read_b128 v[142:145], v141
	ds_read_b128 v[154:157], v141 offset:1024
	ds_read_b128 v[170:173], v141 offset:2048
	ds_read_b128 v[174:177], v141 offset:3072
	v_add_u32_e32 v141, 0x1c000, v139
	ds_read_b128 v[178:181], v141
	ds_read_b128 v[182:185], v141 offset:1024
	ds_read_b128 v[186:189], v141 offset:2048
	ds_read_b128 v[190:193], v141 offset:3072
	s_add_i32 s52, s52, 0x200000
	s_mov_b32 m0, s30
	ds_read_b128 v[194:197], v140 offset:32768
	ds_read_b128 v[198:201], v140 offset:33792
	ds_read_b128 v[202:205], v140 offset:34816
	ds_read_b128 v[228:231], v140 offset:35840
	ds_read_b128 v[232:235], v140 offset:36864
	ds_read_b128 v[236:239], v140 offset:37888
	ds_read_b128 v[240:243], v140 offset:38912
	ds_read_b128 v[244:247], v140 offset:39936
	buffer_load_dwordx4 v131, s[60:63], s52 offen lds
	s_mov_b32 m0, s31
	s_nop 0
	buffer_load_dwordx4 v135, s[60:63], s52 offen lds
	s_waitcnt vmcnt(8)
	s_waitcnt lgkmcnt(0)
	s_setprio 1
	s_barrier
	v_mfma_f32_16x16x32_bf16 v[126:129], v[142:145], v[194:197], v[126:129]
	v_mfma_f32_16x16x32_bf16 v[122:125], v[170:173], v[194:197], v[122:125]
	v_mfma_f32_16x16x32_bf16 v[62:65], v[178:181], v[194:197], v[62:65]
	v_mfma_f32_16x16x32_bf16 v[58:61], v[186:189], v[194:197], v[58:61]
	v_mfma_f32_16x16x32_bf16 v[118:121], v[142:145], v[202:205], v[118:121]
	v_mfma_f32_16x16x32_bf16 v[114:117], v[170:173], v[202:205], v[114:117]
	v_mfma_f32_16x16x32_bf16 v[54:57], v[178:181], v[202:205], v[54:57]
	v_mfma_f32_16x16x32_bf16 v[50:53], v[186:189], v[202:205], v[50:53]
	v_mfma_f32_16x16x32_bf16 v[110:113], v[142:145], v[232:235], v[110:113]
	v_mfma_f32_16x16x32_bf16 v[106:109], v[170:173], v[232:235], v[106:109]
	v_mfma_f32_16x16x32_bf16 v[46:49], v[178:181], v[232:235], v[46:49]
	v_mfma_f32_16x16x32_bf16 v[42:45], v[186:189], v[232:235], v[42:45]
	v_mfma_f32_16x16x32_bf16 v[102:105], v[142:145], v[240:243], v[102:105]
	v_mfma_f32_16x16x32_bf16 v[98:101], v[170:173], v[240:243], v[98:101]
	v_mfma_f32_16x16x32_bf16 v[38:41], v[178:181], v[240:243], v[38:41]
	v_mfma_f32_16x16x32_bf16 v[34:37], v[186:189], v[240:243], v[34:37]
	v_mfma_f32_16x16x32_bf16 v[126:129], v[154:157], v[198:201], v[126:129]
	v_mfma_f32_16x16x32_bf16 v[122:125], v[174:177], v[198:201], v[122:125]
	v_mfma_f32_16x16x32_bf16 v[62:65], v[182:185], v[198:201], v[62:65]
	v_mfma_f32_16x16x32_bf16 v[58:61], v[190:193], v[198:201], v[58:61]
	v_mfma_f32_16x16x32_bf16 v[118:121], v[154:157], v[228:231], v[118:121]
	v_mfma_f32_16x16x32_bf16 v[114:117], v[174:177], v[228:231], v[114:117]
	v_mfma_f32_16x16x32_bf16 v[54:57], v[182:185], v[228:231], v[54:57]
	v_mfma_f32_16x16x32_bf16 v[50:53], v[190:193], v[228:231], v[50:53]
	v_mfma_f32_16x16x32_bf16 v[110:113], v[154:157], v[236:239], v[110:113]
	v_mfma_f32_16x16x32_bf16 v[106:109], v[174:177], v[236:239], v[106:109]
	v_mfma_f32_16x16x32_bf16 v[46:49], v[182:185], v[236:239], v[46:49]
	v_mfma_f32_16x16x32_bf16 v[42:45], v[190:193], v[236:239], v[42:45]
	v_mfma_f32_16x16x32_bf16 v[102:105], v[154:157], v[244:247], v[102:105]
	v_mfma_f32_16x16x32_bf16 v[98:101], v[174:177], v[244:247], v[98:101]
	v_mfma_f32_16x16x32_bf16 v[38:41], v[182:185], v[244:247], v[38:41]
	v_mfma_f32_16x16x32_bf16 v[34:37], v[190:193], v[244:247], v[34:37]
	s_barrier
	s_setprio 0
	s_mov_b32 m0, s33
	s_or_b32 s52, s47, 0x80
	ds_read_b128 v[194:197], v140 offset:49152
	ds_read_b128 v[198:201], v140 offset:50176
	ds_read_b128 v[202:205], v140 offset:51200
	ds_read_b128 v[228:231], v140 offset:52224
	ds_read_b128 v[232:235], v140 offset:53248
	ds_read_b128 v[236:239], v140 offset:54272
	ds_read_b128 v[240:243], v140 offset:55296
	ds_read_b128 v[244:247], v140 offset:56320
	buffer_load_dwordx4 v134, s[64:67], s52 offen lds
	s_mov_b32 m0, s34
	s_add_i32 s47, s47, 0x200080
	buffer_load_dwordx4 v136, s[64:67], s52 offen lds
	s_mov_b32 m0, s37
	s_nop 0
	buffer_load_dwordx4 v134, s[64:67], s47 offen lds
	s_mov_b32 m0, s68
	s_nop 0
	buffer_load_dwordx4 v136, s[64:67], s47 offen lds
	s_mov_b32 m0, s35
	s_nop 0
	buffer_load_dwordx4 v131, s[60:63], s27 offen lds
	s_mov_b32 m0, s36
	s_nop 0
	buffer_load_dwordx4 v135, s[60:63], s27 offen lds
	s_waitcnt vmcnt(8)
	s_waitcnt lgkmcnt(0)
	s_setprio 1
	s_barrier
	v_mfma_f32_16x16x32_bf16 v[94:97], v[142:145], v[194:197], v[94:97]
	v_mfma_f32_16x16x32_bf16 v[90:93], v[170:173], v[194:197], v[90:93]
	v_mfma_f32_16x16x32_bf16 v[30:33], v[178:181], v[194:197], v[30:33]
	v_mfma_f32_16x16x32_bf16 v[26:29], v[186:189], v[194:197], v[26:29]
	v_mfma_f32_16x16x32_bf16 v[86:89], v[142:145], v[202:205], v[86:89]
	v_mfma_f32_16x16x32_bf16 v[82:85], v[170:173], v[202:205], v[82:85]
	v_mfma_f32_16x16x32_bf16 v[22:25], v[178:181], v[202:205], v[22:25]
	v_mfma_f32_16x16x32_bf16 v[18:21], v[186:189], v[202:205], v[18:21]
	v_mfma_f32_16x16x32_bf16 v[78:81], v[142:145], v[232:235], v[78:81]
	v_mfma_f32_16x16x32_bf16 v[74:77], v[170:173], v[232:235], v[74:77]
	v_mfma_f32_16x16x32_bf16 v[14:17], v[178:181], v[232:235], v[14:17]
	v_mfma_f32_16x16x32_bf16 v[10:13], v[186:189], v[232:235], v[10:13]
	v_mfma_f32_16x16x32_bf16 v[70:73], v[142:145], v[240:243], v[70:73]
	v_mfma_f32_16x16x32_bf16 v[66:69], v[170:173], v[240:243], v[66:69]
	v_mfma_f32_16x16x32_bf16 v[6:9], v[178:181], v[240:243], v[6:9]
	v_mfma_f32_16x16x32_bf16 v[2:5], v[186:189], v[240:243], v[2:5]
	v_mfma_f32_16x16x32_bf16 v[94:97], v[154:157], v[198:201], v[94:97]
	v_mfma_f32_16x16x32_bf16 v[90:93], v[174:177], v[198:201], v[90:93]
	v_mfma_f32_16x16x32_bf16 v[30:33], v[182:185], v[198:201], v[30:33]
	v_mfma_f32_16x16x32_bf16 v[26:29], v[190:193], v[198:201], v[26:29]
	v_mfma_f32_16x16x32_bf16 v[86:89], v[154:157], v[228:231], v[86:89]
	v_mfma_f32_16x16x32_bf16 v[82:85], v[174:177], v[228:231], v[82:85]
	v_mfma_f32_16x16x32_bf16 v[22:25], v[182:185], v[228:231], v[22:25]
	v_mfma_f32_16x16x32_bf16 v[18:21], v[190:193], v[228:231], v[18:21]
	v_mfma_f32_16x16x32_bf16 v[78:81], v[154:157], v[236:239], v[78:81]
	v_mfma_f32_16x16x32_bf16 v[74:77], v[174:177], v[236:239], v[74:77]
	v_mfma_f32_16x16x32_bf16 v[14:17], v[182:185], v[236:239], v[14:17]
	v_mfma_f32_16x16x32_bf16 v[10:13], v[190:193], v[236:239], v[10:13]
	v_mfma_f32_16x16x32_bf16 v[70:73], v[154:157], v[244:247], v[70:73]
	v_mfma_f32_16x16x32_bf16 v[66:69], v[174:177], v[244:247], v[66:69]
	v_mfma_f32_16x16x32_bf16 v[6:9], v[182:185], v[244:247], v[6:9]
	v_mfma_f32_16x16x32_bf16 v[2:5], v[190:193], v[244:247], v[2:5]
	s_barrier
	s_setprio 0
	s_add_i32 s26, s26, 2
	s_addk_i32 s19, 0x100
	s_addk_i32 s22, 0x100
	s_cmpk_gt_u32 s26, 0x7d
.LBB0_1223:
	v_add_u32_e32 v141, 0x10000, v139
	ds_read_b128 v[142:145], v141
	ds_read_b128 v[154:157], v141 offset:1024
	ds_read_b128 v[170:173], v141 offset:2048
	ds_read_b128 v[174:177], v141 offset:3072
	v_add_u32_e32 v141, 0x14000, v139
	ds_read_b128 v[178:181], v141
	ds_read_b128 v[182:185], v141 offset:1024
	ds_read_b128 v[186:189], v141 offset:2048
	ds_read_b128 v[190:193], v141 offset:3072
	s_add_i32 s27, s19, 0xffe00080
	s_cmpk_eq_i32 s26, 0x7c
	s_cselect_b32 s52, s8, s27
	s_cselect_b32 s47, s9, s22
	s_or_b32 s27, s52, 0x80
	s_mov_b32 m0, s71
	ds_read_b128 v[194:197], v140
	ds_read_b128 v[198:201], v140 offset:1024
	ds_read_b128 v[202:205], v140 offset:2048
	ds_read_b128 v[228:231], v140 offset:3072
	ds_read_b128 v[232:235], v140 offset:4096
	ds_read_b128 v[236:239], v140 offset:5120
	ds_read_b128 v[240:243], v140 offset:6144
	ds_read_b128 v[244:247], v140 offset:7168
	buffer_load_dwordx4 v131, s[60:63], s19 offen lds
	s_mov_b32 m0, s72
	s_nop 0
	buffer_load_dwordx4 v135, s[60:63], s19 offen lds
	s_waitcnt vmcnt(8)
	s_waitcnt lgkmcnt(0)
	s_setprio 1
	s_barrier
	v_mfma_f32_16x16x32_bf16 v[126:129], v[142:145], v[194:197], v[126:129]
	v_mfma_f32_16x16x32_bf16 v[122:125], v[170:173], v[194:197], v[122:125]
	v_mfma_f32_16x16x32_bf16 v[62:65], v[178:181], v[194:197], v[62:65]
	v_mfma_f32_16x16x32_bf16 v[58:61], v[186:189], v[194:197], v[58:61]
	v_mfma_f32_16x16x32_bf16 v[118:121], v[142:145], v[202:205], v[118:121]
	v_mfma_f32_16x16x32_bf16 v[114:117], v[170:173], v[202:205], v[114:117]
	v_mfma_f32_16x16x32_bf16 v[54:57], v[178:181], v[202:205], v[54:57]
	v_mfma_f32_16x16x32_bf16 v[50:53], v[186:189], v[202:205], v[50:53]
	v_mfma_f32_16x16x32_bf16 v[110:113], v[142:145], v[232:235], v[110:113]
	v_mfma_f32_16x16x32_bf16 v[106:109], v[170:173], v[232:235], v[106:109]
	v_mfma_f32_16x16x32_bf16 v[46:49], v[178:181], v[232:235], v[46:49]
	v_mfma_f32_16x16x32_bf16 v[42:45], v[186:189], v[232:235], v[42:45]
	v_mfma_f32_16x16x32_bf16 v[102:105], v[142:145], v[240:243], v[102:105]
	v_mfma_f32_16x16x32_bf16 v[98:101], v[170:173], v[240:243], v[98:101]
	v_mfma_f32_16x16x32_bf16 v[38:41], v[178:181], v[240:243], v[38:41]
	v_mfma_f32_16x16x32_bf16 v[34:37], v[186:189], v[240:243], v[34:37]
	v_mfma_f32_16x16x32_bf16 v[126:129], v[154:157], v[198:201], v[126:129]
	v_mfma_f32_16x16x32_bf16 v[122:125], v[174:177], v[198:201], v[122:125]
	v_mfma_f32_16x16x32_bf16 v[62:65], v[182:185], v[198:201], v[62:65]
	v_mfma_f32_16x16x32_bf16 v[58:61], v[190:193], v[198:201], v[58:61]
	v_mfma_f32_16x16x32_bf16 v[118:121], v[154:157], v[228:231], v[118:121]
	v_mfma_f32_16x16x32_bf16 v[114:117], v[174:177], v[228:231], v[114:117]
	v_mfma_f32_16x16x32_bf16 v[54:57], v[182:185], v[228:231], v[54:57]
	v_mfma_f32_16x16x32_bf16 v[50:53], v[190:193], v[228:231], v[50:53]
	v_mfma_f32_16x16x32_bf16 v[110:113], v[154:157], v[236:239], v[110:113]
	v_mfma_f32_16x16x32_bf16 v[106:109], v[174:177], v[236:239], v[106:109]
	v_mfma_f32_16x16x32_bf16 v[46:49], v[182:185], v[236:239], v[46:49]
	v_mfma_f32_16x16x32_bf16 v[42:45], v[190:193], v[236:239], v[42:45]
	v_mfma_f32_16x16x32_bf16 v[102:105], v[154:157], v[244:247], v[102:105]
	v_mfma_f32_16x16x32_bf16 v[98:101], v[174:177], v[244:247], v[98:101]
	v_mfma_f32_16x16x32_bf16 v[38:41], v[182:185], v[244:247], v[38:41]
	v_mfma_f32_16x16x32_bf16 v[34:37], v[190:193], v[244:247], v[34:37]
	s_barrier
	s_setprio 0
	s_mov_b32 m0, s2
	s_mov_b32 s66, s62
	s_mov_b32 s67, s63
	ds_read_b128 v[194:197], v140 offset:16384
	ds_read_b128 v[198:201], v140 offset:17408
	ds_read_b128 v[202:205], v140 offset:18432
	ds_read_b128 v[228:231], v140 offset:19456
	ds_read_b128 v[232:235], v140 offset:20480
	ds_read_b128 v[236:239], v140 offset:21504
	ds_read_b128 v[240:243], v140 offset:22528
	ds_read_b128 v[244:247], v140 offset:23552
	buffer_load_dwordx4 v134, s[64:67], s47 offen lds
	s_mov_b32 m0, s21
	s_add_i32 s53, s47, 0x200000
	buffer_load_dwordx4 v136, s[64:67], s47 offen lds
	s_mov_b32 m0, s23
	s_nop 0
	buffer_load_dwordx4 v134, s[64:67], s53 offen lds
	s_mov_b32 m0, s24
	s_nop 0
	buffer_load_dwordx4 v136, s[64:67], s53 offen lds
	s_mov_b32 m0, s16
	s_nop 0
	buffer_load_dwordx4 v131, s[60:63], s52 offen lds
	s_mov_b32 m0, s25
	s_nop 0
	buffer_load_dwordx4 v135, s[60:63], s52 offen lds
	s_waitcnt vmcnt(8)
	s_waitcnt lgkmcnt(0)
	s_setprio 1
	s_barrier
	v_mfma_f32_16x16x32_bf16 v[94:97], v[142:145], v[194:197], v[94:97]
	v_mfma_f32_16x16x32_bf16 v[90:93], v[170:173], v[194:197], v[90:93]
	v_mfma_f32_16x16x32_bf16 v[30:33], v[178:181], v[194:197], v[30:33]
	v_mfma_f32_16x16x32_bf16 v[26:29], v[186:189], v[194:197], v[26:29]
	v_mfma_f32_16x16x32_bf16 v[86:89], v[142:145], v[202:205], v[86:89]
	v_mfma_f32_16x16x32_bf16 v[82:85], v[170:173], v[202:205], v[82:85]
	v_mfma_f32_16x16x32_bf16 v[22:25], v[178:181], v[202:205], v[22:25]
	v_mfma_f32_16x16x32_bf16 v[18:21], v[186:189], v[202:205], v[18:21]
	v_mfma_f32_16x16x32_bf16 v[78:81], v[142:145], v[232:235], v[78:81]
	v_mfma_f32_16x16x32_bf16 v[74:77], v[170:173], v[232:235], v[74:77]
	v_mfma_f32_16x16x32_bf16 v[14:17], v[178:181], v[232:235], v[14:17]
	v_mfma_f32_16x16x32_bf16 v[10:13], v[186:189], v[232:235], v[10:13]
	v_mfma_f32_16x16x32_bf16 v[70:73], v[142:145], v[240:243], v[70:73]
	v_mfma_f32_16x16x32_bf16 v[66:69], v[170:173], v[240:243], v[66:69]
	v_mfma_f32_16x16x32_bf16 v[6:9], v[178:181], v[240:243], v[6:9]
	v_mfma_f32_16x16x32_bf16 v[2:5], v[186:189], v[240:243], v[2:5]
	v_mfma_f32_16x16x32_bf16 v[94:97], v[154:157], v[198:201], v[94:97]
	v_mfma_f32_16x16x32_bf16 v[90:93], v[174:177], v[198:201], v[90:93]
	v_mfma_f32_16x16x32_bf16 v[30:33], v[182:185], v[198:201], v[30:33]
	v_mfma_f32_16x16x32_bf16 v[26:29], v[190:193], v[198:201], v[26:29]
	v_mfma_f32_16x16x32_bf16 v[86:89], v[154:157], v[228:231], v[86:89]
	v_mfma_f32_16x16x32_bf16 v[82:85], v[174:177], v[228:231], v[82:85]
	v_mfma_f32_16x16x32_bf16 v[22:25], v[182:185], v[228:231], v[22:25]
	v_mfma_f32_16x16x32_bf16 v[18:21], v[190:193], v[228:231], v[18:21]
	v_mfma_f32_16x16x32_bf16 v[78:81], v[154:157], v[236:239], v[78:81]
	v_mfma_f32_16x16x32_bf16 v[74:77], v[174:177], v[236:239], v[74:77]
	v_mfma_f32_16x16x32_bf16 v[14:17], v[182:185], v[236:239], v[14:17]
	v_mfma_f32_16x16x32_bf16 v[10:13], v[190:193], v[236:239], v[10:13]
	v_mfma_f32_16x16x32_bf16 v[70:73], v[154:157], v[244:247], v[70:73]
	v_mfma_f32_16x16x32_bf16 v[66:69], v[174:177], v[244:247], v[66:69]
	v_mfma_f32_16x16x32_bf16 v[6:9], v[182:185], v[244:247], v[6:9]
	v_mfma_f32_16x16x32_bf16 v[2:5], v[190:193], v[244:247], v[2:5]
	s_barrier
	s_setprio 0
	v_add_u32_e32 v141, 0x18000, v139
	ds_read_b128 v[142:145], v141
	ds_read_b128 v[154:157], v141 offset:1024
	ds_read_b128 v[170:173], v141 offset:2048
	ds_read_b128 v[174:177], v141 offset:3072
	v_add_u32_e32 v141, 0x1c000, v139
	ds_read_b128 v[178:181], v141
	ds_read_b128 v[182:185], v141 offset:1024
	ds_read_b128 v[186:189], v141 offset:2048
	ds_read_b128 v[190:193], v141 offset:3072
	s_add_i32 s52, s52, 0x200000
	s_mov_b32 m0, s30
	ds_read_b128 v[194:197], v140 offset:32768
	ds_read_b128 v[198:201], v140 offset:33792
	ds_read_b128 v[202:205], v140 offset:34816
	ds_read_b128 v[228:231], v140 offset:35840
	ds_read_b128 v[232:235], v140 offset:36864
	ds_read_b128 v[236:239], v140 offset:37888
	ds_read_b128 v[240:243], v140 offset:38912
	ds_read_b128 v[244:247], v140 offset:39936
	buffer_load_dwordx4 v131, s[60:63], s52 offen lds
	s_mov_b32 m0, s31
	s_nop 0
	buffer_load_dwordx4 v135, s[60:63], s52 offen lds
	s_waitcnt vmcnt(8)
	s_waitcnt lgkmcnt(0)
	s_setprio 1
	s_barrier
	v_mfma_f32_16x16x32_bf16 v[126:129], v[142:145], v[194:197], v[126:129]
	v_mfma_f32_16x16x32_bf16 v[122:125], v[170:173], v[194:197], v[122:125]
	v_mfma_f32_16x16x32_bf16 v[62:65], v[178:181], v[194:197], v[62:65]
	v_mfma_f32_16x16x32_bf16 v[58:61], v[186:189], v[194:197], v[58:61]
	v_mfma_f32_16x16x32_bf16 v[118:121], v[142:145], v[202:205], v[118:121]
	v_mfma_f32_16x16x32_bf16 v[114:117], v[170:173], v[202:205], v[114:117]
	v_mfma_f32_16x16x32_bf16 v[54:57], v[178:181], v[202:205], v[54:57]
	v_mfma_f32_16x16x32_bf16 v[50:53], v[186:189], v[202:205], v[50:53]
	v_mfma_f32_16x16x32_bf16 v[110:113], v[142:145], v[232:235], v[110:113]
	v_mfma_f32_16x16x32_bf16 v[106:109], v[170:173], v[232:235], v[106:109]
	v_mfma_f32_16x16x32_bf16 v[46:49], v[178:181], v[232:235], v[46:49]
	v_mfma_f32_16x16x32_bf16 v[42:45], v[186:189], v[232:235], v[42:45]
	v_mfma_f32_16x16x32_bf16 v[102:105], v[142:145], v[240:243], v[102:105]
	v_mfma_f32_16x16x32_bf16 v[98:101], v[170:173], v[240:243], v[98:101]
	v_mfma_f32_16x16x32_bf16 v[38:41], v[178:181], v[240:243], v[38:41]
	v_mfma_f32_16x16x32_bf16 v[34:37], v[186:189], v[240:243], v[34:37]
	v_mfma_f32_16x16x32_bf16 v[126:129], v[154:157], v[198:201], v[126:129]
	v_mfma_f32_16x16x32_bf16 v[122:125], v[174:177], v[198:201], v[122:125]
	v_mfma_f32_16x16x32_bf16 v[62:65], v[182:185], v[198:201], v[62:65]
	v_mfma_f32_16x16x32_bf16 v[58:61], v[190:193], v[198:201], v[58:61]
	v_mfma_f32_16x16x32_bf16 v[118:121], v[154:157], v[228:231], v[118:121]
	v_mfma_f32_16x16x32_bf16 v[114:117], v[174:177], v[228:231], v[114:117]
	v_mfma_f32_16x16x32_bf16 v[54:57], v[182:185], v[228:231], v[54:57]
	v_mfma_f32_16x16x32_bf16 v[50:53], v[190:193], v[228:231], v[50:53]
	v_mfma_f32_16x16x32_bf16 v[110:113], v[154:157], v[236:239], v[110:113]
	v_mfma_f32_16x16x32_bf16 v[106:109], v[174:177], v[236:239], v[106:109]
	v_mfma_f32_16x16x32_bf16 v[46:49], v[182:185], v[236:239], v[46:49]
	v_mfma_f32_16x16x32_bf16 v[42:45], v[190:193], v[236:239], v[42:45]
	v_mfma_f32_16x16x32_bf16 v[102:105], v[154:157], v[244:247], v[102:105]
	v_mfma_f32_16x16x32_bf16 v[98:101], v[174:177], v[244:247], v[98:101]
	v_mfma_f32_16x16x32_bf16 v[38:41], v[182:185], v[244:247], v[38:41]
	v_mfma_f32_16x16x32_bf16 v[34:37], v[190:193], v[244:247], v[34:37]
	s_barrier
	s_setprio 0
	s_mov_b32 m0, s33
	s_or_b32 s52, s47, 0x80
	ds_read_b128 v[194:197], v140 offset:49152
	ds_read_b128 v[198:201], v140 offset:50176
	ds_read_b128 v[202:205], v140 offset:51200
	ds_read_b128 v[228:231], v140 offset:52224
	ds_read_b128 v[232:235], v140 offset:53248
	ds_read_b128 v[236:239], v140 offset:54272
	ds_read_b128 v[240:243], v140 offset:55296
	ds_read_b128 v[244:247], v140 offset:56320
	buffer_load_dwordx4 v134, s[64:67], s52 offen lds
	s_mov_b32 m0, s34
	s_add_i32 s47, s47, 0x200080
	buffer_load_dwordx4 v136, s[64:67], s52 offen lds
	s_mov_b32 m0, s37
	s_nop 0
	buffer_load_dwordx4 v134, s[64:67], s47 offen lds
	s_mov_b32 m0, s68
	s_nop 0
	buffer_load_dwordx4 v136, s[64:67], s47 offen lds
	s_mov_b32 m0, s35
	s_nop 0
	buffer_load_dwordx4 v131, s[60:63], s27 offen lds
	s_mov_b32 m0, s36
	s_nop 0
	buffer_load_dwordx4 v135, s[60:63], s27 offen lds
	s_waitcnt vmcnt(8)
	s_waitcnt lgkmcnt(0)
	s_setprio 1
	s_barrier
	v_mfma_f32_16x16x32_bf16 v[94:97], v[142:145], v[194:197], v[94:97]
	v_mfma_f32_16x16x32_bf16 v[90:93], v[170:173], v[194:197], v[90:93]
	v_mfma_f32_16x16x32_bf16 v[30:33], v[178:181], v[194:197], v[30:33]
	v_mfma_f32_16x16x32_bf16 v[26:29], v[186:189], v[194:197], v[26:29]
	v_mfma_f32_16x16x32_bf16 v[86:89], v[142:145], v[202:205], v[86:89]
	v_mfma_f32_16x16x32_bf16 v[82:85], v[170:173], v[202:205], v[82:85]
	v_mfma_f32_16x16x32_bf16 v[22:25], v[178:181], v[202:205], v[22:25]
	v_mfma_f32_16x16x32_bf16 v[18:21], v[186:189], v[202:205], v[18:21]
	v_mfma_f32_16x16x32_bf16 v[78:81], v[142:145], v[232:235], v[78:81]
	v_mfma_f32_16x16x32_bf16 v[74:77], v[170:173], v[232:235], v[74:77]
	v_mfma_f32_16x16x32_bf16 v[14:17], v[178:181], v[232:235], v[14:17]
	v_mfma_f32_16x16x32_bf16 v[10:13], v[186:189], v[232:235], v[10:13]
	v_mfma_f32_16x16x32_bf16 v[70:73], v[142:145], v[240:243], v[70:73]
	v_mfma_f32_16x16x32_bf16 v[66:69], v[170:173], v[240:243], v[66:69]
	v_mfma_f32_16x16x32_bf16 v[6:9], v[178:181], v[240:243], v[6:9]
	v_mfma_f32_16x16x32_bf16 v[2:5], v[186:189], v[240:243], v[2:5]
	v_mfma_f32_16x16x32_bf16 v[94:97], v[154:157], v[198:201], v[94:97]
	v_mfma_f32_16x16x32_bf16 v[90:93], v[174:177], v[198:201], v[90:93]
	v_mfma_f32_16x16x32_bf16 v[30:33], v[182:185], v[198:201], v[30:33]
	v_mfma_f32_16x16x32_bf16 v[26:29], v[190:193], v[198:201], v[26:29]
	v_mfma_f32_16x16x32_bf16 v[86:89], v[154:157], v[228:231], v[86:89]
	v_mfma_f32_16x16x32_bf16 v[82:85], v[174:177], v[228:231], v[82:85]
	v_mfma_f32_16x16x32_bf16 v[22:25], v[182:185], v[228:231], v[22:25]
	v_mfma_f32_16x16x32_bf16 v[18:21], v[190:193], v[228:231], v[18:21]
	v_mfma_f32_16x16x32_bf16 v[78:81], v[154:157], v[236:239], v[78:81]
	v_mfma_f32_16x16x32_bf16 v[74:77], v[174:177], v[236:239], v[74:77]
	v_mfma_f32_16x16x32_bf16 v[14:17], v[182:185], v[236:239], v[14:17]
	v_mfma_f32_16x16x32_bf16 v[10:13], v[190:193], v[236:239], v[10:13]
	v_mfma_f32_16x16x32_bf16 v[70:73], v[154:157], v[244:247], v[70:73]
	v_mfma_f32_16x16x32_bf16 v[66:69], v[174:177], v[244:247], v[66:69]
	v_mfma_f32_16x16x32_bf16 v[6:9], v[182:185], v[244:247], v[6:9]
	v_mfma_f32_16x16x32_bf16 v[2:5], v[190:193], v[244:247], v[2:5]
	s_barrier
	s_setprio 0
	s_add_i32 s26, s26, 2
	s_addk_i32 s19, 0x100
	s_addk_i32 s22, 0x100
	s_cmpk_gt_u32 s26, 0x7d
	s_cbranch_scc0 .LBB0_1223
	s_and_b64 vcc, exec, s[42:43]
	s_cbranch_vccz .LBB0_1226
	s_barrier

.LBB0_1252:
	s_lshl_b32 s12, s73, 20
	s_and_b64 s[8:9], s[40:41], exec
	s_cselect_b32 s8, s12, s26
	s_lshl_b32 s22, s82, 20
	s_and_b64 s[70:71], s[40:41], exec
	s_cselect_b32 s9, s22, s27
	s_add_i32 s26, s26, 0x80080
	s_addk_i32 s27, 0x100
	s_mov_b32 s83, -2
	v_add_u32_e32 v141, 0x10000, v139
	ds_read_b128 v[142:145], v141
	ds_read_b128 v[154:157], v141 offset:1024
	ds_read_b128 v[170:173], v141 offset:2048
	ds_read_b128 v[174:177], v141 offset:3072
	v_add_u32_e32 v141, 0x14000, v139
	ds_read_b128 v[178:181], v141
	ds_read_b128 v[182:185], v141 offset:1024
	ds_read_b128 v[186:189], v141 offset:2048
	ds_read_b128 v[190:193], v141 offset:3072
	s_add_i32 s52, s26, 0xfff80080
	s_cmp_eq_u32 s83, 28
	s_cselect_b32 s52, s8, s52
	s_cselect_b32 s85, s9, s27
	s_or_b32 s84, s52, 0x80
	s_mov_b32 m0, s72
	ds_read_b128 v[194:197], v140
	ds_read_b128 v[198:201], v140 offset:1024
	ds_read_b128 v[202:205], v140 offset:2048
	ds_read_b128 v[228:231], v140 offset:3072
	ds_read_b128 v[232:235], v140 offset:4096
	ds_read_b128 v[236:239], v140 offset:5120
	ds_read_b128 v[240:243], v140 offset:6144
	ds_read_b128 v[244:247], v140 offset:7168
	buffer_load_dwordx4 v131, s[60:63], s26 offen lds
	s_mov_b32 m0, s46
	s_nop 0
	buffer_load_dwordx4 v135, s[60:63], s26 offen lds
	s_waitcnt vmcnt(8)
	s_waitcnt lgkmcnt(0)
	s_setprio 1
	s_barrier
	v_mfma_f32_16x16x32_bf16 v[126:129], v[142:145], v[194:197], 0
	v_mfma_f32_16x16x32_bf16 v[122:125], v[170:173], v[194:197], 0
	v_mfma_f32_16x16x32_bf16 v[62:65], v[178:181], v[194:197], 0
	v_mfma_f32_16x16x32_bf16 v[58:61], v[186:189], v[194:197], 0
	v_mfma_f32_16x16x32_bf16 v[118:121], v[142:145], v[202:205], 0
	v_mfma_f32_16x16x32_bf16 v[114:117], v[170:173], v[202:205], 0
	v_mfma_f32_16x16x32_bf16 v[54:57], v[178:181], v[202:205], 0
	v_mfma_f32_16x16x32_bf16 v[50:53], v[186:189], v[202:205], 0
	v_mfma_f32_16x16x32_bf16 v[110:113], v[142:145], v[232:235], 0
	v_mfma_f32_16x16x32_bf16 v[106:109], v[170:173], v[232:235], 0
	v_mfma_f32_16x16x32_bf16 v[46:49], v[178:181], v[232:235], 0
	v_mfma_f32_16x16x32_bf16 v[42:45], v[186:189], v[232:235], 0
	v_mfma_f32_16x16x32_bf16 v[102:105], v[142:145], v[240:243], 0
	v_mfma_f32_16x16x32_bf16 v[98:101], v[170:173], v[240:243], 0
	v_mfma_f32_16x16x32_bf16 v[38:41], v[178:181], v[240:243], 0
	v_mfma_f32_16x16x32_bf16 v[34:37], v[186:189], v[240:243], 0
	v_mfma_f32_16x16x32_bf16 v[126:129], v[154:157], v[198:201], v[126:129]
	v_mfma_f32_16x16x32_bf16 v[122:125], v[174:177], v[198:201], v[122:125]
	v_mfma_f32_16x16x32_bf16 v[62:65], v[182:185], v[198:201], v[62:65]
	v_mfma_f32_16x16x32_bf16 v[58:61], v[190:193], v[198:201], v[58:61]
	v_mfma_f32_16x16x32_bf16 v[118:121], v[154:157], v[228:231], v[118:121]
	v_mfma_f32_16x16x32_bf16 v[114:117], v[174:177], v[228:231], v[114:117]
	v_mfma_f32_16x16x32_bf16 v[54:57], v[182:185], v[228:231], v[54:57]
	v_mfma_f32_16x16x32_bf16 v[50:53], v[190:193], v[228:231], v[50:53]
	v_mfma_f32_16x16x32_bf16 v[110:113], v[154:157], v[236:239], v[110:113]
	v_mfma_f32_16x16x32_bf16 v[106:109], v[174:177], v[236:239], v[106:109]
	v_mfma_f32_16x16x32_bf16 v[46:49], v[182:185], v[236:239], v[46:49]
	v_mfma_f32_16x16x32_bf16 v[42:45], v[190:193], v[236:239], v[42:45]
	v_mfma_f32_16x16x32_bf16 v[102:105], v[154:157], v[244:247], v[102:105]
	v_mfma_f32_16x16x32_bf16 v[98:101], v[174:177], v[244:247], v[98:101]
	v_mfma_f32_16x16x32_bf16 v[38:41], v[182:185], v[244:247], v[38:41]
	v_mfma_f32_16x16x32_bf16 v[34:37], v[190:193], v[244:247], v[34:37]
	s_barrier
	s_setprio 0
	s_mov_b32 m0, s21
	s_mov_b32 s70, s62
	s_mov_b32 s71, s63
	ds_read_b128 v[194:197], v140 offset:16384
	ds_read_b128 v[198:201], v140 offset:17408
	ds_read_b128 v[202:205], v140 offset:18432
	ds_read_b128 v[228:231], v140 offset:19456
	ds_read_b128 v[232:235], v140 offset:20480
	ds_read_b128 v[236:239], v140 offset:21504
	ds_read_b128 v[240:243], v140 offset:22528
	ds_read_b128 v[244:247], v140 offset:23552
	buffer_load_dwordx4 v134, s[68:71], s85 offen lds
	s_mov_b32 m0, s23
	s_add_i32 s53, s85, 0x80000
	buffer_load_dwordx4 v136, s[68:71], s85 offen lds
	s_mov_b32 m0, s24
	s_nop 0
	buffer_load_dwordx4 v134, s[68:71], s53 offen lds
	s_mov_b32 m0, s25
	s_nop 0
	buffer_load_dwordx4 v136, s[68:71], s53 offen lds
	s_mov_b32 m0, s16
	s_nop 0
	buffer_load_dwordx4 v131, s[60:63], s52 offen lds
	s_mov_b32 m0, s30
	s_nop 0
	buffer_load_dwordx4 v135, s[60:63], s52 offen lds
	s_waitcnt vmcnt(8)
	s_waitcnt lgkmcnt(0)
	s_setprio 1
	s_barrier
	v_mfma_f32_16x16x32_bf16 v[94:97], v[142:145], v[194:197], 0
	v_mfma_f32_16x16x32_bf16 v[90:93], v[170:173], v[194:197], 0
	v_mfma_f32_16x16x32_bf16 v[30:33], v[178:181], v[194:197], 0
	v_mfma_f32_16x16x32_bf16 v[26:29], v[186:189], v[194:197], 0
	v_mfma_f32_16x16x32_bf16 v[86:89], v[142:145], v[202:205], 0
	v_mfma_f32_16x16x32_bf16 v[82:85], v[170:173], v[202:205], 0
	v_mfma_f32_16x16x32_bf16 v[22:25], v[178:181], v[202:205], 0
	v_mfma_f32_16x16x32_bf16 v[18:21], v[186:189], v[202:205], 0
	v_mfma_f32_16x16x32_bf16 v[78:81], v[142:145], v[232:235], 0
	v_mfma_f32_16x16x32_bf16 v[74:77], v[170:173], v[232:235], 0
	v_mfma_f32_16x16x32_bf16 v[14:17], v[178:181], v[232:235], 0
	v_mfma_f32_16x16x32_bf16 v[10:13], v[186:189], v[232:235], 0
	v_mfma_f32_16x16x32_bf16 v[70:73], v[142:145], v[240:243], 0
	v_mfma_f32_16x16x32_bf16 v[66:69], v[170:173], v[240:243], 0
	v_mfma_f32_16x16x32_bf16 v[6:9], v[178:181], v[240:243], 0
	v_mfma_f32_16x16x32_bf16 v[2:5], v[186:189], v[240:243], 0
	v_mfma_f32_16x16x32_bf16 v[94:97], v[154:157], v[198:201], v[94:97]
	v_mfma_f32_16x16x32_bf16 v[90:93], v[174:177], v[198:201], v[90:93]
	v_mfma_f32_16x16x32_bf16 v[30:33], v[182:185], v[198:201], v[30:33]
	v_mfma_f32_16x16x32_bf16 v[26:29], v[190:193], v[198:201], v[26:29]
	v_mfma_f32_16x16x32_bf16 v[86:89], v[154:157], v[228:231], v[86:89]
	v_mfma_f32_16x16x32_bf16 v[82:85], v[174:177], v[228:231], v[82:85]
	v_mfma_f32_16x16x32_bf16 v[22:25], v[182:185], v[228:231], v[22:25]
	v_mfma_f32_16x16x32_bf16 v[18:21], v[190:193], v[228:231], v[18:21]
	v_mfma_f32_16x16x32_bf16 v[78:81], v[154:157], v[236:239], v[78:81]
	v_mfma_f32_16x16x32_bf16 v[74:77], v[174:177], v[236:239], v[74:77]
	v_mfma_f32_16x16x32_bf16 v[14:17], v[182:185], v[236:239], v[14:17]
	v_mfma_f32_16x16x32_bf16 v[10:13], v[190:193], v[236:239], v[10:13]
	v_mfma_f32_16x16x32_bf16 v[70:73], v[154:157], v[244:247], v[70:73]
	v_mfma_f32_16x16x32_bf16 v[66:69], v[174:177], v[244:247], v[66:69]
	v_mfma_f32_16x16x32_bf16 v[6:9], v[182:185], v[244:247], v[6:9]
	v_mfma_f32_16x16x32_bf16 v[2:5], v[190:193], v[244:247], v[2:5]
	s_barrier
	s_setprio 0
	v_add_u32_e32 v141, 0x18000, v139
	ds_read_b128 v[142:145], v141
	ds_read_b128 v[154:157], v141 offset:1024
	ds_read_b128 v[170:173], v141 offset:2048
	ds_read_b128 v[174:177], v141 offset:3072
	v_add_u32_e32 v141, 0x1c000, v139
	ds_read_b128 v[178:181], v141
	ds_read_b128 v[182:185], v141 offset:1024
	ds_read_b128 v[186:189], v141 offset:2048
	ds_read_b128 v[190:193], v141 offset:3072
	s_add_i32 s52, s52, 0x80000
	s_mov_b32 m0, s31
	ds_read_b128 v[194:197], v140 offset:32768
	ds_read_b128 v[198:201], v140 offset:33792
	ds_read_b128 v[202:205], v140 offset:34816
	ds_read_b128 v[228:231], v140 offset:35840
	ds_read_b128 v[232:235], v140 offset:36864
	ds_read_b128 v[236:239], v140 offset:37888
	ds_read_b128 v[240:243], v140 offset:38912
	ds_read_b128 v[244:247], v140 offset:39936
	buffer_load_dwordx4 v131, s[60:63], s52 offen lds
	s_mov_b32 m0, s33
	s_nop 0
	buffer_load_dwordx4 v135, s[60:63], s52 offen lds
	s_waitcnt vmcnt(8)
	s_waitcnt lgkmcnt(0)
	s_setprio 1
	s_barrier
	v_mfma_f32_16x16x32_bf16 v[126:129], v[142:145], v[194:197], v[126:129]
	v_mfma_f32_16x16x32_bf16 v[122:125], v[170:173], v[194:197], v[122:125]
	v_mfma_f32_16x16x32_bf16 v[62:65], v[178:181], v[194:197], v[62:65]
	v_mfma_f32_16x16x32_bf16 v[58:61], v[186:189], v[194:197], v[58:61]
	v_mfma_f32_16x16x32_bf16 v[118:121], v[142:145], v[202:205], v[118:121]
	v_mfma_f32_16x16x32_bf16 v[114:117], v[170:173], v[202:205], v[114:117]
	v_mfma_f32_16x16x32_bf16 v[54:57], v[178:181], v[202:205], v[54:57]
	v_mfma_f32_16x16x32_bf16 v[50:53], v[186:189], v[202:205], v[50:53]
	v_mfma_f32_16x16x32_bf16 v[110:113], v[142:145], v[232:235], v[110:113]
	v_mfma_f32_16x16x32_bf16 v[106:109], v[170:173], v[232:235], v[106:109]
	v_mfma_f32_16x16x32_bf16 v[46:49], v[178:181], v[232:235], v[46:49]
	v_mfma_f32_16x16x32_bf16 v[42:45], v[186:189], v[232:235], v[42:45]
	v_mfma_f32_16x16x32_bf16 v[102:105], v[142:145], v[240:243], v[102:105]
	v_mfma_f32_16x16x32_bf16 v[98:101], v[170:173], v[240:243], v[98:101]
	v_mfma_f32_16x16x32_bf16 v[38:41], v[178:181], v[240:243], v[38:41]
	v_mfma_f32_16x16x32_bf16 v[34:37], v[186:189], v[240:243], v[34:37]
	v_mfma_f32_16x16x32_bf16 v[126:129], v[154:157], v[198:201], v[126:129]
	v_mfma_f32_16x16x32_bf16 v[122:125], v[174:177], v[198:201], v[122:125]
	v_mfma_f32_16x16x32_bf16 v[62:65], v[182:185], v[198:201], v[62:65]
	v_mfma_f32_16x16x32_bf16 v[58:61], v[190:193], v[198:201], v[58:61]
	v_mfma_f32_16x16x32_bf16 v[118:121], v[154:157], v[228:231], v[118:121]
	v_mfma_f32_16x16x32_bf16 v[114:117], v[174:177], v[228:231], v[114:117]
	v_mfma_f32_16x16x32_bf16 v[54:57], v[182:185], v[228:231], v[54:57]
	v_mfma_f32_16x16x32_bf16 v[50:53], v[190:193], v[228:231], v[50:53]
	v_mfma_f32_16x16x32_bf16 v[110:113], v[154:157], v[236:239], v[110:113]
	v_mfma_f32_16x16x32_bf16 v[106:109], v[174:177], v[236:239], v[106:109]
	v_mfma_f32_16x16x32_bf16 v[46:49], v[182:185], v[236:239], v[46:49]
	v_mfma_f32_16x16x32_bf16 v[42:45], v[190:193], v[236:239], v[42:45]
	v_mfma_f32_16x16x32_bf16 v[102:105], v[154:157], v[244:247], v[102:105]
	v_mfma_f32_16x16x32_bf16 v[98:101], v[174:177], v[244:247], v[98:101]
	v_mfma_f32_16x16x32_bf16 v[38:41], v[182:185], v[244:247], v[38:41]
	v_mfma_f32_16x16x32_bf16 v[34:37], v[190:193], v[244:247], v[34:37]
	s_barrier
	s_setprio 0
	s_mov_b32 m0, s34
	s_or_b32 s52, s85, 0x80
	ds_read_b128 v[194:197], v140 offset:49152
	ds_read_b128 v[198:201], v140 offset:50176
	ds_read_b128 v[202:205], v140 offset:51200
	ds_read_b128 v[228:231], v140 offset:52224
	ds_read_b128 v[232:235], v140 offset:53248
	ds_read_b128 v[236:239], v140 offset:54272
	ds_read_b128 v[240:243], v140 offset:55296
	ds_read_b128 v[244:247], v140 offset:56320
	buffer_load_dwordx4 v134, s[68:71], s52 offen lds
	s_mov_b32 m0, s35
	s_add_i32 s85, s85, 0x80080
	buffer_load_dwordx4 v136, s[68:71], s52 offen lds
	s_mov_b32 m0, s37
	s_nop 0
	buffer_load_dwordx4 v134, s[68:71], s85 offen lds
	s_mov_b32 m0, s65
	s_nop 0
	buffer_load_dwordx4 v136, s[68:71], s85 offen lds
	s_mov_b32 m0, s14
	s_nop 0
	buffer_load_dwordx4 v131, s[60:63], s84 offen lds
	s_mov_b32 m0, s36
	s_nop 0
	buffer_load_dwordx4 v135, s[60:63], s84 offen lds
	s_waitcnt vmcnt(8)
	s_waitcnt lgkmcnt(0)
	s_setprio 1
	s_barrier
	v_mfma_f32_16x16x32_bf16 v[94:97], v[142:145], v[194:197], v[94:97]
	v_mfma_f32_16x16x32_bf16 v[90:93], v[170:173], v[194:197], v[90:93]
	v_mfma_f32_16x16x32_bf16 v[30:33], v[178:181], v[194:197], v[30:33]
	v_mfma_f32_16x16x32_bf16 v[26:29], v[186:189], v[194:197], v[26:29]
	v_mfma_f32_16x16x32_bf16 v[86:89], v[142:145], v[202:205], v[86:89]
	v_mfma_f32_16x16x32_bf16 v[82:85], v[170:173], v[202:205], v[82:85]
	v_mfma_f32_16x16x32_bf16 v[22:25], v[178:181], v[202:205], v[22:25]
	v_mfma_f32_16x16x32_bf16 v[18:21], v[186:189], v[202:205], v[18:21]
	v_mfma_f32_16x16x32_bf16 v[78:81], v[142:145], v[232:235], v[78:81]
	v_mfma_f32_16x16x32_bf16 v[74:77], v[170:173], v[232:235], v[74:77]
	v_mfma_f32_16x16x32_bf16 v[14:17], v[178:181], v[232:235], v[14:17]
	v_mfma_f32_16x16x32_bf16 v[10:13], v[186:189], v[232:235], v[10:13]
	v_mfma_f32_16x16x32_bf16 v[70:73], v[142:145], v[240:243], v[70:73]
	v_mfma_f32_16x16x32_bf16 v[66:69], v[170:173], v[240:243], v[66:69]
	v_mfma_f32_16x16x32_bf16 v[6:9], v[178:181], v[240:243], v[6:9]
	v_mfma_f32_16x16x32_bf16 v[2:5], v[186:189], v[240:243], v[2:5]
	v_mfma_f32_16x16x32_bf16 v[94:97], v[154:157], v[198:201], v[94:97]
	v_mfma_f32_16x16x32_bf16 v[90:93], v[174:177], v[198:201], v[90:93]
	v_mfma_f32_16x16x32_bf16 v[30:33], v[182:185], v[198:201], v[30:33]
	v_mfma_f32_16x16x32_bf16 v[26:29], v[190:193], v[198:201], v[26:29]
	v_mfma_f32_16x16x32_bf16 v[86:89], v[154:157], v[228:231], v[86:89]
	v_mfma_f32_16x16x32_bf16 v[82:85], v[174:177], v[228:231], v[82:85]
	v_mfma_f32_16x16x32_bf16 v[22:25], v[182:185], v[228:231], v[22:25]
	v_mfma_f32_16x16x32_bf16 v[18:21], v[190:193], v[228:231], v[18:21]
	v_mfma_f32_16x16x32_bf16 v[78:81], v[154:157], v[236:239], v[78:81]
	v_mfma_f32_16x16x32_bf16 v[74:77], v[174:177], v[236:239], v[74:77]
	v_mfma_f32_16x16x32_bf16 v[14:17], v[182:185], v[236:239], v[14:17]
	v_mfma_f32_16x16x32_bf16 v[10:13], v[190:193], v[236:239], v[10:13]
	v_mfma_f32_16x16x32_bf16 v[70:73], v[154:157], v[244:247], v[70:73]
	v_mfma_f32_16x16x32_bf16 v[66:69], v[174:177], v[244:247], v[66:69]
	v_mfma_f32_16x16x32_bf16 v[6:9], v[182:185], v[244:247], v[6:9]
	v_mfma_f32_16x16x32_bf16 v[2:5], v[190:193], v[244:247], v[2:5]
	s_barrier
	s_setprio 0
	s_add_i32 s83, s83, 2
	s_addk_i32 s26, 0x100
	s_addk_i32 s27, 0x100
	s_cmp_gt_u32 s83, 29
.LBB0_1253:
	v_add_u32_e32 v141, 0x10000, v139
	ds_read_b128 v[142:145], v141
	ds_read_b128 v[154:157], v141 offset:1024
	ds_read_b128 v[170:173], v141 offset:2048
	ds_read_b128 v[174:177], v141 offset:3072
	v_add_u32_e32 v141, 0x14000, v139
	ds_read_b128 v[178:181], v141
	ds_read_b128 v[182:185], v141 offset:1024
	ds_read_b128 v[186:189], v141 offset:2048
	ds_read_b128 v[190:193], v141 offset:3072
	s_add_i32 s52, s26, 0xfff80080
	s_cmp_eq_u32 s83, 28
	s_cselect_b32 s52, s8, s52
	s_cselect_b32 s85, s9, s27
	s_or_b32 s84, s52, 0x80
	s_mov_b32 m0, s72
	ds_read_b128 v[194:197], v140
	ds_read_b128 v[198:201], v140 offset:1024
	ds_read_b128 v[202:205], v140 offset:2048
	ds_read_b128 v[228:231], v140 offset:3072
	ds_read_b128 v[232:235], v140 offset:4096
	ds_read_b128 v[236:239], v140 offset:5120
	ds_read_b128 v[240:243], v140 offset:6144
	ds_read_b128 v[244:247], v140 offset:7168
	buffer_load_dwordx4 v131, s[60:63], s26 offen lds
	s_mov_b32 m0, s46
	s_nop 0
	buffer_load_dwordx4 v135, s[60:63], s26 offen lds
	s_waitcnt vmcnt(8)
	s_waitcnt lgkmcnt(0)
	s_setprio 1
	s_barrier
	v_mfma_f32_16x16x32_bf16 v[126:129], v[142:145], v[194:197], v[126:129]
	v_mfma_f32_16x16x32_bf16 v[122:125], v[170:173], v[194:197], v[122:125]
	v_mfma_f32_16x16x32_bf16 v[62:65], v[178:181], v[194:197], v[62:65]
	v_mfma_f32_16x16x32_bf16 v[58:61], v[186:189], v[194:197], v[58:61]
	v_mfma_f32_16x16x32_bf16 v[118:121], v[142:145], v[202:205], v[118:121]
	v_mfma_f32_16x16x32_bf16 v[114:117], v[170:173], v[202:205], v[114:117]
	v_mfma_f32_16x16x32_bf16 v[54:57], v[178:181], v[202:205], v[54:57]
	v_mfma_f32_16x16x32_bf16 v[50:53], v[186:189], v[202:205], v[50:53]
	v_mfma_f32_16x16x32_bf16 v[110:113], v[142:145], v[232:235], v[110:113]
	v_mfma_f32_16x16x32_bf16 v[106:109], v[170:173], v[232:235], v[106:109]
	v_mfma_f32_16x16x32_bf16 v[46:49], v[178:181], v[232:235], v[46:49]
	v_mfma_f32_16x16x32_bf16 v[42:45], v[186:189], v[232:235], v[42:45]
	v_mfma_f32_16x16x32_bf16 v[102:105], v[142:145], v[240:243], v[102:105]
	v_mfma_f32_16x16x32_bf16 v[98:101], v[170:173], v[240:243], v[98:101]
	v_mfma_f32_16x16x32_bf16 v[38:41], v[178:181], v[240:243], v[38:41]
	v_mfma_f32_16x16x32_bf16 v[34:37], v[186:189], v[240:243], v[34:37]
	v_mfma_f32_16x16x32_bf16 v[126:129], v[154:157], v[198:201], v[126:129]
	v_mfma_f32_16x16x32_bf16 v[122:125], v[174:177], v[198:201], v[122:125]
	v_mfma_f32_16x16x32_bf16 v[62:65], v[182:185], v[198:201], v[62:65]
	v_mfma_f32_16x16x32_bf16 v[58:61], v[190:193], v[198:201], v[58:61]
	v_mfma_f32_16x16x32_bf16 v[118:121], v[154:157], v[228:231], v[118:121]
	v_mfma_f32_16x16x32_bf16 v[114:117], v[174:177], v[228:231], v[114:117]
	v_mfma_f32_16x16x32_bf16 v[54:57], v[182:185], v[228:231], v[54:57]
	v_mfma_f32_16x16x32_bf16 v[50:53], v[190:193], v[228:231], v[50:53]
	v_mfma_f32_16x16x32_bf16 v[110:113], v[154:157], v[236:239], v[110:113]
	v_mfma_f32_16x16x32_bf16 v[106:109], v[174:177], v[236:239], v[106:109]
	v_mfma_f32_16x16x32_bf16 v[46:49], v[182:185], v[236:239], v[46:49]
	v_mfma_f32_16x16x32_bf16 v[42:45], v[190:193], v[236:239], v[42:45]
	v_mfma_f32_16x16x32_bf16 v[102:105], v[154:157], v[244:247], v[102:105]
	v_mfma_f32_16x16x32_bf16 v[98:101], v[174:177], v[244:247], v[98:101]
	v_mfma_f32_16x16x32_bf16 v[38:41], v[182:185], v[244:247], v[38:41]
	v_mfma_f32_16x16x32_bf16 v[34:37], v[190:193], v[244:247], v[34:37]
	s_barrier
	s_setprio 0
	s_mov_b32 m0, s21
	s_mov_b32 s70, s62
	s_mov_b32 s71, s63
	ds_read_b128 v[194:197], v140 offset:16384
	ds_read_b128 v[198:201], v140 offset:17408
	ds_read_b128 v[202:205], v140 offset:18432
	ds_read_b128 v[228:231], v140 offset:19456
	ds_read_b128 v[232:235], v140 offset:20480
	ds_read_b128 v[236:239], v140 offset:21504
	ds_read_b128 v[240:243], v140 offset:22528
	ds_read_b128 v[244:247], v140 offset:23552
	buffer_load_dwordx4 v134, s[68:71], s85 offen lds
	s_mov_b32 m0, s23
	s_add_i32 s53, s85, 0x80000
	buffer_load_dwordx4 v136, s[68:71], s85 offen lds
	s_mov_b32 m0, s24
	s_nop 0
	buffer_load_dwordx4 v134, s[68:71], s53 offen lds
	s_mov_b32 m0, s25
	s_nop 0
	buffer_load_dwordx4 v136, s[68:71], s53 offen lds
	s_mov_b32 m0, s16
	s_nop 0
	buffer_load_dwordx4 v131, s[60:63], s52 offen lds
	s_mov_b32 m0, s30
	s_nop 0
	buffer_load_dwordx4 v135, s[60:63], s52 offen lds
	s_waitcnt vmcnt(8)
	s_waitcnt lgkmcnt(0)
	s_setprio 1
	s_barrier
	v_mfma_f32_16x16x32_bf16 v[94:97], v[142:145], v[194:197], v[94:97]
	v_mfma_f32_16x16x32_bf16 v[90:93], v[170:173], v[194:197], v[90:93]
	v_mfma_f32_16x16x32_bf16 v[30:33], v[178:181], v[194:197], v[30:33]
	v_mfma_f32_16x16x32_bf16 v[26:29], v[186:189], v[194:197], v[26:29]
	v_mfma_f32_16x16x32_bf16 v[86:89], v[142:145], v[202:205], v[86:89]
	v_mfma_f32_16x16x32_bf16 v[82:85], v[170:173], v[202:205], v[82:85]
	v_mfma_f32_16x16x32_bf16 v[22:25], v[178:181], v[202:205], v[22:25]
	v_mfma_f32_16x16x32_bf16 v[18:21], v[186:189], v[202:205], v[18:21]
	v_mfma_f32_16x16x32_bf16 v[78:81], v[142:145], v[232:235], v[78:81]
	v_mfma_f32_16x16x32_bf16 v[74:77], v[170:173], v[232:235], v[74:77]
	v_mfma_f32_16x16x32_bf16 v[14:17], v[178:181], v[232:235], v[14:17]
	v_mfma_f32_16x16x32_bf16 v[10:13], v[186:189], v[232:235], v[10:13]
	v_mfma_f32_16x16x32_bf16 v[70:73], v[142:145], v[240:243], v[70:73]
	v_mfma_f32_16x16x32_bf16 v[66:69], v[170:173], v[240:243], v[66:69]
	v_mfma_f32_16x16x32_bf16 v[6:9], v[178:181], v[240:243], v[6:9]
	v_mfma_f32_16x16x32_bf16 v[2:5], v[186:189], v[240:243], v[2:5]
	v_mfma_f32_16x16x32_bf16 v[94:97], v[154:157], v[198:201], v[94:97]
	v_mfma_f32_16x16x32_bf16 v[90:93], v[174:177], v[198:201], v[90:93]
	v_mfma_f32_16x16x32_bf16 v[30:33], v[182:185], v[198:201], v[30:33]
	v_mfma_f32_16x16x32_bf16 v[26:29], v[190:193], v[198:201], v[26:29]
	v_mfma_f32_16x16x32_bf16 v[86:89], v[154:157], v[228:231], v[86:89]
	v_mfma_f32_16x16x32_bf16 v[82:85], v[174:177], v[228:231], v[82:85]
	v_mfma_f32_16x16x32_bf16 v[22:25], v[182:185], v[228:231], v[22:25]
	v_mfma_f32_16x16x32_bf16 v[18:21], v[190:193], v[228:231], v[18:21]
	v_mfma_f32_16x16x32_bf16 v[78:81], v[154:157], v[236:239], v[78:81]
	v_mfma_f32_16x16x32_bf16 v[74:77], v[174:177], v[236:239], v[74:77]
	v_mfma_f32_16x16x32_bf16 v[14:17], v[182:185], v[236:239], v[14:17]
	v_mfma_f32_16x16x32_bf16 v[10:13], v[190:193], v[236:239], v[10:13]
	v_mfma_f32_16x16x32_bf16 v[70:73], v[154:157], v[244:247], v[70:73]
	v_mfma_f32_16x16x32_bf16 v[66:69], v[174:177], v[244:247], v[66:69]
	v_mfma_f32_16x16x32_bf16 v[6:9], v[182:185], v[244:247], v[6:9]
	v_mfma_f32_16x16x32_bf16 v[2:5], v[190:193], v[244:247], v[2:5]
	s_barrier
	s_setprio 0
	v_add_u32_e32 v141, 0x18000, v139
	ds_read_b128 v[142:145], v141
	ds_read_b128 v[154:157], v141 offset:1024
	ds_read_b128 v[170:173], v141 offset:2048
	ds_read_b128 v[174:177], v141 offset:3072
	v_add_u32_e32 v141, 0x1c000, v139
	ds_read_b128 v[178:181], v141
	ds_read_b128 v[182:185], v141 offset:1024
	ds_read_b128 v[186:189], v141 offset:2048
	ds_read_b128 v[190:193], v141 offset:3072
	s_add_i32 s52, s52, 0x80000
	s_mov_b32 m0, s31
	ds_read_b128 v[194:197], v140 offset:32768
	ds_read_b128 v[198:201], v140 offset:33792
	ds_read_b128 v[202:205], v140 offset:34816
	ds_read_b128 v[228:231], v140 offset:35840
	ds_read_b128 v[232:235], v140 offset:36864
	ds_read_b128 v[236:239], v140 offset:37888
	ds_read_b128 v[240:243], v140 offset:38912
	ds_read_b128 v[244:247], v140 offset:39936
	buffer_load_dwordx4 v131, s[60:63], s52 offen lds
	s_mov_b32 m0, s33
	s_nop 0
	buffer_load_dwordx4 v135, s[60:63], s52 offen lds
	s_waitcnt vmcnt(8)
	s_waitcnt lgkmcnt(0)
	s_setprio 1
	s_barrier
	v_mfma_f32_16x16x32_bf16 v[126:129], v[142:145], v[194:197], v[126:129]
	v_mfma_f32_16x16x32_bf16 v[122:125], v[170:173], v[194:197], v[122:125]
	v_mfma_f32_16x16x32_bf16 v[62:65], v[178:181], v[194:197], v[62:65]
	v_mfma_f32_16x16x32_bf16 v[58:61], v[186:189], v[194:197], v[58:61]
	v_mfma_f32_16x16x32_bf16 v[118:121], v[142:145], v[202:205], v[118:121]
	v_mfma_f32_16x16x32_bf16 v[114:117], v[170:173], v[202:205], v[114:117]
	v_mfma_f32_16x16x32_bf16 v[54:57], v[178:181], v[202:205], v[54:57]
	v_mfma_f32_16x16x32_bf16 v[50:53], v[186:189], v[202:205], v[50:53]
	v_mfma_f32_16x16x32_bf16 v[110:113], v[142:145], v[232:235], v[110:113]
	v_mfma_f32_16x16x32_bf16 v[106:109], v[170:173], v[232:235], v[106:109]
	v_mfma_f32_16x16x32_bf16 v[46:49], v[178:181], v[232:235], v[46:49]
	v_mfma_f32_16x16x32_bf16 v[42:45], v[186:189], v[232:235], v[42:45]
	v_mfma_f32_16x16x32_bf16 v[102:105], v[142:145], v[240:243], v[102:105]
	v_mfma_f32_16x16x32_bf16 v[98:101], v[170:173], v[240:243], v[98:101]
	v_mfma_f32_16x16x32_bf16 v[38:41], v[178:181], v[240:243], v[38:41]
	v_mfma_f32_16x16x32_bf16 v[34:37], v[186:189], v[240:243], v[34:37]
	v_mfma_f32_16x16x32_bf16 v[126:129], v[154:157], v[198:201], v[126:129]
	v_mfma_f32_16x16x32_bf16 v[122:125], v[174:177], v[198:201], v[122:125]
	v_mfma_f32_16x16x32_bf16 v[62:65], v[182:185], v[198:201], v[62:65]
	v_mfma_f32_16x16x32_bf16 v[58:61], v[190:193], v[198:201], v[58:61]
	v_mfma_f32_16x16x32_bf16 v[118:121], v[154:157], v[228:231], v[118:121]
	v_mfma_f32_16x16x32_bf16 v[114:117], v[174:177], v[228:231], v[114:117]
	v_mfma_f32_16x16x32_bf16 v[54:57], v[182:185], v[228:231], v[54:57]
	v_mfma_f32_16x16x32_bf16 v[50:53], v[190:193], v[228:231], v[50:53]
	v_mfma_f32_16x16x32_bf16 v[110:113], v[154:157], v[236:239], v[110:113]
	v_mfma_f32_16x16x32_bf16 v[106:109], v[174:177], v[236:239], v[106:109]
	v_mfma_f32_16x16x32_bf16 v[46:49], v[182:185], v[236:239], v[46:49]
	v_mfma_f32_16x16x32_bf16 v[42:45], v[190:193], v[236:239], v[42:45]
	v_mfma_f32_16x16x32_bf16 v[102:105], v[154:157], v[244:247], v[102:105]
	v_mfma_f32_16x16x32_bf16 v[98:101], v[174:177], v[244:247], v[98:101]
	v_mfma_f32_16x16x32_bf16 v[38:41], v[182:185], v[244:247], v[38:41]
	v_mfma_f32_16x16x32_bf16 v[34:37], v[190:193], v[244:247], v[34:37]
	s_barrier
	s_setprio 0
	s_mov_b32 m0, s34
	s_or_b32 s52, s85, 0x80
	ds_read_b128 v[194:197], v140 offset:49152
	ds_read_b128 v[198:201], v140 offset:50176
	ds_read_b128 v[202:205], v140 offset:51200
	ds_read_b128 v[228:231], v140 offset:52224
	ds_read_b128 v[232:235], v140 offset:53248
	ds_read_b128 v[236:239], v140 offset:54272
	ds_read_b128 v[240:243], v140 offset:55296
	ds_read_b128 v[244:247], v140 offset:56320
	buffer_load_dwordx4 v134, s[68:71], s52 offen lds
	s_mov_b32 m0, s35
	s_add_i32 s85, s85, 0x80080
	buffer_load_dwordx4 v136, s[68:71], s52 offen lds
	s_mov_b32 m0, s37
	s_nop 0
	buffer_load_dwordx4 v134, s[68:71], s85 offen lds
	s_mov_b32 m0, s65
	s_nop 0
	buffer_load_dwordx4 v136, s[68:71], s85 offen lds
	s_mov_b32 m0, s14
	s_nop 0
	buffer_load_dwordx4 v131, s[60:63], s84 offen lds
	s_mov_b32 m0, s36
	s_nop 0
	buffer_load_dwordx4 v135, s[60:63], s84 offen lds
	s_waitcnt vmcnt(8)
	s_waitcnt lgkmcnt(0)
	s_setprio 1
	s_barrier
	v_mfma_f32_16x16x32_bf16 v[94:97], v[142:145], v[194:197], v[94:97]
	v_mfma_f32_16x16x32_bf16 v[90:93], v[170:173], v[194:197], v[90:93]
	v_mfma_f32_16x16x32_bf16 v[30:33], v[178:181], v[194:197], v[30:33]
	v_mfma_f32_16x16x32_bf16 v[26:29], v[186:189], v[194:197], v[26:29]
	v_mfma_f32_16x16x32_bf16 v[86:89], v[142:145], v[202:205], v[86:89]
	v_mfma_f32_16x16x32_bf16 v[82:85], v[170:173], v[202:205], v[82:85]
	v_mfma_f32_16x16x32_bf16 v[22:25], v[178:181], v[202:205], v[22:25]
	v_mfma_f32_16x16x32_bf16 v[18:21], v[186:189], v[202:205], v[18:21]
	v_mfma_f32_16x16x32_bf16 v[78:81], v[142:145], v[232:235], v[78:81]
	v_mfma_f32_16x16x32_bf16 v[74:77], v[170:173], v[232:235], v[74:77]
	v_mfma_f32_16x16x32_bf16 v[14:17], v[178:181], v[232:235], v[14:17]
	v_mfma_f32_16x16x32_bf16 v[10:13], v[186:189], v[232:235], v[10:13]
	v_mfma_f32_16x16x32_bf16 v[70:73], v[142:145], v[240:243], v[70:73]
	v_mfma_f32_16x16x32_bf16 v[66:69], v[170:173], v[240:243], v[66:69]
	v_mfma_f32_16x16x32_bf16 v[6:9], v[178:181], v[240:243], v[6:9]
	v_mfma_f32_16x16x32_bf16 v[2:5], v[186:189], v[240:243], v[2:5]
	v_mfma_f32_16x16x32_bf16 v[94:97], v[154:157], v[198:201], v[94:97]
	v_mfma_f32_16x16x32_bf16 v[90:93], v[174:177], v[198:201], v[90:93]
	v_mfma_f32_16x16x32_bf16 v[30:33], v[182:185], v[198:201], v[30:33]
	v_mfma_f32_16x16x32_bf16 v[26:29], v[190:193], v[198:201], v[26:29]
	v_mfma_f32_16x16x32_bf16 v[86:89], v[154:157], v[228:231], v[86:89]
	v_mfma_f32_16x16x32_bf16 v[82:85], v[174:177], v[228:231], v[82:85]
	v_mfma_f32_16x16x32_bf16 v[22:25], v[182:185], v[228:231], v[22:25]
	v_mfma_f32_16x16x32_bf16 v[18:21], v[190:193], v[228:231], v[18:21]
	v_mfma_f32_16x16x32_bf16 v[78:81], v[154:157], v[236:239], v[78:81]
	v_mfma_f32_16x16x32_bf16 v[74:77], v[174:177], v[236:239], v[74:77]
	v_mfma_f32_16x16x32_bf16 v[14:17], v[182:185], v[236:239], v[14:17]
	v_mfma_f32_16x16x32_bf16 v[10:13], v[190:193], v[236:239], v[10:13]
	v_mfma_f32_16x16x32_bf16 v[70:73], v[154:157], v[244:247], v[70:73]
	v_mfma_f32_16x16x32_bf16 v[66:69], v[174:177], v[244:247], v[66:69]
	v_mfma_f32_16x16x32_bf16 v[6:9], v[182:185], v[244:247], v[6:9]
	v_mfma_f32_16x16x32_bf16 v[2:5], v[190:193], v[244:247], v[2:5]
	s_barrier
	s_setprio 0
	s_add_i32 s83, s83, 2
	s_addk_i32 s26, 0x100
	s_addk_i32 s27, 0x100
	s_cmp_gt_u32 s83, 29
	s_cbranch_scc0 .LBB0_1253
	s_and_b64 vcc, exec, s[44:45]
	s_cbranch_vccz .LBB0_1256
	s_barrier

.LBB0_1282:
	s_lshl_b32 s46, s85, 20
	s_and_b64 s[8:9], s[40:41], exec
	s_cselect_b32 s8, s46, s19
	s_lshl_b32 s47, s14, 20
	s_and_b64 s[26:27], s[40:41], exec
	s_cselect_b32 s9, s47, s22
	s_add_i32 s19, s19, 0x80080
	s_addk_i32 s22, 0x100
	s_mov_b32 s26, -2
	v_add_u32_e32 v141, 0x10000, v139
	ds_read_b128 v[142:145], v141
	ds_read_b128 v[154:157], v141 offset:1024
	ds_read_b128 v[170:173], v141 offset:2048
	ds_read_b128 v[174:177], v141 offset:3072
	v_add_u32_e32 v141, 0x14000, v139
	ds_read_b128 v[178:181], v141
	ds_read_b128 v[182:185], v141 offset:1024
	ds_read_b128 v[186:189], v141 offset:2048
	ds_read_b128 v[190:193], v141 offset:3072
	s_add_i32 s27, s19, 0xfff80080
	s_cmp_eq_u32 s26, 28
	s_cselect_b32 s52, s8, s27
	s_cselect_b32 s83, s9, s22
	s_or_b32 s27, s52, 0x80
	s_mov_b32 m0, s73
	ds_read_b128 v[194:197], v140
	ds_read_b128 v[198:201], v140 offset:1024
	ds_read_b128 v[202:205], v140 offset:2048
	ds_read_b128 v[228:231], v140 offset:3072
	ds_read_b128 v[232:235], v140 offset:4096
	ds_read_b128 v[236:239], v140 offset:5120
	ds_read_b128 v[240:243], v140 offset:6144
	ds_read_b128 v[244:247], v140 offset:7168
	buffer_load_dwordx4 v131, s[60:63], s19 offen lds
	s_mov_b32 m0, s82
	s_nop 0
	buffer_load_dwordx4 v135, s[60:63], s19 offen lds
	s_waitcnt vmcnt(8)
	s_waitcnt lgkmcnt(0)
	s_setprio 1
	s_barrier
	v_mfma_f32_16x16x32_bf16 v[126:129], v[142:145], v[194:197], 0
	v_mfma_f32_16x16x32_bf16 v[122:125], v[170:173], v[194:197], 0
	v_mfma_f32_16x16x32_bf16 v[62:65], v[178:181], v[194:197], 0
	v_mfma_f32_16x16x32_bf16 v[58:61], v[186:189], v[194:197], 0
	v_mfma_f32_16x16x32_bf16 v[118:121], v[142:145], v[202:205], 0
	v_mfma_f32_16x16x32_bf16 v[114:117], v[170:173], v[202:205], 0
	v_mfma_f32_16x16x32_bf16 v[54:57], v[178:181], v[202:205], 0
	v_mfma_f32_16x16x32_bf16 v[50:53], v[186:189], v[202:205], 0
	v_mfma_f32_16x16x32_bf16 v[110:113], v[142:145], v[232:235], 0
	v_mfma_f32_16x16x32_bf16 v[106:109], v[170:173], v[232:235], 0
	v_mfma_f32_16x16x32_bf16 v[46:49], v[178:181], v[232:235], 0
	v_mfma_f32_16x16x32_bf16 v[42:45], v[186:189], v[232:235], 0
	v_mfma_f32_16x16x32_bf16 v[102:105], v[142:145], v[240:243], 0
	v_mfma_f32_16x16x32_bf16 v[98:101], v[170:173], v[240:243], 0
	v_mfma_f32_16x16x32_bf16 v[38:41], v[178:181], v[240:243], 0
	v_mfma_f32_16x16x32_bf16 v[34:37], v[186:189], v[240:243], 0
	v_mfma_f32_16x16x32_bf16 v[126:129], v[154:157], v[198:201], v[126:129]
	v_mfma_f32_16x16x32_bf16 v[122:125], v[174:177], v[198:201], v[122:125]
	v_mfma_f32_16x16x32_bf16 v[62:65], v[182:185], v[198:201], v[62:65]
	v_mfma_f32_16x16x32_bf16 v[58:61], v[190:193], v[198:201], v[58:61]
	v_mfma_f32_16x16x32_bf16 v[118:121], v[154:157], v[228:231], v[118:121]
	v_mfma_f32_16x16x32_bf16 v[114:117], v[174:177], v[228:231], v[114:117]
	v_mfma_f32_16x16x32_bf16 v[54:57], v[182:185], v[228:231], v[54:57]
	v_mfma_f32_16x16x32_bf16 v[50:53], v[190:193], v[228:231], v[50:53]
	v_mfma_f32_16x16x32_bf16 v[110:113], v[154:157], v[236:239], v[110:113]
	v_mfma_f32_16x16x32_bf16 v[106:109], v[174:177], v[236:239], v[106:109]
	v_mfma_f32_16x16x32_bf16 v[46:49], v[182:185], v[236:239], v[46:49]
	v_mfma_f32_16x16x32_bf16 v[42:45], v[190:193], v[236:239], v[42:45]
	v_mfma_f32_16x16x32_bf16 v[102:105], v[154:157], v[244:247], v[102:105]
	v_mfma_f32_16x16x32_bf16 v[98:101], v[174:177], v[244:247], v[98:101]
	v_mfma_f32_16x16x32_bf16 v[38:41], v[182:185], v[244:247], v[38:41]
	v_mfma_f32_16x16x32_bf16 v[34:37], v[190:193], v[244:247], v[34:37]
	s_barrier
	s_setprio 0
	s_mov_b32 m0, s21
	s_mov_b32 s70, s62
	s_mov_b32 s71, s63
	ds_read_b128 v[194:197], v140 offset:16384
	ds_read_b128 v[198:201], v140 offset:17408
	ds_read_b128 v[202:205], v140 offset:18432
	ds_read_b128 v[228:231], v140 offset:19456
	ds_read_b128 v[232:235], v140 offset:20480
	ds_read_b128 v[236:239], v140 offset:21504
	ds_read_b128 v[240:243], v140 offset:22528
	ds_read_b128 v[244:247], v140 offset:23552
	buffer_load_dwordx4 v134, s[68:71], s83 offen lds
	s_mov_b32 m0, s23
	s_add_i32 s53, s83, 0x80000
	buffer_load_dwordx4 v136, s[68:71], s83 offen lds
	s_mov_b32 m0, s24
	s_nop 0
	buffer_load_dwordx4 v134, s[68:71], s53 offen lds
	s_mov_b32 m0, s25
	s_nop 0
	buffer_load_dwordx4 v136, s[68:71], s53 offen lds
	s_mov_b32 m0, s2
	s_nop 0
	buffer_load_dwordx4 v131, s[60:63], s52 offen lds
	s_mov_b32 m0, s30
	s_nop 0
	buffer_load_dwordx4 v135, s[60:63], s52 offen lds
	s_waitcnt vmcnt(8)
	s_waitcnt lgkmcnt(0)
	s_setprio 1
	s_barrier
	v_mfma_f32_16x16x32_bf16 v[94:97], v[142:145], v[194:197], 0
	v_mfma_f32_16x16x32_bf16 v[90:93], v[170:173], v[194:197], 0
	v_mfma_f32_16x16x32_bf16 v[30:33], v[178:181], v[194:197], 0
	v_mfma_f32_16x16x32_bf16 v[26:29], v[186:189], v[194:197], 0
	v_mfma_f32_16x16x32_bf16 v[86:89], v[142:145], v[202:205], 0
	v_mfma_f32_16x16x32_bf16 v[82:85], v[170:173], v[202:205], 0
	v_mfma_f32_16x16x32_bf16 v[22:25], v[178:181], v[202:205], 0
	v_mfma_f32_16x16x32_bf16 v[18:21], v[186:189], v[202:205], 0
	v_mfma_f32_16x16x32_bf16 v[78:81], v[142:145], v[232:235], 0
	v_mfma_f32_16x16x32_bf16 v[74:77], v[170:173], v[232:235], 0
	v_mfma_f32_16x16x32_bf16 v[14:17], v[178:181], v[232:235], 0
	v_mfma_f32_16x16x32_bf16 v[10:13], v[186:189], v[232:235], 0
	v_mfma_f32_16x16x32_bf16 v[70:73], v[142:145], v[240:243], 0
	v_mfma_f32_16x16x32_bf16 v[66:69], v[170:173], v[240:243], 0
	v_mfma_f32_16x16x32_bf16 v[6:9], v[178:181], v[240:243], 0
	v_mfma_f32_16x16x32_bf16 v[2:5], v[186:189], v[240:243], 0
	v_mfma_f32_16x16x32_bf16 v[94:97], v[154:157], v[198:201], v[94:97]
	v_mfma_f32_16x16x32_bf16 v[90:93], v[174:177], v[198:201], v[90:93]
	v_mfma_f32_16x16x32_bf16 v[30:33], v[182:185], v[198:201], v[30:33]
	v_mfma_f32_16x16x32_bf16 v[26:29], v[190:193], v[198:201], v[26:29]
	v_mfma_f32_16x16x32_bf16 v[86:89], v[154:157], v[228:231], v[86:89]
	v_mfma_f32_16x16x32_bf16 v[82:85], v[174:177], v[228:231], v[82:85]
	v_mfma_f32_16x16x32_bf16 v[22:25], v[182:185], v[228:231], v[22:25]
	v_mfma_f32_16x16x32_bf16 v[18:21], v[190:193], v[228:231], v[18:21]
	v_mfma_f32_16x16x32_bf16 v[78:81], v[154:157], v[236:239], v[78:81]
	v_mfma_f32_16x16x32_bf16 v[74:77], v[174:177], v[236:239], v[74:77]
	v_mfma_f32_16x16x32_bf16 v[14:17], v[182:185], v[236:239], v[14:17]
	v_mfma_f32_16x16x32_bf16 v[10:13], v[190:193], v[236:239], v[10:13]
	v_mfma_f32_16x16x32_bf16 v[70:73], v[154:157], v[244:247], v[70:73]
	v_mfma_f32_16x16x32_bf16 v[66:69], v[174:177], v[244:247], v[66:69]
	v_mfma_f32_16x16x32_bf16 v[6:9], v[182:185], v[244:247], v[6:9]
	v_mfma_f32_16x16x32_bf16 v[2:5], v[190:193], v[244:247], v[2:5]
	s_barrier
	s_setprio 0
	v_add_u32_e32 v141, 0x18000, v139
	ds_read_b128 v[142:145], v141
	ds_read_b128 v[154:157], v141 offset:1024
	ds_read_b128 v[170:173], v141 offset:2048
	ds_read_b128 v[174:177], v141 offset:3072
	v_add_u32_e32 v141, 0x1c000, v139
	ds_read_b128 v[178:181], v141
	ds_read_b128 v[182:185], v141 offset:1024
	ds_read_b128 v[186:189], v141 offset:2048
	ds_read_b128 v[190:193], v141 offset:3072
	s_add_i32 s52, s52, 0x80000
	s_mov_b32 m0, s31
	ds_read_b128 v[194:197], v140 offset:32768
	ds_read_b128 v[198:201], v140 offset:33792
	ds_read_b128 v[202:205], v140 offset:34816
	ds_read_b128 v[228:231], v140 offset:35840
	ds_read_b128 v[232:235], v140 offset:36864
	ds_read_b128 v[236:239], v140 offset:37888
	ds_read_b128 v[240:243], v140 offset:38912
	ds_read_b128 v[244:247], v140 offset:39936
	buffer_load_dwordx4 v131, s[60:63], s52 offen lds
	s_mov_b32 m0, s33
	s_nop 0
	buffer_load_dwordx4 v135, s[60:63], s52 offen lds
	s_waitcnt vmcnt(8)
	s_waitcnt lgkmcnt(0)
	s_setprio 1
	s_barrier
	v_mfma_f32_16x16x32_bf16 v[126:129], v[142:145], v[194:197], v[126:129]
	v_mfma_f32_16x16x32_bf16 v[122:125], v[170:173], v[194:197], v[122:125]
	v_mfma_f32_16x16x32_bf16 v[62:65], v[178:181], v[194:197], v[62:65]
	v_mfma_f32_16x16x32_bf16 v[58:61], v[186:189], v[194:197], v[58:61]
	v_mfma_f32_16x16x32_bf16 v[118:121], v[142:145], v[202:205], v[118:121]
	v_mfma_f32_16x16x32_bf16 v[114:117], v[170:173], v[202:205], v[114:117]
	v_mfma_f32_16x16x32_bf16 v[54:57], v[178:181], v[202:205], v[54:57]
	v_mfma_f32_16x16x32_bf16 v[50:53], v[186:189], v[202:205], v[50:53]
	v_mfma_f32_16x16x32_bf16 v[110:113], v[142:145], v[232:235], v[110:113]
	v_mfma_f32_16x16x32_bf16 v[106:109], v[170:173], v[232:235], v[106:109]
	v_mfma_f32_16x16x32_bf16 v[46:49], v[178:181], v[232:235], v[46:49]
	v_mfma_f32_16x16x32_bf16 v[42:45], v[186:189], v[232:235], v[42:45]
	v_mfma_f32_16x16x32_bf16 v[102:105], v[142:145], v[240:243], v[102:105]
	v_mfma_f32_16x16x32_bf16 v[98:101], v[170:173], v[240:243], v[98:101]
	v_mfma_f32_16x16x32_bf16 v[38:41], v[178:181], v[240:243], v[38:41]
	v_mfma_f32_16x16x32_bf16 v[34:37], v[186:189], v[240:243], v[34:37]
	v_mfma_f32_16x16x32_bf16 v[126:129], v[154:157], v[198:201], v[126:129]
	v_mfma_f32_16x16x32_bf16 v[122:125], v[174:177], v[198:201], v[122:125]
	v_mfma_f32_16x16x32_bf16 v[62:65], v[182:185], v[198:201], v[62:65]
	v_mfma_f32_16x16x32_bf16 v[58:61], v[190:193], v[198:201], v[58:61]
	v_mfma_f32_16x16x32_bf16 v[118:121], v[154:157], v[228:231], v[118:121]
	v_mfma_f32_16x16x32_bf16 v[114:117], v[174:177], v[228:231], v[114:117]
	v_mfma_f32_16x16x32_bf16 v[54:57], v[182:185], v[228:231], v[54:57]
	v_mfma_f32_16x16x32_bf16 v[50:53], v[190:193], v[228:231], v[50:53]
	v_mfma_f32_16x16x32_bf16 v[110:113], v[154:157], v[236:239], v[110:113]
	v_mfma_f32_16x16x32_bf16 v[106:109], v[174:177], v[236:239], v[106:109]
	v_mfma_f32_16x16x32_bf16 v[46:49], v[182:185], v[236:239], v[46:49]
	v_mfma_f32_16x16x32_bf16 v[42:45], v[190:193], v[236:239], v[42:45]
	v_mfma_f32_16x16x32_bf16 v[102:105], v[154:157], v[244:247], v[102:105]
	v_mfma_f32_16x16x32_bf16 v[98:101], v[174:177], v[244:247], v[98:101]
	v_mfma_f32_16x16x32_bf16 v[38:41], v[182:185], v[244:247], v[38:41]
	v_mfma_f32_16x16x32_bf16 v[34:37], v[190:193], v[244:247], v[34:37]
	s_barrier
	s_setprio 0
	s_mov_b32 m0, s34
	s_or_b32 s52, s83, 0x80
	ds_read_b128 v[194:197], v140 offset:49152
	ds_read_b128 v[198:201], v140 offset:50176
	ds_read_b128 v[202:205], v140 offset:51200
	ds_read_b128 v[228:231], v140 offset:52224
	ds_read_b128 v[232:235], v140 offset:53248
	ds_read_b128 v[236:239], v140 offset:54272
	ds_read_b128 v[240:243], v140 offset:55296
	ds_read_b128 v[244:247], v140 offset:56320
	buffer_load_dwordx4 v134, s[68:71], s52 offen lds
	s_mov_b32 m0, s35
	s_add_i32 s83, s83, 0x80080
	buffer_load_dwordx4 v136, s[68:71], s52 offen lds
	s_mov_b32 m0, s65
	s_nop 0
	buffer_load_dwordx4 v134, s[68:71], s83 offen lds
	s_mov_b32 m0, s66
	s_nop 0
	buffer_load_dwordx4 v136, s[68:71], s83 offen lds
	s_mov_b32 m0, s36
	s_nop 0
	buffer_load_dwordx4 v131, s[60:63], s27 offen lds
	s_mov_b32 m0, s37
	s_nop 0
	buffer_load_dwordx4 v135, s[60:63], s27 offen lds
	s_waitcnt vmcnt(8)
	s_waitcnt lgkmcnt(0)
	s_setprio 1
	s_barrier
	v_mfma_f32_16x16x32_bf16 v[94:97], v[142:145], v[194:197], v[94:97]
	v_mfma_f32_16x16x32_bf16 v[90:93], v[170:173], v[194:197], v[90:93]
	v_mfma_f32_16x16x32_bf16 v[30:33], v[178:181], v[194:197], v[30:33]
	v_mfma_f32_16x16x32_bf16 v[26:29], v[186:189], v[194:197], v[26:29]
	v_mfma_f32_16x16x32_bf16 v[86:89], v[142:145], v[202:205], v[86:89]
	v_mfma_f32_16x16x32_bf16 v[82:85], v[170:173], v[202:205], v[82:85]
	v_mfma_f32_16x16x32_bf16 v[22:25], v[178:181], v[202:205], v[22:25]
	v_mfma_f32_16x16x32_bf16 v[18:21], v[186:189], v[202:205], v[18:21]
	v_mfma_f32_16x16x32_bf16 v[78:81], v[142:145], v[232:235], v[78:81]
	v_mfma_f32_16x16x32_bf16 v[74:77], v[170:173], v[232:235], v[74:77]
	v_mfma_f32_16x16x32_bf16 v[14:17], v[178:181], v[232:235], v[14:17]
	v_mfma_f32_16x16x32_bf16 v[10:13], v[186:189], v[232:235], v[10:13]
	v_mfma_f32_16x16x32_bf16 v[70:73], v[142:145], v[240:243], v[70:73]
	v_mfma_f32_16x16x32_bf16 v[66:69], v[170:173], v[240:243], v[66:69]
	v_mfma_f32_16x16x32_bf16 v[6:9], v[178:181], v[240:243], v[6:9]
	v_mfma_f32_16x16x32_bf16 v[2:5], v[186:189], v[240:243], v[2:5]
	v_mfma_f32_16x16x32_bf16 v[94:97], v[154:157], v[198:201], v[94:97]
	v_mfma_f32_16x16x32_bf16 v[90:93], v[174:177], v[198:201], v[90:93]
	v_mfma_f32_16x16x32_bf16 v[30:33], v[182:185], v[198:201], v[30:33]
	v_mfma_f32_16x16x32_bf16 v[26:29], v[190:193], v[198:201], v[26:29]
	v_mfma_f32_16x16x32_bf16 v[86:89], v[154:157], v[228:231], v[86:89]
	v_mfma_f32_16x16x32_bf16 v[82:85], v[174:177], v[228:231], v[82:85]
	v_mfma_f32_16x16x32_bf16 v[22:25], v[182:185], v[228:231], v[22:25]
	v_mfma_f32_16x16x32_bf16 v[18:21], v[190:193], v[228:231], v[18:21]
	v_mfma_f32_16x16x32_bf16 v[78:81], v[154:157], v[236:239], v[78:81]
	v_mfma_f32_16x16x32_bf16 v[74:77], v[174:177], v[236:239], v[74:77]
	v_mfma_f32_16x16x32_bf16 v[14:17], v[182:185], v[236:239], v[14:17]
	v_mfma_f32_16x16x32_bf16 v[10:13], v[190:193], v[236:239], v[10:13]
	v_mfma_f32_16x16x32_bf16 v[70:73], v[154:157], v[244:247], v[70:73]
	v_mfma_f32_16x16x32_bf16 v[66:69], v[174:177], v[244:247], v[66:69]
	v_mfma_f32_16x16x32_bf16 v[6:9], v[182:185], v[244:247], v[6:9]
	v_mfma_f32_16x16x32_bf16 v[2:5], v[190:193], v[244:247], v[2:5]
	s_barrier
	s_setprio 0
	s_add_i32 s26, s26, 2
	s_addk_i32 s19, 0x100
	s_addk_i32 s22, 0x100
	s_cmp_gt_u32 s26, 29
.LBB0_1283:
	v_add_u32_e32 v141, 0x10000, v139
	ds_read_b128 v[142:145], v141
	ds_read_b128 v[154:157], v141 offset:1024
	ds_read_b128 v[170:173], v141 offset:2048
	ds_read_b128 v[174:177], v141 offset:3072
	v_add_u32_e32 v141, 0x14000, v139
	ds_read_b128 v[178:181], v141
	ds_read_b128 v[182:185], v141 offset:1024
	ds_read_b128 v[186:189], v141 offset:2048
	ds_read_b128 v[190:193], v141 offset:3072
	s_add_i32 s27, s19, 0xfff80080
	s_cmp_eq_u32 s26, 28
	s_cselect_b32 s52, s8, s27
	s_cselect_b32 s83, s9, s22
	s_or_b32 s27, s52, 0x80
	s_mov_b32 m0, s73
	ds_read_b128 v[194:197], v140
	ds_read_b128 v[198:201], v140 offset:1024
	ds_read_b128 v[202:205], v140 offset:2048
	ds_read_b128 v[228:231], v140 offset:3072
	ds_read_b128 v[232:235], v140 offset:4096
	ds_read_b128 v[236:239], v140 offset:5120
	ds_read_b128 v[240:243], v140 offset:6144
	ds_read_b128 v[244:247], v140 offset:7168
	buffer_load_dwordx4 v131, s[60:63], s19 offen lds
	s_mov_b32 m0, s82
	s_nop 0
	buffer_load_dwordx4 v135, s[60:63], s19 offen lds
	s_waitcnt vmcnt(8)
	s_waitcnt lgkmcnt(0)
	s_setprio 1
	s_barrier
	v_mfma_f32_16x16x32_bf16 v[126:129], v[142:145], v[194:197], v[126:129]
	v_mfma_f32_16x16x32_bf16 v[122:125], v[170:173], v[194:197], v[122:125]
	v_mfma_f32_16x16x32_bf16 v[62:65], v[178:181], v[194:197], v[62:65]
	v_mfma_f32_16x16x32_bf16 v[58:61], v[186:189], v[194:197], v[58:61]
	v_mfma_f32_16x16x32_bf16 v[118:121], v[142:145], v[202:205], v[118:121]
	v_mfma_f32_16x16x32_bf16 v[114:117], v[170:173], v[202:205], v[114:117]
	v_mfma_f32_16x16x32_bf16 v[54:57], v[178:181], v[202:205], v[54:57]
	v_mfma_f32_16x16x32_bf16 v[50:53], v[186:189], v[202:205], v[50:53]
	v_mfma_f32_16x16x32_bf16 v[110:113], v[142:145], v[232:235], v[110:113]
	v_mfma_f32_16x16x32_bf16 v[106:109], v[170:173], v[232:235], v[106:109]
	v_mfma_f32_16x16x32_bf16 v[46:49], v[178:181], v[232:235], v[46:49]
	v_mfma_f32_16x16x32_bf16 v[42:45], v[186:189], v[232:235], v[42:45]
	v_mfma_f32_16x16x32_bf16 v[102:105], v[142:145], v[240:243], v[102:105]
	v_mfma_f32_16x16x32_bf16 v[98:101], v[170:173], v[240:243], v[98:101]
	v_mfma_f32_16x16x32_bf16 v[38:41], v[178:181], v[240:243], v[38:41]
	v_mfma_f32_16x16x32_bf16 v[34:37], v[186:189], v[240:243], v[34:37]
	v_mfma_f32_16x16x32_bf16 v[126:129], v[154:157], v[198:201], v[126:129]
	v_mfma_f32_16x16x32_bf16 v[122:125], v[174:177], v[198:201], v[122:125]
	v_mfma_f32_16x16x32_bf16 v[62:65], v[182:185], v[198:201], v[62:65]
	v_mfma_f32_16x16x32_bf16 v[58:61], v[190:193], v[198:201], v[58:61]
	v_mfma_f32_16x16x32_bf16 v[118:121], v[154:157], v[228:231], v[118:121]
	v_mfma_f32_16x16x32_bf16 v[114:117], v[174:177], v[228:231], v[114:117]
	v_mfma_f32_16x16x32_bf16 v[54:57], v[182:185], v[228:231], v[54:57]
	v_mfma_f32_16x16x32_bf16 v[50:53], v[190:193], v[228:231], v[50:53]
	v_mfma_f32_16x16x32_bf16 v[110:113], v[154:157], v[236:239], v[110:113]
	v_mfma_f32_16x16x32_bf16 v[106:109], v[174:177], v[236:239], v[106:109]
	v_mfma_f32_16x16x32_bf16 v[46:49], v[182:185], v[236:239], v[46:49]
	v_mfma_f32_16x16x32_bf16 v[42:45], v[190:193], v[236:239], v[42:45]
	v_mfma_f32_16x16x32_bf16 v[102:105], v[154:157], v[244:247], v[102:105]
	v_mfma_f32_16x16x32_bf16 v[98:101], v[174:177], v[244:247], v[98:101]
	v_mfma_f32_16x16x32_bf16 v[38:41], v[182:185], v[244:247], v[38:41]
	v_mfma_f32_16x16x32_bf16 v[34:37], v[190:193], v[244:247], v[34:37]
	s_barrier
	s_setprio 0
	s_mov_b32 m0, s21
	s_mov_b32 s70, s62
	s_mov_b32 s71, s63
	ds_read_b128 v[194:197], v140 offset:16384
	ds_read_b128 v[198:201], v140 offset:17408
	ds_read_b128 v[202:205], v140 offset:18432
	ds_read_b128 v[228:231], v140 offset:19456
	ds_read_b128 v[232:235], v140 offset:20480
	ds_read_b128 v[236:239], v140 offset:21504
	ds_read_b128 v[240:243], v140 offset:22528
	ds_read_b128 v[244:247], v140 offset:23552
	buffer_load_dwordx4 v134, s[68:71], s83 offen lds
	s_mov_b32 m0, s23
	s_add_i32 s53, s83, 0x80000
	buffer_load_dwordx4 v136, s[68:71], s83 offen lds
	s_mov_b32 m0, s24
	s_nop 0
	buffer_load_dwordx4 v134, s[68:71], s53 offen lds
	s_mov_b32 m0, s25
	s_nop 0
	buffer_load_dwordx4 v136, s[68:71], s53 offen lds
	s_mov_b32 m0, s2
	s_nop 0
	buffer_load_dwordx4 v131, s[60:63], s52 offen lds
	s_mov_b32 m0, s30
	s_nop 0
	buffer_load_dwordx4 v135, s[60:63], s52 offen lds
	s_waitcnt vmcnt(8)
	s_waitcnt lgkmcnt(0)
	s_setprio 1
	s_barrier
	v_mfma_f32_16x16x32_bf16 v[94:97], v[142:145], v[194:197], v[94:97]
	v_mfma_f32_16x16x32_bf16 v[90:93], v[170:173], v[194:197], v[90:93]
	v_mfma_f32_16x16x32_bf16 v[30:33], v[178:181], v[194:197], v[30:33]
	v_mfma_f32_16x16x32_bf16 v[26:29], v[186:189], v[194:197], v[26:29]
	v_mfma_f32_16x16x32_bf16 v[86:89], v[142:145], v[202:205], v[86:89]
	v_mfma_f32_16x16x32_bf16 v[82:85], v[170:173], v[202:205], v[82:85]
	v_mfma_f32_16x16x32_bf16 v[22:25], v[178:181], v[202:205], v[22:25]
	v_mfma_f32_16x16x32_bf16 v[18:21], v[186:189], v[202:205], v[18:21]
	v_mfma_f32_16x16x32_bf16 v[78:81], v[142:145], v[232:235], v[78:81]
	v_mfma_f32_16x16x32_bf16 v[74:77], v[170:173], v[232:235], v[74:77]
	v_mfma_f32_16x16x32_bf16 v[14:17], v[178:181], v[232:235], v[14:17]
	v_mfma_f32_16x16x32_bf16 v[10:13], v[186:189], v[232:235], v[10:13]
	v_mfma_f32_16x16x32_bf16 v[70:73], v[142:145], v[240:243], v[70:73]
	v_mfma_f32_16x16x32_bf16 v[66:69], v[170:173], v[240:243], v[66:69]
	v_mfma_f32_16x16x32_bf16 v[6:9], v[178:181], v[240:243], v[6:9]
	v_mfma_f32_16x16x32_bf16 v[2:5], v[186:189], v[240:243], v[2:5]
	v_mfma_f32_16x16x32_bf16 v[94:97], v[154:157], v[198:201], v[94:97]
	v_mfma_f32_16x16x32_bf16 v[90:93], v[174:177], v[198:201], v[90:93]
	v_mfma_f32_16x16x32_bf16 v[30:33], v[182:185], v[198:201], v[30:33]
	v_mfma_f32_16x16x32_bf16 v[26:29], v[190:193], v[198:201], v[26:29]
	v_mfma_f32_16x16x32_bf16 v[86:89], v[154:157], v[228:231], v[86:89]
	v_mfma_f32_16x16x32_bf16 v[82:85], v[174:177], v[228:231], v[82:85]
	v_mfma_f32_16x16x32_bf16 v[22:25], v[182:185], v[228:231], v[22:25]
	v_mfma_f32_16x16x32_bf16 v[18:21], v[190:193], v[228:231], v[18:21]
	v_mfma_f32_16x16x32_bf16 v[78:81], v[154:157], v[236:239], v[78:81]
	v_mfma_f32_16x16x32_bf16 v[74:77], v[174:177], v[236:239], v[74:77]
	v_mfma_f32_16x16x32_bf16 v[14:17], v[182:185], v[236:239], v[14:17]
	v_mfma_f32_16x16x32_bf16 v[10:13], v[190:193], v[236:239], v[10:13]
	v_mfma_f32_16x16x32_bf16 v[70:73], v[154:157], v[244:247], v[70:73]
	v_mfma_f32_16x16x32_bf16 v[66:69], v[174:177], v[244:247], v[66:69]
	v_mfma_f32_16x16x32_bf16 v[6:9], v[182:185], v[244:247], v[6:9]
	v_mfma_f32_16x16x32_bf16 v[2:5], v[190:193], v[244:247], v[2:5]
	s_barrier
	s_setprio 0
	v_add_u32_e32 v141, 0x18000, v139
	ds_read_b128 v[142:145], v141
	ds_read_b128 v[154:157], v141 offset:1024
	ds_read_b128 v[170:173], v141 offset:2048
	ds_read_b128 v[174:177], v141 offset:3072
	v_add_u32_e32 v141, 0x1c000, v139
	ds_read_b128 v[178:181], v141
	ds_read_b128 v[182:185], v141 offset:1024
	ds_read_b128 v[186:189], v141 offset:2048
	ds_read_b128 v[190:193], v141 offset:3072
	s_add_i32 s52, s52, 0x80000
	s_mov_b32 m0, s31
	ds_read_b128 v[194:197], v140 offset:32768
	ds_read_b128 v[198:201], v140 offset:33792
	ds_read_b128 v[202:205], v140 offset:34816
	ds_read_b128 v[228:231], v140 offset:35840
	ds_read_b128 v[232:235], v140 offset:36864
	ds_read_b128 v[236:239], v140 offset:37888
	ds_read_b128 v[240:243], v140 offset:38912
	ds_read_b128 v[244:247], v140 offset:39936
	buffer_load_dwordx4 v131, s[60:63], s52 offen lds
	s_mov_b32 m0, s33
	s_nop 0
	buffer_load_dwordx4 v135, s[60:63], s52 offen lds
	s_waitcnt vmcnt(8)
	s_waitcnt lgkmcnt(0)
	s_setprio 1
	s_barrier
	v_mfma_f32_16x16x32_bf16 v[126:129], v[142:145], v[194:197], v[126:129]
	v_mfma_f32_16x16x32_bf16 v[122:125], v[170:173], v[194:197], v[122:125]
	v_mfma_f32_16x16x32_bf16 v[62:65], v[178:181], v[194:197], v[62:65]
	v_mfma_f32_16x16x32_bf16 v[58:61], v[186:189], v[194:197], v[58:61]
	v_mfma_f32_16x16x32_bf16 v[118:121], v[142:145], v[202:205], v[118:121]
	v_mfma_f32_16x16x32_bf16 v[114:117], v[170:173], v[202:205], v[114:117]
	v_mfma_f32_16x16x32_bf16 v[54:57], v[178:181], v[202:205], v[54:57]
	v_mfma_f32_16x16x32_bf16 v[50:53], v[186:189], v[202:205], v[50:53]
	v_mfma_f32_16x16x32_bf16 v[110:113], v[142:145], v[232:235], v[110:113]
	v_mfma_f32_16x16x32_bf16 v[106:109], v[170:173], v[232:235], v[106:109]
	v_mfma_f32_16x16x32_bf16 v[46:49], v[178:181], v[232:235], v[46:49]
	v_mfma_f32_16x16x32_bf16 v[42:45], v[186:189], v[232:235], v[42:45]
	v_mfma_f32_16x16x32_bf16 v[102:105], v[142:145], v[240:243], v[102:105]
	v_mfma_f32_16x16x32_bf16 v[98:101], v[170:173], v[240:243], v[98:101]
	v_mfma_f32_16x16x32_bf16 v[38:41], v[178:181], v[240:243], v[38:41]
	v_mfma_f32_16x16x32_bf16 v[34:37], v[186:189], v[240:243], v[34:37]
	v_mfma_f32_16x16x32_bf16 v[126:129], v[154:157], v[198:201], v[126:129]
	v_mfma_f32_16x16x32_bf16 v[122:125], v[174:177], v[198:201], v[122:125]
	v_mfma_f32_16x16x32_bf16 v[62:65], v[182:185], v[198:201], v[62:65]
	v_mfma_f32_16x16x32_bf16 v[58:61], v[190:193], v[198:201], v[58:61]
	v_mfma_f32_16x16x32_bf16 v[118:121], v[154:157], v[228:231], v[118:121]
	v_mfma_f32_16x16x32_bf16 v[114:117], v[174:177], v[228:231], v[114:117]
	v_mfma_f32_16x16x32_bf16 v[54:57], v[182:185], v[228:231], v[54:57]
	v_mfma_f32_16x16x32_bf16 v[50:53], v[190:193], v[228:231], v[50:53]
	v_mfma_f32_16x16x32_bf16 v[110:113], v[154:157], v[236:239], v[110:113]
	v_mfma_f32_16x16x32_bf16 v[106:109], v[174:177], v[236:239], v[106:109]
	v_mfma_f32_16x16x32_bf16 v[46:49], v[182:185], v[236:239], v[46:49]
	v_mfma_f32_16x16x32_bf16 v[42:45], v[190:193], v[236:239], v[42:45]
	v_mfma_f32_16x16x32_bf16 v[102:105], v[154:157], v[244:247], v[102:105]
	v_mfma_f32_16x16x32_bf16 v[98:101], v[174:177], v[244:247], v[98:101]
	v_mfma_f32_16x16x32_bf16 v[38:41], v[182:185], v[244:247], v[38:41]
	v_mfma_f32_16x16x32_bf16 v[34:37], v[190:193], v[244:247], v[34:37]
	s_barrier
	s_setprio 0
	s_mov_b32 m0, s34
	s_or_b32 s52, s83, 0x80
	ds_read_b128 v[194:197], v140 offset:49152
	ds_read_b128 v[198:201], v140 offset:50176
	ds_read_b128 v[202:205], v140 offset:51200
	ds_read_b128 v[228:231], v140 offset:52224
	ds_read_b128 v[232:235], v140 offset:53248
	ds_read_b128 v[236:239], v140 offset:54272
	ds_read_b128 v[240:243], v140 offset:55296
	ds_read_b128 v[244:247], v140 offset:56320
	buffer_load_dwordx4 v134, s[68:71], s52 offen lds
	s_mov_b32 m0, s35
	s_add_i32 s83, s83, 0x80080
	buffer_load_dwordx4 v136, s[68:71], s52 offen lds
	s_mov_b32 m0, s65
	s_nop 0
	buffer_load_dwordx4 v134, s[68:71], s83 offen lds
	s_mov_b32 m0, s66
	s_nop 0
	buffer_load_dwordx4 v136, s[68:71], s83 offen lds
	s_mov_b32 m0, s36
	s_nop 0
	buffer_load_dwordx4 v131, s[60:63], s27 offen lds
	s_mov_b32 m0, s37
	s_nop 0
	buffer_load_dwordx4 v135, s[60:63], s27 offen lds
	s_waitcnt vmcnt(8)
	s_waitcnt lgkmcnt(0)
	s_setprio 1
	s_barrier
	v_mfma_f32_16x16x32_bf16 v[94:97], v[142:145], v[194:197], v[94:97]
	v_mfma_f32_16x16x32_bf16 v[90:93], v[170:173], v[194:197], v[90:93]
	v_mfma_f32_16x16x32_bf16 v[30:33], v[178:181], v[194:197], v[30:33]
	v_mfma_f32_16x16x32_bf16 v[26:29], v[186:189], v[194:197], v[26:29]
	v_mfma_f32_16x16x32_bf16 v[86:89], v[142:145], v[202:205], v[86:89]
	v_mfma_f32_16x16x32_bf16 v[82:85], v[170:173], v[202:205], v[82:85]
	v_mfma_f32_16x16x32_bf16 v[22:25], v[178:181], v[202:205], v[22:25]
	v_mfma_f32_16x16x32_bf16 v[18:21], v[186:189], v[202:205], v[18:21]
	v_mfma_f32_16x16x32_bf16 v[78:81], v[142:145], v[232:235], v[78:81]
	v_mfma_f32_16x16x32_bf16 v[74:77], v[170:173], v[232:235], v[74:77]
	v_mfma_f32_16x16x32_bf16 v[14:17], v[178:181], v[232:235], v[14:17]
	v_mfma_f32_16x16x32_bf16 v[10:13], v[186:189], v[232:235], v[10:13]
	v_mfma_f32_16x16x32_bf16 v[70:73], v[142:145], v[240:243], v[70:73]
	v_mfma_f32_16x16x32_bf16 v[66:69], v[170:173], v[240:243], v[66:69]
	v_mfma_f32_16x16x32_bf16 v[6:9], v[178:181], v[240:243], v[6:9]
	v_mfma_f32_16x16x32_bf16 v[2:5], v[186:189], v[240:243], v[2:5]
	v_mfma_f32_16x16x32_bf16 v[94:97], v[154:157], v[198:201], v[94:97]
	v_mfma_f32_16x16x32_bf16 v[90:93], v[174:177], v[198:201], v[90:93]
	v_mfma_f32_16x16x32_bf16 v[30:33], v[182:185], v[198:201], v[30:33]
	v_mfma_f32_16x16x32_bf16 v[26:29], v[190:193], v[198:201], v[26:29]
	v_mfma_f32_16x16x32_bf16 v[86:89], v[154:157], v[228:231], v[86:89]
	v_mfma_f32_16x16x32_bf16 v[82:85], v[174:177], v[228:231], v[82:85]
	v_mfma_f32_16x16x32_bf16 v[22:25], v[182:185], v[228:231], v[22:25]
	v_mfma_f32_16x16x32_bf16 v[18:21], v[190:193], v[228:231], v[18:21]
	v_mfma_f32_16x16x32_bf16 v[78:81], v[154:157], v[236:239], v[78:81]
	v_mfma_f32_16x16x32_bf16 v[74:77], v[174:177], v[236:239], v[74:77]
	v_mfma_f32_16x16x32_bf16 v[14:17], v[182:185], v[236:239], v[14:17]
	v_mfma_f32_16x16x32_bf16 v[10:13], v[190:193], v[236:239], v[10:13]
	v_mfma_f32_16x16x32_bf16 v[70:73], v[154:157], v[244:247], v[70:73]
	v_mfma_f32_16x16x32_bf16 v[66:69], v[174:177], v[244:247], v[66:69]
	v_mfma_f32_16x16x32_bf16 v[6:9], v[182:185], v[244:247], v[6:9]
	v_mfma_f32_16x16x32_bf16 v[2:5], v[190:193], v[244:247], v[2:5]
	s_barrier
	s_setprio 0
	s_add_i32 s26, s26, 2
	s_addk_i32 s19, 0x100
	s_addk_i32 s22, 0x100
	s_cmp_gt_u32 s26, 29
	s_cbranch_scc0 .LBB0_1283
	s_and_b64 vcc, exec, s[44:45]
	s_cbranch_vccz .LBB0_1286
	s_barrier

.LBB0_1588:
	s_lshl_b32 s85, s84, 20
	s_and_b64 s[8:9], s[42:43], exec
	s_cselect_b32 s8, s85, s13
	s_lshl_b32 s48, s73, 20
	s_and_b64 s[22:23], s[42:43], exec
	s_cselect_b32 s9, s48, s21
	s_add_i32 s13, s13, 0x80080
	s_addk_i32 s21, 0x100
	s_mov_b32 s22, -2
	s_waitcnt lgkmcnt(0)
	v_add_u32_e32 v170, 0x10000, v140
	v_add_u32_e32 v186, 0x14000, v140
	ds_read_b128 v[132:135], v170
	ds_read_b128 v[142:145], v170 offset:1024
	ds_read_b128 v[154:157], v170 offset:2048
	ds_read_b128 v[170:173], v170 offset:3072
	ds_read_b128 v[174:177], v186
	ds_read_b128 v[178:181], v186 offset:1024
	ds_read_b128 v[182:185], v186 offset:2048
	ds_read_b128 v[186:189], v186 offset:3072
	s_add_i32 s23, s13, 0xfff80080
	s_cmp_eq_u32 s22, 28
	s_cselect_b32 s27, s8, s23
	s_cselect_b32 s26, s9, s21
	s_or_b32 s23, s27, 0x80
	s_mov_b32 m0, s70
	ds_read_b128 v[190:193], v141
	ds_read_b128 v[194:197], v141 offset:1024
	ds_read_b128 v[198:201], v141 offset:2048
	ds_read_b128 v[202:205], v141 offset:3072
	ds_read_b128 v[228:231], v141 offset:4096
	ds_read_b128 v[232:235], v141 offset:5120
	ds_read_b128 v[236:239], v141 offset:6144
	ds_read_b128 v[240:243], v141 offset:7168
	buffer_load_dwordx4 v136, s[60:63], s13 offen lds
	s_mov_b32 m0, s72
	s_nop 0
	buffer_load_dwordx4 v138, s[60:63], s13 offen lds
	s_waitcnt vmcnt(8)
	s_waitcnt lgkmcnt(0)
	s_setprio 1
	s_barrier
	v_mfma_f32_16x16x32_bf16 v[126:129], v[132:135], v[190:193], 0
	v_mfma_f32_16x16x32_bf16 v[106:109], v[154:157], v[190:193], 0
	v_mfma_f32_16x16x32_bf16 v[122:125], v[174:177], v[190:193], 0
	v_mfma_f32_16x16x32_bf16 v[110:113], v[182:185], v[190:193], 0
	v_mfma_f32_16x16x32_bf16 v[118:121], v[132:135], v[198:201], 0
	v_mfma_f32_16x16x32_bf16 v[114:117], v[154:157], v[198:201], 0
	v_mfma_f32_16x16x32_bf16 v[102:105], v[174:177], v[198:201], 0
	v_mfma_f32_16x16x32_bf16 v[98:101], v[182:185], v[198:201], 0
	v_mfma_f32_16x16x32_bf16 v[94:97], v[132:135], v[228:231], 0
	v_mfma_f32_16x16x32_bf16 v[90:93], v[154:157], v[228:231], 0
	v_mfma_f32_16x16x32_bf16 v[86:89], v[174:177], v[228:231], 0
	v_mfma_f32_16x16x32_bf16 v[82:85], v[182:185], v[228:231], 0
	v_mfma_f32_16x16x32_bf16 v[78:81], v[132:135], v[236:239], 0
	v_mfma_f32_16x16x32_bf16 v[74:77], v[154:157], v[236:239], 0
	v_mfma_f32_16x16x32_bf16 v[70:73], v[174:177], v[236:239], 0
	v_mfma_f32_16x16x32_bf16 v[66:69], v[182:185], v[236:239], 0
	v_mfma_f32_16x16x32_bf16 v[126:129], v[142:145], v[194:197], v[126:129]
	v_mfma_f32_16x16x32_bf16 v[106:109], v[170:173], v[194:197], v[106:109]
	v_mfma_f32_16x16x32_bf16 v[122:125], v[178:181], v[194:197], v[122:125]
	v_mfma_f32_16x16x32_bf16 v[110:113], v[186:189], v[194:197], v[110:113]
	v_mfma_f32_16x16x32_bf16 v[118:121], v[142:145], v[202:205], v[118:121]
	v_mfma_f32_16x16x32_bf16 v[114:117], v[170:173], v[202:205], v[114:117]
	v_mfma_f32_16x16x32_bf16 v[102:105], v[178:181], v[202:205], v[102:105]
	v_mfma_f32_16x16x32_bf16 v[98:101], v[186:189], v[202:205], v[98:101]
	v_mfma_f32_16x16x32_bf16 v[94:97], v[142:145], v[232:235], v[94:97]
	v_mfma_f32_16x16x32_bf16 v[90:93], v[170:173], v[232:235], v[90:93]
	v_mfma_f32_16x16x32_bf16 v[86:89], v[178:181], v[232:235], v[86:89]
	v_mfma_f32_16x16x32_bf16 v[82:85], v[186:189], v[232:235], v[82:85]
	v_mfma_f32_16x16x32_bf16 v[78:81], v[142:145], v[240:243], v[78:81]
	v_mfma_f32_16x16x32_bf16 v[74:77], v[170:173], v[240:243], v[74:77]
	v_mfma_f32_16x16x32_bf16 v[70:73], v[178:181], v[240:243], v[70:73]
	v_mfma_f32_16x16x32_bf16 v[66:69], v[186:189], v[240:243], v[66:69]
	s_barrier
	s_setprio 0
	s_mov_b32 m0, s15
	s_mov_b32 s46, s62
	s_mov_b32 s47, s63
	ds_read_b128 v[190:193], v141 offset:16384
	ds_read_b128 v[194:197], v141 offset:17408
	ds_read_b128 v[198:201], v141 offset:18432
	ds_read_b128 v[202:205], v141 offset:19456
	ds_read_b128 v[228:231], v141 offset:20480
	ds_read_b128 v[232:235], v141 offset:21504
	ds_read_b128 v[236:239], v141 offset:22528
	ds_read_b128 v[240:243], v141 offset:23552
	buffer_load_dwordx4 v137, s[44:47], s26 offen lds
	s_mov_b32 m0, s16
	s_add_i32 s49, s26, 0x80000
	buffer_load_dwordx4 v139, s[44:47], s26 offen lds
	s_mov_b32 m0, s18
	s_nop 0
	buffer_load_dwordx4 v137, s[44:47], s49 offen lds
	s_mov_b32 m0, s19
	s_nop 0
	buffer_load_dwordx4 v139, s[44:47], s49 offen lds
	s_mov_b32 m0, s14
	s_nop 0
	buffer_load_dwordx4 v136, s[60:63], s27 offen lds
	s_mov_b32 m0, s24
	s_nop 0
	buffer_load_dwordx4 v138, s[60:63], s27 offen lds
	s_waitcnt vmcnt(8)
	s_waitcnt lgkmcnt(0)
	s_setprio 1
	s_barrier
	v_mfma_f32_16x16x32_bf16 v[62:65], v[132:135], v[190:193], 0
	v_mfma_f32_16x16x32_bf16 v[58:61], v[154:157], v[190:193], 0
	v_mfma_f32_16x16x32_bf16 v[54:57], v[174:177], v[190:193], 0
	v_mfma_f32_16x16x32_bf16 v[50:53], v[182:185], v[190:193], 0
	v_mfma_f32_16x16x32_bf16 v[46:49], v[132:135], v[198:201], 0
	v_mfma_f32_16x16x32_bf16 v[42:45], v[154:157], v[198:201], 0
	v_mfma_f32_16x16x32_bf16 v[38:41], v[174:177], v[198:201], 0
	v_mfma_f32_16x16x32_bf16 v[34:37], v[182:185], v[198:201], 0
	v_mfma_f32_16x16x32_bf16 v[30:33], v[132:135], v[228:231], 0
	v_mfma_f32_16x16x32_bf16 v[26:29], v[154:157], v[228:231], 0
	v_mfma_f32_16x16x32_bf16 v[22:25], v[174:177], v[228:231], 0
	v_mfma_f32_16x16x32_bf16 v[18:21], v[182:185], v[228:231], 0
	v_mfma_f32_16x16x32_bf16 v[14:17], v[132:135], v[236:239], 0
	v_mfma_f32_16x16x32_bf16 v[10:13], v[154:157], v[236:239], 0
	v_mfma_f32_16x16x32_bf16 v[6:9], v[174:177], v[236:239], 0
	v_mfma_f32_16x16x32_bf16 v[2:5], v[182:185], v[236:239], 0
	v_mfma_f32_16x16x32_bf16 v[62:65], v[142:145], v[194:197], v[62:65]
	v_mfma_f32_16x16x32_bf16 v[58:61], v[170:173], v[194:197], v[58:61]
	v_mfma_f32_16x16x32_bf16 v[54:57], v[178:181], v[194:197], v[54:57]
	v_mfma_f32_16x16x32_bf16 v[50:53], v[186:189], v[194:197], v[50:53]
	v_mfma_f32_16x16x32_bf16 v[46:49], v[142:145], v[202:205], v[46:49]
	v_mfma_f32_16x16x32_bf16 v[42:45], v[170:173], v[202:205], v[42:45]
	v_mfma_f32_16x16x32_bf16 v[38:41], v[178:181], v[202:205], v[38:41]
	v_mfma_f32_16x16x32_bf16 v[34:37], v[186:189], v[202:205], v[34:37]
	v_mfma_f32_16x16x32_bf16 v[30:33], v[142:145], v[232:235], v[30:33]
	v_mfma_f32_16x16x32_bf16 v[26:29], v[170:173], v[232:235], v[26:29]
	v_mfma_f32_16x16x32_bf16 v[22:25], v[178:181], v[232:235], v[22:25]
	v_mfma_f32_16x16x32_bf16 v[18:21], v[186:189], v[232:235], v[18:21]
	v_mfma_f32_16x16x32_bf16 v[14:17], v[142:145], v[240:243], v[14:17]
	v_mfma_f32_16x16x32_bf16 v[10:13], v[170:173], v[240:243], v[10:13]
	v_mfma_f32_16x16x32_bf16 v[6:9], v[178:181], v[240:243], v[6:9]
	v_mfma_f32_16x16x32_bf16 v[2:5], v[186:189], v[240:243], v[2:5]
	s_barrier
	s_setprio 0
	v_add_u32_e32 v170, 0x18000, v140
	v_add_u32_e32 v186, 0x1c000, v140
	ds_read_b128 v[132:135], v170
	ds_read_b128 v[142:145], v170 offset:1024
	ds_read_b128 v[154:157], v170 offset:2048
	ds_read_b128 v[170:173], v170 offset:3072
	ds_read_b128 v[174:177], v186
	ds_read_b128 v[178:181], v186 offset:1024
	ds_read_b128 v[182:185], v186 offset:2048
	ds_read_b128 v[186:189], v186 offset:3072
	s_add_i32 s27, s27, 0x80000
	s_mov_b32 m0, s25
	ds_read_b128 v[190:193], v141 offset:32768
	ds_read_b128 v[194:197], v141 offset:33792
	ds_read_b128 v[198:201], v141 offset:34816
	ds_read_b128 v[202:205], v141 offset:35840
	ds_read_b128 v[228:231], v141 offset:36864
	ds_read_b128 v[232:235], v141 offset:37888
	ds_read_b128 v[236:239], v141 offset:38912
	ds_read_b128 v[240:243], v141 offset:39936
	buffer_load_dwordx4 v136, s[60:63], s27 offen lds
	s_mov_b32 m0, s30
	s_nop 0
	buffer_load_dwordx4 v138, s[60:63], s27 offen lds
	s_waitcnt vmcnt(8)
	s_waitcnt lgkmcnt(0)
	s_setprio 1
	s_barrier
	v_mfma_f32_16x16x32_bf16 v[126:129], v[132:135], v[190:193], v[126:129]
	v_mfma_f32_16x16x32_bf16 v[106:109], v[154:157], v[190:193], v[106:109]
	v_mfma_f32_16x16x32_bf16 v[122:125], v[174:177], v[190:193], v[122:125]
	v_mfma_f32_16x16x32_bf16 v[110:113], v[182:185], v[190:193], v[110:113]
	v_mfma_f32_16x16x32_bf16 v[118:121], v[132:135], v[198:201], v[118:121]
	v_mfma_f32_16x16x32_bf16 v[114:117], v[154:157], v[198:201], v[114:117]
	v_mfma_f32_16x16x32_bf16 v[102:105], v[174:177], v[198:201], v[102:105]
	v_mfma_f32_16x16x32_bf16 v[98:101], v[182:185], v[198:201], v[98:101]
	v_mfma_f32_16x16x32_bf16 v[94:97], v[132:135], v[228:231], v[94:97]
	v_mfma_f32_16x16x32_bf16 v[90:93], v[154:157], v[228:231], v[90:93]
	v_mfma_f32_16x16x32_bf16 v[86:89], v[174:177], v[228:231], v[86:89]
	v_mfma_f32_16x16x32_bf16 v[82:85], v[182:185], v[228:231], v[82:85]
	v_mfma_f32_16x16x32_bf16 v[78:81], v[132:135], v[236:239], v[78:81]
	v_mfma_f32_16x16x32_bf16 v[74:77], v[154:157], v[236:239], v[74:77]
	v_mfma_f32_16x16x32_bf16 v[70:73], v[174:177], v[236:239], v[70:73]
	v_mfma_f32_16x16x32_bf16 v[66:69], v[182:185], v[236:239], v[66:69]
	v_mfma_f32_16x16x32_bf16 v[126:129], v[142:145], v[194:197], v[126:129]
	v_mfma_f32_16x16x32_bf16 v[106:109], v[170:173], v[194:197], v[106:109]
	v_mfma_f32_16x16x32_bf16 v[122:125], v[178:181], v[194:197], v[122:125]
	v_mfma_f32_16x16x32_bf16 v[110:113], v[186:189], v[194:197], v[110:113]
	v_mfma_f32_16x16x32_bf16 v[118:121], v[142:145], v[202:205], v[118:121]
	v_mfma_f32_16x16x32_bf16 v[114:117], v[170:173], v[202:205], v[114:117]
	v_mfma_f32_16x16x32_bf16 v[102:105], v[178:181], v[202:205], v[102:105]
	v_mfma_f32_16x16x32_bf16 v[98:101], v[186:189], v[202:205], v[98:101]
	v_mfma_f32_16x16x32_bf16 v[94:97], v[142:145], v[232:235], v[94:97]
	v_mfma_f32_16x16x32_bf16 v[90:93], v[170:173], v[232:235], v[90:93]
	v_mfma_f32_16x16x32_bf16 v[86:89], v[178:181], v[232:235], v[86:89]
	v_mfma_f32_16x16x32_bf16 v[82:85], v[186:189], v[232:235], v[82:85]
	v_mfma_f32_16x16x32_bf16 v[78:81], v[142:145], v[240:243], v[78:81]
	v_mfma_f32_16x16x32_bf16 v[74:77], v[170:173], v[240:243], v[74:77]
	v_mfma_f32_16x16x32_bf16 v[70:73], v[178:181], v[240:243], v[70:73]
	v_mfma_f32_16x16x32_bf16 v[66:69], v[186:189], v[240:243], v[66:69]
	s_barrier
	s_setprio 0
	s_mov_b32 m0, s36
	s_or_b32 s27, s26, 0x80
	ds_read_b128 v[190:193], v141 offset:49152
	ds_read_b128 v[194:197], v141 offset:50176
	ds_read_b128 v[198:201], v141 offset:51200
	ds_read_b128 v[202:205], v141 offset:52224
	ds_read_b128 v[228:231], v141 offset:53248
	ds_read_b128 v[232:235], v141 offset:54272
	ds_read_b128 v[236:239], v141 offset:55296
	ds_read_b128 v[240:243], v141 offset:56320
	buffer_load_dwordx4 v137, s[44:47], s27 offen lds
	s_mov_b32 m0, s37
	s_add_i32 s26, s26, 0x80080
	buffer_load_dwordx4 v139, s[44:47], s27 offen lds
	s_mov_b32 m0, s68
	s_nop 0
	buffer_load_dwordx4 v137, s[44:47], s26 offen lds
	s_mov_b32 m0, s69
	s_nop 0
	buffer_load_dwordx4 v139, s[44:47], s26 offen lds
	s_mov_b32 m0, s66
	s_nop 0
	buffer_load_dwordx4 v136, s[60:63], s23 offen lds
	s_mov_b32 m0, s67
	s_nop 0
	buffer_load_dwordx4 v138, s[60:63], s23 offen lds
	s_waitcnt vmcnt(8)
	s_waitcnt lgkmcnt(0)
	s_setprio 1
	s_barrier
	v_mfma_f32_16x16x32_bf16 v[62:65], v[132:135], v[190:193], v[62:65]
	v_mfma_f32_16x16x32_bf16 v[58:61], v[154:157], v[190:193], v[58:61]
	v_mfma_f32_16x16x32_bf16 v[54:57], v[174:177], v[190:193], v[54:57]
	v_mfma_f32_16x16x32_bf16 v[50:53], v[182:185], v[190:193], v[50:53]
	v_mfma_f32_16x16x32_bf16 v[46:49], v[132:135], v[198:201], v[46:49]
	v_mfma_f32_16x16x32_bf16 v[42:45], v[154:157], v[198:201], v[42:45]
	v_mfma_f32_16x16x32_bf16 v[38:41], v[174:177], v[198:201], v[38:41]
	v_mfma_f32_16x16x32_bf16 v[34:37], v[182:185], v[198:201], v[34:37]
	v_mfma_f32_16x16x32_bf16 v[30:33], v[132:135], v[228:231], v[30:33]
	v_mfma_f32_16x16x32_bf16 v[26:29], v[154:157], v[228:231], v[26:29]
	v_mfma_f32_16x16x32_bf16 v[22:25], v[174:177], v[228:231], v[22:25]
	v_mfma_f32_16x16x32_bf16 v[18:21], v[182:185], v[228:231], v[18:21]
	v_mfma_f32_16x16x32_bf16 v[14:17], v[132:135], v[236:239], v[14:17]
	v_mfma_f32_16x16x32_bf16 v[10:13], v[154:157], v[236:239], v[10:13]
	v_mfma_f32_16x16x32_bf16 v[6:9], v[174:177], v[236:239], v[6:9]
	v_mfma_f32_16x16x32_bf16 v[2:5], v[182:185], v[236:239], v[2:5]
	v_mfma_f32_16x16x32_bf16 v[62:65], v[142:145], v[194:197], v[62:65]
	v_mfma_f32_16x16x32_bf16 v[58:61], v[170:173], v[194:197], v[58:61]
	v_mfma_f32_16x16x32_bf16 v[54:57], v[178:181], v[194:197], v[54:57]
	v_mfma_f32_16x16x32_bf16 v[50:53], v[186:189], v[194:197], v[50:53]
	v_mfma_f32_16x16x32_bf16 v[46:49], v[142:145], v[202:205], v[46:49]
	v_mfma_f32_16x16x32_bf16 v[42:45], v[170:173], v[202:205], v[42:45]
	v_mfma_f32_16x16x32_bf16 v[38:41], v[178:181], v[202:205], v[38:41]
	v_mfma_f32_16x16x32_bf16 v[34:37], v[186:189], v[202:205], v[34:37]
	v_mfma_f32_16x16x32_bf16 v[30:33], v[142:145], v[232:235], v[30:33]
	v_mfma_f32_16x16x32_bf16 v[26:29], v[170:173], v[232:235], v[26:29]
	v_mfma_f32_16x16x32_bf16 v[22:25], v[178:181], v[232:235], v[22:25]
	v_mfma_f32_16x16x32_bf16 v[18:21], v[186:189], v[232:235], v[18:21]
	v_mfma_f32_16x16x32_bf16 v[14:17], v[142:145], v[240:243], v[14:17]
	v_mfma_f32_16x16x32_bf16 v[10:13], v[170:173], v[240:243], v[10:13]
	v_mfma_f32_16x16x32_bf16 v[6:9], v[178:181], v[240:243], v[6:9]
	v_mfma_f32_16x16x32_bf16 v[2:5], v[186:189], v[240:243], v[2:5]
	s_barrier
	s_setprio 0
	s_add_i32 s22, s22, 2
	s_addk_i32 s13, 0x100
	s_addk_i32 s21, 0x100
	s_cmp_gt_u32 s22, 29
.LBB0_1589:
	v_add_u32_e32 v170, 0x10000, v140
	v_add_u32_e32 v186, 0x14000, v140
	ds_read_b128 v[132:135], v170
	ds_read_b128 v[142:145], v170 offset:1024
	ds_read_b128 v[154:157], v170 offset:2048
	ds_read_b128 v[170:173], v170 offset:3072
	ds_read_b128 v[174:177], v186
	ds_read_b128 v[178:181], v186 offset:1024
	ds_read_b128 v[182:185], v186 offset:2048
	ds_read_b128 v[186:189], v186 offset:3072
	s_add_i32 s23, s13, 0xfff80080
	s_cmp_eq_u32 s22, 28
	s_cselect_b32 s27, s8, s23
	s_cselect_b32 s26, s9, s21
	s_or_b32 s23, s27, 0x80
	s_mov_b32 m0, s70
	ds_read_b128 v[190:193], v141
	ds_read_b128 v[194:197], v141 offset:1024
	ds_read_b128 v[198:201], v141 offset:2048
	ds_read_b128 v[202:205], v141 offset:3072
	ds_read_b128 v[228:231], v141 offset:4096
	ds_read_b128 v[232:235], v141 offset:5120
	ds_read_b128 v[236:239], v141 offset:6144
	ds_read_b128 v[240:243], v141 offset:7168
	buffer_load_dwordx4 v136, s[60:63], s13 offen lds
	s_mov_b32 m0, s72
	s_nop 0
	buffer_load_dwordx4 v138, s[60:63], s13 offen lds
	s_waitcnt vmcnt(8)
	s_waitcnt lgkmcnt(0)
	s_setprio 1
	s_barrier
	v_mfma_f32_16x16x32_bf16 v[126:129], v[132:135], v[190:193], v[126:129]
	v_mfma_f32_16x16x32_bf16 v[106:109], v[154:157], v[190:193], v[106:109]
	v_mfma_f32_16x16x32_bf16 v[122:125], v[174:177], v[190:193], v[122:125]
	v_mfma_f32_16x16x32_bf16 v[110:113], v[182:185], v[190:193], v[110:113]
	v_mfma_f32_16x16x32_bf16 v[118:121], v[132:135], v[198:201], v[118:121]
	v_mfma_f32_16x16x32_bf16 v[114:117], v[154:157], v[198:201], v[114:117]
	v_mfma_f32_16x16x32_bf16 v[102:105], v[174:177], v[198:201], v[102:105]
	v_mfma_f32_16x16x32_bf16 v[98:101], v[182:185], v[198:201], v[98:101]
	v_mfma_f32_16x16x32_bf16 v[94:97], v[132:135], v[228:231], v[94:97]
	v_mfma_f32_16x16x32_bf16 v[90:93], v[154:157], v[228:231], v[90:93]
	v_mfma_f32_16x16x32_bf16 v[86:89], v[174:177], v[228:231], v[86:89]
	v_mfma_f32_16x16x32_bf16 v[82:85], v[182:185], v[228:231], v[82:85]
	v_mfma_f32_16x16x32_bf16 v[78:81], v[132:135], v[236:239], v[78:81]
	v_mfma_f32_16x16x32_bf16 v[74:77], v[154:157], v[236:239], v[74:77]
	v_mfma_f32_16x16x32_bf16 v[70:73], v[174:177], v[236:239], v[70:73]
	v_mfma_f32_16x16x32_bf16 v[66:69], v[182:185], v[236:239], v[66:69]
	v_mfma_f32_16x16x32_bf16 v[126:129], v[142:145], v[194:197], v[126:129]
	v_mfma_f32_16x16x32_bf16 v[106:109], v[170:173], v[194:197], v[106:109]
	v_mfma_f32_16x16x32_bf16 v[122:125], v[178:181], v[194:197], v[122:125]
	v_mfma_f32_16x16x32_bf16 v[110:113], v[186:189], v[194:197], v[110:113]
	v_mfma_f32_16x16x32_bf16 v[118:121], v[142:145], v[202:205], v[118:121]
	v_mfma_f32_16x16x32_bf16 v[114:117], v[170:173], v[202:205], v[114:117]
	v_mfma_f32_16x16x32_bf16 v[102:105], v[178:181], v[202:205], v[102:105]
	v_mfma_f32_16x16x32_bf16 v[98:101], v[186:189], v[202:205], v[98:101]
	v_mfma_f32_16x16x32_bf16 v[94:97], v[142:145], v[232:235], v[94:97]
	v_mfma_f32_16x16x32_bf16 v[90:93], v[170:173], v[232:235], v[90:93]
	v_mfma_f32_16x16x32_bf16 v[86:89], v[178:181], v[232:235], v[86:89]
	v_mfma_f32_16x16x32_bf16 v[82:85], v[186:189], v[232:235], v[82:85]
	v_mfma_f32_16x16x32_bf16 v[78:81], v[142:145], v[240:243], v[78:81]
	v_mfma_f32_16x16x32_bf16 v[74:77], v[170:173], v[240:243], v[74:77]
	v_mfma_f32_16x16x32_bf16 v[70:73], v[178:181], v[240:243], v[70:73]
	v_mfma_f32_16x16x32_bf16 v[66:69], v[186:189], v[240:243], v[66:69]
	s_barrier
	s_setprio 0
	s_mov_b32 m0, s15
	s_mov_b32 s46, s62
	s_mov_b32 s47, s63
	ds_read_b128 v[190:193], v141 offset:16384
	ds_read_b128 v[194:197], v141 offset:17408
	ds_read_b128 v[198:201], v141 offset:18432
	ds_read_b128 v[202:205], v141 offset:19456
	ds_read_b128 v[228:231], v141 offset:20480
	ds_read_b128 v[232:235], v141 offset:21504
	ds_read_b128 v[236:239], v141 offset:22528
	ds_read_b128 v[240:243], v141 offset:23552
	buffer_load_dwordx4 v137, s[44:47], s26 offen lds
	s_mov_b32 m0, s16
	s_add_i32 s49, s26, 0x80000
	buffer_load_dwordx4 v139, s[44:47], s26 offen lds
	s_mov_b32 m0, s18
	s_nop 0
	buffer_load_dwordx4 v137, s[44:47], s49 offen lds
	s_mov_b32 m0, s19
	s_nop 0
	buffer_load_dwordx4 v139, s[44:47], s49 offen lds
	s_mov_b32 m0, s14
	s_nop 0
	buffer_load_dwordx4 v136, s[60:63], s27 offen lds
	s_mov_b32 m0, s24
	s_nop 0
	buffer_load_dwordx4 v138, s[60:63], s27 offen lds
	s_waitcnt vmcnt(8)
	s_waitcnt lgkmcnt(0)
	s_setprio 1
	s_barrier
	v_mfma_f32_16x16x32_bf16 v[62:65], v[132:135], v[190:193], v[62:65]
	v_mfma_f32_16x16x32_bf16 v[58:61], v[154:157], v[190:193], v[58:61]
	v_mfma_f32_16x16x32_bf16 v[54:57], v[174:177], v[190:193], v[54:57]
	v_mfma_f32_16x16x32_bf16 v[50:53], v[182:185], v[190:193], v[50:53]
	v_mfma_f32_16x16x32_bf16 v[46:49], v[132:135], v[198:201], v[46:49]
	v_mfma_f32_16x16x32_bf16 v[42:45], v[154:157], v[198:201], v[42:45]
	v_mfma_f32_16x16x32_bf16 v[38:41], v[174:177], v[198:201], v[38:41]
	v_mfma_f32_16x16x32_bf16 v[34:37], v[182:185], v[198:201], v[34:37]
	v_mfma_f32_16x16x32_bf16 v[30:33], v[132:135], v[228:231], v[30:33]
	v_mfma_f32_16x16x32_bf16 v[26:29], v[154:157], v[228:231], v[26:29]
	v_mfma_f32_16x16x32_bf16 v[22:25], v[174:177], v[228:231], v[22:25]
	v_mfma_f32_16x16x32_bf16 v[18:21], v[182:185], v[228:231], v[18:21]
	v_mfma_f32_16x16x32_bf16 v[14:17], v[132:135], v[236:239], v[14:17]
	v_mfma_f32_16x16x32_bf16 v[10:13], v[154:157], v[236:239], v[10:13]
	v_mfma_f32_16x16x32_bf16 v[6:9], v[174:177], v[236:239], v[6:9]
	v_mfma_f32_16x16x32_bf16 v[2:5], v[182:185], v[236:239], v[2:5]
	v_mfma_f32_16x16x32_bf16 v[62:65], v[142:145], v[194:197], v[62:65]
	v_mfma_f32_16x16x32_bf16 v[58:61], v[170:173], v[194:197], v[58:61]
	v_mfma_f32_16x16x32_bf16 v[54:57], v[178:181], v[194:197], v[54:57]
	v_mfma_f32_16x16x32_bf16 v[50:53], v[186:189], v[194:197], v[50:53]
	v_mfma_f32_16x16x32_bf16 v[46:49], v[142:145], v[202:205], v[46:49]
	v_mfma_f32_16x16x32_bf16 v[42:45], v[170:173], v[202:205], v[42:45]
	v_mfma_f32_16x16x32_bf16 v[38:41], v[178:181], v[202:205], v[38:41]
	v_mfma_f32_16x16x32_bf16 v[34:37], v[186:189], v[202:205], v[34:37]
	v_mfma_f32_16x16x32_bf16 v[30:33], v[142:145], v[232:235], v[30:33]
	v_mfma_f32_16x16x32_bf16 v[26:29], v[170:173], v[232:235], v[26:29]
	v_mfma_f32_16x16x32_bf16 v[22:25], v[178:181], v[232:235], v[22:25]
	v_mfma_f32_16x16x32_bf16 v[18:21], v[186:189], v[232:235], v[18:21]
	v_mfma_f32_16x16x32_bf16 v[14:17], v[142:145], v[240:243], v[14:17]
	v_mfma_f32_16x16x32_bf16 v[10:13], v[170:173], v[240:243], v[10:13]
	v_mfma_f32_16x16x32_bf16 v[6:9], v[178:181], v[240:243], v[6:9]
	v_mfma_f32_16x16x32_bf16 v[2:5], v[186:189], v[240:243], v[2:5]
	s_barrier
	s_setprio 0
	v_add_u32_e32 v170, 0x18000, v140
	v_add_u32_e32 v186, 0x1c000, v140
	ds_read_b128 v[132:135], v170
	ds_read_b128 v[142:145], v170 offset:1024
	ds_read_b128 v[154:157], v170 offset:2048
	ds_read_b128 v[170:173], v170 offset:3072
	ds_read_b128 v[174:177], v186
	ds_read_b128 v[178:181], v186 offset:1024
	ds_read_b128 v[182:185], v186 offset:2048
	ds_read_b128 v[186:189], v186 offset:3072
	s_add_i32 s27, s27, 0x80000
	s_mov_b32 m0, s25
	ds_read_b128 v[190:193], v141 offset:32768
	ds_read_b128 v[194:197], v141 offset:33792
	ds_read_b128 v[198:201], v141 offset:34816
	ds_read_b128 v[202:205], v141 offset:35840
	ds_read_b128 v[228:231], v141 offset:36864
	ds_read_b128 v[232:235], v141 offset:37888
	ds_read_b128 v[236:239], v141 offset:38912
	ds_read_b128 v[240:243], v141 offset:39936
	buffer_load_dwordx4 v136, s[60:63], s27 offen lds
	s_mov_b32 m0, s30
	s_nop 0
	buffer_load_dwordx4 v138, s[60:63], s27 offen lds
	s_waitcnt vmcnt(8)
	s_waitcnt lgkmcnt(0)
	s_setprio 1
	s_barrier
	v_mfma_f32_16x16x32_bf16 v[126:129], v[132:135], v[190:193], v[126:129]
	v_mfma_f32_16x16x32_bf16 v[106:109], v[154:157], v[190:193], v[106:109]
	v_mfma_f32_16x16x32_bf16 v[122:125], v[174:177], v[190:193], v[122:125]
	v_mfma_f32_16x16x32_bf16 v[110:113], v[182:185], v[190:193], v[110:113]
	v_mfma_f32_16x16x32_bf16 v[118:121], v[132:135], v[198:201], v[118:121]
	v_mfma_f32_16x16x32_bf16 v[114:117], v[154:157], v[198:201], v[114:117]
	v_mfma_f32_16x16x32_bf16 v[102:105], v[174:177], v[198:201], v[102:105]
	v_mfma_f32_16x16x32_bf16 v[98:101], v[182:185], v[198:201], v[98:101]
	v_mfma_f32_16x16x32_bf16 v[94:97], v[132:135], v[228:231], v[94:97]
	v_mfma_f32_16x16x32_bf16 v[90:93], v[154:157], v[228:231], v[90:93]
	v_mfma_f32_16x16x32_bf16 v[86:89], v[174:177], v[228:231], v[86:89]
	v_mfma_f32_16x16x32_bf16 v[82:85], v[182:185], v[228:231], v[82:85]
	v_mfma_f32_16x16x32_bf16 v[78:81], v[132:135], v[236:239], v[78:81]
	v_mfma_f32_16x16x32_bf16 v[74:77], v[154:157], v[236:239], v[74:77]
	v_mfma_f32_16x16x32_bf16 v[70:73], v[174:177], v[236:239], v[70:73]
	v_mfma_f32_16x16x32_bf16 v[66:69], v[182:185], v[236:239], v[66:69]
	v_mfma_f32_16x16x32_bf16 v[126:129], v[142:145], v[194:197], v[126:129]
	v_mfma_f32_16x16x32_bf16 v[106:109], v[170:173], v[194:197], v[106:109]
	v_mfma_f32_16x16x32_bf16 v[122:125], v[178:181], v[194:197], v[122:125]
	v_mfma_f32_16x16x32_bf16 v[110:113], v[186:189], v[194:197], v[110:113]
	v_mfma_f32_16x16x32_bf16 v[118:121], v[142:145], v[202:205], v[118:121]
	v_mfma_f32_16x16x32_bf16 v[114:117], v[170:173], v[202:205], v[114:117]
	v_mfma_f32_16x16x32_bf16 v[102:105], v[178:181], v[202:205], v[102:105]
	v_mfma_f32_16x16x32_bf16 v[98:101], v[186:189], v[202:205], v[98:101]
	v_mfma_f32_16x16x32_bf16 v[94:97], v[142:145], v[232:235], v[94:97]
	v_mfma_f32_16x16x32_bf16 v[90:93], v[170:173], v[232:235], v[90:93]
	v_mfma_f32_16x16x32_bf16 v[86:89], v[178:181], v[232:235], v[86:89]
	v_mfma_f32_16x16x32_bf16 v[82:85], v[186:189], v[232:235], v[82:85]
	v_mfma_f32_16x16x32_bf16 v[78:81], v[142:145], v[240:243], v[78:81]
	v_mfma_f32_16x16x32_bf16 v[74:77], v[170:173], v[240:243], v[74:77]
	v_mfma_f32_16x16x32_bf16 v[70:73], v[178:181], v[240:243], v[70:73]
	v_mfma_f32_16x16x32_bf16 v[66:69], v[186:189], v[240:243], v[66:69]
	s_barrier
	s_setprio 0
	s_mov_b32 m0, s36
	s_or_b32 s27, s26, 0x80
	ds_read_b128 v[190:193], v141 offset:49152
	ds_read_b128 v[194:197], v141 offset:50176
	ds_read_b128 v[198:201], v141 offset:51200
	ds_read_b128 v[202:205], v141 offset:52224
	ds_read_b128 v[228:231], v141 offset:53248
	ds_read_b128 v[232:235], v141 offset:54272
	ds_read_b128 v[236:239], v141 offset:55296
	ds_read_b128 v[240:243], v141 offset:56320
	buffer_load_dwordx4 v137, s[44:47], s27 offen lds
	s_mov_b32 m0, s37
	s_add_i32 s26, s26, 0x80080
	buffer_load_dwordx4 v139, s[44:47], s27 offen lds
	s_mov_b32 m0, s68
	s_nop 0
	buffer_load_dwordx4 v137, s[44:47], s26 offen lds
	s_mov_b32 m0, s69
	s_nop 0
	buffer_load_dwordx4 v139, s[44:47], s26 offen lds
	s_mov_b32 m0, s66
	s_nop 0
	buffer_load_dwordx4 v136, s[60:63], s23 offen lds
	s_mov_b32 m0, s67
	s_nop 0
	buffer_load_dwordx4 v138, s[60:63], s23 offen lds
	s_waitcnt vmcnt(8)
	s_waitcnt lgkmcnt(0)
	s_setprio 1
	s_barrier
	v_mfma_f32_16x16x32_bf16 v[62:65], v[132:135], v[190:193], v[62:65]
	v_mfma_f32_16x16x32_bf16 v[58:61], v[154:157], v[190:193], v[58:61]
	v_mfma_f32_16x16x32_bf16 v[54:57], v[174:177], v[190:193], v[54:57]
	v_mfma_f32_16x16x32_bf16 v[50:53], v[182:185], v[190:193], v[50:53]
	v_mfma_f32_16x16x32_bf16 v[46:49], v[132:135], v[198:201], v[46:49]
	v_mfma_f32_16x16x32_bf16 v[42:45], v[154:157], v[198:201], v[42:45]
	v_mfma_f32_16x16x32_bf16 v[38:41], v[174:177], v[198:201], v[38:41]
	v_mfma_f32_16x16x32_bf16 v[34:37], v[182:185], v[198:201], v[34:37]
	v_mfma_f32_16x16x32_bf16 v[30:33], v[132:135], v[228:231], v[30:33]
	v_mfma_f32_16x16x32_bf16 v[26:29], v[154:157], v[228:231], v[26:29]
	v_mfma_f32_16x16x32_bf16 v[22:25], v[174:177], v[228:231], v[22:25]
	v_mfma_f32_16x16x32_bf16 v[18:21], v[182:185], v[228:231], v[18:21]
	v_mfma_f32_16x16x32_bf16 v[14:17], v[132:135], v[236:239], v[14:17]
	v_mfma_f32_16x16x32_bf16 v[10:13], v[154:157], v[236:239], v[10:13]
	v_mfma_f32_16x16x32_bf16 v[6:9], v[174:177], v[236:239], v[6:9]
	v_mfma_f32_16x16x32_bf16 v[2:5], v[182:185], v[236:239], v[2:5]
	v_mfma_f32_16x16x32_bf16 v[62:65], v[142:145], v[194:197], v[62:65]
	v_mfma_f32_16x16x32_bf16 v[58:61], v[170:173], v[194:197], v[58:61]
	v_mfma_f32_16x16x32_bf16 v[54:57], v[178:181], v[194:197], v[54:57]
	v_mfma_f32_16x16x32_bf16 v[50:53], v[186:189], v[194:197], v[50:53]
	v_mfma_f32_16x16x32_bf16 v[46:49], v[142:145], v[202:205], v[46:49]
	v_mfma_f32_16x16x32_bf16 v[42:45], v[170:173], v[202:205], v[42:45]
	v_mfma_f32_16x16x32_bf16 v[38:41], v[178:181], v[202:205], v[38:41]
	v_mfma_f32_16x16x32_bf16 v[34:37], v[186:189], v[202:205], v[34:37]
	v_mfma_f32_16x16x32_bf16 v[30:33], v[142:145], v[232:235], v[30:33]
	v_mfma_f32_16x16x32_bf16 v[26:29], v[170:173], v[232:235], v[26:29]
	v_mfma_f32_16x16x32_bf16 v[22:25], v[178:181], v[232:235], v[22:25]
	v_mfma_f32_16x16x32_bf16 v[18:21], v[186:189], v[232:235], v[18:21]
	v_mfma_f32_16x16x32_bf16 v[14:17], v[142:145], v[240:243], v[14:17]
	v_mfma_f32_16x16x32_bf16 v[10:13], v[170:173], v[240:243], v[10:13]
	v_mfma_f32_16x16x32_bf16 v[6:9], v[178:181], v[240:243], v[6:9]
	v_mfma_f32_16x16x32_bf16 v[2:5], v[186:189], v[240:243], v[2:5]
	s_barrier
	s_setprio 0
	s_add_i32 s22, s22, 2
	s_addk_i32 s13, 0x100
	s_addk_i32 s21, 0x100
	s_cmp_gt_u32 s22, 29
	s_cbranch_scc0 .LBB0_1589
	s_and_b64 vcc, exec, s[64:65]
	s_cbranch_vccz .LBB0_1592
	s_barrier

.LBB0_1879:
	s_lshl_b32 s18, s91, 20
	s_and_b64 s[8:9], s[48:49], exec
	s_cselect_b32 s8, s18, s95
	s_lshl_b32 s19, s92, 20
	s_and_b64 s[42:43], s[48:49], exec
	s_cselect_b32 s9, s19, s94
	s_add_i32 vcc_lo, s95, 0x80080
	s_add_i32 vcc_hi, s94, 0x100
	s_mov_b32 s94, -2
	v_add_u32_e32 v139, 0x10000, v136
	ds_read_b128 v[140:143], v139
	ds_read_b128 v[154:157], v139 offset:1024
	ds_read_b128 v[170:173], v139 offset:2048
	ds_read_b128 v[174:177], v139 offset:3072
	v_add_u32_e32 v139, 0x14000, v136
	ds_read_b128 v[178:181], v139
	ds_read_b128 v[182:185], v139 offset:1024
	ds_read_b128 v[186:189], v139 offset:2048
	ds_read_b128 v[190:193], v139 offset:3072
	s_add_i32 s42, vcc_lo, 0xfff80080
	s_cmp_eq_u32 s94, 28
	s_cselect_b32 s52, s8, s42
	s_cselect_b32 s96, s9, vcc_hi
	s_or_b32 s95, s52, 0x80
	s_mov_b32 m0, s72
	ds_read_b128 v[194:197], v137
	ds_read_b128 v[198:201], v137 offset:1024
	ds_read_b128 v[202:205], v137 offset:2048
	ds_read_b128 v[228:231], v137 offset:3072
	ds_read_b128 v[232:235], v137 offset:4096
	ds_read_b128 v[236:239], v137 offset:5120
	ds_read_b128 v[240:243], v137 offset:6144
	ds_read_b128 v[244:247], v137 offset:7168
	buffer_load_dwordx4 v132, s[60:63], vcc_lo offen lds
	s_mov_b32 m0, s47
	s_nop 0
	buffer_load_dwordx4 v134, s[60:63], vcc_lo offen lds
	s_waitcnt vmcnt(8)
	s_waitcnt lgkmcnt(0)
	s_setprio 1
	s_barrier
	v_mfma_f32_16x16x32_bf16 v[114:117], v[140:143], v[194:197], 0
	v_mfma_f32_16x16x32_bf16 v[110:113], v[170:173], v[194:197], 0
	v_mfma_f32_16x16x32_bf16 v[126:129], v[178:181], v[194:197], 0
	v_mfma_f32_16x16x32_bf16 v[122:125], v[186:189], v[194:197], 0
	v_mfma_f32_16x16x32_bf16 v[106:109], v[140:143], v[202:205], 0
	v_mfma_f32_16x16x32_bf16 v[102:105], v[170:173], v[202:205], 0
	v_mfma_f32_16x16x32_bf16 v[118:121], v[178:181], v[202:205], 0
	v_mfma_f32_16x16x32_bf16 v[98:101], v[186:189], v[202:205], 0
	v_mfma_f32_16x16x32_bf16 v[94:97], v[140:143], v[232:235], 0
	v_mfma_f32_16x16x32_bf16 v[86:89], v[170:173], v[232:235], 0
	v_mfma_f32_16x16x32_bf16 v[90:93], v[178:181], v[232:235], 0
	v_mfma_f32_16x16x32_bf16 v[82:85], v[186:189], v[232:235], 0
	v_mfma_f32_16x16x32_bf16 v[78:81], v[140:143], v[240:243], 0
	v_mfma_f32_16x16x32_bf16 v[70:73], v[170:173], v[240:243], 0
	v_mfma_f32_16x16x32_bf16 v[74:77], v[178:181], v[240:243], 0
	v_mfma_f32_16x16x32_bf16 v[66:69], v[186:189], v[240:243], 0
	v_mfma_f32_16x16x32_bf16 v[114:117], v[154:157], v[198:201], v[114:117]
	v_mfma_f32_16x16x32_bf16 v[110:113], v[174:177], v[198:201], v[110:113]
	v_mfma_f32_16x16x32_bf16 v[126:129], v[182:185], v[198:201], v[126:129]
	v_mfma_f32_16x16x32_bf16 v[122:125], v[190:193], v[198:201], v[122:125]
	v_mfma_f32_16x16x32_bf16 v[106:109], v[154:157], v[228:231], v[106:109]
	v_mfma_f32_16x16x32_bf16 v[102:105], v[174:177], v[228:231], v[102:105]
	v_mfma_f32_16x16x32_bf16 v[118:121], v[182:185], v[228:231], v[118:121]
	v_mfma_f32_16x16x32_bf16 v[98:101], v[190:193], v[228:231], v[98:101]
	v_mfma_f32_16x16x32_bf16 v[94:97], v[154:157], v[236:239], v[94:97]
	v_mfma_f32_16x16x32_bf16 v[86:89], v[174:177], v[236:239], v[86:89]
	v_mfma_f32_16x16x32_bf16 v[90:93], v[182:185], v[236:239], v[90:93]
	v_mfma_f32_16x16x32_bf16 v[82:85], v[190:193], v[236:239], v[82:85]
	v_mfma_f32_16x16x32_bf16 v[78:81], v[154:157], v[244:247], v[78:81]
	v_mfma_f32_16x16x32_bf16 v[70:73], v[174:177], v[244:247], v[70:73]
	v_mfma_f32_16x16x32_bf16 v[74:77], v[182:185], v[244:247], v[74:77]
	v_mfma_f32_16x16x32_bf16 v[66:69], v[190:193], v[244:247], v[66:69]
	s_barrier
	s_setprio 0
	s_mov_b32 m0, s13
	s_mov_b32 s42, s62
	s_mov_b32 s43, s63
	ds_read_b128 v[194:197], v137 offset:16384
	ds_read_b128 v[198:201], v137 offset:17408
	ds_read_b128 v[202:205], v137 offset:18432
	ds_read_b128 v[228:231], v137 offset:19456
	ds_read_b128 v[232:235], v137 offset:20480
	ds_read_b128 v[236:239], v137 offset:21504
	ds_read_b128 v[240:243], v137 offset:22528
	ds_read_b128 v[244:247], v137 offset:23552
	buffer_load_dwordx4 v133, s[40:43], s96 offen lds
	s_mov_b32 m0, s14
	s_add_i32 s53, s96, 0x80000
	buffer_load_dwordx4 v135, s[40:43], s96 offen lds
	s_mov_b32 m0, s15
	s_nop 0
	buffer_load_dwordx4 v133, s[40:43], s53 offen lds
	s_mov_b32 m0, s16
	s_nop 0
	buffer_load_dwordx4 v135, s[40:43], s53 offen lds
	s_mov_b32 m0, s2
	s_nop 0
	buffer_load_dwordx4 v132, s[60:63], s52 offen lds
	s_mov_b32 m0, s21
	s_nop 0
	buffer_load_dwordx4 v134, s[60:63], s52 offen lds
	s_waitcnt vmcnt(8)
	s_waitcnt lgkmcnt(0)
	s_setprio 1
	s_barrier
	v_mfma_f32_16x16x32_bf16 v[62:65], v[140:143], v[194:197], 0
	v_mfma_f32_16x16x32_bf16 v[54:57], v[170:173], v[194:197], 0
	v_mfma_f32_16x16x32_bf16 v[58:61], v[178:181], v[194:197], 0
	v_mfma_f32_16x16x32_bf16 v[50:53], v[186:189], v[194:197], 0
	v_mfma_f32_16x16x32_bf16 v[46:49], v[140:143], v[202:205], 0
	v_mfma_f32_16x16x32_bf16 v[38:41], v[170:173], v[202:205], 0
	v_mfma_f32_16x16x32_bf16 v[42:45], v[178:181], v[202:205], 0
	v_mfma_f32_16x16x32_bf16 v[34:37], v[186:189], v[202:205], 0
	v_mfma_f32_16x16x32_bf16 v[30:33], v[140:143], v[232:235], 0
	v_mfma_f32_16x16x32_bf16 v[22:25], v[170:173], v[232:235], 0
	v_mfma_f32_16x16x32_bf16 v[26:29], v[178:181], v[232:235], 0
	v_mfma_f32_16x16x32_bf16 v[18:21], v[186:189], v[232:235], 0
	v_mfma_f32_16x16x32_bf16 v[14:17], v[140:143], v[240:243], 0
	v_mfma_f32_16x16x32_bf16 v[6:9], v[170:173], v[240:243], 0
	v_mfma_f32_16x16x32_bf16 v[10:13], v[178:181], v[240:243], 0
	v_mfma_f32_16x16x32_bf16 v[2:5], v[186:189], v[240:243], 0
	v_mfma_f32_16x16x32_bf16 v[62:65], v[154:157], v[198:201], v[62:65]
	v_mfma_f32_16x16x32_bf16 v[54:57], v[174:177], v[198:201], v[54:57]
	v_mfma_f32_16x16x32_bf16 v[58:61], v[182:185], v[198:201], v[58:61]
	v_mfma_f32_16x16x32_bf16 v[50:53], v[190:193], v[198:201], v[50:53]
	v_mfma_f32_16x16x32_bf16 v[46:49], v[154:157], v[228:231], v[46:49]
	v_mfma_f32_16x16x32_bf16 v[38:41], v[174:177], v[228:231], v[38:41]
	v_mfma_f32_16x16x32_bf16 v[42:45], v[182:185], v[228:231], v[42:45]
	v_mfma_f32_16x16x32_bf16 v[34:37], v[190:193], v[228:231], v[34:37]
	v_mfma_f32_16x16x32_bf16 v[30:33], v[154:157], v[236:239], v[30:33]
	v_mfma_f32_16x16x32_bf16 v[22:25], v[174:177], v[236:239], v[22:25]
	v_mfma_f32_16x16x32_bf16 v[26:29], v[182:185], v[236:239], v[26:29]
	v_mfma_f32_16x16x32_bf16 v[18:21], v[190:193], v[236:239], v[18:21]
	v_mfma_f32_16x16x32_bf16 v[14:17], v[154:157], v[244:247], v[14:17]
	v_mfma_f32_16x16x32_bf16 v[6:9], v[174:177], v[244:247], v[6:9]
	v_mfma_f32_16x16x32_bf16 v[10:13], v[182:185], v[244:247], v[10:13]
	v_mfma_f32_16x16x32_bf16 v[2:5], v[190:193], v[244:247], v[2:5]
	s_barrier
	s_setprio 0
	v_add_u32_e32 v139, 0x18000, v136
	ds_read_b128 v[140:143], v139
	ds_read_b128 v[154:157], v139 offset:1024
	ds_read_b128 v[170:173], v139 offset:2048
	ds_read_b128 v[174:177], v139 offset:3072
	v_add_u32_e32 v139, 0x1c000, v136
	ds_read_b128 v[178:181], v139
	ds_read_b128 v[182:185], v139 offset:1024
	ds_read_b128 v[186:189], v139 offset:2048
	ds_read_b128 v[190:193], v139 offset:3072
	s_add_i32 s52, s52, 0x80000
	s_mov_b32 m0, s23
	ds_read_b128 v[194:197], v137 offset:32768
	ds_read_b128 v[198:201], v137 offset:33792
	ds_read_b128 v[202:205], v137 offset:34816
	ds_read_b128 v[228:231], v137 offset:35840
	ds_read_b128 v[232:235], v137 offset:36864
	ds_read_b128 v[236:239], v137 offset:37888
	ds_read_b128 v[240:243], v137 offset:38912
	ds_read_b128 v[244:247], v137 offset:39936
	buffer_load_dwordx4 v132, s[60:63], s52 offen lds
	s_mov_b32 m0, s24
	s_nop 0
	buffer_load_dwordx4 v134, s[60:63], s52 offen lds
	s_waitcnt vmcnt(8)
	s_waitcnt lgkmcnt(0)
	s_setprio 1
	s_barrier
	v_mfma_f32_16x16x32_bf16 v[114:117], v[140:143], v[194:197], v[114:117]
	v_mfma_f32_16x16x32_bf16 v[110:113], v[170:173], v[194:197], v[110:113]
	v_mfma_f32_16x16x32_bf16 v[126:129], v[178:181], v[194:197], v[126:129]
	v_mfma_f32_16x16x32_bf16 v[122:125], v[186:189], v[194:197], v[122:125]
	v_mfma_f32_16x16x32_bf16 v[106:109], v[140:143], v[202:205], v[106:109]
	v_mfma_f32_16x16x32_bf16 v[102:105], v[170:173], v[202:205], v[102:105]
	v_mfma_f32_16x16x32_bf16 v[118:121], v[178:181], v[202:205], v[118:121]
	v_mfma_f32_16x16x32_bf16 v[98:101], v[186:189], v[202:205], v[98:101]
	v_mfma_f32_16x16x32_bf16 v[94:97], v[140:143], v[232:235], v[94:97]
	v_mfma_f32_16x16x32_bf16 v[86:89], v[170:173], v[232:235], v[86:89]
	v_mfma_f32_16x16x32_bf16 v[90:93], v[178:181], v[232:235], v[90:93]
	v_mfma_f32_16x16x32_bf16 v[82:85], v[186:189], v[232:235], v[82:85]
	v_mfma_f32_16x16x32_bf16 v[78:81], v[140:143], v[240:243], v[78:81]
	v_mfma_f32_16x16x32_bf16 v[70:73], v[170:173], v[240:243], v[70:73]
	v_mfma_f32_16x16x32_bf16 v[74:77], v[178:181], v[240:243], v[74:77]
	v_mfma_f32_16x16x32_bf16 v[66:69], v[186:189], v[240:243], v[66:69]
	v_mfma_f32_16x16x32_bf16 v[114:117], v[154:157], v[198:201], v[114:117]
	v_mfma_f32_16x16x32_bf16 v[110:113], v[174:177], v[198:201], v[110:113]
	v_mfma_f32_16x16x32_bf16 v[126:129], v[182:185], v[198:201], v[126:129]
	v_mfma_f32_16x16x32_bf16 v[122:125], v[190:193], v[198:201], v[122:125]
	v_mfma_f32_16x16x32_bf16 v[106:109], v[154:157], v[228:231], v[106:109]
	v_mfma_f32_16x16x32_bf16 v[102:105], v[174:177], v[228:231], v[102:105]
	v_mfma_f32_16x16x32_bf16 v[118:121], v[182:185], v[228:231], v[118:121]
	v_mfma_f32_16x16x32_bf16 v[98:101], v[190:193], v[228:231], v[98:101]
	v_mfma_f32_16x16x32_bf16 v[94:97], v[154:157], v[236:239], v[94:97]
	v_mfma_f32_16x16x32_bf16 v[86:89], v[174:177], v[236:239], v[86:89]
	v_mfma_f32_16x16x32_bf16 v[90:93], v[182:185], v[236:239], v[90:93]
	v_mfma_f32_16x16x32_bf16 v[82:85], v[190:193], v[236:239], v[82:85]
	v_mfma_f32_16x16x32_bf16 v[78:81], v[154:157], v[244:247], v[78:81]
	v_mfma_f32_16x16x32_bf16 v[70:73], v[174:177], v[244:247], v[70:73]
	v_mfma_f32_16x16x32_bf16 v[74:77], v[182:185], v[244:247], v[74:77]
	v_mfma_f32_16x16x32_bf16 v[66:69], v[190:193], v[244:247], v[66:69]
	s_barrier
	s_setprio 0
	s_mov_b32 m0, s31
	s_or_b32 s52, s96, 0x80
	ds_read_b128 v[194:197], v137 offset:49152
	ds_read_b128 v[198:201], v137 offset:50176
	ds_read_b128 v[202:205], v137 offset:51200
	ds_read_b128 v[228:231], v137 offset:52224
	ds_read_b128 v[232:235], v137 offset:53248
	ds_read_b128 v[236:239], v137 offset:54272
	ds_read_b128 v[240:243], v137 offset:55296
	ds_read_b128 v[244:247], v137 offset:56320
	buffer_load_dwordx4 v133, s[40:43], s52 offen lds
	s_mov_b32 m0, s33
	s_add_i32 s96, s96, 0x80080
	buffer_load_dwordx4 v135, s[40:43], s52 offen lds
	s_mov_b32 m0, s36
	s_nop 0
	buffer_load_dwordx4 v133, s[40:43], s96 offen lds
	s_mov_b32 m0, s37
	s_nop 0
	buffer_load_dwordx4 v135, s[40:43], s96 offen lds
	s_mov_b32 m0, s34
	s_nop 0
	buffer_load_dwordx4 v132, s[60:63], s95 offen lds
	s_mov_b32 m0, s35
	s_nop 0
	buffer_load_dwordx4 v134, s[60:63], s95 offen lds
	s_waitcnt vmcnt(8)
	s_waitcnt lgkmcnt(0)
	s_setprio 1
	s_barrier
	v_mfma_f32_16x16x32_bf16 v[62:65], v[140:143], v[194:197], v[62:65]
	v_mfma_f32_16x16x32_bf16 v[54:57], v[170:173], v[194:197], v[54:57]
	v_mfma_f32_16x16x32_bf16 v[58:61], v[178:181], v[194:197], v[58:61]
	v_mfma_f32_16x16x32_bf16 v[50:53], v[186:189], v[194:197], v[50:53]
	v_mfma_f32_16x16x32_bf16 v[46:49], v[140:143], v[202:205], v[46:49]
	v_mfma_f32_16x16x32_bf16 v[38:41], v[170:173], v[202:205], v[38:41]
	v_mfma_f32_16x16x32_bf16 v[42:45], v[178:181], v[202:205], v[42:45]
	v_mfma_f32_16x16x32_bf16 v[34:37], v[186:189], v[202:205], v[34:37]
	v_mfma_f32_16x16x32_bf16 v[30:33], v[140:143], v[232:235], v[30:33]
	v_mfma_f32_16x16x32_bf16 v[22:25], v[170:173], v[232:235], v[22:25]
	v_mfma_f32_16x16x32_bf16 v[26:29], v[178:181], v[232:235], v[26:29]
	v_mfma_f32_16x16x32_bf16 v[18:21], v[186:189], v[232:235], v[18:21]
	v_mfma_f32_16x16x32_bf16 v[14:17], v[140:143], v[240:243], v[14:17]
	v_mfma_f32_16x16x32_bf16 v[6:9], v[170:173], v[240:243], v[6:9]
	v_mfma_f32_16x16x32_bf16 v[10:13], v[178:181], v[240:243], v[10:13]
	v_mfma_f32_16x16x32_bf16 v[2:5], v[186:189], v[240:243], v[2:5]
	v_mfma_f32_16x16x32_bf16 v[62:65], v[154:157], v[198:201], v[62:65]
	v_mfma_f32_16x16x32_bf16 v[54:57], v[174:177], v[198:201], v[54:57]
	v_mfma_f32_16x16x32_bf16 v[58:61], v[182:185], v[198:201], v[58:61]
	v_mfma_f32_16x16x32_bf16 v[50:53], v[190:193], v[198:201], v[50:53]
	v_mfma_f32_16x16x32_bf16 v[46:49], v[154:157], v[228:231], v[46:49]
	v_mfma_f32_16x16x32_bf16 v[38:41], v[174:177], v[228:231], v[38:41]
	v_mfma_f32_16x16x32_bf16 v[42:45], v[182:185], v[228:231], v[42:45]
	v_mfma_f32_16x16x32_bf16 v[34:37], v[190:193], v[228:231], v[34:37]
	v_mfma_f32_16x16x32_bf16 v[30:33], v[154:157], v[236:239], v[30:33]
	v_mfma_f32_16x16x32_bf16 v[22:25], v[174:177], v[236:239], v[22:25]
	v_mfma_f32_16x16x32_bf16 v[26:29], v[182:185], v[236:239], v[26:29]
	v_mfma_f32_16x16x32_bf16 v[18:21], v[190:193], v[236:239], v[18:21]
	v_mfma_f32_16x16x32_bf16 v[14:17], v[154:157], v[244:247], v[14:17]
	v_mfma_f32_16x16x32_bf16 v[6:9], v[174:177], v[244:247], v[6:9]
	v_mfma_f32_16x16x32_bf16 v[10:13], v[182:185], v[244:247], v[10:13]
	v_mfma_f32_16x16x32_bf16 v[2:5], v[190:193], v[244:247], v[2:5]
	s_barrier
	s_setprio 0
	s_add_i32 s94, s94, 2
	s_addk_i32 vcc_lo, 0x100
	s_addk_i32 vcc_hi, 0x100
	s_cmp_gt_u32 s94, 29
.LBB0_1880:
	v_add_u32_e32 v139, 0x10000, v136
	ds_read_b128 v[140:143], v139
	ds_read_b128 v[154:157], v139 offset:1024
	ds_read_b128 v[170:173], v139 offset:2048
	ds_read_b128 v[174:177], v139 offset:3072
	v_add_u32_e32 v139, 0x14000, v136
	ds_read_b128 v[178:181], v139
	ds_read_b128 v[182:185], v139 offset:1024
	ds_read_b128 v[186:189], v139 offset:2048
	ds_read_b128 v[190:193], v139 offset:3072
	s_add_i32 s42, vcc_lo, 0xfff80080
	s_cmp_eq_u32 s94, 28
	s_cselect_b32 s52, s8, s42
	s_cselect_b32 s96, s9, vcc_hi
	s_or_b32 s95, s52, 0x80
	s_mov_b32 m0, s72
	ds_read_b128 v[194:197], v137
	ds_read_b128 v[198:201], v137 offset:1024
	ds_read_b128 v[202:205], v137 offset:2048
	ds_read_b128 v[228:231], v137 offset:3072
	ds_read_b128 v[232:235], v137 offset:4096
	ds_read_b128 v[236:239], v137 offset:5120
	ds_read_b128 v[240:243], v137 offset:6144
	ds_read_b128 v[244:247], v137 offset:7168
	buffer_load_dwordx4 v132, s[60:63], vcc_lo offen lds
	s_mov_b32 m0, s47
	s_nop 0
	buffer_load_dwordx4 v134, s[60:63], vcc_lo offen lds
	s_waitcnt vmcnt(8)
	s_waitcnt lgkmcnt(0)
	s_setprio 1
	s_barrier
	v_mfma_f32_16x16x32_bf16 v[114:117], v[140:143], v[194:197], v[114:117]
	v_mfma_f32_16x16x32_bf16 v[110:113], v[170:173], v[194:197], v[110:113]
	v_mfma_f32_16x16x32_bf16 v[126:129], v[178:181], v[194:197], v[126:129]
	v_mfma_f32_16x16x32_bf16 v[122:125], v[186:189], v[194:197], v[122:125]
	v_mfma_f32_16x16x32_bf16 v[106:109], v[140:143], v[202:205], v[106:109]
	v_mfma_f32_16x16x32_bf16 v[102:105], v[170:173], v[202:205], v[102:105]
	v_mfma_f32_16x16x32_bf16 v[118:121], v[178:181], v[202:205], v[118:121]
	v_mfma_f32_16x16x32_bf16 v[98:101], v[186:189], v[202:205], v[98:101]
	v_mfma_f32_16x16x32_bf16 v[94:97], v[140:143], v[232:235], v[94:97]
	v_mfma_f32_16x16x32_bf16 v[86:89], v[170:173], v[232:235], v[86:89]
	v_mfma_f32_16x16x32_bf16 v[90:93], v[178:181], v[232:235], v[90:93]
	v_mfma_f32_16x16x32_bf16 v[82:85], v[186:189], v[232:235], v[82:85]
	v_mfma_f32_16x16x32_bf16 v[78:81], v[140:143], v[240:243], v[78:81]
	v_mfma_f32_16x16x32_bf16 v[70:73], v[170:173], v[240:243], v[70:73]
	v_mfma_f32_16x16x32_bf16 v[74:77], v[178:181], v[240:243], v[74:77]
	v_mfma_f32_16x16x32_bf16 v[66:69], v[186:189], v[240:243], v[66:69]
	v_mfma_f32_16x16x32_bf16 v[114:117], v[154:157], v[198:201], v[114:117]
	v_mfma_f32_16x16x32_bf16 v[110:113], v[174:177], v[198:201], v[110:113]
	v_mfma_f32_16x16x32_bf16 v[126:129], v[182:185], v[198:201], v[126:129]
	v_mfma_f32_16x16x32_bf16 v[122:125], v[190:193], v[198:201], v[122:125]
	v_mfma_f32_16x16x32_bf16 v[106:109], v[154:157], v[228:231], v[106:109]
	v_mfma_f32_16x16x32_bf16 v[102:105], v[174:177], v[228:231], v[102:105]
	v_mfma_f32_16x16x32_bf16 v[118:121], v[182:185], v[228:231], v[118:121]
	v_mfma_f32_16x16x32_bf16 v[98:101], v[190:193], v[228:231], v[98:101]
	v_mfma_f32_16x16x32_bf16 v[94:97], v[154:157], v[236:239], v[94:97]
	v_mfma_f32_16x16x32_bf16 v[86:89], v[174:177], v[236:239], v[86:89]
	v_mfma_f32_16x16x32_bf16 v[90:93], v[182:185], v[236:239], v[90:93]
	v_mfma_f32_16x16x32_bf16 v[82:85], v[190:193], v[236:239], v[82:85]
	v_mfma_f32_16x16x32_bf16 v[78:81], v[154:157], v[244:247], v[78:81]
	v_mfma_f32_16x16x32_bf16 v[70:73], v[174:177], v[244:247], v[70:73]
	v_mfma_f32_16x16x32_bf16 v[74:77], v[182:185], v[244:247], v[74:77]
	v_mfma_f32_16x16x32_bf16 v[66:69], v[190:193], v[244:247], v[66:69]
	s_barrier
	s_setprio 0
	s_mov_b32 m0, s13
	s_mov_b32 s42, s62
	s_mov_b32 s43, s63
	ds_read_b128 v[194:197], v137 offset:16384
	ds_read_b128 v[198:201], v137 offset:17408
	ds_read_b128 v[202:205], v137 offset:18432
	ds_read_b128 v[228:231], v137 offset:19456
	ds_read_b128 v[232:235], v137 offset:20480
	ds_read_b128 v[236:239], v137 offset:21504
	ds_read_b128 v[240:243], v137 offset:22528
	ds_read_b128 v[244:247], v137 offset:23552
	buffer_load_dwordx4 v133, s[40:43], s96 offen lds
	s_mov_b32 m0, s14
	s_add_i32 s53, s96, 0x80000
	buffer_load_dwordx4 v135, s[40:43], s96 offen lds
	s_mov_b32 m0, s15
	s_nop 0
	buffer_load_dwordx4 v133, s[40:43], s53 offen lds
	s_mov_b32 m0, s16
	s_nop 0
	buffer_load_dwordx4 v135, s[40:43], s53 offen lds
	s_mov_b32 m0, s2
	s_nop 0
	buffer_load_dwordx4 v132, s[60:63], s52 offen lds
	s_mov_b32 m0, s21
	s_nop 0
	buffer_load_dwordx4 v134, s[60:63], s52 offen lds
	s_waitcnt vmcnt(8)
	s_waitcnt lgkmcnt(0)
	s_setprio 1
	s_barrier
	v_mfma_f32_16x16x32_bf16 v[62:65], v[140:143], v[194:197], v[62:65]
	v_mfma_f32_16x16x32_bf16 v[54:57], v[170:173], v[194:197], v[54:57]
	v_mfma_f32_16x16x32_bf16 v[58:61], v[178:181], v[194:197], v[58:61]
	v_mfma_f32_16x16x32_bf16 v[50:53], v[186:189], v[194:197], v[50:53]
	v_mfma_f32_16x16x32_bf16 v[46:49], v[140:143], v[202:205], v[46:49]
	v_mfma_f32_16x16x32_bf16 v[38:41], v[170:173], v[202:205], v[38:41]
	v_mfma_f32_16x16x32_bf16 v[42:45], v[178:181], v[202:205], v[42:45]
	v_mfma_f32_16x16x32_bf16 v[34:37], v[186:189], v[202:205], v[34:37]
	v_mfma_f32_16x16x32_bf16 v[30:33], v[140:143], v[232:235], v[30:33]
	v_mfma_f32_16x16x32_bf16 v[22:25], v[170:173], v[232:235], v[22:25]
	v_mfma_f32_16x16x32_bf16 v[26:29], v[178:181], v[232:235], v[26:29]
	v_mfma_f32_16x16x32_bf16 v[18:21], v[186:189], v[232:235], v[18:21]
	v_mfma_f32_16x16x32_bf16 v[14:17], v[140:143], v[240:243], v[14:17]
	v_mfma_f32_16x16x32_bf16 v[6:9], v[170:173], v[240:243], v[6:9]
	v_mfma_f32_16x16x32_bf16 v[10:13], v[178:181], v[240:243], v[10:13]
	v_mfma_f32_16x16x32_bf16 v[2:5], v[186:189], v[240:243], v[2:5]
	v_mfma_f32_16x16x32_bf16 v[62:65], v[154:157], v[198:201], v[62:65]
	v_mfma_f32_16x16x32_bf16 v[54:57], v[174:177], v[198:201], v[54:57]
	v_mfma_f32_16x16x32_bf16 v[58:61], v[182:185], v[198:201], v[58:61]
	v_mfma_f32_16x16x32_bf16 v[50:53], v[190:193], v[198:201], v[50:53]
	v_mfma_f32_16x16x32_bf16 v[46:49], v[154:157], v[228:231], v[46:49]
	v_mfma_f32_16x16x32_bf16 v[38:41], v[174:177], v[228:231], v[38:41]
	v_mfma_f32_16x16x32_bf16 v[42:45], v[182:185], v[228:231], v[42:45]
	v_mfma_f32_16x16x32_bf16 v[34:37], v[190:193], v[228:231], v[34:37]
	v_mfma_f32_16x16x32_bf16 v[30:33], v[154:157], v[236:239], v[30:33]
	v_mfma_f32_16x16x32_bf16 v[22:25], v[174:177], v[236:239], v[22:25]
	v_mfma_f32_16x16x32_bf16 v[26:29], v[182:185], v[236:239], v[26:29]
	v_mfma_f32_16x16x32_bf16 v[18:21], v[190:193], v[236:239], v[18:21]
	v_mfma_f32_16x16x32_bf16 v[14:17], v[154:157], v[244:247], v[14:17]
	v_mfma_f32_16x16x32_bf16 v[6:9], v[174:177], v[244:247], v[6:9]
	v_mfma_f32_16x16x32_bf16 v[10:13], v[182:185], v[244:247], v[10:13]
	v_mfma_f32_16x16x32_bf16 v[2:5], v[190:193], v[244:247], v[2:5]
	s_barrier
	s_setprio 0
	v_add_u32_e32 v139, 0x18000, v136
	ds_read_b128 v[140:143], v139
	ds_read_b128 v[154:157], v139 offset:1024
	ds_read_b128 v[170:173], v139 offset:2048
	ds_read_b128 v[174:177], v139 offset:3072
	v_add_u32_e32 v139, 0x1c000, v136
	ds_read_b128 v[178:181], v139
	ds_read_b128 v[182:185], v139 offset:1024
	ds_read_b128 v[186:189], v139 offset:2048
	ds_read_b128 v[190:193], v139 offset:3072
	s_add_i32 s52, s52, 0x80000
	s_mov_b32 m0, s23
	ds_read_b128 v[194:197], v137 offset:32768
	ds_read_b128 v[198:201], v137 offset:33792
	ds_read_b128 v[202:205], v137 offset:34816
	ds_read_b128 v[228:231], v137 offset:35840
	ds_read_b128 v[232:235], v137 offset:36864
	ds_read_b128 v[236:239], v137 offset:37888
	ds_read_b128 v[240:243], v137 offset:38912
	ds_read_b128 v[244:247], v137 offset:39936
	buffer_load_dwordx4 v132, s[60:63], s52 offen lds
	s_mov_b32 m0, s24
	s_nop 0
	buffer_load_dwordx4 v134, s[60:63], s52 offen lds
	s_waitcnt vmcnt(8)
	s_waitcnt lgkmcnt(0)
	s_setprio 1
	s_barrier
	v_mfma_f32_16x16x32_bf16 v[114:117], v[140:143], v[194:197], v[114:117]
	v_mfma_f32_16x16x32_bf16 v[110:113], v[170:173], v[194:197], v[110:113]
	v_mfma_f32_16x16x32_bf16 v[126:129], v[178:181], v[194:197], v[126:129]
	v_mfma_f32_16x16x32_bf16 v[122:125], v[186:189], v[194:197], v[122:125]
	v_mfma_f32_16x16x32_bf16 v[106:109], v[140:143], v[202:205], v[106:109]
	v_mfma_f32_16x16x32_bf16 v[102:105], v[170:173], v[202:205], v[102:105]
	v_mfma_f32_16x16x32_bf16 v[118:121], v[178:181], v[202:205], v[118:121]
	v_mfma_f32_16x16x32_bf16 v[98:101], v[186:189], v[202:205], v[98:101]
	v_mfma_f32_16x16x32_bf16 v[94:97], v[140:143], v[232:235], v[94:97]
	v_mfma_f32_16x16x32_bf16 v[86:89], v[170:173], v[232:235], v[86:89]
	v_mfma_f32_16x16x32_bf16 v[90:93], v[178:181], v[232:235], v[90:93]
	v_mfma_f32_16x16x32_bf16 v[82:85], v[186:189], v[232:235], v[82:85]
	v_mfma_f32_16x16x32_bf16 v[78:81], v[140:143], v[240:243], v[78:81]
	v_mfma_f32_16x16x32_bf16 v[70:73], v[170:173], v[240:243], v[70:73]
	v_mfma_f32_16x16x32_bf16 v[74:77], v[178:181], v[240:243], v[74:77]
	v_mfma_f32_16x16x32_bf16 v[66:69], v[186:189], v[240:243], v[66:69]
	v_mfma_f32_16x16x32_bf16 v[114:117], v[154:157], v[198:201], v[114:117]
	v_mfma_f32_16x16x32_bf16 v[110:113], v[174:177], v[198:201], v[110:113]
	v_mfma_f32_16x16x32_bf16 v[126:129], v[182:185], v[198:201], v[126:129]
	v_mfma_f32_16x16x32_bf16 v[122:125], v[190:193], v[198:201], v[122:125]
	v_mfma_f32_16x16x32_bf16 v[106:109], v[154:157], v[228:231], v[106:109]
	v_mfma_f32_16x16x32_bf16 v[102:105], v[174:177], v[228:231], v[102:105]
	v_mfma_f32_16x16x32_bf16 v[118:121], v[182:185], v[228:231], v[118:121]
	v_mfma_f32_16x16x32_bf16 v[98:101], v[190:193], v[228:231], v[98:101]
	v_mfma_f32_16x16x32_bf16 v[94:97], v[154:157], v[236:239], v[94:97]
	v_mfma_f32_16x16x32_bf16 v[86:89], v[174:177], v[236:239], v[86:89]
	v_mfma_f32_16x16x32_bf16 v[90:93], v[182:185], v[236:239], v[90:93]
	v_mfma_f32_16x16x32_bf16 v[82:85], v[190:193], v[236:239], v[82:85]
	v_mfma_f32_16x16x32_bf16 v[78:81], v[154:157], v[244:247], v[78:81]
	v_mfma_f32_16x16x32_bf16 v[70:73], v[174:177], v[244:247], v[70:73]
	v_mfma_f32_16x16x32_bf16 v[74:77], v[182:185], v[244:247], v[74:77]
	v_mfma_f32_16x16x32_bf16 v[66:69], v[190:193], v[244:247], v[66:69]
	s_barrier
	s_setprio 0
	s_mov_b32 m0, s31
	s_or_b32 s52, s96, 0x80
	ds_read_b128 v[194:197], v137 offset:49152
	ds_read_b128 v[198:201], v137 offset:50176
	ds_read_b128 v[202:205], v137 offset:51200
	ds_read_b128 v[228:231], v137 offset:52224
	ds_read_b128 v[232:235], v137 offset:53248
	ds_read_b128 v[236:239], v137 offset:54272
	ds_read_b128 v[240:243], v137 offset:55296
	ds_read_b128 v[244:247], v137 offset:56320
	buffer_load_dwordx4 v133, s[40:43], s52 offen lds
	s_mov_b32 m0, s33
	s_add_i32 s96, s96, 0x80080
	buffer_load_dwordx4 v135, s[40:43], s52 offen lds
	s_mov_b32 m0, s36
	s_nop 0
	buffer_load_dwordx4 v133, s[40:43], s96 offen lds
	s_mov_b32 m0, s37
	s_nop 0
	buffer_load_dwordx4 v135, s[40:43], s96 offen lds
	s_mov_b32 m0, s34
	s_nop 0
	buffer_load_dwordx4 v132, s[60:63], s95 offen lds
	s_mov_b32 m0, s35
	s_nop 0
	buffer_load_dwordx4 v134, s[60:63], s95 offen lds
	s_waitcnt vmcnt(8)
	s_waitcnt lgkmcnt(0)
	s_setprio 1
	s_barrier
	v_mfma_f32_16x16x32_bf16 v[62:65], v[140:143], v[194:197], v[62:65]
	v_mfma_f32_16x16x32_bf16 v[54:57], v[170:173], v[194:197], v[54:57]
	v_mfma_f32_16x16x32_bf16 v[58:61], v[178:181], v[194:197], v[58:61]
	v_mfma_f32_16x16x32_bf16 v[50:53], v[186:189], v[194:197], v[50:53]
	v_mfma_f32_16x16x32_bf16 v[46:49], v[140:143], v[202:205], v[46:49]
	v_mfma_f32_16x16x32_bf16 v[38:41], v[170:173], v[202:205], v[38:41]
	v_mfma_f32_16x16x32_bf16 v[42:45], v[178:181], v[202:205], v[42:45]
	v_mfma_f32_16x16x32_bf16 v[34:37], v[186:189], v[202:205], v[34:37]
	v_mfma_f32_16x16x32_bf16 v[30:33], v[140:143], v[232:235], v[30:33]
	v_mfma_f32_16x16x32_bf16 v[22:25], v[170:173], v[232:235], v[22:25]
	v_mfma_f32_16x16x32_bf16 v[26:29], v[178:181], v[232:235], v[26:29]
	v_mfma_f32_16x16x32_bf16 v[18:21], v[186:189], v[232:235], v[18:21]
	v_mfma_f32_16x16x32_bf16 v[14:17], v[140:143], v[240:243], v[14:17]
	v_mfma_f32_16x16x32_bf16 v[6:9], v[170:173], v[240:243], v[6:9]
	v_mfma_f32_16x16x32_bf16 v[10:13], v[178:181], v[240:243], v[10:13]
	v_mfma_f32_16x16x32_bf16 v[2:5], v[186:189], v[240:243], v[2:5]
	v_mfma_f32_16x16x32_bf16 v[62:65], v[154:157], v[198:201], v[62:65]
	v_mfma_f32_16x16x32_bf16 v[54:57], v[174:177], v[198:201], v[54:57]
	v_mfma_f32_16x16x32_bf16 v[58:61], v[182:185], v[198:201], v[58:61]
	v_mfma_f32_16x16x32_bf16 v[50:53], v[190:193], v[198:201], v[50:53]
	v_mfma_f32_16x16x32_bf16 v[46:49], v[154:157], v[228:231], v[46:49]
	v_mfma_f32_16x16x32_bf16 v[38:41], v[174:177], v[228:231], v[38:41]
	v_mfma_f32_16x16x32_bf16 v[42:45], v[182:185], v[228:231], v[42:45]
	v_mfma_f32_16x16x32_bf16 v[34:37], v[190:193], v[228:231], v[34:37]
	v_mfma_f32_16x16x32_bf16 v[30:33], v[154:157], v[236:239], v[30:33]
	v_mfma_f32_16x16x32_bf16 v[22:25], v[174:177], v[236:239], v[22:25]
	v_mfma_f32_16x16x32_bf16 v[26:29], v[182:185], v[236:239], v[26:29]
	v_mfma_f32_16x16x32_bf16 v[18:21], v[190:193], v[236:239], v[18:21]
	v_mfma_f32_16x16x32_bf16 v[14:17], v[154:157], v[244:247], v[14:17]
	v_mfma_f32_16x16x32_bf16 v[6:9], v[174:177], v[244:247], v[6:9]
	v_mfma_f32_16x16x32_bf16 v[10:13], v[182:185], v[244:247], v[10:13]
	v_mfma_f32_16x16x32_bf16 v[2:5], v[190:193], v[244:247], v[2:5]
	s_barrier
	s_setprio 0
	s_add_i32 s94, s94, 2
	s_addk_i32 vcc_lo, 0x100
	s_addk_i32 vcc_hi, 0x100
	s_cmp_gt_u32 s94, 29
	s_cbranch_scc0 .LBB0_1880
	s_and_b64 vcc, exec, s[64:65]
	s_cbranch_vccz .LBB0_1883
	s_barrier

.LBB0_2155:
	s_mul_i32 s49, s48, 0x2c0000
	s_and_b64 s[8:9], s[42:43], exec
	s_mul_i32 s23, s15, 0x2c0000
	s_cselect_b32 s8, s49, s21
	s_cselect_b32 s9, s23, s13
	s_addk_i32 s13, 0x100
	s_add_i32 s21, s21, 0xc000
	s_mov_b32 s22, -2
	s_waitcnt lgkmcnt(0)
	v_add_u32_e32 v170, 0x10000, v140
	v_add_u32_e32 v186, 0x14000, v140
	ds_read_b128 v[132:135], v170
	ds_read_b128 v[142:145], v170 offset:1024
	ds_read_b128 v[154:157], v170 offset:2048
	ds_read_b128 v[170:173], v170 offset:3072
	ds_read_b128 v[174:177], v186
	ds_read_b128 v[178:181], v186 offset:1024
	ds_read_b128 v[182:185], v186 offset:2048
	ds_read_b128 v[186:189], v186 offset:3072
	s_add_i32 s26, s21, 0x4000
	s_cmpk_eq_i32 s22, 0x54
	s_cselect_b32 s52, s8, s26
	s_cselect_b32 s27, s9, s13
	s_or_b32 s26, s52, 0x8000
	s_mov_b32 m0, s84
	ds_read_b128 v[190:193], v141
	ds_read_b128 v[194:197], v141 offset:1024
	ds_read_b128 v[198:201], v141 offset:2048
	ds_read_b128 v[202:205], v141 offset:3072
	ds_read_b128 v[228:231], v141 offset:4096
	ds_read_b128 v[232:235], v141 offset:5120
	ds_read_b128 v[236:239], v141 offset:6144
	ds_read_b128 v[240:243], v141 offset:7168
	buffer_load_dwordx4 v136, s[60:63], s21 offen lds
	s_mov_b32 m0, s16
	s_nop 0
	buffer_load_dwordx4 v138, s[60:63], s21 offen lds
	s_waitcnt vmcnt(8)
	s_waitcnt lgkmcnt(0)
	s_setprio 1
	s_barrier
	v_mfma_f32_16x16x32_bf16 v[126:129], v[132:135], v[190:193], 0
	v_mfma_f32_16x16x32_bf16 v[106:109], v[154:157], v[190:193], 0
	v_mfma_f32_16x16x32_bf16 v[122:125], v[174:177], v[190:193], 0
	v_mfma_f32_16x16x32_bf16 v[110:113], v[182:185], v[190:193], 0
	v_mfma_f32_16x16x32_bf16 v[118:121], v[132:135], v[198:201], 0
	v_mfma_f32_16x16x32_bf16 v[114:117], v[154:157], v[198:201], 0
	v_mfma_f32_16x16x32_bf16 v[102:105], v[174:177], v[198:201], 0
	v_mfma_f32_16x16x32_bf16 v[98:101], v[182:185], v[198:201], 0
	v_mfma_f32_16x16x32_bf16 v[94:97], v[132:135], v[228:231], 0
	v_mfma_f32_16x16x32_bf16 v[90:93], v[154:157], v[228:231], 0
	v_mfma_f32_16x16x32_bf16 v[86:89], v[174:177], v[228:231], 0
	v_mfma_f32_16x16x32_bf16 v[82:85], v[182:185], v[228:231], 0
	v_mfma_f32_16x16x32_bf16 v[78:81], v[132:135], v[236:239], 0
	v_mfma_f32_16x16x32_bf16 v[74:77], v[154:157], v[236:239], 0
	v_mfma_f32_16x16x32_bf16 v[70:73], v[174:177], v[236:239], 0
	v_mfma_f32_16x16x32_bf16 v[66:69], v[182:185], v[236:239], 0
	v_mfma_f32_16x16x32_bf16 v[126:129], v[142:145], v[194:197], v[126:129]
	v_mfma_f32_16x16x32_bf16 v[106:109], v[170:173], v[194:197], v[106:109]
	v_mfma_f32_16x16x32_bf16 v[122:125], v[178:181], v[194:197], v[122:125]
	v_mfma_f32_16x16x32_bf16 v[110:113], v[186:189], v[194:197], v[110:113]
	v_mfma_f32_16x16x32_bf16 v[118:121], v[142:145], v[202:205], v[118:121]
	v_mfma_f32_16x16x32_bf16 v[114:117], v[170:173], v[202:205], v[114:117]
	v_mfma_f32_16x16x32_bf16 v[102:105], v[178:181], v[202:205], v[102:105]
	v_mfma_f32_16x16x32_bf16 v[98:101], v[186:189], v[202:205], v[98:101]
	v_mfma_f32_16x16x32_bf16 v[94:97], v[142:145], v[232:235], v[94:97]
	v_mfma_f32_16x16x32_bf16 v[90:93], v[170:173], v[232:235], v[90:93]
	v_mfma_f32_16x16x32_bf16 v[86:89], v[178:181], v[232:235], v[86:89]
	v_mfma_f32_16x16x32_bf16 v[82:85], v[186:189], v[232:235], v[82:85]
	v_mfma_f32_16x16x32_bf16 v[78:81], v[142:145], v[240:243], v[78:81]
	v_mfma_f32_16x16x32_bf16 v[74:77], v[170:173], v[240:243], v[74:77]
	v_mfma_f32_16x16x32_bf16 v[70:73], v[178:181], v[240:243], v[70:73]
	v_mfma_f32_16x16x32_bf16 v[66:69], v[186:189], v[240:243], v[66:69]
	s_barrier
	s_setprio 0
	s_mov_b32 m0, s18
	s_mov_b32 s46, s62
	s_mov_b32 s47, s63
	ds_read_b128 v[190:193], v141 offset:16384
	ds_read_b128 v[194:197], v141 offset:17408
	ds_read_b128 v[198:201], v141 offset:18432
	ds_read_b128 v[202:205], v141 offset:19456
	ds_read_b128 v[228:231], v141 offset:20480
	ds_read_b128 v[232:235], v141 offset:21504
	ds_read_b128 v[236:239], v141 offset:22528
	ds_read_b128 v[240:243], v141 offset:23552
	buffer_load_dwordx4 v137, s[44:47], s27 offen lds
	s_mov_b32 m0, s19
	s_add_i32 s53, s27, 0x160000
	buffer_load_dwordx4 v139, s[44:47], s27 offen lds
	s_mov_b32 m0, s24
	s_nop 0
	buffer_load_dwordx4 v137, s[44:47], s53 offen lds
	s_mov_b32 m0, s25
	s_nop 0
	buffer_load_dwordx4 v139, s[44:47], s53 offen lds
	s_mov_b32 m0, s14
	s_nop 0
	buffer_load_dwordx4 v136, s[60:63], s52 offen lds
	s_mov_b32 m0, s30
	s_nop 0
	buffer_load_dwordx4 v138, s[60:63], s52 offen lds
	s_waitcnt vmcnt(8)
	s_waitcnt lgkmcnt(0)
	s_setprio 1
	s_barrier
	v_mfma_f32_16x16x32_bf16 v[62:65], v[132:135], v[190:193], 0
	v_mfma_f32_16x16x32_bf16 v[58:61], v[154:157], v[190:193], 0
	v_mfma_f32_16x16x32_bf16 v[54:57], v[174:177], v[190:193], 0
	v_mfma_f32_16x16x32_bf16 v[50:53], v[182:185], v[190:193], 0
	v_mfma_f32_16x16x32_bf16 v[46:49], v[132:135], v[198:201], 0
	v_mfma_f32_16x16x32_bf16 v[42:45], v[154:157], v[198:201], 0
	v_mfma_f32_16x16x32_bf16 v[38:41], v[174:177], v[198:201], 0
	v_mfma_f32_16x16x32_bf16 v[34:37], v[182:185], v[198:201], 0
	v_mfma_f32_16x16x32_bf16 v[30:33], v[132:135], v[228:231], 0
	v_mfma_f32_16x16x32_bf16 v[26:29], v[154:157], v[228:231], 0
	v_mfma_f32_16x16x32_bf16 v[22:25], v[174:177], v[228:231], 0
	v_mfma_f32_16x16x32_bf16 v[18:21], v[182:185], v[228:231], 0
	v_mfma_f32_16x16x32_bf16 v[14:17], v[132:135], v[236:239], 0
	v_mfma_f32_16x16x32_bf16 v[10:13], v[154:157], v[236:239], 0
	v_mfma_f32_16x16x32_bf16 v[6:9], v[174:177], v[236:239], 0
	v_mfma_f32_16x16x32_bf16 v[2:5], v[182:185], v[236:239], 0
	v_mfma_f32_16x16x32_bf16 v[62:65], v[142:145], v[194:197], v[62:65]
	v_mfma_f32_16x16x32_bf16 v[58:61], v[170:173], v[194:197], v[58:61]
	v_mfma_f32_16x16x32_bf16 v[54:57], v[178:181], v[194:197], v[54:57]
	v_mfma_f32_16x16x32_bf16 v[50:53], v[186:189], v[194:197], v[50:53]
	v_mfma_f32_16x16x32_bf16 v[46:49], v[142:145], v[202:205], v[46:49]
	v_mfma_f32_16x16x32_bf16 v[42:45], v[170:173], v[202:205], v[42:45]
	v_mfma_f32_16x16x32_bf16 v[38:41], v[178:181], v[202:205], v[38:41]
	v_mfma_f32_16x16x32_bf16 v[34:37], v[186:189], v[202:205], v[34:37]
	v_mfma_f32_16x16x32_bf16 v[30:33], v[142:145], v[232:235], v[30:33]
	v_mfma_f32_16x16x32_bf16 v[26:29], v[170:173], v[232:235], v[26:29]
	v_mfma_f32_16x16x32_bf16 v[22:25], v[178:181], v[232:235], v[22:25]
	v_mfma_f32_16x16x32_bf16 v[18:21], v[186:189], v[232:235], v[18:21]
	v_mfma_f32_16x16x32_bf16 v[14:17], v[142:145], v[240:243], v[14:17]
	v_mfma_f32_16x16x32_bf16 v[10:13], v[170:173], v[240:243], v[10:13]
	v_mfma_f32_16x16x32_bf16 v[6:9], v[178:181], v[240:243], v[6:9]
	v_mfma_f32_16x16x32_bf16 v[2:5], v[186:189], v[240:243], v[2:5]
	s_barrier
	s_setprio 0
	v_add_u32_e32 v170, 0x18000, v140
	v_add_u32_e32 v186, 0x1c000, v140
	ds_read_b128 v[132:135], v170
	ds_read_b128 v[142:145], v170 offset:1024
	ds_read_b128 v[154:157], v170 offset:2048
	ds_read_b128 v[170:173], v170 offset:3072
	ds_read_b128 v[174:177], v186
	ds_read_b128 v[178:181], v186 offset:1024
	ds_read_b128 v[182:185], v186 offset:2048
	ds_read_b128 v[186:189], v186 offset:3072
	s_bitset1_b32 s52, 14
	s_mov_b32 m0, s31
	ds_read_b128 v[190:193], v141 offset:32768
	ds_read_b128 v[194:197], v141 offset:33792
	ds_read_b128 v[198:201], v141 offset:34816
	ds_read_b128 v[202:205], v141 offset:35840
	ds_read_b128 v[228:231], v141 offset:36864
	ds_read_b128 v[232:235], v141 offset:37888
	ds_read_b128 v[236:239], v141 offset:38912
	ds_read_b128 v[240:243], v141 offset:39936
	buffer_load_dwordx4 v136, s[60:63], s52 offen lds
	s_mov_b32 m0, s33
	s_nop 0
	buffer_load_dwordx4 v138, s[60:63], s52 offen lds
	s_waitcnt vmcnt(8)
	s_waitcnt lgkmcnt(0)
	s_setprio 1
	s_barrier
	v_mfma_f32_16x16x32_bf16 v[126:129], v[132:135], v[190:193], v[126:129]
	v_mfma_f32_16x16x32_bf16 v[106:109], v[154:157], v[190:193], v[106:109]
	v_mfma_f32_16x16x32_bf16 v[122:125], v[174:177], v[190:193], v[122:125]
	v_mfma_f32_16x16x32_bf16 v[110:113], v[182:185], v[190:193], v[110:113]
	v_mfma_f32_16x16x32_bf16 v[118:121], v[132:135], v[198:201], v[118:121]
	v_mfma_f32_16x16x32_bf16 v[114:117], v[154:157], v[198:201], v[114:117]
	v_mfma_f32_16x16x32_bf16 v[102:105], v[174:177], v[198:201], v[102:105]
	v_mfma_f32_16x16x32_bf16 v[98:101], v[182:185], v[198:201], v[98:101]
	v_mfma_f32_16x16x32_bf16 v[94:97], v[132:135], v[228:231], v[94:97]
	v_mfma_f32_16x16x32_bf16 v[90:93], v[154:157], v[228:231], v[90:93]
	v_mfma_f32_16x16x32_bf16 v[86:89], v[174:177], v[228:231], v[86:89]
	v_mfma_f32_16x16x32_bf16 v[82:85], v[182:185], v[228:231], v[82:85]
	v_mfma_f32_16x16x32_bf16 v[78:81], v[132:135], v[236:239], v[78:81]
	v_mfma_f32_16x16x32_bf16 v[74:77], v[154:157], v[236:239], v[74:77]
	v_mfma_f32_16x16x32_bf16 v[70:73], v[174:177], v[236:239], v[70:73]
	v_mfma_f32_16x16x32_bf16 v[66:69], v[182:185], v[236:239], v[66:69]
	v_mfma_f32_16x16x32_bf16 v[126:129], v[142:145], v[194:197], v[126:129]
	v_mfma_f32_16x16x32_bf16 v[106:109], v[170:173], v[194:197], v[106:109]
	v_mfma_f32_16x16x32_bf16 v[122:125], v[178:181], v[194:197], v[122:125]
	v_mfma_f32_16x16x32_bf16 v[110:113], v[186:189], v[194:197], v[110:113]
	v_mfma_f32_16x16x32_bf16 v[118:121], v[142:145], v[202:205], v[118:121]
	v_mfma_f32_16x16x32_bf16 v[114:117], v[170:173], v[202:205], v[114:117]
	v_mfma_f32_16x16x32_bf16 v[102:105], v[178:181], v[202:205], v[102:105]
	v_mfma_f32_16x16x32_bf16 v[98:101], v[186:189], v[202:205], v[98:101]
	v_mfma_f32_16x16x32_bf16 v[94:97], v[142:145], v[232:235], v[94:97]
	v_mfma_f32_16x16x32_bf16 v[90:93], v[170:173], v[232:235], v[90:93]
	v_mfma_f32_16x16x32_bf16 v[86:89], v[178:181], v[232:235], v[86:89]
	v_mfma_f32_16x16x32_bf16 v[82:85], v[186:189], v[232:235], v[82:85]
	v_mfma_f32_16x16x32_bf16 v[78:81], v[142:145], v[240:243], v[78:81]
	v_mfma_f32_16x16x32_bf16 v[74:77], v[170:173], v[240:243], v[74:77]
	v_mfma_f32_16x16x32_bf16 v[70:73], v[178:181], v[240:243], v[70:73]
	v_mfma_f32_16x16x32_bf16 v[66:69], v[186:189], v[240:243], v[66:69]
	s_barrier
	s_setprio 0
	s_mov_b32 m0, s68
	s_or_b32 s52, s27, 0x80
	ds_read_b128 v[190:193], v141 offset:49152
	ds_read_b128 v[194:197], v141 offset:50176
	ds_read_b128 v[198:201], v141 offset:51200
	ds_read_b128 v[202:205], v141 offset:52224
	ds_read_b128 v[228:231], v141 offset:53248
	ds_read_b128 v[232:235], v141 offset:54272
	ds_read_b128 v[236:239], v141 offset:55296
	ds_read_b128 v[240:243], v141 offset:56320
	buffer_load_dwordx4 v137, s[44:47], s52 offen lds
	s_mov_b32 m0, s69
	s_add_i32 s27, s27, 0x160080
	buffer_load_dwordx4 v139, s[44:47], s52 offen lds
	s_mov_b32 m0, s72
	s_nop 0
	buffer_load_dwordx4 v137, s[44:47], s27 offen lds
	s_mov_b32 m0, s73
	s_nop 0
	buffer_load_dwordx4 v139, s[44:47], s27 offen lds
	s_mov_b32 m0, s70
	s_nop 0
	buffer_load_dwordx4 v136, s[60:63], s26 offen lds
	s_mov_b32 m0, s71
	s_nop 0
	buffer_load_dwordx4 v138, s[60:63], s26 offen lds
	s_waitcnt vmcnt(8)
	s_waitcnt lgkmcnt(0)
	s_setprio 1
	s_barrier
	v_mfma_f32_16x16x32_bf16 v[62:65], v[132:135], v[190:193], v[62:65]
	v_mfma_f32_16x16x32_bf16 v[58:61], v[154:157], v[190:193], v[58:61]
	v_mfma_f32_16x16x32_bf16 v[54:57], v[174:177], v[190:193], v[54:57]
	v_mfma_f32_16x16x32_bf16 v[50:53], v[182:185], v[190:193], v[50:53]
	v_mfma_f32_16x16x32_bf16 v[46:49], v[132:135], v[198:201], v[46:49]
	v_mfma_f32_16x16x32_bf16 v[42:45], v[154:157], v[198:201], v[42:45]
	v_mfma_f32_16x16x32_bf16 v[38:41], v[174:177], v[198:201], v[38:41]
	v_mfma_f32_16x16x32_bf16 v[34:37], v[182:185], v[198:201], v[34:37]
	v_mfma_f32_16x16x32_bf16 v[30:33], v[132:135], v[228:231], v[30:33]
	v_mfma_f32_16x16x32_bf16 v[26:29], v[154:157], v[228:231], v[26:29]
	v_mfma_f32_16x16x32_bf16 v[22:25], v[174:177], v[228:231], v[22:25]
	v_mfma_f32_16x16x32_bf16 v[18:21], v[182:185], v[228:231], v[18:21]
	v_mfma_f32_16x16x32_bf16 v[14:17], v[132:135], v[236:239], v[14:17]
	v_mfma_f32_16x16x32_bf16 v[10:13], v[154:157], v[236:239], v[10:13]
	v_mfma_f32_16x16x32_bf16 v[6:9], v[174:177], v[236:239], v[6:9]
	v_mfma_f32_16x16x32_bf16 v[2:5], v[182:185], v[236:239], v[2:5]
	v_mfma_f32_16x16x32_bf16 v[62:65], v[142:145], v[194:197], v[62:65]
	v_mfma_f32_16x16x32_bf16 v[58:61], v[170:173], v[194:197], v[58:61]
	v_mfma_f32_16x16x32_bf16 v[54:57], v[178:181], v[194:197], v[54:57]
	v_mfma_f32_16x16x32_bf16 v[50:53], v[186:189], v[194:197], v[50:53]
	v_mfma_f32_16x16x32_bf16 v[46:49], v[142:145], v[202:205], v[46:49]
	v_mfma_f32_16x16x32_bf16 v[42:45], v[170:173], v[202:205], v[42:45]
	v_mfma_f32_16x16x32_bf16 v[38:41], v[178:181], v[202:205], v[38:41]
	v_mfma_f32_16x16x32_bf16 v[34:37], v[186:189], v[202:205], v[34:37]
	v_mfma_f32_16x16x32_bf16 v[30:33], v[142:145], v[232:235], v[30:33]
	v_mfma_f32_16x16x32_bf16 v[26:29], v[170:173], v[232:235], v[26:29]
	v_mfma_f32_16x16x32_bf16 v[22:25], v[178:181], v[232:235], v[22:25]
	v_mfma_f32_16x16x32_bf16 v[18:21], v[186:189], v[232:235], v[18:21]
	v_mfma_f32_16x16x32_bf16 v[14:17], v[142:145], v[240:243], v[14:17]
	v_mfma_f32_16x16x32_bf16 v[10:13], v[170:173], v[240:243], v[10:13]
	v_mfma_f32_16x16x32_bf16 v[6:9], v[178:181], v[240:243], v[6:9]
	v_mfma_f32_16x16x32_bf16 v[2:5], v[186:189], v[240:243], v[2:5]
	s_barrier
	s_setprio 0
	s_addk_i32 s13, 0x100
	s_add_i32 s22, s22, 2
	s_add_i32 s21, s21, 0x10000
	s_cmpk_gt_u32 s22, 0x55
.LBB0_2156:
	v_add_u32_e32 v170, 0x10000, v140
	v_add_u32_e32 v186, 0x14000, v140
	ds_read_b128 v[132:135], v170
	ds_read_b128 v[142:145], v170 offset:1024
	ds_read_b128 v[154:157], v170 offset:2048
	ds_read_b128 v[170:173], v170 offset:3072
	ds_read_b128 v[174:177], v186
	ds_read_b128 v[178:181], v186 offset:1024
	ds_read_b128 v[182:185], v186 offset:2048
	ds_read_b128 v[186:189], v186 offset:3072
	s_add_i32 s26, s21, 0x4000
	s_cmpk_eq_i32 s22, 0x54
	s_cselect_b32 s52, s8, s26
	s_cselect_b32 s27, s9, s13
	s_or_b32 s26, s52, 0x8000
	s_mov_b32 m0, s84
	ds_read_b128 v[190:193], v141
	ds_read_b128 v[194:197], v141 offset:1024
	ds_read_b128 v[198:201], v141 offset:2048
	ds_read_b128 v[202:205], v141 offset:3072
	ds_read_b128 v[228:231], v141 offset:4096
	ds_read_b128 v[232:235], v141 offset:5120
	ds_read_b128 v[236:239], v141 offset:6144
	ds_read_b128 v[240:243], v141 offset:7168
	buffer_load_dwordx4 v136, s[60:63], s21 offen lds
	s_mov_b32 m0, s16
	s_nop 0
	buffer_load_dwordx4 v138, s[60:63], s21 offen lds
	s_waitcnt vmcnt(8)
	s_waitcnt lgkmcnt(0)
	s_setprio 1
	s_barrier
	v_mfma_f32_16x16x32_bf16 v[126:129], v[132:135], v[190:193], v[126:129]
	v_mfma_f32_16x16x32_bf16 v[106:109], v[154:157], v[190:193], v[106:109]
	v_mfma_f32_16x16x32_bf16 v[122:125], v[174:177], v[190:193], v[122:125]
	v_mfma_f32_16x16x32_bf16 v[110:113], v[182:185], v[190:193], v[110:113]
	v_mfma_f32_16x16x32_bf16 v[118:121], v[132:135], v[198:201], v[118:121]
	v_mfma_f32_16x16x32_bf16 v[114:117], v[154:157], v[198:201], v[114:117]
	v_mfma_f32_16x16x32_bf16 v[102:105], v[174:177], v[198:201], v[102:105]
	v_mfma_f32_16x16x32_bf16 v[98:101], v[182:185], v[198:201], v[98:101]
	v_mfma_f32_16x16x32_bf16 v[94:97], v[132:135], v[228:231], v[94:97]
	v_mfma_f32_16x16x32_bf16 v[90:93], v[154:157], v[228:231], v[90:93]
	v_mfma_f32_16x16x32_bf16 v[86:89], v[174:177], v[228:231], v[86:89]
	v_mfma_f32_16x16x32_bf16 v[82:85], v[182:185], v[228:231], v[82:85]
	v_mfma_f32_16x16x32_bf16 v[78:81], v[132:135], v[236:239], v[78:81]
	v_mfma_f32_16x16x32_bf16 v[74:77], v[154:157], v[236:239], v[74:77]
	v_mfma_f32_16x16x32_bf16 v[70:73], v[174:177], v[236:239], v[70:73]
	v_mfma_f32_16x16x32_bf16 v[66:69], v[182:185], v[236:239], v[66:69]
	v_mfma_f32_16x16x32_bf16 v[126:129], v[142:145], v[194:197], v[126:129]
	v_mfma_f32_16x16x32_bf16 v[106:109], v[170:173], v[194:197], v[106:109]
	v_mfma_f32_16x16x32_bf16 v[122:125], v[178:181], v[194:197], v[122:125]
	v_mfma_f32_16x16x32_bf16 v[110:113], v[186:189], v[194:197], v[110:113]
	v_mfma_f32_16x16x32_bf16 v[118:121], v[142:145], v[202:205], v[118:121]
	v_mfma_f32_16x16x32_bf16 v[114:117], v[170:173], v[202:205], v[114:117]
	v_mfma_f32_16x16x32_bf16 v[102:105], v[178:181], v[202:205], v[102:105]
	v_mfma_f32_16x16x32_bf16 v[98:101], v[186:189], v[202:205], v[98:101]
	v_mfma_f32_16x16x32_bf16 v[94:97], v[142:145], v[232:235], v[94:97]
	v_mfma_f32_16x16x32_bf16 v[90:93], v[170:173], v[232:235], v[90:93]
	v_mfma_f32_16x16x32_bf16 v[86:89], v[178:181], v[232:235], v[86:89]
	v_mfma_f32_16x16x32_bf16 v[82:85], v[186:189], v[232:235], v[82:85]
	v_mfma_f32_16x16x32_bf16 v[78:81], v[142:145], v[240:243], v[78:81]
	v_mfma_f32_16x16x32_bf16 v[74:77], v[170:173], v[240:243], v[74:77]
	v_mfma_f32_16x16x32_bf16 v[70:73], v[178:181], v[240:243], v[70:73]
	v_mfma_f32_16x16x32_bf16 v[66:69], v[186:189], v[240:243], v[66:69]
	s_barrier
	s_setprio 0
	s_mov_b32 m0, s18
	s_mov_b32 s46, s62
	s_mov_b32 s47, s63
	ds_read_b128 v[190:193], v141 offset:16384
	ds_read_b128 v[194:197], v141 offset:17408
	ds_read_b128 v[198:201], v141 offset:18432
	ds_read_b128 v[202:205], v141 offset:19456
	ds_read_b128 v[228:231], v141 offset:20480
	ds_read_b128 v[232:235], v141 offset:21504
	ds_read_b128 v[236:239], v141 offset:22528
	ds_read_b128 v[240:243], v141 offset:23552
	buffer_load_dwordx4 v137, s[44:47], s27 offen lds
	s_mov_b32 m0, s19
	s_add_i32 s53, s27, 0x160000
	buffer_load_dwordx4 v139, s[44:47], s27 offen lds
	s_mov_b32 m0, s24
	s_nop 0
	buffer_load_dwordx4 v137, s[44:47], s53 offen lds
	s_mov_b32 m0, s25
	s_nop 0
	buffer_load_dwordx4 v139, s[44:47], s53 offen lds
	s_mov_b32 m0, s14
	s_nop 0
	buffer_load_dwordx4 v136, s[60:63], s52 offen lds
	s_mov_b32 m0, s30
	s_nop 0
	buffer_load_dwordx4 v138, s[60:63], s52 offen lds
	s_waitcnt vmcnt(8)
	s_waitcnt lgkmcnt(0)
	s_setprio 1
	s_barrier
	v_mfma_f32_16x16x32_bf16 v[62:65], v[132:135], v[190:193], v[62:65]
	v_mfma_f32_16x16x32_bf16 v[58:61], v[154:157], v[190:193], v[58:61]
	v_mfma_f32_16x16x32_bf16 v[54:57], v[174:177], v[190:193], v[54:57]
	v_mfma_f32_16x16x32_bf16 v[50:53], v[182:185], v[190:193], v[50:53]
	v_mfma_f32_16x16x32_bf16 v[46:49], v[132:135], v[198:201], v[46:49]
	v_mfma_f32_16x16x32_bf16 v[42:45], v[154:157], v[198:201], v[42:45]
	v_mfma_f32_16x16x32_bf16 v[38:41], v[174:177], v[198:201], v[38:41]
	v_mfma_f32_16x16x32_bf16 v[34:37], v[182:185], v[198:201], v[34:37]
	v_mfma_f32_16x16x32_bf16 v[30:33], v[132:135], v[228:231], v[30:33]
	v_mfma_f32_16x16x32_bf16 v[26:29], v[154:157], v[228:231], v[26:29]
	v_mfma_f32_16x16x32_bf16 v[22:25], v[174:177], v[228:231], v[22:25]
	v_mfma_f32_16x16x32_bf16 v[18:21], v[182:185], v[228:231], v[18:21]
	v_mfma_f32_16x16x32_bf16 v[14:17], v[132:135], v[236:239], v[14:17]
	v_mfma_f32_16x16x32_bf16 v[10:13], v[154:157], v[236:239], v[10:13]
	v_mfma_f32_16x16x32_bf16 v[6:9], v[174:177], v[236:239], v[6:9]
	v_mfma_f32_16x16x32_bf16 v[2:5], v[182:185], v[236:239], v[2:5]
	v_mfma_f32_16x16x32_bf16 v[62:65], v[142:145], v[194:197], v[62:65]
	v_mfma_f32_16x16x32_bf16 v[58:61], v[170:173], v[194:197], v[58:61]
	v_mfma_f32_16x16x32_bf16 v[54:57], v[178:181], v[194:197], v[54:57]
	v_mfma_f32_16x16x32_bf16 v[50:53], v[186:189], v[194:197], v[50:53]
	v_mfma_f32_16x16x32_bf16 v[46:49], v[142:145], v[202:205], v[46:49]
	v_mfma_f32_16x16x32_bf16 v[42:45], v[170:173], v[202:205], v[42:45]
	v_mfma_f32_16x16x32_bf16 v[38:41], v[178:181], v[202:205], v[38:41]
	v_mfma_f32_16x16x32_bf16 v[34:37], v[186:189], v[202:205], v[34:37]
	v_mfma_f32_16x16x32_bf16 v[30:33], v[142:145], v[232:235], v[30:33]
	v_mfma_f32_16x16x32_bf16 v[26:29], v[170:173], v[232:235], v[26:29]
	v_mfma_f32_16x16x32_bf16 v[22:25], v[178:181], v[232:235], v[22:25]
	v_mfma_f32_16x16x32_bf16 v[18:21], v[186:189], v[232:235], v[18:21]
	v_mfma_f32_16x16x32_bf16 v[14:17], v[142:145], v[240:243], v[14:17]
	v_mfma_f32_16x16x32_bf16 v[10:13], v[170:173], v[240:243], v[10:13]
	v_mfma_f32_16x16x32_bf16 v[6:9], v[178:181], v[240:243], v[6:9]
	v_mfma_f32_16x16x32_bf16 v[2:5], v[186:189], v[240:243], v[2:5]
	s_barrier
	s_setprio 0
	v_add_u32_e32 v170, 0x18000, v140
	v_add_u32_e32 v186, 0x1c000, v140
	ds_read_b128 v[132:135], v170
	ds_read_b128 v[142:145], v170 offset:1024
	ds_read_b128 v[154:157], v170 offset:2048
	ds_read_b128 v[170:173], v170 offset:3072
	ds_read_b128 v[174:177], v186
	ds_read_b128 v[178:181], v186 offset:1024
	ds_read_b128 v[182:185], v186 offset:2048
	ds_read_b128 v[186:189], v186 offset:3072
	s_bitset1_b32 s52, 14
	s_mov_b32 m0, s31
	ds_read_b128 v[190:193], v141 offset:32768
	ds_read_b128 v[194:197], v141 offset:33792
	ds_read_b128 v[198:201], v141 offset:34816
	ds_read_b128 v[202:205], v141 offset:35840
	ds_read_b128 v[228:231], v141 offset:36864
	ds_read_b128 v[232:235], v141 offset:37888
	ds_read_b128 v[236:239], v141 offset:38912
	ds_read_b128 v[240:243], v141 offset:39936
	buffer_load_dwordx4 v136, s[60:63], s52 offen lds
	s_mov_b32 m0, s33
	s_nop 0
	buffer_load_dwordx4 v138, s[60:63], s52 offen lds
	s_waitcnt vmcnt(8)
	s_waitcnt lgkmcnt(0)
	s_setprio 1
	s_barrier
	v_mfma_f32_16x16x32_bf16 v[126:129], v[132:135], v[190:193], v[126:129]
	v_mfma_f32_16x16x32_bf16 v[106:109], v[154:157], v[190:193], v[106:109]
	v_mfma_f32_16x16x32_bf16 v[122:125], v[174:177], v[190:193], v[122:125]
	v_mfma_f32_16x16x32_bf16 v[110:113], v[182:185], v[190:193], v[110:113]
	v_mfma_f32_16x16x32_bf16 v[118:121], v[132:135], v[198:201], v[118:121]
	v_mfma_f32_16x16x32_bf16 v[114:117], v[154:157], v[198:201], v[114:117]
	v_mfma_f32_16x16x32_bf16 v[102:105], v[174:177], v[198:201], v[102:105]
	v_mfma_f32_16x16x32_bf16 v[98:101], v[182:185], v[198:201], v[98:101]
	v_mfma_f32_16x16x32_bf16 v[94:97], v[132:135], v[228:231], v[94:97]
	v_mfma_f32_16x16x32_bf16 v[90:93], v[154:157], v[228:231], v[90:93]
	v_mfma_f32_16x16x32_bf16 v[86:89], v[174:177], v[228:231], v[86:89]
	v_mfma_f32_16x16x32_bf16 v[82:85], v[182:185], v[228:231], v[82:85]
	v_mfma_f32_16x16x32_bf16 v[78:81], v[132:135], v[236:239], v[78:81]
	v_mfma_f32_16x16x32_bf16 v[74:77], v[154:157], v[236:239], v[74:77]
	v_mfma_f32_16x16x32_bf16 v[70:73], v[174:177], v[236:239], v[70:73]
	v_mfma_f32_16x16x32_bf16 v[66:69], v[182:185], v[236:239], v[66:69]
	v_mfma_f32_16x16x32_bf16 v[126:129], v[142:145], v[194:197], v[126:129]
	v_mfma_f32_16x16x32_bf16 v[106:109], v[170:173], v[194:197], v[106:109]
	v_mfma_f32_16x16x32_bf16 v[122:125], v[178:181], v[194:197], v[122:125]
	v_mfma_f32_16x16x32_bf16 v[110:113], v[186:189], v[194:197], v[110:113]
	v_mfma_f32_16x16x32_bf16 v[118:121], v[142:145], v[202:205], v[118:121]
	v_mfma_f32_16x16x32_bf16 v[114:117], v[170:173], v[202:205], v[114:117]
	v_mfma_f32_16x16x32_bf16 v[102:105], v[178:181], v[202:205], v[102:105]
	v_mfma_f32_16x16x32_bf16 v[98:101], v[186:189], v[202:205], v[98:101]
	v_mfma_f32_16x16x32_bf16 v[94:97], v[142:145], v[232:235], v[94:97]
	v_mfma_f32_16x16x32_bf16 v[90:93], v[170:173], v[232:235], v[90:93]
	v_mfma_f32_16x16x32_bf16 v[86:89], v[178:181], v[232:235], v[86:89]
	v_mfma_f32_16x16x32_bf16 v[82:85], v[186:189], v[232:235], v[82:85]
	v_mfma_f32_16x16x32_bf16 v[78:81], v[142:145], v[240:243], v[78:81]
	v_mfma_f32_16x16x32_bf16 v[74:77], v[170:173], v[240:243], v[74:77]
	v_mfma_f32_16x16x32_bf16 v[70:73], v[178:181], v[240:243], v[70:73]
	v_mfma_f32_16x16x32_bf16 v[66:69], v[186:189], v[240:243], v[66:69]
	s_barrier
	s_setprio 0
	s_mov_b32 m0, s68
	s_or_b32 s52, s27, 0x80
	ds_read_b128 v[190:193], v141 offset:49152
	ds_read_b128 v[194:197], v141 offset:50176
	ds_read_b128 v[198:201], v141 offset:51200
	ds_read_b128 v[202:205], v141 offset:52224
	ds_read_b128 v[228:231], v141 offset:53248
	ds_read_b128 v[232:235], v141 offset:54272
	ds_read_b128 v[236:239], v141 offset:55296
	ds_read_b128 v[240:243], v141 offset:56320
	buffer_load_dwordx4 v137, s[44:47], s52 offen lds
	s_mov_b32 m0, s69
	s_add_i32 s27, s27, 0x160080
	buffer_load_dwordx4 v139, s[44:47], s52 offen lds
	s_mov_b32 m0, s72
	s_nop 0
	buffer_load_dwordx4 v137, s[44:47], s27 offen lds
	s_mov_b32 m0, s73
	s_nop 0
	buffer_load_dwordx4 v139, s[44:47], s27 offen lds
	s_mov_b32 m0, s70
	s_nop 0
	buffer_load_dwordx4 v136, s[60:63], s26 offen lds
	s_mov_b32 m0, s71
	s_nop 0
	buffer_load_dwordx4 v138, s[60:63], s26 offen lds
	s_waitcnt vmcnt(8)
	s_waitcnt lgkmcnt(0)
	s_setprio 1
	s_barrier
	v_mfma_f32_16x16x32_bf16 v[62:65], v[132:135], v[190:193], v[62:65]
	v_mfma_f32_16x16x32_bf16 v[58:61], v[154:157], v[190:193], v[58:61]
	v_mfma_f32_16x16x32_bf16 v[54:57], v[174:177], v[190:193], v[54:57]
	v_mfma_f32_16x16x32_bf16 v[50:53], v[182:185], v[190:193], v[50:53]
	v_mfma_f32_16x16x32_bf16 v[46:49], v[132:135], v[198:201], v[46:49]
	v_mfma_f32_16x16x32_bf16 v[42:45], v[154:157], v[198:201], v[42:45]
	v_mfma_f32_16x16x32_bf16 v[38:41], v[174:177], v[198:201], v[38:41]
	v_mfma_f32_16x16x32_bf16 v[34:37], v[182:185], v[198:201], v[34:37]
	v_mfma_f32_16x16x32_bf16 v[30:33], v[132:135], v[228:231], v[30:33]
	v_mfma_f32_16x16x32_bf16 v[26:29], v[154:157], v[228:231], v[26:29]
	v_mfma_f32_16x16x32_bf16 v[22:25], v[174:177], v[228:231], v[22:25]
	v_mfma_f32_16x16x32_bf16 v[18:21], v[182:185], v[228:231], v[18:21]
	v_mfma_f32_16x16x32_bf16 v[14:17], v[132:135], v[236:239], v[14:17]
	v_mfma_f32_16x16x32_bf16 v[10:13], v[154:157], v[236:239], v[10:13]
	v_mfma_f32_16x16x32_bf16 v[6:9], v[174:177], v[236:239], v[6:9]
	v_mfma_f32_16x16x32_bf16 v[2:5], v[182:185], v[236:239], v[2:5]
	v_mfma_f32_16x16x32_bf16 v[62:65], v[142:145], v[194:197], v[62:65]
	v_mfma_f32_16x16x32_bf16 v[58:61], v[170:173], v[194:197], v[58:61]
	v_mfma_f32_16x16x32_bf16 v[54:57], v[178:181], v[194:197], v[54:57]
	v_mfma_f32_16x16x32_bf16 v[50:53], v[186:189], v[194:197], v[50:53]
	v_mfma_f32_16x16x32_bf16 v[46:49], v[142:145], v[202:205], v[46:49]
	v_mfma_f32_16x16x32_bf16 v[42:45], v[170:173], v[202:205], v[42:45]
	v_mfma_f32_16x16x32_bf16 v[38:41], v[178:181], v[202:205], v[38:41]
	v_mfma_f32_16x16x32_bf16 v[34:37], v[186:189], v[202:205], v[34:37]
	v_mfma_f32_16x16x32_bf16 v[30:33], v[142:145], v[232:235], v[30:33]
	v_mfma_f32_16x16x32_bf16 v[26:29], v[170:173], v[232:235], v[26:29]
	v_mfma_f32_16x16x32_bf16 v[22:25], v[178:181], v[232:235], v[22:25]
	v_mfma_f32_16x16x32_bf16 v[18:21], v[186:189], v[232:235], v[18:21]
	v_mfma_f32_16x16x32_bf16 v[14:17], v[142:145], v[240:243], v[14:17]
	v_mfma_f32_16x16x32_bf16 v[10:13], v[170:173], v[240:243], v[10:13]
	v_mfma_f32_16x16x32_bf16 v[6:9], v[178:181], v[240:243], v[6:9]
	v_mfma_f32_16x16x32_bf16 v[2:5], v[186:189], v[240:243], v[2:5]
	s_barrier
	s_setprio 0
	s_addk_i32 s13, 0x100
	s_add_i32 s22, s22, 2
	s_add_i32 s21, s21, 0x10000
	s_cmpk_gt_u32 s22, 0x55
	s_cbranch_scc0 .LBB0_2156
	s_and_b64 vcc, exec, s[66:67]
	s_cbranch_vccz .LBB0_2159
	s_barrier

.LBB0_2173:
	v_mov_b32_e32 v125, 0
	s_mul_i32 s69, s68, s12
	s_mul_i32 s70, s67, s12
	s_andn2_b64 vcc, exec, s[34:35]
	v_mov_b32_e32 v124, v125
	v_mov_b32_e32 v123, v125
	v_mov_b32_e32 v122, v125
	v_mov_b32_e32 v129, v125
	v_mov_b32_e32 v128, v125
	v_mov_b32_e32 v127, v125
	v_mov_b32_e32 v126, v125
	v_mov_b32_e32 v113, v125
	v_mov_b32_e32 v112, v125
	v_mov_b32_e32 v111, v125
	v_mov_b32_e32 v110, v125
	v_mov_b32_e32 v109, v125
	v_mov_b32_e32 v108, v125
	v_mov_b32_e32 v107, v125
	v_mov_b32_e32 v106, v125
	v_mov_b32_e32 v97, v125
	v_mov_b32_e32 v96, v125
	v_mov_b32_e32 v95, v125
	v_mov_b32_e32 v94, v125
	v_mov_b32_e32 v93, v125
	v_mov_b32_e32 v92, v125
	v_mov_b32_e32 v91, v125
	v_mov_b32_e32 v90, v125
	v_mov_b32_e32 v81, v125
	v_mov_b32_e32 v80, v125
	v_mov_b32_e32 v79, v125
	v_mov_b32_e32 v78, v125
	v_mov_b32_e32 v77, v125
	v_mov_b32_e32 v76, v125
	v_mov_b32_e32 v75, v125
	v_mov_b32_e32 v74, v125
	v_mov_b32_e32 v121, v125
	v_mov_b32_e32 v120, v125
	v_mov_b32_e32 v119, v125
	v_mov_b32_e32 v118, v125
	v_mov_b32_e32 v117, v125
	v_mov_b32_e32 v116, v125
	v_mov_b32_e32 v115, v125
	v_mov_b32_e32 v114, v125
	v_mov_b32_e32 v105, v125
	v_mov_b32_e32 v104, v125
	v_mov_b32_e32 v103, v125
	v_mov_b32_e32 v102, v125
	v_mov_b32_e32 v101, v125
	v_mov_b32_e32 v100, v125
	v_mov_b32_e32 v99, v125
	v_mov_b32_e32 v98, v125
	v_mov_b32_e32 v89, v125
	v_mov_b32_e32 v88, v125
	v_mov_b32_e32 v87, v125
	v_mov_b32_e32 v86, v125
	v_mov_b32_e32 v85, v125
	v_mov_b32_e32 v84, v125
	v_mov_b32_e32 v83, v125
	v_mov_b32_e32 v82, v125
	v_mov_b32_e32 v73, v125
	v_mov_b32_e32 v72, v125
	v_mov_b32_e32 v71, v125
	v_mov_b32_e32 v70, v125
	v_mov_b32_e32 v69, v125
	v_mov_b32_e32 v68, v125
	v_mov_b32_e32 v67, v125
	v_mov_b32_e32 v66, v125
	v_mov_b32_e32 v65, v125
	v_mov_b32_e32 v64, v125
	v_mov_b32_e32 v63, v125
	v_mov_b32_e32 v62, v125
	v_mov_b32_e32 v61, v125
	v_mov_b32_e32 v60, v125
	v_mov_b32_e32 v59, v125
	v_mov_b32_e32 v58, v125
	v_mov_b32_e32 v49, v125
	v_mov_b32_e32 v48, v125
	v_mov_b32_e32 v47, v125
	v_mov_b32_e32 v46, v125
	v_mov_b32_e32 v45, v125
	v_mov_b32_e32 v44, v125
	v_mov_b32_e32 v43, v125
	v_mov_b32_e32 v42, v125
	v_mov_b32_e32 v33, v125
	v_mov_b32_e32 v32, v125
	v_mov_b32_e32 v31, v125
	v_mov_b32_e32 v30, v125
	v_mov_b32_e32 v29, v125
	v_mov_b32_e32 v28, v125
	v_mov_b32_e32 v27, v125
	v_mov_b32_e32 v26, v125
	v_mov_b32_e32 v17, v125
	v_mov_b32_e32 v16, v125
	v_mov_b32_e32 v15, v125
	v_mov_b32_e32 v14, v125
	v_mov_b32_e32 v13, v125
	v_mov_b32_e32 v12, v125
	v_mov_b32_e32 v11, v125
	v_mov_b32_e32 v10, v125
	v_mov_b32_e32 v57, v125
	v_mov_b32_e32 v56, v125
	v_mov_b32_e32 v55, v125
	v_mov_b32_e32 v54, v125
	v_mov_b32_e32 v53, v125
	v_mov_b32_e32 v52, v125
	v_mov_b32_e32 v51, v125
	v_mov_b32_e32 v50, v125
	v_mov_b32_e32 v41, v125
	v_mov_b32_e32 v40, v125
	v_mov_b32_e32 v39, v125
	v_mov_b32_e32 v38, v125
	v_mov_b32_e32 v37, v125
	v_mov_b32_e32 v36, v125
	v_mov_b32_e32 v35, v125
	v_mov_b32_e32 v34, v125
	v_mov_b32_e32 v25, v125
	v_mov_b32_e32 v24, v125
	v_mov_b32_e32 v23, v125
	v_mov_b32_e32 v22, v125
	v_mov_b32_e32 v21, v125
	v_mov_b32_e32 v20, v125
	v_mov_b32_e32 v19, v125
	v_mov_b32_e32 v18, v125
	v_mov_b32_e32 v9, v125
	v_mov_b32_e32 v8, v125
	v_mov_b32_e32 v7, v125
	v_mov_b32_e32 v6, v125
	v_mov_b32_e32 v5, v125
	v_mov_b32_e32 v4, v125
	v_mov_b32_e32 v3, v125
	v_mov_b32_e32 v2, v125
	s_cbranch_vccnz .LBB0_2177
	s_and_b64 s[8:9], s[40:41], exec
	s_cselect_b32 s8, s69, s73
	s_cselect_b32 s9, s70, s82
	s_addk_i32 s73, 0x80
	s_addk_i32 s82, 0x100
	s_mov_b32 s83, 0
	v_add_u32_e32 v144, 0x10000, v134
	ds_read_b128 v[136:139], v144
	ds_read_b128 v[140:143], v144 offset:1024
	ds_read_b128 v[154:157], v144 offset:2048
	ds_read_b128 v[170:173], v144 offset:3072
	v_add_u32_e32 v144, 0x14000, v134
	ds_read_b128 v[174:177], v144
	ds_read_b128 v[178:181], v144 offset:1024
	ds_read_b128 v[182:185], v144 offset:2048
	ds_read_b128 v[186:189], v144 offset:3072
	s_add_i32 s46, s73, 0x80
	s_cmp_eq_u32 s49, s83
	s_cselect_b32 s52, s8, s46
	s_cselect_b32 s85, s9, s82
	s_add_i32 s84, s52, 0x80
	s_add_i32 s46, s2, s73
	s_mov_b32 m0, s64
	ds_read_b128 v[190:193], v135
	ds_read_b128 v[194:197], v135 offset:1024
	ds_read_b128 v[198:201], v135 offset:2048
	ds_read_b128 v[202:205], v135 offset:3072
	ds_read_b128 v[228:231], v135 offset:4096
	ds_read_b128 v[232:235], v135 offset:5120
	ds_read_b128 v[236:239], v135 offset:6144
	ds_read_b128 v[240:243], v135 offset:7168
	buffer_load_dwordx4 v130, s[60:63], s46 offen lds
	s_mov_b32 m0, s65
	s_nop 0
	buffer_load_dwordx4 v132, s[60:63], s46 offen lds
	s_waitcnt vmcnt(8)
	s_waitcnt lgkmcnt(0)
	s_setprio 1
	s_barrier
	v_mfma_f32_16x16x32_bf16 v[122:125], v[136:139], v[190:193], 0
	v_mfma_f32_16x16x32_bf16 v[126:129], v[154:157], v[190:193], 0
	v_mfma_f32_16x16x32_bf16 v[118:121], v[174:177], v[190:193], 0
	v_mfma_f32_16x16x32_bf16 v[114:117], v[182:185], v[190:193], 0
	v_mfma_f32_16x16x32_bf16 v[110:113], v[136:139], v[198:201], 0
	v_mfma_f32_16x16x32_bf16 v[106:109], v[154:157], v[198:201], 0
	v_mfma_f32_16x16x32_bf16 v[102:105], v[174:177], v[198:201], 0
	v_mfma_f32_16x16x32_bf16 v[98:101], v[182:185], v[198:201], 0
	v_mfma_f32_16x16x32_bf16 v[94:97], v[136:139], v[228:231], 0
	v_mfma_f32_16x16x32_bf16 v[90:93], v[154:157], v[228:231], 0
	v_mfma_f32_16x16x32_bf16 v[86:89], v[174:177], v[228:231], 0
	v_mfma_f32_16x16x32_bf16 v[82:85], v[182:185], v[228:231], 0
	v_mfma_f32_16x16x32_bf16 v[78:81], v[136:139], v[236:239], 0
	v_mfma_f32_16x16x32_bf16 v[74:77], v[154:157], v[236:239], 0
	v_mfma_f32_16x16x32_bf16 v[70:73], v[174:177], v[236:239], 0
	v_mfma_f32_16x16x32_bf16 v[66:69], v[182:185], v[236:239], 0
	v_mfma_f32_16x16x32_bf16 v[122:125], v[140:143], v[194:197], v[122:125]
	v_mfma_f32_16x16x32_bf16 v[126:129], v[170:173], v[194:197], v[126:129]
	v_mfma_f32_16x16x32_bf16 v[118:121], v[178:181], v[194:197], v[118:121]
	v_mfma_f32_16x16x32_bf16 v[114:117], v[186:189], v[194:197], v[114:117]
	v_mfma_f32_16x16x32_bf16 v[110:113], v[140:143], v[202:205], v[110:113]
	v_mfma_f32_16x16x32_bf16 v[106:109], v[170:173], v[202:205], v[106:109]
	v_mfma_f32_16x16x32_bf16 v[102:105], v[178:181], v[202:205], v[102:105]
	v_mfma_f32_16x16x32_bf16 v[98:101], v[186:189], v[202:205], v[98:101]
	v_mfma_f32_16x16x32_bf16 v[94:97], v[140:143], v[232:235], v[94:97]
	v_mfma_f32_16x16x32_bf16 v[90:93], v[170:173], v[232:235], v[90:93]
	v_mfma_f32_16x16x32_bf16 v[86:89], v[178:181], v[232:235], v[86:89]
	v_mfma_f32_16x16x32_bf16 v[82:85], v[186:189], v[232:235], v[82:85]
	v_mfma_f32_16x16x32_bf16 v[78:81], v[140:143], v[240:243], v[78:81]
	v_mfma_f32_16x16x32_bf16 v[74:77], v[170:173], v[240:243], v[74:77]
	v_mfma_f32_16x16x32_bf16 v[70:73], v[178:181], v[240:243], v[70:73]
	v_mfma_f32_16x16x32_bf16 v[66:69], v[186:189], v[240:243], v[66:69]
	s_barrier
	s_setprio 0
	s_mov_b32 m0, s14
	s_mov_b32 s46, s62
	s_mov_b32 s47, s63
	ds_read_b128 v[190:193], v135 offset:16384
	ds_read_b128 v[194:197], v135 offset:17408
	ds_read_b128 v[198:201], v135 offset:18432
	ds_read_b128 v[202:205], v135 offset:19456
	ds_read_b128 v[228:231], v135 offset:20480
	ds_read_b128 v[232:235], v135 offset:21504
	ds_read_b128 v[236:239], v135 offset:22528
	ds_read_b128 v[240:243], v135 offset:23552
	buffer_load_dwordx4 v131, s[44:47], s85 offen lds
	s_mov_b32 m0, s15
	s_add_i32 s53, s85, s2
	buffer_load_dwordx4 v133, s[44:47], s85 offen lds
	s_mov_b32 m0, s16
	s_nop 0
	buffer_load_dwordx4 v131, s[44:47], s53 offen lds
	s_mov_b32 m0, s18
	s_nop 0
	buffer_load_dwordx4 v133, s[44:47], s53 offen lds
	s_mov_b32 m0, s13
	s_nop 0
	buffer_load_dwordx4 v130, s[60:63], s52 offen lds
	s_mov_b32 m0, s19
	s_nop 0
	buffer_load_dwordx4 v132, s[60:63], s52 offen lds
	s_waitcnt vmcnt(8)
	s_waitcnt lgkmcnt(0)
	s_setprio 1
	s_barrier
	v_mfma_f32_16x16x32_bf16 v[62:65], v[136:139], v[190:193], 0
	v_mfma_f32_16x16x32_bf16 v[58:61], v[154:157], v[190:193], 0
	v_mfma_f32_16x16x32_bf16 v[54:57], v[174:177], v[190:193], 0
	v_mfma_f32_16x16x32_bf16 v[50:53], v[182:185], v[190:193], 0
	v_mfma_f32_16x16x32_bf16 v[46:49], v[136:139], v[198:201], 0
	v_mfma_f32_16x16x32_bf16 v[42:45], v[154:157], v[198:201], 0
	v_mfma_f32_16x16x32_bf16 v[38:41], v[174:177], v[198:201], 0
	v_mfma_f32_16x16x32_bf16 v[34:37], v[182:185], v[198:201], 0
	v_mfma_f32_16x16x32_bf16 v[30:33], v[136:139], v[228:231], 0
	v_mfma_f32_16x16x32_bf16 v[26:29], v[154:157], v[228:231], 0
	v_mfma_f32_16x16x32_bf16 v[22:25], v[174:177], v[228:231], 0
	v_mfma_f32_16x16x32_bf16 v[18:21], v[182:185], v[228:231], 0
	v_mfma_f32_16x16x32_bf16 v[14:17], v[136:139], v[236:239], 0
	v_mfma_f32_16x16x32_bf16 v[10:13], v[154:157], v[236:239], 0
	v_mfma_f32_16x16x32_bf16 v[6:9], v[174:177], v[236:239], 0
	v_mfma_f32_16x16x32_bf16 v[2:5], v[182:185], v[236:239], 0
	v_mfma_f32_16x16x32_bf16 v[62:65], v[140:143], v[194:197], v[62:65]
	v_mfma_f32_16x16x32_bf16 v[58:61], v[170:173], v[194:197], v[58:61]
	v_mfma_f32_16x16x32_bf16 v[54:57], v[178:181], v[194:197], v[54:57]
	v_mfma_f32_16x16x32_bf16 v[50:53], v[186:189], v[194:197], v[50:53]
	v_mfma_f32_16x16x32_bf16 v[46:49], v[140:143], v[202:205], v[46:49]
	v_mfma_f32_16x16x32_bf16 v[42:45], v[170:173], v[202:205], v[42:45]
	v_mfma_f32_16x16x32_bf16 v[38:41], v[178:181], v[202:205], v[38:41]
	v_mfma_f32_16x16x32_bf16 v[34:37], v[186:189], v[202:205], v[34:37]
	v_mfma_f32_16x16x32_bf16 v[30:33], v[140:143], v[232:235], v[30:33]
	v_mfma_f32_16x16x32_bf16 v[26:29], v[170:173], v[232:235], v[26:29]
	v_mfma_f32_16x16x32_bf16 v[22:25], v[178:181], v[232:235], v[22:25]
	v_mfma_f32_16x16x32_bf16 v[18:21], v[186:189], v[232:235], v[18:21]
	v_mfma_f32_16x16x32_bf16 v[14:17], v[140:143], v[240:243], v[14:17]
	v_mfma_f32_16x16x32_bf16 v[10:13], v[170:173], v[240:243], v[10:13]
	v_mfma_f32_16x16x32_bf16 v[6:9], v[178:181], v[240:243], v[6:9]
	v_mfma_f32_16x16x32_bf16 v[2:5], v[186:189], v[240:243], v[2:5]
	s_barrier
	s_setprio 0
	v_add_u32_e32 v144, 0x18000, v134
	ds_read_b128 v[136:139], v144
	ds_read_b128 v[140:143], v144 offset:1024
	ds_read_b128 v[154:157], v144 offset:2048
	ds_read_b128 v[170:173], v144 offset:3072
	v_add_u32_e32 v144, 0x1c000, v134
	ds_read_b128 v[174:177], v144
	ds_read_b128 v[178:181], v144 offset:1024
	ds_read_b128 v[182:185], v144 offset:2048
	ds_read_b128 v[186:189], v144 offset:3072
	s_add_i32 s52, s52, s2
	s_mov_b32 m0, s21
	ds_read_b128 v[190:193], v135 offset:32768
	ds_read_b128 v[194:197], v135 offset:33792
	ds_read_b128 v[198:201], v135 offset:34816
	ds_read_b128 v[202:205], v135 offset:35840
	ds_read_b128 v[228:231], v135 offset:36864
	ds_read_b128 v[232:235], v135 offset:37888
	ds_read_b128 v[236:239], v135 offset:38912
	ds_read_b128 v[240:243], v135 offset:39936
	buffer_load_dwordx4 v130, s[60:63], s52 offen lds
	s_mov_b32 m0, s22
	s_nop 0
	buffer_load_dwordx4 v132, s[60:63], s52 offen lds
	s_waitcnt vmcnt(8)
	s_waitcnt lgkmcnt(0)
	s_setprio 1
	s_barrier
	v_mfma_f32_16x16x32_bf16 v[122:125], v[136:139], v[190:193], v[122:125]
	v_mfma_f32_16x16x32_bf16 v[126:129], v[154:157], v[190:193], v[126:129]
	v_mfma_f32_16x16x32_bf16 v[118:121], v[174:177], v[190:193], v[118:121]
	v_mfma_f32_16x16x32_bf16 v[114:117], v[182:185], v[190:193], v[114:117]
	v_mfma_f32_16x16x32_bf16 v[110:113], v[136:139], v[198:201], v[110:113]
	v_mfma_f32_16x16x32_bf16 v[106:109], v[154:157], v[198:201], v[106:109]
	v_mfma_f32_16x16x32_bf16 v[102:105], v[174:177], v[198:201], v[102:105]
	v_mfma_f32_16x16x32_bf16 v[98:101], v[182:185], v[198:201], v[98:101]
	v_mfma_f32_16x16x32_bf16 v[94:97], v[136:139], v[228:231], v[94:97]
	v_mfma_f32_16x16x32_bf16 v[90:93], v[154:157], v[228:231], v[90:93]
	v_mfma_f32_16x16x32_bf16 v[86:89], v[174:177], v[228:231], v[86:89]
	v_mfma_f32_16x16x32_bf16 v[82:85], v[182:185], v[228:231], v[82:85]
	v_mfma_f32_16x16x32_bf16 v[78:81], v[136:139], v[236:239], v[78:81]
	v_mfma_f32_16x16x32_bf16 v[74:77], v[154:157], v[236:239], v[74:77]
	v_mfma_f32_16x16x32_bf16 v[70:73], v[174:177], v[236:239], v[70:73]
	v_mfma_f32_16x16x32_bf16 v[66:69], v[182:185], v[236:239], v[66:69]
	v_mfma_f32_16x16x32_bf16 v[122:125], v[140:143], v[194:197], v[122:125]
	v_mfma_f32_16x16x32_bf16 v[126:129], v[170:173], v[194:197], v[126:129]
	v_mfma_f32_16x16x32_bf16 v[118:121], v[178:181], v[194:197], v[118:121]
	v_mfma_f32_16x16x32_bf16 v[114:117], v[186:189], v[194:197], v[114:117]
	v_mfma_f32_16x16x32_bf16 v[110:113], v[140:143], v[202:205], v[110:113]
	v_mfma_f32_16x16x32_bf16 v[106:109], v[170:173], v[202:205], v[106:109]
	v_mfma_f32_16x16x32_bf16 v[102:105], v[178:181], v[202:205], v[102:105]
	v_mfma_f32_16x16x32_bf16 v[98:101], v[186:189], v[202:205], v[98:101]
	v_mfma_f32_16x16x32_bf16 v[94:97], v[140:143], v[232:235], v[94:97]
	v_mfma_f32_16x16x32_bf16 v[90:93], v[170:173], v[232:235], v[90:93]
	v_mfma_f32_16x16x32_bf16 v[86:89], v[178:181], v[232:235], v[86:89]
	v_mfma_f32_16x16x32_bf16 v[82:85], v[186:189], v[232:235], v[82:85]
	v_mfma_f32_16x16x32_bf16 v[78:81], v[140:143], v[240:243], v[78:81]
	v_mfma_f32_16x16x32_bf16 v[74:77], v[170:173], v[240:243], v[74:77]
	v_mfma_f32_16x16x32_bf16 v[70:73], v[178:181], v[240:243], v[70:73]
	v_mfma_f32_16x16x32_bf16 v[66:69], v[186:189], v[240:243], v[66:69]
	s_barrier
	s_setprio 0
	s_mov_b32 m0, s33
	s_add_i32 s52, s85, 0x80
	ds_read_b128 v[190:193], v135 offset:49152
	ds_read_b128 v[194:197], v135 offset:50176
	ds_read_b128 v[198:201], v135 offset:51200
	ds_read_b128 v[202:205], v135 offset:52224
	ds_read_b128 v[228:231], v135 offset:53248
	ds_read_b128 v[232:235], v135 offset:54272
	ds_read_b128 v[236:239], v135 offset:55296
	ds_read_b128 v[240:243], v135 offset:56320
	buffer_load_dwordx4 v131, s[44:47], s52 offen lds
	s_mov_b32 m0, s36
	s_nop 0
	buffer_load_dwordx4 v133, s[44:47], s52 offen lds
	s_add_i32 s52, s52, s2
	s_mov_b32 m0, s43
	s_nop 0
	buffer_load_dwordx4 v131, s[44:47], s52 offen lds
	s_mov_b32 m0, s48
	s_nop 0
	buffer_load_dwordx4 v133, s[44:47], s52 offen lds
	s_mov_b32 m0, s37
	s_nop 0
	buffer_load_dwordx4 v130, s[60:63], s84 offen lds
	s_mov_b32 m0, s42
	s_nop 0
	buffer_load_dwordx4 v132, s[60:63], s84 offen lds
	s_waitcnt vmcnt(8)
	s_waitcnt lgkmcnt(0)
	s_setprio 1
	s_barrier
	v_mfma_f32_16x16x32_bf16 v[62:65], v[136:139], v[190:193], v[62:65]
	v_mfma_f32_16x16x32_bf16 v[58:61], v[154:157], v[190:193], v[58:61]
	v_mfma_f32_16x16x32_bf16 v[54:57], v[174:177], v[190:193], v[54:57]
	v_mfma_f32_16x16x32_bf16 v[50:53], v[182:185], v[190:193], v[50:53]
	v_mfma_f32_16x16x32_bf16 v[46:49], v[136:139], v[198:201], v[46:49]
	v_mfma_f32_16x16x32_bf16 v[42:45], v[154:157], v[198:201], v[42:45]
	v_mfma_f32_16x16x32_bf16 v[38:41], v[174:177], v[198:201], v[38:41]
	v_mfma_f32_16x16x32_bf16 v[34:37], v[182:185], v[198:201], v[34:37]
	v_mfma_f32_16x16x32_bf16 v[30:33], v[136:139], v[228:231], v[30:33]
	v_mfma_f32_16x16x32_bf16 v[26:29], v[154:157], v[228:231], v[26:29]
	v_mfma_f32_16x16x32_bf16 v[22:25], v[174:177], v[228:231], v[22:25]
	v_mfma_f32_16x16x32_bf16 v[18:21], v[182:185], v[228:231], v[18:21]
	v_mfma_f32_16x16x32_bf16 v[14:17], v[136:139], v[236:239], v[14:17]
	v_mfma_f32_16x16x32_bf16 v[10:13], v[154:157], v[236:239], v[10:13]
	v_mfma_f32_16x16x32_bf16 v[6:9], v[174:177], v[236:239], v[6:9]
	v_mfma_f32_16x16x32_bf16 v[2:5], v[182:185], v[236:239], v[2:5]
	v_mfma_f32_16x16x32_bf16 v[62:65], v[140:143], v[194:197], v[62:65]
	v_mfma_f32_16x16x32_bf16 v[58:61], v[170:173], v[194:197], v[58:61]
	v_mfma_f32_16x16x32_bf16 v[54:57], v[178:181], v[194:197], v[54:57]
	v_mfma_f32_16x16x32_bf16 v[50:53], v[186:189], v[194:197], v[50:53]
	v_mfma_f32_16x16x32_bf16 v[46:49], v[140:143], v[202:205], v[46:49]
	v_mfma_f32_16x16x32_bf16 v[42:45], v[170:173], v[202:205], v[42:45]
	v_mfma_f32_16x16x32_bf16 v[38:41], v[178:181], v[202:205], v[38:41]
	v_mfma_f32_16x16x32_bf16 v[34:37], v[186:189], v[202:205], v[34:37]
	v_mfma_f32_16x16x32_bf16 v[30:33], v[140:143], v[232:235], v[30:33]
	v_mfma_f32_16x16x32_bf16 v[26:29], v[170:173], v[232:235], v[26:29]
	v_mfma_f32_16x16x32_bf16 v[22:25], v[178:181], v[232:235], v[22:25]
	v_mfma_f32_16x16x32_bf16 v[18:21], v[186:189], v[232:235], v[18:21]
	v_mfma_f32_16x16x32_bf16 v[14:17], v[140:143], v[240:243], v[14:17]
	v_mfma_f32_16x16x32_bf16 v[10:13], v[170:173], v[240:243], v[10:13]
	v_mfma_f32_16x16x32_bf16 v[6:9], v[178:181], v[240:243], v[6:9]
	v_mfma_f32_16x16x32_bf16 v[2:5], v[186:189], v[240:243], v[2:5]
	s_barrier
	s_setprio 0
	s_add_i32 s83, s83, 2
	s_addk_i32 s73, 0x100
	s_addk_i32 s82, 0x100
	s_cmp_ge_i32 s83, s23
.LBB0_2175:
	v_add_u32_e32 v144, 0x10000, v134
	ds_read_b128 v[136:139], v144
	ds_read_b128 v[140:143], v144 offset:1024
	ds_read_b128 v[154:157], v144 offset:2048
	ds_read_b128 v[170:173], v144 offset:3072
	v_add_u32_e32 v144, 0x14000, v134
	ds_read_b128 v[174:177], v144
	ds_read_b128 v[178:181], v144 offset:1024
	ds_read_b128 v[182:185], v144 offset:2048
	ds_read_b128 v[186:189], v144 offset:3072
	s_add_i32 s46, s73, 0x80
	s_cmp_eq_u32 s49, s83
	s_cselect_b32 s52, s8, s46
	s_cselect_b32 s85, s9, s82
	s_add_i32 s84, s52, 0x80
	s_add_i32 s46, s2, s73
	s_mov_b32 m0, s64
	ds_read_b128 v[190:193], v135
	ds_read_b128 v[194:197], v135 offset:1024
	ds_read_b128 v[198:201], v135 offset:2048
	ds_read_b128 v[202:205], v135 offset:3072
	ds_read_b128 v[228:231], v135 offset:4096
	ds_read_b128 v[232:235], v135 offset:5120
	ds_read_b128 v[236:239], v135 offset:6144
	ds_read_b128 v[240:243], v135 offset:7168
	buffer_load_dwordx4 v130, s[60:63], s46 offen lds
	s_mov_b32 m0, s65
	s_nop 0
	buffer_load_dwordx4 v132, s[60:63], s46 offen lds
	s_waitcnt vmcnt(8)
	s_waitcnt lgkmcnt(0)
	s_setprio 1
	s_barrier
	v_mfma_f32_16x16x32_bf16 v[122:125], v[136:139], v[190:193], v[122:125]
	v_mfma_f32_16x16x32_bf16 v[126:129], v[154:157], v[190:193], v[126:129]
	v_mfma_f32_16x16x32_bf16 v[118:121], v[174:177], v[190:193], v[118:121]
	v_mfma_f32_16x16x32_bf16 v[114:117], v[182:185], v[190:193], v[114:117]
	v_mfma_f32_16x16x32_bf16 v[110:113], v[136:139], v[198:201], v[110:113]
	v_mfma_f32_16x16x32_bf16 v[106:109], v[154:157], v[198:201], v[106:109]
	v_mfma_f32_16x16x32_bf16 v[102:105], v[174:177], v[198:201], v[102:105]
	v_mfma_f32_16x16x32_bf16 v[98:101], v[182:185], v[198:201], v[98:101]
	v_mfma_f32_16x16x32_bf16 v[94:97], v[136:139], v[228:231], v[94:97]
	v_mfma_f32_16x16x32_bf16 v[90:93], v[154:157], v[228:231], v[90:93]
	v_mfma_f32_16x16x32_bf16 v[86:89], v[174:177], v[228:231], v[86:89]
	v_mfma_f32_16x16x32_bf16 v[82:85], v[182:185], v[228:231], v[82:85]
	v_mfma_f32_16x16x32_bf16 v[78:81], v[136:139], v[236:239], v[78:81]
	v_mfma_f32_16x16x32_bf16 v[74:77], v[154:157], v[236:239], v[74:77]
	v_mfma_f32_16x16x32_bf16 v[70:73], v[174:177], v[236:239], v[70:73]
	v_mfma_f32_16x16x32_bf16 v[66:69], v[182:185], v[236:239], v[66:69]
	v_mfma_f32_16x16x32_bf16 v[122:125], v[140:143], v[194:197], v[122:125]
	v_mfma_f32_16x16x32_bf16 v[126:129], v[170:173], v[194:197], v[126:129]
	v_mfma_f32_16x16x32_bf16 v[118:121], v[178:181], v[194:197], v[118:121]
	v_mfma_f32_16x16x32_bf16 v[114:117], v[186:189], v[194:197], v[114:117]
	v_mfma_f32_16x16x32_bf16 v[110:113], v[140:143], v[202:205], v[110:113]
	v_mfma_f32_16x16x32_bf16 v[106:109], v[170:173], v[202:205], v[106:109]
	v_mfma_f32_16x16x32_bf16 v[102:105], v[178:181], v[202:205], v[102:105]
	v_mfma_f32_16x16x32_bf16 v[98:101], v[186:189], v[202:205], v[98:101]
	v_mfma_f32_16x16x32_bf16 v[94:97], v[140:143], v[232:235], v[94:97]
	v_mfma_f32_16x16x32_bf16 v[90:93], v[170:173], v[232:235], v[90:93]
	v_mfma_f32_16x16x32_bf16 v[86:89], v[178:181], v[232:235], v[86:89]
	v_mfma_f32_16x16x32_bf16 v[82:85], v[186:189], v[232:235], v[82:85]
	v_mfma_f32_16x16x32_bf16 v[78:81], v[140:143], v[240:243], v[78:81]
	v_mfma_f32_16x16x32_bf16 v[74:77], v[170:173], v[240:243], v[74:77]
	v_mfma_f32_16x16x32_bf16 v[70:73], v[178:181], v[240:243], v[70:73]
	v_mfma_f32_16x16x32_bf16 v[66:69], v[186:189], v[240:243], v[66:69]
	s_barrier
	s_setprio 0
	s_mov_b32 m0, s14
	s_mov_b32 s46, s62
	s_mov_b32 s47, s63
	ds_read_b128 v[190:193], v135 offset:16384
	ds_read_b128 v[194:197], v135 offset:17408
	ds_read_b128 v[198:201], v135 offset:18432
	ds_read_b128 v[202:205], v135 offset:19456
	ds_read_b128 v[228:231], v135 offset:20480
	ds_read_b128 v[232:235], v135 offset:21504
	ds_read_b128 v[236:239], v135 offset:22528
	ds_read_b128 v[240:243], v135 offset:23552
	buffer_load_dwordx4 v131, s[44:47], s85 offen lds
	s_mov_b32 m0, s15
	s_add_i32 s53, s85, s2
	buffer_load_dwordx4 v133, s[44:47], s85 offen lds
	s_mov_b32 m0, s16
	s_nop 0
	buffer_load_dwordx4 v131, s[44:47], s53 offen lds
	s_mov_b32 m0, s18
	s_nop 0
	buffer_load_dwordx4 v133, s[44:47], s53 offen lds
	s_mov_b32 m0, s13
	s_nop 0
	buffer_load_dwordx4 v130, s[60:63], s52 offen lds
	s_mov_b32 m0, s19
	s_nop 0
	buffer_load_dwordx4 v132, s[60:63], s52 offen lds
	s_waitcnt vmcnt(8)
	s_waitcnt lgkmcnt(0)
	s_setprio 1
	s_barrier
	v_mfma_f32_16x16x32_bf16 v[62:65], v[136:139], v[190:193], v[62:65]
	v_mfma_f32_16x16x32_bf16 v[58:61], v[154:157], v[190:193], v[58:61]
	v_mfma_f32_16x16x32_bf16 v[54:57], v[174:177], v[190:193], v[54:57]
	v_mfma_f32_16x16x32_bf16 v[50:53], v[182:185], v[190:193], v[50:53]
	v_mfma_f32_16x16x32_bf16 v[46:49], v[136:139], v[198:201], v[46:49]
	v_mfma_f32_16x16x32_bf16 v[42:45], v[154:157], v[198:201], v[42:45]
	v_mfma_f32_16x16x32_bf16 v[38:41], v[174:177], v[198:201], v[38:41]
	v_mfma_f32_16x16x32_bf16 v[34:37], v[182:185], v[198:201], v[34:37]
	v_mfma_f32_16x16x32_bf16 v[30:33], v[136:139], v[228:231], v[30:33]
	v_mfma_f32_16x16x32_bf16 v[26:29], v[154:157], v[228:231], v[26:29]
	v_mfma_f32_16x16x32_bf16 v[22:25], v[174:177], v[228:231], v[22:25]
	v_mfma_f32_16x16x32_bf16 v[18:21], v[182:185], v[228:231], v[18:21]
	v_mfma_f32_16x16x32_bf16 v[14:17], v[136:139], v[236:239], v[14:17]
	v_mfma_f32_16x16x32_bf16 v[10:13], v[154:157], v[236:239], v[10:13]
	v_mfma_f32_16x16x32_bf16 v[6:9], v[174:177], v[236:239], v[6:9]
	v_mfma_f32_16x16x32_bf16 v[2:5], v[182:185], v[236:239], v[2:5]
	v_mfma_f32_16x16x32_bf16 v[62:65], v[140:143], v[194:197], v[62:65]
	v_mfma_f32_16x16x32_bf16 v[58:61], v[170:173], v[194:197], v[58:61]
	v_mfma_f32_16x16x32_bf16 v[54:57], v[178:181], v[194:197], v[54:57]
	v_mfma_f32_16x16x32_bf16 v[50:53], v[186:189], v[194:197], v[50:53]
	v_mfma_f32_16x16x32_bf16 v[46:49], v[140:143], v[202:205], v[46:49]
	v_mfma_f32_16x16x32_bf16 v[42:45], v[170:173], v[202:205], v[42:45]
	v_mfma_f32_16x16x32_bf16 v[38:41], v[178:181], v[202:205], v[38:41]
	v_mfma_f32_16x16x32_bf16 v[34:37], v[186:189], v[202:205], v[34:37]
	v_mfma_f32_16x16x32_bf16 v[30:33], v[140:143], v[232:235], v[30:33]
	v_mfma_f32_16x16x32_bf16 v[26:29], v[170:173], v[232:235], v[26:29]
	v_mfma_f32_16x16x32_bf16 v[22:25], v[178:181], v[232:235], v[22:25]
	v_mfma_f32_16x16x32_bf16 v[18:21], v[186:189], v[232:235], v[18:21]
	v_mfma_f32_16x16x32_bf16 v[14:17], v[140:143], v[240:243], v[14:17]
	v_mfma_f32_16x16x32_bf16 v[10:13], v[170:173], v[240:243], v[10:13]
	v_mfma_f32_16x16x32_bf16 v[6:9], v[178:181], v[240:243], v[6:9]
	v_mfma_f32_16x16x32_bf16 v[2:5], v[186:189], v[240:243], v[2:5]
	s_barrier
	s_setprio 0
	v_add_u32_e32 v144, 0x18000, v134
	ds_read_b128 v[136:139], v144
	ds_read_b128 v[140:143], v144 offset:1024
	ds_read_b128 v[154:157], v144 offset:2048
	ds_read_b128 v[170:173], v144 offset:3072
	v_add_u32_e32 v144, 0x1c000, v134
	ds_read_b128 v[174:177], v144
	ds_read_b128 v[178:181], v144 offset:1024
	ds_read_b128 v[182:185], v144 offset:2048
	ds_read_b128 v[186:189], v144 offset:3072
	s_add_i32 s52, s52, s2
	s_mov_b32 m0, s21
	ds_read_b128 v[190:193], v135 offset:32768
	ds_read_b128 v[194:197], v135 offset:33792
	ds_read_b128 v[198:201], v135 offset:34816
	ds_read_b128 v[202:205], v135 offset:35840
	ds_read_b128 v[228:231], v135 offset:36864
	ds_read_b128 v[232:235], v135 offset:37888
	ds_read_b128 v[236:239], v135 offset:38912
	ds_read_b128 v[240:243], v135 offset:39936
	buffer_load_dwordx4 v130, s[60:63], s52 offen lds
	s_mov_b32 m0, s22
	s_nop 0
	buffer_load_dwordx4 v132, s[60:63], s52 offen lds
	s_waitcnt vmcnt(8)
	s_waitcnt lgkmcnt(0)
	s_setprio 1
	s_barrier
	v_mfma_f32_16x16x32_bf16 v[122:125], v[136:139], v[190:193], v[122:125]
	v_mfma_f32_16x16x32_bf16 v[126:129], v[154:157], v[190:193], v[126:129]
	v_mfma_f32_16x16x32_bf16 v[118:121], v[174:177], v[190:193], v[118:121]
	v_mfma_f32_16x16x32_bf16 v[114:117], v[182:185], v[190:193], v[114:117]
	v_mfma_f32_16x16x32_bf16 v[110:113], v[136:139], v[198:201], v[110:113]
	v_mfma_f32_16x16x32_bf16 v[106:109], v[154:157], v[198:201], v[106:109]
	v_mfma_f32_16x16x32_bf16 v[102:105], v[174:177], v[198:201], v[102:105]
	v_mfma_f32_16x16x32_bf16 v[98:101], v[182:185], v[198:201], v[98:101]
	v_mfma_f32_16x16x32_bf16 v[94:97], v[136:139], v[228:231], v[94:97]
	v_mfma_f32_16x16x32_bf16 v[90:93], v[154:157], v[228:231], v[90:93]
	v_mfma_f32_16x16x32_bf16 v[86:89], v[174:177], v[228:231], v[86:89]
	v_mfma_f32_16x16x32_bf16 v[82:85], v[182:185], v[228:231], v[82:85]
	v_mfma_f32_16x16x32_bf16 v[78:81], v[136:139], v[236:239], v[78:81]
	v_mfma_f32_16x16x32_bf16 v[74:77], v[154:157], v[236:239], v[74:77]
	v_mfma_f32_16x16x32_bf16 v[70:73], v[174:177], v[236:239], v[70:73]
	v_mfma_f32_16x16x32_bf16 v[66:69], v[182:185], v[236:239], v[66:69]
	v_mfma_f32_16x16x32_bf16 v[122:125], v[140:143], v[194:197], v[122:125]
	v_mfma_f32_16x16x32_bf16 v[126:129], v[170:173], v[194:197], v[126:129]
	v_mfma_f32_16x16x32_bf16 v[118:121], v[178:181], v[194:197], v[118:121]
	v_mfma_f32_16x16x32_bf16 v[114:117], v[186:189], v[194:197], v[114:117]
	v_mfma_f32_16x16x32_bf16 v[110:113], v[140:143], v[202:205], v[110:113]
	v_mfma_f32_16x16x32_bf16 v[106:109], v[170:173], v[202:205], v[106:109]
	v_mfma_f32_16x16x32_bf16 v[102:105], v[178:181], v[202:205], v[102:105]
	v_mfma_f32_16x16x32_bf16 v[98:101], v[186:189], v[202:205], v[98:101]
	v_mfma_f32_16x16x32_bf16 v[94:97], v[140:143], v[232:235], v[94:97]
	v_mfma_f32_16x16x32_bf16 v[90:93], v[170:173], v[232:235], v[90:93]
	v_mfma_f32_16x16x32_bf16 v[86:89], v[178:181], v[232:235], v[86:89]
	v_mfma_f32_16x16x32_bf16 v[82:85], v[186:189], v[232:235], v[82:85]
	v_mfma_f32_16x16x32_bf16 v[78:81], v[140:143], v[240:243], v[78:81]
	v_mfma_f32_16x16x32_bf16 v[74:77], v[170:173], v[240:243], v[74:77]
	v_mfma_f32_16x16x32_bf16 v[70:73], v[178:181], v[240:243], v[70:73]
	v_mfma_f32_16x16x32_bf16 v[66:69], v[186:189], v[240:243], v[66:69]
	s_barrier
	s_setprio 0
	s_mov_b32 m0, s33
	s_add_i32 s52, s85, 0x80
	ds_read_b128 v[190:193], v135 offset:49152
	ds_read_b128 v[194:197], v135 offset:50176
	ds_read_b128 v[198:201], v135 offset:51200
	ds_read_b128 v[202:205], v135 offset:52224
	ds_read_b128 v[228:231], v135 offset:53248
	ds_read_b128 v[232:235], v135 offset:54272
	ds_read_b128 v[236:239], v135 offset:55296
	ds_read_b128 v[240:243], v135 offset:56320
	buffer_load_dwordx4 v131, s[44:47], s52 offen lds
	s_mov_b32 m0, s36
	s_nop 0
	buffer_load_dwordx4 v133, s[44:47], s52 offen lds
	s_add_i32 s52, s52, s2
	s_mov_b32 m0, s43
	s_nop 0
	buffer_load_dwordx4 v131, s[44:47], s52 offen lds
	s_mov_b32 m0, s48
	s_nop 0
	buffer_load_dwordx4 v133, s[44:47], s52 offen lds
	s_mov_b32 m0, s37
	s_nop 0
	buffer_load_dwordx4 v130, s[60:63], s84 offen lds
	s_mov_b32 m0, s42
	s_nop 0
	buffer_load_dwordx4 v132, s[60:63], s84 offen lds
	s_waitcnt vmcnt(8)
	s_waitcnt lgkmcnt(0)
	s_setprio 1
	s_barrier
	v_mfma_f32_16x16x32_bf16 v[62:65], v[136:139], v[190:193], v[62:65]
	v_mfma_f32_16x16x32_bf16 v[58:61], v[154:157], v[190:193], v[58:61]
	v_mfma_f32_16x16x32_bf16 v[54:57], v[174:177], v[190:193], v[54:57]
	v_mfma_f32_16x16x32_bf16 v[50:53], v[182:185], v[190:193], v[50:53]
	v_mfma_f32_16x16x32_bf16 v[46:49], v[136:139], v[198:201], v[46:49]
	v_mfma_f32_16x16x32_bf16 v[42:45], v[154:157], v[198:201], v[42:45]
	v_mfma_f32_16x16x32_bf16 v[38:41], v[174:177], v[198:201], v[38:41]
	v_mfma_f32_16x16x32_bf16 v[34:37], v[182:185], v[198:201], v[34:37]
	v_mfma_f32_16x16x32_bf16 v[30:33], v[136:139], v[228:231], v[30:33]
	v_mfma_f32_16x16x32_bf16 v[26:29], v[154:157], v[228:231], v[26:29]
	v_mfma_f32_16x16x32_bf16 v[22:25], v[174:177], v[228:231], v[22:25]
	v_mfma_f32_16x16x32_bf16 v[18:21], v[182:185], v[228:231], v[18:21]
	v_mfma_f32_16x16x32_bf16 v[14:17], v[136:139], v[236:239], v[14:17]
	v_mfma_f32_16x16x32_bf16 v[10:13], v[154:157], v[236:239], v[10:13]
	v_mfma_f32_16x16x32_bf16 v[6:9], v[174:177], v[236:239], v[6:9]
	v_mfma_f32_16x16x32_bf16 v[2:5], v[182:185], v[236:239], v[2:5]
	v_mfma_f32_16x16x32_bf16 v[62:65], v[140:143], v[194:197], v[62:65]
	v_mfma_f32_16x16x32_bf16 v[58:61], v[170:173], v[194:197], v[58:61]
	v_mfma_f32_16x16x32_bf16 v[54:57], v[178:181], v[194:197], v[54:57]
	v_mfma_f32_16x16x32_bf16 v[50:53], v[186:189], v[194:197], v[50:53]
	v_mfma_f32_16x16x32_bf16 v[46:49], v[140:143], v[202:205], v[46:49]
	v_mfma_f32_16x16x32_bf16 v[42:45], v[170:173], v[202:205], v[42:45]
	v_mfma_f32_16x16x32_bf16 v[38:41], v[178:181], v[202:205], v[38:41]
	v_mfma_f32_16x16x32_bf16 v[34:37], v[186:189], v[202:205], v[34:37]
	v_mfma_f32_16x16x32_bf16 v[30:33], v[140:143], v[232:235], v[30:33]
	v_mfma_f32_16x16x32_bf16 v[26:29], v[170:173], v[232:235], v[26:29]
	v_mfma_f32_16x16x32_bf16 v[22:25], v[178:181], v[232:235], v[22:25]
	v_mfma_f32_16x16x32_bf16 v[18:21], v[186:189], v[232:235], v[18:21]
	v_mfma_f32_16x16x32_bf16 v[14:17], v[140:143], v[240:243], v[14:17]
	v_mfma_f32_16x16x32_bf16 v[10:13], v[170:173], v[240:243], v[10:13]
	v_mfma_f32_16x16x32_bf16 v[6:9], v[178:181], v[240:243], v[6:9]
	v_mfma_f32_16x16x32_bf16 v[2:5], v[186:189], v[240:243], v[2:5]
	s_barrier
	s_setprio 0
	s_add_i32 s83, s83, 2
	s_addk_i32 s73, 0x100
	s_addk_i32 s82, 0x100
	s_cmp_ge_i32 s83, s23
	s_cbranch_scc0 .LBB0_2175
	v_readlane_b32 s83, v252, 30

.LBB0_2449:
	s_lshl_b32 s73, s72, 20
	s_and_b64 s[8:9], s[40:41], exec
	s_cselect_b32 s8, s73, s13
	s_lshl_b32 s84, s71, 20
	s_and_b64 s[24:25], s[40:41], exec
	s_cselect_b32 s9, s84, s21
	s_add_i32 s13, s13, 0x80080
	s_addk_i32 s21, 0x100
	s_mov_b32 s22, -2
	s_waitcnt lgkmcnt(0)
	v_add_u32_e32 v142, 0x10000, v188
	v_add_u32_e32 v182, 0x14000, v188
	ds_read_b128 v[130:133], v142
	ds_read_b128 v[134:137], v142 offset:1024
	ds_read_b128 v[138:141], v142 offset:2048
	ds_read_b128 v[142:145], v142 offset:3072
	ds_read_b128 v[154:157], v182
	ds_read_b128 v[174:177], v182 offset:1024
	ds_read_b128 v[178:181], v182 offset:2048
	ds_read_b128 v[190:193], v182 offset:3072
	s_add_i32 s24, s13, 0xfff80080
	s_cmp_eq_u32 s22, 28
	s_cselect_b32 s52, s8, s24
	s_cselect_b32 s25, s9, s21
	s_or_b32 s24, s52, 0x80
	s_mov_b32 m0, s68
	ds_read_b128 v[194:197], v189
	ds_read_b128 v[198:201], v189 offset:1024
	ds_read_b128 v[202:205], v189 offset:2048
	ds_read_b128 v[228:231], v189 offset:3072
	ds_read_b128 v[232:235], v189 offset:4096
	ds_read_b128 v[236:239], v189 offset:5120
	ds_read_b128 v[240:243], v189 offset:6144
	ds_read_b128 v[244:247], v189 offset:7168
	buffer_load_dwordx4 v184, s[60:63], s13 offen lds
	s_mov_b32 m0, s70
	s_nop 0
	buffer_load_dwordx4 v186, s[60:63], s13 offen lds
	s_waitcnt vmcnt(8)
	s_waitcnt lgkmcnt(0)
	s_setprio 1
	s_barrier
	v_mfma_f32_16x16x32_bf16 v[126:129], v[130:133], v[194:197], 0
	v_mfma_f32_16x16x32_bf16 v[122:125], v[138:141], v[194:197], 0
	v_mfma_f32_16x16x32_bf16 v[118:121], v[154:157], v[194:197], 0
	v_mfma_f32_16x16x32_bf16 v[114:117], v[178:181], v[194:197], 0
	v_mfma_f32_16x16x32_bf16 v[110:113], v[130:133], v[202:205], 0
	v_mfma_f32_16x16x32_bf16 v[106:109], v[138:141], v[202:205], 0
	v_mfma_f32_16x16x32_bf16 v[102:105], v[154:157], v[202:205], 0
	v_mfma_f32_16x16x32_bf16 v[98:101], v[178:181], v[202:205], 0
	v_mfma_f32_16x16x32_bf16 v[94:97], v[130:133], v[232:235], 0
	v_mfma_f32_16x16x32_bf16 v[90:93], v[138:141], v[232:235], 0
	v_mfma_f32_16x16x32_bf16 v[86:89], v[154:157], v[232:235], 0
	v_mfma_f32_16x16x32_bf16 v[82:85], v[178:181], v[232:235], 0
	v_mfma_f32_16x16x32_bf16 v[78:81], v[130:133], v[240:243], 0
	v_mfma_f32_16x16x32_bf16 v[74:77], v[138:141], v[240:243], 0
	v_mfma_f32_16x16x32_bf16 v[70:73], v[154:157], v[240:243], 0
	v_mfma_f32_16x16x32_bf16 v[66:69], v[178:181], v[240:243], 0
	v_mfma_f32_16x16x32_bf16 v[126:129], v[134:137], v[198:201], v[126:129]
	v_mfma_f32_16x16x32_bf16 v[122:125], v[142:145], v[198:201], v[122:125]
	v_mfma_f32_16x16x32_bf16 v[118:121], v[174:177], v[198:201], v[118:121]
	v_mfma_f32_16x16x32_bf16 v[114:117], v[190:193], v[198:201], v[114:117]
	v_mfma_f32_16x16x32_bf16 v[110:113], v[134:137], v[228:231], v[110:113]
	v_mfma_f32_16x16x32_bf16 v[106:109], v[142:145], v[228:231], v[106:109]
	v_mfma_f32_16x16x32_bf16 v[102:105], v[174:177], v[228:231], v[102:105]
	v_mfma_f32_16x16x32_bf16 v[98:101], v[190:193], v[228:231], v[98:101]
	v_mfma_f32_16x16x32_bf16 v[94:97], v[134:137], v[236:239], v[94:97]
	v_mfma_f32_16x16x32_bf16 v[90:93], v[142:145], v[236:239], v[90:93]
	v_mfma_f32_16x16x32_bf16 v[86:89], v[174:177], v[236:239], v[86:89]
	v_mfma_f32_16x16x32_bf16 v[82:85], v[190:193], v[236:239], v[82:85]
	v_mfma_f32_16x16x32_bf16 v[78:81], v[134:137], v[244:247], v[78:81]
	v_mfma_f32_16x16x32_bf16 v[74:77], v[142:145], v[244:247], v[74:77]
	v_mfma_f32_16x16x32_bf16 v[70:73], v[174:177], v[244:247], v[70:73]
	v_mfma_f32_16x16x32_bf16 v[66:69], v[190:193], v[244:247], v[66:69]
	s_barrier
	s_setprio 0
	s_mov_b32 m0, s16
	s_mov_b32 s46, s62
	s_mov_b32 s47, s63
	ds_read_b128 v[194:197], v189 offset:16384
	ds_read_b128 v[198:201], v189 offset:17408
	ds_read_b128 v[202:205], v189 offset:18432
	ds_read_b128 v[228:231], v189 offset:19456
	ds_read_b128 v[232:235], v189 offset:20480
	ds_read_b128 v[236:239], v189 offset:21504
	ds_read_b128 v[240:243], v189 offset:22528
	ds_read_b128 v[244:247], v189 offset:23552
	buffer_load_dwordx4 v185, s[44:47], s25 offen lds
	s_mov_b32 m0, s18
	s_add_i32 s53, s25, 0x80000
	buffer_load_dwordx4 v187, s[44:47], s25 offen lds
	s_mov_b32 m0, s19
	s_nop 0
	buffer_load_dwordx4 v185, s[44:47], s53 offen lds
	s_mov_b32 m0, s23
	s_nop 0
	buffer_load_dwordx4 v187, s[44:47], s53 offen lds
	s_mov_b32 m0, s15
	s_nop 0
	buffer_load_dwordx4 v184, s[60:63], s52 offen lds
	s_mov_b32 m0, s26
	s_nop 0
	buffer_load_dwordx4 v186, s[60:63], s52 offen lds
	s_waitcnt vmcnt(8)
	s_waitcnt lgkmcnt(0)
	s_setprio 1
	s_barrier
	v_mfma_f32_16x16x32_bf16 v[62:65], v[130:133], v[194:197], 0
	v_mfma_f32_16x16x32_bf16 v[58:61], v[138:141], v[194:197], 0
	v_mfma_f32_16x16x32_bf16 v[54:57], v[154:157], v[194:197], 0
	v_mfma_f32_16x16x32_bf16 v[50:53], v[178:181], v[194:197], 0
	v_mfma_f32_16x16x32_bf16 v[46:49], v[130:133], v[202:205], 0
	v_mfma_f32_16x16x32_bf16 v[42:45], v[138:141], v[202:205], 0
	v_mfma_f32_16x16x32_bf16 v[38:41], v[154:157], v[202:205], 0
	v_mfma_f32_16x16x32_bf16 v[34:37], v[178:181], v[202:205], 0
	v_mfma_f32_16x16x32_bf16 v[30:33], v[130:133], v[232:235], 0
	v_mfma_f32_16x16x32_bf16 v[26:29], v[138:141], v[232:235], 0
	v_mfma_f32_16x16x32_bf16 v[22:25], v[154:157], v[232:235], 0
	v_mfma_f32_16x16x32_bf16 v[18:21], v[178:181], v[232:235], 0
	v_mfma_f32_16x16x32_bf16 v[14:17], v[130:133], v[240:243], 0
	v_mfma_f32_16x16x32_bf16 v[10:13], v[138:141], v[240:243], 0
	v_mfma_f32_16x16x32_bf16 v[6:9], v[154:157], v[240:243], 0
	v_mfma_f32_16x16x32_bf16 v[2:5], v[178:181], v[240:243], 0
	v_mfma_f32_16x16x32_bf16 v[62:65], v[134:137], v[198:201], v[62:65]
	v_mfma_f32_16x16x32_bf16 v[58:61], v[142:145], v[198:201], v[58:61]
	v_mfma_f32_16x16x32_bf16 v[54:57], v[174:177], v[198:201], v[54:57]
	v_mfma_f32_16x16x32_bf16 v[50:53], v[190:193], v[198:201], v[50:53]
	v_mfma_f32_16x16x32_bf16 v[46:49], v[134:137], v[228:231], v[46:49]
	v_mfma_f32_16x16x32_bf16 v[42:45], v[142:145], v[228:231], v[42:45]
	v_mfma_f32_16x16x32_bf16 v[38:41], v[174:177], v[228:231], v[38:41]
	v_mfma_f32_16x16x32_bf16 v[34:37], v[190:193], v[228:231], v[34:37]
	v_mfma_f32_16x16x32_bf16 v[30:33], v[134:137], v[236:239], v[30:33]
	v_mfma_f32_16x16x32_bf16 v[26:29], v[142:145], v[236:239], v[26:29]
	v_mfma_f32_16x16x32_bf16 v[22:25], v[174:177], v[236:239], v[22:25]
	v_mfma_f32_16x16x32_bf16 v[18:21], v[190:193], v[236:239], v[18:21]
	v_mfma_f32_16x16x32_bf16 v[14:17], v[134:137], v[244:247], v[14:17]
	v_mfma_f32_16x16x32_bf16 v[10:13], v[142:145], v[244:247], v[10:13]
	v_mfma_f32_16x16x32_bf16 v[6:9], v[174:177], v[244:247], v[6:9]
	v_mfma_f32_16x16x32_bf16 v[2:5], v[190:193], v[244:247], v[2:5]
	s_barrier
	s_setprio 0
	v_add_u32_e32 v142, 0x18000, v188
	v_add_u32_e32 v182, 0x1c000, v188
	ds_read_b128 v[130:133], v142
	ds_read_b128 v[134:137], v142 offset:1024
	ds_read_b128 v[138:141], v142 offset:2048
	ds_read_b128 v[142:145], v142 offset:3072
	ds_read_b128 v[154:157], v182
	ds_read_b128 v[174:177], v182 offset:1024
	ds_read_b128 v[178:181], v182 offset:2048
	ds_read_b128 v[190:193], v182 offset:3072
	s_add_i32 s52, s52, 0x80000
	s_mov_b32 m0, s27
	ds_read_b128 v[194:197], v189 offset:32768
	ds_read_b128 v[198:201], v189 offset:33792
	ds_read_b128 v[202:205], v189 offset:34816
	ds_read_b128 v[228:231], v189 offset:35840
	ds_read_b128 v[232:235], v189 offset:36864
	ds_read_b128 v[236:239], v189 offset:37888
	ds_read_b128 v[240:243], v189 offset:38912
	ds_read_b128 v[244:247], v189 offset:39936
	buffer_load_dwordx4 v184, s[60:63], s52 offen lds
	s_mov_b32 m0, s30
	s_nop 0
	buffer_load_dwordx4 v186, s[60:63], s52 offen lds
	s_waitcnt vmcnt(8)
	s_waitcnt lgkmcnt(0)
	s_setprio 1
	s_barrier
	v_mfma_f32_16x16x32_bf16 v[126:129], v[130:133], v[194:197], v[126:129]
	v_mfma_f32_16x16x32_bf16 v[122:125], v[138:141], v[194:197], v[122:125]
	v_mfma_f32_16x16x32_bf16 v[118:121], v[154:157], v[194:197], v[118:121]
	v_mfma_f32_16x16x32_bf16 v[114:117], v[178:181], v[194:197], v[114:117]
	v_mfma_f32_16x16x32_bf16 v[110:113], v[130:133], v[202:205], v[110:113]
	v_mfma_f32_16x16x32_bf16 v[106:109], v[138:141], v[202:205], v[106:109]
	v_mfma_f32_16x16x32_bf16 v[102:105], v[154:157], v[202:205], v[102:105]
	v_mfma_f32_16x16x32_bf16 v[98:101], v[178:181], v[202:205], v[98:101]
	v_mfma_f32_16x16x32_bf16 v[94:97], v[130:133], v[232:235], v[94:97]
	v_mfma_f32_16x16x32_bf16 v[90:93], v[138:141], v[232:235], v[90:93]
	v_mfma_f32_16x16x32_bf16 v[86:89], v[154:157], v[232:235], v[86:89]
	v_mfma_f32_16x16x32_bf16 v[82:85], v[178:181], v[232:235], v[82:85]
	v_mfma_f32_16x16x32_bf16 v[78:81], v[130:133], v[240:243], v[78:81]
	v_mfma_f32_16x16x32_bf16 v[74:77], v[138:141], v[240:243], v[74:77]
	v_mfma_f32_16x16x32_bf16 v[70:73], v[154:157], v[240:243], v[70:73]
	v_mfma_f32_16x16x32_bf16 v[66:69], v[178:181], v[240:243], v[66:69]
	v_mfma_f32_16x16x32_bf16 v[126:129], v[134:137], v[198:201], v[126:129]
	v_mfma_f32_16x16x32_bf16 v[122:125], v[142:145], v[198:201], v[122:125]
	v_mfma_f32_16x16x32_bf16 v[118:121], v[174:177], v[198:201], v[118:121]
	v_mfma_f32_16x16x32_bf16 v[114:117], v[190:193], v[198:201], v[114:117]
	v_mfma_f32_16x16x32_bf16 v[110:113], v[134:137], v[228:231], v[110:113]
	v_mfma_f32_16x16x32_bf16 v[106:109], v[142:145], v[228:231], v[106:109]
	v_mfma_f32_16x16x32_bf16 v[102:105], v[174:177], v[228:231], v[102:105]
	v_mfma_f32_16x16x32_bf16 v[98:101], v[190:193], v[228:231], v[98:101]
	v_mfma_f32_16x16x32_bf16 v[94:97], v[134:137], v[236:239], v[94:97]
	v_mfma_f32_16x16x32_bf16 v[90:93], v[142:145], v[236:239], v[90:93]
	v_mfma_f32_16x16x32_bf16 v[86:89], v[174:177], v[236:239], v[86:89]
	v_mfma_f32_16x16x32_bf16 v[82:85], v[190:193], v[236:239], v[82:85]
	v_mfma_f32_16x16x32_bf16 v[78:81], v[134:137], v[244:247], v[78:81]
	v_mfma_f32_16x16x32_bf16 v[74:77], v[142:145], v[244:247], v[74:77]
	v_mfma_f32_16x16x32_bf16 v[70:73], v[174:177], v[244:247], v[70:73]
	v_mfma_f32_16x16x32_bf16 v[66:69], v[190:193], v[244:247], v[66:69]
	s_barrier
	s_setprio 0
	s_mov_b32 m0, s36
	s_or_b32 s52, s25, 0x80
	ds_read_b128 v[194:197], v189 offset:49152
	ds_read_b128 v[198:201], v189 offset:50176
	ds_read_b128 v[202:205], v189 offset:51200
	ds_read_b128 v[228:231], v189 offset:52224
	ds_read_b128 v[232:235], v189 offset:53248
	ds_read_b128 v[236:239], v189 offset:54272
	ds_read_b128 v[240:243], v189 offset:55296
	ds_read_b128 v[244:247], v189 offset:56320
	buffer_load_dwordx4 v185, s[44:47], s52 offen lds
	s_mov_b32 m0, s37
	s_add_i32 s25, s25, 0x80080
	buffer_load_dwordx4 v187, s[44:47], s52 offen lds
	s_mov_b32 m0, s66
	s_nop 0
	buffer_load_dwordx4 v185, s[44:47], s25 offen lds
	s_mov_b32 m0, s67
	s_nop 0
	buffer_load_dwordx4 v187, s[44:47], s25 offen lds
	s_mov_b32 m0, s48
	s_nop 0
	buffer_load_dwordx4 v184, s[60:63], s24 offen lds
	s_mov_b32 m0, s49
	s_nop 0
	buffer_load_dwordx4 v186, s[60:63], s24 offen lds
	s_waitcnt vmcnt(8)
	s_waitcnt lgkmcnt(0)
	s_setprio 1
	s_barrier
	v_mfma_f32_16x16x32_bf16 v[62:65], v[130:133], v[194:197], v[62:65]
	v_mfma_f32_16x16x32_bf16 v[58:61], v[138:141], v[194:197], v[58:61]
	v_mfma_f32_16x16x32_bf16 v[54:57], v[154:157], v[194:197], v[54:57]
	v_mfma_f32_16x16x32_bf16 v[50:53], v[178:181], v[194:197], v[50:53]
	v_mfma_f32_16x16x32_bf16 v[46:49], v[130:133], v[202:205], v[46:49]
	v_mfma_f32_16x16x32_bf16 v[42:45], v[138:141], v[202:205], v[42:45]
	v_mfma_f32_16x16x32_bf16 v[38:41], v[154:157], v[202:205], v[38:41]
	v_mfma_f32_16x16x32_bf16 v[34:37], v[178:181], v[202:205], v[34:37]
	v_mfma_f32_16x16x32_bf16 v[30:33], v[130:133], v[232:235], v[30:33]
	v_mfma_f32_16x16x32_bf16 v[26:29], v[138:141], v[232:235], v[26:29]
	v_mfma_f32_16x16x32_bf16 v[22:25], v[154:157], v[232:235], v[22:25]
	v_mfma_f32_16x16x32_bf16 v[18:21], v[178:181], v[232:235], v[18:21]
	v_mfma_f32_16x16x32_bf16 v[14:17], v[130:133], v[240:243], v[14:17]
	v_mfma_f32_16x16x32_bf16 v[10:13], v[138:141], v[240:243], v[10:13]
	v_mfma_f32_16x16x32_bf16 v[6:9], v[154:157], v[240:243], v[6:9]
	v_mfma_f32_16x16x32_bf16 v[2:5], v[178:181], v[240:243], v[2:5]
	v_mfma_f32_16x16x32_bf16 v[62:65], v[134:137], v[198:201], v[62:65]
	v_mfma_f32_16x16x32_bf16 v[58:61], v[142:145], v[198:201], v[58:61]
	v_mfma_f32_16x16x32_bf16 v[54:57], v[174:177], v[198:201], v[54:57]
	v_mfma_f32_16x16x32_bf16 v[50:53], v[190:193], v[198:201], v[50:53]
	v_mfma_f32_16x16x32_bf16 v[46:49], v[134:137], v[228:231], v[46:49]
	v_mfma_f32_16x16x32_bf16 v[42:45], v[142:145], v[228:231], v[42:45]
	v_mfma_f32_16x16x32_bf16 v[38:41], v[174:177], v[228:231], v[38:41]
	v_mfma_f32_16x16x32_bf16 v[34:37], v[190:193], v[228:231], v[34:37]
	v_mfma_f32_16x16x32_bf16 v[30:33], v[134:137], v[236:239], v[30:33]
	v_mfma_f32_16x16x32_bf16 v[26:29], v[142:145], v[236:239], v[26:29]
	v_mfma_f32_16x16x32_bf16 v[22:25], v[174:177], v[236:239], v[22:25]
	v_mfma_f32_16x16x32_bf16 v[18:21], v[190:193], v[236:239], v[18:21]
	v_mfma_f32_16x16x32_bf16 v[14:17], v[134:137], v[244:247], v[14:17]
	v_mfma_f32_16x16x32_bf16 v[10:13], v[142:145], v[244:247], v[10:13]
	v_mfma_f32_16x16x32_bf16 v[6:9], v[174:177], v[244:247], v[6:9]
	v_mfma_f32_16x16x32_bf16 v[2:5], v[190:193], v[244:247], v[2:5]
	s_barrier
	s_setprio 0
	s_add_i32 s22, s22, 2
	s_addk_i32 s13, 0x100
	s_addk_i32 s21, 0x100
	s_cmp_gt_u32 s22, 29
.LBB0_2450:
	v_add_u32_e32 v142, 0x10000, v188
	v_add_u32_e32 v182, 0x14000, v188
	ds_read_b128 v[130:133], v142
	ds_read_b128 v[134:137], v142 offset:1024
	ds_read_b128 v[138:141], v142 offset:2048
	ds_read_b128 v[142:145], v142 offset:3072
	ds_read_b128 v[154:157], v182
	ds_read_b128 v[174:177], v182 offset:1024
	ds_read_b128 v[178:181], v182 offset:2048
	ds_read_b128 v[190:193], v182 offset:3072
	s_add_i32 s24, s13, 0xfff80080
	s_cmp_eq_u32 s22, 28
	s_cselect_b32 s52, s8, s24
	s_cselect_b32 s25, s9, s21
	s_or_b32 s24, s52, 0x80
	s_mov_b32 m0, s68
	ds_read_b128 v[194:197], v189
	ds_read_b128 v[198:201], v189 offset:1024
	ds_read_b128 v[202:205], v189 offset:2048
	ds_read_b128 v[228:231], v189 offset:3072
	ds_read_b128 v[232:235], v189 offset:4096
	ds_read_b128 v[236:239], v189 offset:5120
	ds_read_b128 v[240:243], v189 offset:6144
	ds_read_b128 v[244:247], v189 offset:7168
	buffer_load_dwordx4 v184, s[60:63], s13 offen lds
	s_mov_b32 m0, s70
	s_nop 0
	buffer_load_dwordx4 v186, s[60:63], s13 offen lds
	s_waitcnt vmcnt(8)
	s_waitcnt lgkmcnt(0)
	s_setprio 1
	s_barrier
	v_mfma_f32_16x16x32_bf16 v[126:129], v[130:133], v[194:197], v[126:129]
	v_mfma_f32_16x16x32_bf16 v[122:125], v[138:141], v[194:197], v[122:125]
	v_mfma_f32_16x16x32_bf16 v[118:121], v[154:157], v[194:197], v[118:121]
	v_mfma_f32_16x16x32_bf16 v[114:117], v[178:181], v[194:197], v[114:117]
	v_mfma_f32_16x16x32_bf16 v[110:113], v[130:133], v[202:205], v[110:113]
	v_mfma_f32_16x16x32_bf16 v[106:109], v[138:141], v[202:205], v[106:109]
	v_mfma_f32_16x16x32_bf16 v[102:105], v[154:157], v[202:205], v[102:105]
	v_mfma_f32_16x16x32_bf16 v[98:101], v[178:181], v[202:205], v[98:101]
	v_mfma_f32_16x16x32_bf16 v[94:97], v[130:133], v[232:235], v[94:97]
	v_mfma_f32_16x16x32_bf16 v[90:93], v[138:141], v[232:235], v[90:93]
	v_mfma_f32_16x16x32_bf16 v[86:89], v[154:157], v[232:235], v[86:89]
	v_mfma_f32_16x16x32_bf16 v[82:85], v[178:181], v[232:235], v[82:85]
	v_mfma_f32_16x16x32_bf16 v[78:81], v[130:133], v[240:243], v[78:81]
	v_mfma_f32_16x16x32_bf16 v[74:77], v[138:141], v[240:243], v[74:77]
	v_mfma_f32_16x16x32_bf16 v[70:73], v[154:157], v[240:243], v[70:73]
	v_mfma_f32_16x16x32_bf16 v[66:69], v[178:181], v[240:243], v[66:69]
	v_mfma_f32_16x16x32_bf16 v[126:129], v[134:137], v[198:201], v[126:129]
	v_mfma_f32_16x16x32_bf16 v[122:125], v[142:145], v[198:201], v[122:125]
	v_mfma_f32_16x16x32_bf16 v[118:121], v[174:177], v[198:201], v[118:121]
	v_mfma_f32_16x16x32_bf16 v[114:117], v[190:193], v[198:201], v[114:117]
	v_mfma_f32_16x16x32_bf16 v[110:113], v[134:137], v[228:231], v[110:113]
	v_mfma_f32_16x16x32_bf16 v[106:109], v[142:145], v[228:231], v[106:109]
	v_mfma_f32_16x16x32_bf16 v[102:105], v[174:177], v[228:231], v[102:105]
	v_mfma_f32_16x16x32_bf16 v[98:101], v[190:193], v[228:231], v[98:101]
	v_mfma_f32_16x16x32_bf16 v[94:97], v[134:137], v[236:239], v[94:97]
	v_mfma_f32_16x16x32_bf16 v[90:93], v[142:145], v[236:239], v[90:93]
	v_mfma_f32_16x16x32_bf16 v[86:89], v[174:177], v[236:239], v[86:89]
	v_mfma_f32_16x16x32_bf16 v[82:85], v[190:193], v[236:239], v[82:85]
	v_mfma_f32_16x16x32_bf16 v[78:81], v[134:137], v[244:247], v[78:81]
	v_mfma_f32_16x16x32_bf16 v[74:77], v[142:145], v[244:247], v[74:77]
	v_mfma_f32_16x16x32_bf16 v[70:73], v[174:177], v[244:247], v[70:73]
	v_mfma_f32_16x16x32_bf16 v[66:69], v[190:193], v[244:247], v[66:69]
	s_barrier
	s_setprio 0
	s_mov_b32 m0, s16
	s_mov_b32 s46, s62
	s_mov_b32 s47, s63
	ds_read_b128 v[194:197], v189 offset:16384
	ds_read_b128 v[198:201], v189 offset:17408
	ds_read_b128 v[202:205], v189 offset:18432
	ds_read_b128 v[228:231], v189 offset:19456
	ds_read_b128 v[232:235], v189 offset:20480
	ds_read_b128 v[236:239], v189 offset:21504
	ds_read_b128 v[240:243], v189 offset:22528
	ds_read_b128 v[244:247], v189 offset:23552
	buffer_load_dwordx4 v185, s[44:47], s25 offen lds
	s_mov_b32 m0, s18
	s_add_i32 s53, s25, 0x80000
	buffer_load_dwordx4 v187, s[44:47], s25 offen lds
	s_mov_b32 m0, s19
	s_nop 0
	buffer_load_dwordx4 v185, s[44:47], s53 offen lds
	s_mov_b32 m0, s23
	s_nop 0
	buffer_load_dwordx4 v187, s[44:47], s53 offen lds
	s_mov_b32 m0, s15
	s_nop 0
	buffer_load_dwordx4 v184, s[60:63], s52 offen lds
	s_mov_b32 m0, s26
	s_nop 0
	buffer_load_dwordx4 v186, s[60:63], s52 offen lds
	s_waitcnt vmcnt(8)
	s_waitcnt lgkmcnt(0)
	s_setprio 1
	s_barrier
	v_mfma_f32_16x16x32_bf16 v[62:65], v[130:133], v[194:197], v[62:65]
	v_mfma_f32_16x16x32_bf16 v[58:61], v[138:141], v[194:197], v[58:61]
	v_mfma_f32_16x16x32_bf16 v[54:57], v[154:157], v[194:197], v[54:57]
	v_mfma_f32_16x16x32_bf16 v[50:53], v[178:181], v[194:197], v[50:53]
	v_mfma_f32_16x16x32_bf16 v[46:49], v[130:133], v[202:205], v[46:49]
	v_mfma_f32_16x16x32_bf16 v[42:45], v[138:141], v[202:205], v[42:45]
	v_mfma_f32_16x16x32_bf16 v[38:41], v[154:157], v[202:205], v[38:41]
	v_mfma_f32_16x16x32_bf16 v[34:37], v[178:181], v[202:205], v[34:37]
	v_mfma_f32_16x16x32_bf16 v[30:33], v[130:133], v[232:235], v[30:33]
	v_mfma_f32_16x16x32_bf16 v[26:29], v[138:141], v[232:235], v[26:29]
	v_mfma_f32_16x16x32_bf16 v[22:25], v[154:157], v[232:235], v[22:25]
	v_mfma_f32_16x16x32_bf16 v[18:21], v[178:181], v[232:235], v[18:21]
	v_mfma_f32_16x16x32_bf16 v[14:17], v[130:133], v[240:243], v[14:17]
	v_mfma_f32_16x16x32_bf16 v[10:13], v[138:141], v[240:243], v[10:13]
	v_mfma_f32_16x16x32_bf16 v[6:9], v[154:157], v[240:243], v[6:9]
	v_mfma_f32_16x16x32_bf16 v[2:5], v[178:181], v[240:243], v[2:5]
	v_mfma_f32_16x16x32_bf16 v[62:65], v[134:137], v[198:201], v[62:65]
	v_mfma_f32_16x16x32_bf16 v[58:61], v[142:145], v[198:201], v[58:61]
	v_mfma_f32_16x16x32_bf16 v[54:57], v[174:177], v[198:201], v[54:57]
	v_mfma_f32_16x16x32_bf16 v[50:53], v[190:193], v[198:201], v[50:53]
	v_mfma_f32_16x16x32_bf16 v[46:49], v[134:137], v[228:231], v[46:49]
	v_mfma_f32_16x16x32_bf16 v[42:45], v[142:145], v[228:231], v[42:45]
	v_mfma_f32_16x16x32_bf16 v[38:41], v[174:177], v[228:231], v[38:41]
	v_mfma_f32_16x16x32_bf16 v[34:37], v[190:193], v[228:231], v[34:37]
	v_mfma_f32_16x16x32_bf16 v[30:33], v[134:137], v[236:239], v[30:33]
	v_mfma_f32_16x16x32_bf16 v[26:29], v[142:145], v[236:239], v[26:29]
	v_mfma_f32_16x16x32_bf16 v[22:25], v[174:177], v[236:239], v[22:25]
	v_mfma_f32_16x16x32_bf16 v[18:21], v[190:193], v[236:239], v[18:21]
	v_mfma_f32_16x16x32_bf16 v[14:17], v[134:137], v[244:247], v[14:17]
	v_mfma_f32_16x16x32_bf16 v[10:13], v[142:145], v[244:247], v[10:13]
	v_mfma_f32_16x16x32_bf16 v[6:9], v[174:177], v[244:247], v[6:9]
	v_mfma_f32_16x16x32_bf16 v[2:5], v[190:193], v[244:247], v[2:5]
	s_barrier
	s_setprio 0
	v_add_u32_e32 v142, 0x18000, v188
	v_add_u32_e32 v182, 0x1c000, v188
	ds_read_b128 v[130:133], v142
	ds_read_b128 v[134:137], v142 offset:1024
	ds_read_b128 v[138:141], v142 offset:2048
	ds_read_b128 v[142:145], v142 offset:3072
	ds_read_b128 v[154:157], v182
	ds_read_b128 v[174:177], v182 offset:1024
	ds_read_b128 v[178:181], v182 offset:2048
	ds_read_b128 v[190:193], v182 offset:3072
	s_add_i32 s52, s52, 0x80000
	s_mov_b32 m0, s27
	ds_read_b128 v[194:197], v189 offset:32768
	ds_read_b128 v[198:201], v189 offset:33792
	ds_read_b128 v[202:205], v189 offset:34816
	ds_read_b128 v[228:231], v189 offset:35840
	ds_read_b128 v[232:235], v189 offset:36864
	ds_read_b128 v[236:239], v189 offset:37888
	ds_read_b128 v[240:243], v189 offset:38912
	ds_read_b128 v[244:247], v189 offset:39936
	buffer_load_dwordx4 v184, s[60:63], s52 offen lds
	s_mov_b32 m0, s30
	s_nop 0
	buffer_load_dwordx4 v186, s[60:63], s52 offen lds
	s_waitcnt vmcnt(8)
	s_waitcnt lgkmcnt(0)
	s_setprio 1
	s_barrier
	v_mfma_f32_16x16x32_bf16 v[126:129], v[130:133], v[194:197], v[126:129]
	v_mfma_f32_16x16x32_bf16 v[122:125], v[138:141], v[194:197], v[122:125]
	v_mfma_f32_16x16x32_bf16 v[118:121], v[154:157], v[194:197], v[118:121]
	v_mfma_f32_16x16x32_bf16 v[114:117], v[178:181], v[194:197], v[114:117]
	v_mfma_f32_16x16x32_bf16 v[110:113], v[130:133], v[202:205], v[110:113]
	v_mfma_f32_16x16x32_bf16 v[106:109], v[138:141], v[202:205], v[106:109]
	v_mfma_f32_16x16x32_bf16 v[102:105], v[154:157], v[202:205], v[102:105]
	v_mfma_f32_16x16x32_bf16 v[98:101], v[178:181], v[202:205], v[98:101]
	v_mfma_f32_16x16x32_bf16 v[94:97], v[130:133], v[232:235], v[94:97]
	v_mfma_f32_16x16x32_bf16 v[90:93], v[138:141], v[232:235], v[90:93]
	v_mfma_f32_16x16x32_bf16 v[86:89], v[154:157], v[232:235], v[86:89]
	v_mfma_f32_16x16x32_bf16 v[82:85], v[178:181], v[232:235], v[82:85]
	v_mfma_f32_16x16x32_bf16 v[78:81], v[130:133], v[240:243], v[78:81]
	v_mfma_f32_16x16x32_bf16 v[74:77], v[138:141], v[240:243], v[74:77]
	v_mfma_f32_16x16x32_bf16 v[70:73], v[154:157], v[240:243], v[70:73]
	v_mfma_f32_16x16x32_bf16 v[66:69], v[178:181], v[240:243], v[66:69]
	v_mfma_f32_16x16x32_bf16 v[126:129], v[134:137], v[198:201], v[126:129]
	v_mfma_f32_16x16x32_bf16 v[122:125], v[142:145], v[198:201], v[122:125]
	v_mfma_f32_16x16x32_bf16 v[118:121], v[174:177], v[198:201], v[118:121]
	v_mfma_f32_16x16x32_bf16 v[114:117], v[190:193], v[198:201], v[114:117]
	v_mfma_f32_16x16x32_bf16 v[110:113], v[134:137], v[228:231], v[110:113]
	v_mfma_f32_16x16x32_bf16 v[106:109], v[142:145], v[228:231], v[106:109]
	v_mfma_f32_16x16x32_bf16 v[102:105], v[174:177], v[228:231], v[102:105]
	v_mfma_f32_16x16x32_bf16 v[98:101], v[190:193], v[228:231], v[98:101]
	v_mfma_f32_16x16x32_bf16 v[94:97], v[134:137], v[236:239], v[94:97]
	v_mfma_f32_16x16x32_bf16 v[90:93], v[142:145], v[236:239], v[90:93]
	v_mfma_f32_16x16x32_bf16 v[86:89], v[174:177], v[236:239], v[86:89]
	v_mfma_f32_16x16x32_bf16 v[82:85], v[190:193], v[236:239], v[82:85]
	v_mfma_f32_16x16x32_bf16 v[78:81], v[134:137], v[244:247], v[78:81]
	v_mfma_f32_16x16x32_bf16 v[74:77], v[142:145], v[244:247], v[74:77]
	v_mfma_f32_16x16x32_bf16 v[70:73], v[174:177], v[244:247], v[70:73]
	v_mfma_f32_16x16x32_bf16 v[66:69], v[190:193], v[244:247], v[66:69]
	s_barrier
	s_setprio 0
	s_mov_b32 m0, s36
	s_or_b32 s52, s25, 0x80
	ds_read_b128 v[194:197], v189 offset:49152
	ds_read_b128 v[198:201], v189 offset:50176
	ds_read_b128 v[202:205], v189 offset:51200
	ds_read_b128 v[228:231], v189 offset:52224
	ds_read_b128 v[232:235], v189 offset:53248
	ds_read_b128 v[236:239], v189 offset:54272
	ds_read_b128 v[240:243], v189 offset:55296
	ds_read_b128 v[244:247], v189 offset:56320
	buffer_load_dwordx4 v185, s[44:47], s52 offen lds
	s_mov_b32 m0, s37
	s_add_i32 s25, s25, 0x80080
	buffer_load_dwordx4 v187, s[44:47], s52 offen lds
	s_mov_b32 m0, s66
	s_nop 0
	buffer_load_dwordx4 v185, s[44:47], s25 offen lds
	s_mov_b32 m0, s67
	s_nop 0
	buffer_load_dwordx4 v187, s[44:47], s25 offen lds
	s_mov_b32 m0, s48
	s_nop 0
	buffer_load_dwordx4 v184, s[60:63], s24 offen lds
	s_mov_b32 m0, s49
	s_nop 0
	buffer_load_dwordx4 v186, s[60:63], s24 offen lds
	s_waitcnt vmcnt(8)
	s_waitcnt lgkmcnt(0)
	s_setprio 1
	s_barrier
	v_mfma_f32_16x16x32_bf16 v[62:65], v[130:133], v[194:197], v[62:65]
	v_mfma_f32_16x16x32_bf16 v[58:61], v[138:141], v[194:197], v[58:61]
	v_mfma_f32_16x16x32_bf16 v[54:57], v[154:157], v[194:197], v[54:57]
	v_mfma_f32_16x16x32_bf16 v[50:53], v[178:181], v[194:197], v[50:53]
	v_mfma_f32_16x16x32_bf16 v[46:49], v[130:133], v[202:205], v[46:49]
	v_mfma_f32_16x16x32_bf16 v[42:45], v[138:141], v[202:205], v[42:45]
	v_mfma_f32_16x16x32_bf16 v[38:41], v[154:157], v[202:205], v[38:41]
	v_mfma_f32_16x16x32_bf16 v[34:37], v[178:181], v[202:205], v[34:37]
	v_mfma_f32_16x16x32_bf16 v[30:33], v[130:133], v[232:235], v[30:33]
	v_mfma_f32_16x16x32_bf16 v[26:29], v[138:141], v[232:235], v[26:29]
	v_mfma_f32_16x16x32_bf16 v[22:25], v[154:157], v[232:235], v[22:25]
	v_mfma_f32_16x16x32_bf16 v[18:21], v[178:181], v[232:235], v[18:21]
	v_mfma_f32_16x16x32_bf16 v[14:17], v[130:133], v[240:243], v[14:17]
	v_mfma_f32_16x16x32_bf16 v[10:13], v[138:141], v[240:243], v[10:13]
	v_mfma_f32_16x16x32_bf16 v[6:9], v[154:157], v[240:243], v[6:9]
	v_mfma_f32_16x16x32_bf16 v[2:5], v[178:181], v[240:243], v[2:5]
	v_mfma_f32_16x16x32_bf16 v[62:65], v[134:137], v[198:201], v[62:65]
	v_mfma_f32_16x16x32_bf16 v[58:61], v[142:145], v[198:201], v[58:61]
	v_mfma_f32_16x16x32_bf16 v[54:57], v[174:177], v[198:201], v[54:57]
	v_mfma_f32_16x16x32_bf16 v[50:53], v[190:193], v[198:201], v[50:53]
	v_mfma_f32_16x16x32_bf16 v[46:49], v[134:137], v[228:231], v[46:49]
	v_mfma_f32_16x16x32_bf16 v[42:45], v[142:145], v[228:231], v[42:45]
	v_mfma_f32_16x16x32_bf16 v[38:41], v[174:177], v[228:231], v[38:41]
	v_mfma_f32_16x16x32_bf16 v[34:37], v[190:193], v[228:231], v[34:37]
	v_mfma_f32_16x16x32_bf16 v[30:33], v[134:137], v[236:239], v[30:33]
	v_mfma_f32_16x16x32_bf16 v[26:29], v[142:145], v[236:239], v[26:29]
	v_mfma_f32_16x16x32_bf16 v[22:25], v[174:177], v[236:239], v[22:25]
	v_mfma_f32_16x16x32_bf16 v[18:21], v[190:193], v[236:239], v[18:21]
	v_mfma_f32_16x16x32_bf16 v[14:17], v[134:137], v[244:247], v[14:17]
	v_mfma_f32_16x16x32_bf16 v[10:13], v[142:145], v[244:247], v[10:13]
	v_mfma_f32_16x16x32_bf16 v[6:9], v[174:177], v[244:247], v[6:9]
	v_mfma_f32_16x16x32_bf16 v[2:5], v[190:193], v[244:247], v[2:5]
	s_barrier
	s_setprio 0
	s_add_i32 s22, s22, 2
	s_addk_i32 s13, 0x100
	s_addk_i32 s21, 0x100
	s_cmp_gt_u32 s22, 29
	s_cbranch_scc0 .LBB0_2450
	s_and_b64 vcc, exec, s[64:65]
	s_cbranch_vccz .LBB0_2453
	s_barrier
